# speedup vs baseline: 1.0392x; 1.0080x over previous
.LBB0_86:
	s_ashr_i32 s37, s36, 31
	s_lshl_b64 s[36:37], s[36:37], 20
	s_add_u32 s36, s48, s36
	s_addc_u32 s37, s49, s37
	s_ashr_i32 s5, s4, 31
	v_lshlrev_b32_e32 v3, 6, v1
	s_lshl_b64 s[4:5], s[4:5], 20
	v_and_b32_e32 v2, 48, v1
	v_and_b32_e32 v4, 0x3c0, v3
	v_lshlrev_b32_e32 v1, 2, v1
	s_add_u32 s4, s46, s4
	v_or_b32_e32 v5, v4, v2
	v_and_b32_e32 v1, 32, v1
	v_lshlrev_b32_e32 v0, 13, v0
	s_mov_b32 s72, 0x18000
	s_addc_u32 s5, s47, s5
	v_and_b32_e32 v111, 0x6000, v0
	s_add_i32 s40, s1, 0x10000
	s_add_i32 s41, s1, 0x18000
	s_add_i32 s64, s1, 0x12000
	s_add_i32 s65, s1, 0x1a000
	s_add_i32 s68, s1, 0x14000
	s_add_i32 s69, s1, 0x1c000
	s_add_i32 s70, s1, 0x16000
	s_add_i32 s71, s1, 0x1e000
	v_bitop3_b32 v0, v5, s72, v1 bitop3:0xde
	s_mov_b32 s72, 0x10400
	v_bitop3_b32 v149, v5, s72, v1 bitop3:0xde
	s_add_u32 s72, s44, s2
	s_addc_u32 s73, s45, s3
	s_add_i32 s2, s74, s75
	s_ashr_i32 s3, s2, 31
	s_waitcnt vmcnt(0)
	s_lshl_b64 s[2:3], s[2:3], 20
	v_bitop3_b32 v110, v4, v1, v2 bitop3:0x36
	v_and_b32_e32 v112, 0xffffc000, v3
	s_add_u32 s74, s10, s2
	v_mov_b32_e32 v4, 0
	v_or_b32_e32 v113, 0x800, v112
	v_or_b32_e32 v114, 0x1000, v112
	v_or_b32_e32 v115, 0x1800, v112
	v_or_b32_e32 v116, 0x2000, v112
	v_or_b32_e32 v117, 0x2800, v112
	v_or_b32_e32 v118, 0x3000, v112
	v_or_b32_e32 v119, 0x3800, v112
	v_bitop3_b32 v145, v5, s33, v1 bitop3:0xde
	s_addc_u32 s75, s11, s3
	s_mov_b64 s[2:3], 0
	s_mov_b32 s76, 1
	v_add_u32_e32 v150, v0, v111
	v_mov_b32_e32 v5, v4
	v_mov_b32_e32 v6, v4
	v_mov_b32_e32 v7, v4
	v_mov_b32_e32 v72, v4
	v_mov_b32_e32 v73, v4
	v_mov_b32_e32 v74, v4
	v_mov_b32_e32 v75, v4
	v_mov_b32_e32 v12, v4
	v_mov_b32_e32 v13, v4
	v_mov_b32_e32 v14, v4
	v_mov_b32_e32 v15, v4
	v_mov_b32_e32 v76, v4
	v_mov_b32_e32 v77, v4
	v_mov_b32_e32 v78, v4
	v_mov_b32_e32 v79, v4
	v_mov_b32_e32 v16, v4
	v_mov_b32_e32 v17, v4
	v_mov_b32_e32 v18, v4
	v_mov_b32_e32 v19, v4
	v_mov_b32_e32 v80, v4
	v_mov_b32_e32 v81, v4
	v_mov_b32_e32 v82, v4
	v_mov_b32_e32 v83, v4
	v_mov_b32_e32 v20, v4
	v_mov_b32_e32 v21, v4
	v_mov_b32_e32 v22, v4
	v_mov_b32_e32 v23, v4
	v_mov_b32_e32 v84, v4
	v_mov_b32_e32 v85, v4
	v_mov_b32_e32 v86, v4
	v_mov_b32_e32 v87, v4
	v_mov_b32_e32 v24, v4
	v_mov_b32_e32 v25, v4
	v_mov_b32_e32 v26, v4
	v_mov_b32_e32 v27, v4
	v_mov_b32_e32 v88, v4
	v_mov_b32_e32 v89, v4
	v_mov_b32_e32 v90, v4
	v_mov_b32_e32 v91, v4
	v_mov_b32_e32 v28, v4
	v_mov_b32_e32 v29, v4
	v_mov_b32_e32 v30, v4
	v_mov_b32_e32 v31, v4
	v_mov_b32_e32 v92, v4
	v_mov_b32_e32 v93, v4
	v_mov_b32_e32 v94, v4
	v_mov_b32_e32 v95, v4
	v_mov_b32_e32 v32, v4
	v_mov_b32_e32 v33, v4
	v_mov_b32_e32 v34, v4
	v_mov_b32_e32 v35, v4
	v_mov_b32_e32 v96, v4
	v_mov_b32_e32 v97, v4
	v_mov_b32_e32 v98, v4
	v_mov_b32_e32 v99, v4
	v_mov_b32_e32 v36, v4
	v_mov_b32_e32 v37, v4
	v_mov_b32_e32 v38, v4
	v_mov_b32_e32 v39, v4
	v_mov_b32_e32 v100, v4
	v_mov_b32_e32 v101, v4
	v_mov_b32_e32 v102, v4
	v_mov_b32_e32 v103, v4
	v_mov_b32_e32 v40, v4
	v_mov_b32_e32 v41, v4
	v_mov_b32_e32 v42, v4
	v_mov_b32_e32 v43, v4
	v_mov_b32_e32 v120, v4
	v_mov_b32_e32 v121, v4
	v_mov_b32_e32 v122, v4
	v_mov_b32_e32 v123, v4
	v_mov_b32_e32 v44, v4
	v_mov_b32_e32 v45, v4
	v_mov_b32_e32 v46, v4
	v_mov_b32_e32 v47, v4
	v_mov_b32_e32 v124, v4
	v_mov_b32_e32 v125, v4
	v_mov_b32_e32 v126, v4
	v_mov_b32_e32 v127, v4
	v_mov_b32_e32 v48, v4
	v_mov_b32_e32 v49, v4
	v_mov_b32_e32 v50, v4
	v_mov_b32_e32 v51, v4
	v_mov_b32_e32 v128, v4
	v_mov_b32_e32 v129, v4
	v_mov_b32_e32 v130, v4
	v_mov_b32_e32 v131, v4
	v_mov_b32_e32 v52, v4
	v_mov_b32_e32 v53, v4
	v_mov_b32_e32 v54, v4
	v_mov_b32_e32 v55, v4
	v_mov_b32_e32 v132, v4
	v_mov_b32_e32 v133, v4
	v_mov_b32_e32 v134, v4
	v_mov_b32_e32 v135, v4
	v_mov_b32_e32 v56, v4
	v_mov_b32_e32 v57, v4
	v_mov_b32_e32 v58, v4
	v_mov_b32_e32 v59, v4
	v_mov_b32_e32 v136, v4
	v_mov_b32_e32 v137, v4
	v_mov_b32_e32 v138, v4
	v_mov_b32_e32 v139, v4
	v_mov_b32_e32 v60, v4
	v_mov_b32_e32 v61, v4
	v_mov_b32_e32 v62, v4
	v_mov_b32_e32 v63, v4
	v_mov_b32_e32 v140, v4
	v_mov_b32_e32 v141, v4
	v_mov_b32_e32 v142, v4
	v_mov_b32_e32 v143, v4
	v_mov_b32_e32 v64, v4
	v_mov_b32_e32 v65, v4
	v_mov_b32_e32 v66, v4
	v_mov_b32_e32 v67, v4
	v_mov_b32_e32 v0, v4
	v_mov_b32_e32 v1, v4
	v_mov_b32_e32 v2, v4
	v_mov_b32_e32 v3, v4
	v_mov_b32_e32 v68, v4
	v_mov_b32_e32 v69, v4
	v_mov_b32_e32 v70, v4
	v_mov_b32_e32 v71, v4
	v_mov_b32_e32 v8, v4
	v_mov_b32_e32 v9, v4
	v_mov_b32_e32 v10, v4
	v_mov_b32_e32 v11, v4
	s_waitcnt lgkmcnt(0)
	s_barrier
	s_add_u32 s77, s74, s2
	s_addc_u32 s82, s75, s3
	s_add_u32 s78, s77, 0x1b900080
	s_addc_u32 s79, s82, 0
	s_add_u32 s83, s72, s2
	s_addc_u32 s84, s73, s3
	s_add_u32 s80, s83, 0x3400080
	s_addc_u32 s81, s84, 0
	v_add_u32_e32 v151, v110, v111
	v_add_u32_e32 v189, v110, v112
	ds_read_b128 v[152:155], v151 offset:32768
	ds_read_b128 v[156:159], v189
	s_mov_b32 m0, s41
	s_nop 0
	global_load_lds_dwordx4 v104, s[80:81]
	ds_read_b128 v[160:163], v151 offset:34816
	s_mov_b32 m0, s65
	s_nop 0
	global_load_lds_dwordx4 v106, s[80:81]
	ds_read_b128 v[164:167], v189 offset:2048
	ds_read_b128 v[168:171], v151 offset:36864
	s_mov_b32 m0, s69
	s_nop 0
	global_load_lds_dwordx4 v108, s[80:81]
	ds_read_b128 v[172:175], v151 offset:38912
	ds_read_b128 v[176:179], v189 offset:4096
	ds_read_b128 v[180:183], v189 offset:6144
	s_branch .Lmy_rot_87
.LBB0_87:
	s_add_u32 s77, s74, s2
	s_addc_u32 s82, s75, s3
	s_add_u32 s78, s77, 0x1b900080
	s_addc_u32 s79, s82, 0
	s_add_u32 s83, s72, s2
	s_addc_u32 s84, s73, s3
	s_add_u32 s80, s83, 0x3400080
	s_addc_u32 s81, s84, 0
	v_add_u32_e32 v151, v110, v111
	v_add_u32_e32 v189, v110, v112
	ds_read_b128 v[152:155], v151 offset:32768
	ds_read_b128 v[156:159], v189
	s_mov_b32 m0, s41
	v_mfma_f32_16x16x32_bf16 v[76:79], v[160:163], v[176:179], v[76:79]
	global_load_lds_dwordx4 v104, s[80:81]
	v_mfma_f32_16x16x32_bf16 v[64:67], v[160:163], v[180:183], v[64:67]
	ds_read_b128 v[160:163], v151 offset:34816
	v_mfma_f32_16x16x32_bf16 v[12:15], v[164:167], v[176:179], v[12:15]
	s_mov_b32 m0, s65
	v_mfma_f32_16x16x32_bf16 v[0:3], v[164:167], v[180:183], v[0:3]
	global_load_lds_dwordx4 v106, s[80:81]
	ds_read_b128 v[164:167], v189 offset:2048
	v_mfma_f32_16x16x32_bf16 v[72:75], v[168:171], v[176:179], v[72:75]
	v_mfma_f32_16x16x32_bf16 v[68:71], v[168:171], v[180:183], v[68:71]
	ds_read_b128 v[168:171], v151 offset:36864
	s_mov_b32 m0, s69
	v_mfma_f32_16x16x32_bf16 v[4:7], v[172:175], v[176:179], v[4:7]
	global_load_lds_dwordx4 v108, s[80:81]
	v_mfma_f32_16x16x32_bf16 v[8:11], v[172:175], v[180:183], v[8:11]
	ds_read_b128 v[172:175], v151 offset:38912
	ds_read_b128 v[176:179], v189 offset:4096
	ds_read_b128 v[180:183], v189 offset:6144
.Lmy_rot_87:
	s_waitcnt lgkmcnt(6)
	v_mfma_f32_16x16x32_bf16 v[140:143], v[152:155], v[156:159], v[140:143]
	s_waitcnt lgkmcnt(5)
	s_mov_b32 m0, s71
	v_mfma_f32_16x16x32_bf16 v[60:63], v[160:163], v[156:159], v[60:63]
	global_load_lds_dwordx4 v146, s[80:81]
	s_waitcnt lgkmcnt(4)
	v_mfma_f32_16x16x32_bf16 v[132:135], v[152:155], v[164:167], v[132:135]
	v_mfma_f32_16x16x32_bf16 v[52:55], v[160:163], v[164:167], v[52:55]
	s_waitcnt lgkmcnt(3)
	s_mov_b32 m0, s40
	v_mfma_f32_16x16x32_bf16 v[136:139], v[168:171], v[156:159], v[136:139]
	global_load_lds_dwordx4 v104, s[78:79]
	v_mfma_f32_16x16x32_bf16 v[128:131], v[168:171], v[164:167], v[128:131]
	s_waitcnt lgkmcnt(2)
	v_mfma_f32_16x16x32_bf16 v[56:59], v[172:175], v[156:159], v[56:59]
	ds_read_b128 v[156:159], v189 offset:8192
	s_mov_b32 m0, s64
	v_mfma_f32_16x16x32_bf16 v[48:51], v[172:175], v[164:167], v[48:51]
	global_load_lds_dwordx4 v106, s[78:79]
	ds_read_b128 v[164:167], v189 offset:10240
	s_waitcnt lgkmcnt(3)
	v_mfma_f32_16x16x32_bf16 v[124:127], v[152:155], v[176:179], v[124:127]
	v_mfma_f32_16x16x32_bf16 v[44:47], v[160:163], v[176:179], v[44:47]
	s_mov_b32 m0, s68
	v_mfma_f32_16x16x32_bf16 v[120:123], v[168:171], v[176:179], v[120:123]
	global_load_lds_dwordx4 v108, s[78:79]
	v_mfma_f32_16x16x32_bf16 v[40:43], v[172:175], v[176:179], v[40:43]
	ds_read_b128 v[176:179], v189 offset:12288
	s_waitcnt lgkmcnt(3)
	v_mfma_f32_16x16x32_bf16 v[100:103], v[152:155], v[180:183], v[100:103]
	s_mov_b32 m0, s70
	v_mfma_f32_16x16x32_bf16 v[36:39], v[160:163], v[180:183], v[36:39]
	global_load_lds_dwordx4 v146, s[78:79]
	v_mfma_f32_16x16x32_bf16 v[96:99], v[168:171], v[180:183], v[96:99]
	v_mfma_f32_16x16x32_bf16 v[32:35], v[172:175], v[180:183], v[32:35]
	ds_read_b128 v[180:183], v189 offset:14336
	s_waitcnt lgkmcnt(3)
	v_mfma_f32_16x16x32_bf16 v[28:31], v[160:163], v[156:159], v[28:31]
	s_waitcnt lgkmcnt(2)
	v_mfma_f32_16x16x32_bf16 v[20:23], v[160:163], v[164:167], v[20:23]
	s_waitcnt lgkmcnt(1)
	v_mfma_f32_16x16x32_bf16 v[12:15], v[160:163], v[176:179], v[12:15]
	s_waitcnt lgkmcnt(0)
	v_mfma_f32_16x16x32_bf16 v[0:3], v[160:163], v[180:183], v[0:3]
	ds_read_b128 v[160:163], v151 offset:33792
	v_mfma_f32_16x16x32_bf16 v[92:95], v[152:155], v[156:159], v[92:95]
	v_mfma_f32_16x16x32_bf16 v[84:87], v[152:155], v[164:167], v[84:87]
	v_mfma_f32_16x16x32_bf16 v[76:79], v[152:155], v[176:179], v[76:79]
	v_mfma_f32_16x16x32_bf16 v[64:67], v[152:155], v[180:183], v[64:67]
	ds_read_b128 v[152:155], v189 offset:1024
	v_mfma_f32_16x16x32_bf16 v[80:83], v[168:171], v[164:167], v[80:83]
	v_mfma_f32_16x16x32_bf16 v[16:19], v[172:175], v[164:167], v[16:19]
	ds_read_b128 v[164:167], v151 offset:35840
	v_mfma_f32_16x16x32_bf16 v[88:91], v[168:171], v[156:159], v[88:91]
	v_mfma_f32_16x16x32_bf16 v[24:27], v[172:175], v[156:159], v[24:27]
	ds_read_b128 v[156:159], v189 offset:3072
	v_mfma_f32_16x16x32_bf16 v[72:75], v[168:171], v[176:179], v[72:75]
	v_mfma_f32_16x16x32_bf16 v[4:7], v[172:175], v[176:179], v[4:7]
	ds_read_b128 v[176:179], v189 offset:5120
	v_mfma_f32_16x16x32_bf16 v[68:71], v[168:171], v[180:183], v[68:71]
	ds_read_b128 v[168:171], v151 offset:37888
	v_mfma_f32_16x16x32_bf16 v[8:11], v[172:175], v[180:183], v[8:11]
	ds_read_b128 v[172:175], v151 offset:39936
	ds_read_b128 v[180:183], v189 offset:7168
	s_waitcnt lgkmcnt(6)
	v_mfma_f32_16x16x32_bf16 v[140:143], v[160:163], v[152:155], v[140:143]
	s_waitcnt lgkmcnt(5)
	v_mfma_f32_16x16x32_bf16 v[60:63], v[164:167], v[152:155], v[60:63]
	s_waitcnt lgkmcnt(4)
	v_mfma_f32_16x16x32_bf16 v[132:135], v[160:163], v[156:159], v[132:135]
	v_mfma_f32_16x16x32_bf16 v[52:55], v[164:167], v[156:159], v[52:55]
	s_waitcnt lgkmcnt(3)
	v_mfma_f32_16x16x32_bf16 v[124:127], v[160:163], v[176:179], v[124:127]
	v_mfma_f32_16x16x32_bf16 v[44:47], v[164:167], v[176:179], v[44:47]
	s_waitcnt lgkmcnt(2)
	v_mfma_f32_16x16x32_bf16 v[136:139], v[168:171], v[152:155], v[136:139]
	s_waitcnt lgkmcnt(1)
	v_mfma_f32_16x16x32_bf16 v[56:59], v[172:175], v[152:155], v[56:59]
	ds_read_b128 v[152:155], v189 offset:9216
	v_mfma_f32_16x16x32_bf16 v[128:131], v[168:171], v[156:159], v[128:131]
	v_mfma_f32_16x16x32_bf16 v[48:51], v[172:175], v[156:159], v[48:51]
	ds_read_b128 v[156:159], v189 offset:11264
	v_mfma_f32_16x16x32_bf16 v[120:123], v[168:171], v[176:179], v[120:123]
	v_mfma_f32_16x16x32_bf16 v[40:43], v[172:175], v[176:179], v[40:43]
	ds_read_b128 v[176:179], v189 offset:13312
	s_waitcnt lgkmcnt(3)
	v_mfma_f32_16x16x32_bf16 v[100:103], v[160:163], v[180:183], v[100:103]
	v_mfma_f32_16x16x32_bf16 v[36:39], v[164:167], v[180:183], v[36:39]
	v_mfma_f32_16x16x32_bf16 v[96:99], v[168:171], v[180:183], v[96:99]
	v_mfma_f32_16x16x32_bf16 v[32:35], v[172:175], v[180:183], v[32:35]
	ds_read_b128 v[180:183], v189 offset:15360
	s_waitcnt lgkmcnt(3)
	v_mfma_f32_16x16x32_bf16 v[92:95], v[160:163], v[152:155], v[92:95]
	v_mfma_f32_16x16x32_bf16 v[28:31], v[164:167], v[152:155], v[28:31]
	v_mfma_f32_16x16x32_bf16 v[88:91], v[168:171], v[152:155], v[88:91]
	v_mfma_f32_16x16x32_bf16 v[24:27], v[172:175], v[152:155], v[24:27]
	s_waitcnt lgkmcnt(2)
	v_mfma_f32_16x16x32_bf16 v[84:87], v[160:163], v[156:159], v[84:87]
	v_mfma_f32_16x16x32_bf16 v[20:23], v[164:167], v[156:159], v[20:23]
	v_mfma_f32_16x16x32_bf16 v[80:83], v[168:171], v[156:159], v[80:83]
	v_mfma_f32_16x16x32_bf16 v[16:19], v[172:175], v[156:159], v[16:19]
	s_add_u32 s77, s77, 0x1b900100
	s_addc_u32 s78, s82, 0
	s_add_u32 s80, s83, 0x3400100
	s_addc_u32 s81, s84, 0
	s_cmp_lt_u32 s76, 31
	s_cselect_b32 s79, s78, s37
	s_cselect_b32 s78, s77, s36
	s_waitcnt vmcnt(0)
	s_waitcnt lgkmcnt(0)
	s_barrier
	s_cselect_b32 s81, s81, s5
	s_cselect_b32 s80, s80, s4
	ds_read_b128 v[152:155], v150
	v_add_u32_e32 v151, v145, v112
	ds_read_b128 v[156:159], v151
	s_mov_b32 m0, s39
	v_mfma_f32_16x16x32_bf16 v[76:79], v[160:163], v[176:179], v[76:79]
	global_load_lds_dwordx4 v104, s[80:81]
	v_mfma_f32_16x16x32_bf16 v[64:67], v[160:163], v[180:183], v[64:67]
	ds_read_b128 v[160:163], v150 offset:2048
	v_mfma_f32_16x16x32_bf16 v[12:15], v[164:167], v[176:179], v[12:15]
	s_mov_b32 m0, s54
	v_mfma_f32_16x16x32_bf16 v[0:3], v[164:167], v[180:183], v[0:3]
	global_load_lds_dwordx4 v106, s[80:81]
	v_add_u32_e32 v151, v145, v113
	ds_read_b128 v[164:167], v151
	v_mfma_f32_16x16x32_bf16 v[72:75], v[168:171], v[176:179], v[72:75]
	v_mfma_f32_16x16x32_bf16 v[68:71], v[168:171], v[180:183], v[68:71]
	ds_read_b128 v[168:171], v150 offset:4096
	s_mov_b32 m0, s58
	v_mfma_f32_16x16x32_bf16 v[4:7], v[172:175], v[176:179], v[4:7]
	global_load_lds_dwordx4 v108, s[80:81]
	v_mfma_f32_16x16x32_bf16 v[8:11], v[172:175], v[180:183], v[8:11]
	ds_read_b128 v[172:175], v150 offset:6144
	v_add_u32_e32 v151, v145, v114
	ds_read_b128 v[176:179], v151
	v_add_u32_e32 v151, v145, v115
	ds_read_b128 v[180:183], v151
	s_waitcnt lgkmcnt(6)
	v_mfma_f32_16x16x32_bf16 v[140:143], v[152:155], v[156:159], v[140:143]
	s_waitcnt lgkmcnt(5)
	s_mov_b32 m0, s63
	v_mfma_f32_16x16x32_bf16 v[60:63], v[160:163], v[156:159], v[60:63]
	global_load_lds_dwordx4 v146, s[80:81]
	s_waitcnt lgkmcnt(4)
	v_mfma_f32_16x16x32_bf16 v[132:135], v[152:155], v[164:167], v[132:135]
	v_mfma_f32_16x16x32_bf16 v[52:55], v[160:163], v[164:167], v[52:55]
	s_waitcnt lgkmcnt(3)
	s_mov_b32 m0, s1
	v_mfma_f32_16x16x32_bf16 v[136:139], v[168:171], v[156:159], v[136:139]
	global_load_lds_dwordx4 v104, s[78:79]
	v_mfma_f32_16x16x32_bf16 v[128:131], v[168:171], v[164:167], v[128:131]
	s_waitcnt lgkmcnt(2)
	v_mfma_f32_16x16x32_bf16 v[56:59], v[172:175], v[156:159], v[56:59]
	v_add_u32_e32 v151, v145, v116
	ds_read_b128 v[156:159], v151
	s_mov_b32 m0, s53
	v_mfma_f32_16x16x32_bf16 v[48:51], v[172:175], v[164:167], v[48:51]
	global_load_lds_dwordx4 v106, s[78:79]
	v_add_u32_e32 v151, v145, v117
	ds_read_b128 v[164:167], v151
	s_waitcnt lgkmcnt(3)
	v_mfma_f32_16x16x32_bf16 v[124:127], v[152:155], v[176:179], v[124:127]
	v_mfma_f32_16x16x32_bf16 v[44:47], v[160:163], v[176:179], v[44:47]
	s_mov_b32 m0, s55
	v_mfma_f32_16x16x32_bf16 v[120:123], v[168:171], v[176:179], v[120:123]
	global_load_lds_dwordx4 v108, s[78:79]
	v_mfma_f32_16x16x32_bf16 v[40:43], v[172:175], v[176:179], v[40:43]
	v_add_u32_e32 v151, v145, v118
	ds_read_b128 v[176:179], v151
	s_waitcnt lgkmcnt(3)
	v_mfma_f32_16x16x32_bf16 v[100:103], v[152:155], v[180:183], v[100:103]
	s_mov_b32 m0, s62
	v_mfma_f32_16x16x32_bf16 v[36:39], v[160:163], v[180:183], v[36:39]
	global_load_lds_dwordx4 v146, s[78:79]
	v_mfma_f32_16x16x32_bf16 v[96:99], v[168:171], v[180:183], v[96:99]
	v_mfma_f32_16x16x32_bf16 v[32:35], v[172:175], v[180:183], v[32:35]
	v_add_u32_e32 v151, v145, v119
	ds_read_b128 v[180:183], v151
	s_waitcnt lgkmcnt(3)
	v_mfma_f32_16x16x32_bf16 v[28:31], v[160:163], v[156:159], v[28:31]
	s_waitcnt lgkmcnt(2)
	v_mfma_f32_16x16x32_bf16 v[20:23], v[160:163], v[164:167], v[20:23]
	s_waitcnt lgkmcnt(1)
	v_mfma_f32_16x16x32_bf16 v[12:15], v[160:163], v[176:179], v[12:15]
	s_waitcnt lgkmcnt(0)
	v_mfma_f32_16x16x32_bf16 v[0:3], v[160:163], v[180:183], v[0:3]
	ds_read_b128 v[160:163], v150 offset:1024
	v_mfma_f32_16x16x32_bf16 v[92:95], v[152:155], v[156:159], v[92:95]
	v_mfma_f32_16x16x32_bf16 v[84:87], v[152:155], v[164:167], v[84:87]
	v_mfma_f32_16x16x32_bf16 v[76:79], v[152:155], v[176:179], v[76:79]
	v_mfma_f32_16x16x32_bf16 v[64:67], v[152:155], v[180:183], v[64:67]
	v_add_u32_e32 v151, v149, v112
	ds_read_b128 v[152:155], v151
	v_mfma_f32_16x16x32_bf16 v[80:83], v[168:171], v[164:167], v[80:83]
	v_mfma_f32_16x16x32_bf16 v[16:19], v[172:175], v[164:167], v[16:19]
	ds_read_b128 v[164:167], v150 offset:3072
	v_mfma_f32_16x16x32_bf16 v[88:91], v[168:171], v[156:159], v[88:91]
	v_mfma_f32_16x16x32_bf16 v[24:27], v[172:175], v[156:159], v[24:27]
	v_add_u32_e32 v151, v149, v113
	ds_read_b128 v[156:159], v151
	v_mfma_f32_16x16x32_bf16 v[72:75], v[168:171], v[176:179], v[72:75]
	v_mfma_f32_16x16x32_bf16 v[4:7], v[172:175], v[176:179], v[4:7]
	v_add_u32_e32 v151, v149, v114
	ds_read_b128 v[176:179], v151
	v_mfma_f32_16x16x32_bf16 v[68:71], v[168:171], v[180:183], v[68:71]
	ds_read_b128 v[168:171], v150 offset:5120
	v_mfma_f32_16x16x32_bf16 v[8:11], v[172:175], v[180:183], v[8:11]
	ds_read_b128 v[172:175], v150 offset:7168
	v_add_u32_e32 v151, v149, v115
	ds_read_b128 v[180:183], v151
	s_waitcnt lgkmcnt(6)
	v_mfma_f32_16x16x32_bf16 v[140:143], v[160:163], v[152:155], v[140:143]
	s_waitcnt lgkmcnt(5)
	v_mfma_f32_16x16x32_bf16 v[60:63], v[164:167], v[152:155], v[60:63]
	s_waitcnt lgkmcnt(4)
	v_mfma_f32_16x16x32_bf16 v[132:135], v[160:163], v[156:159], v[132:135]
	v_mfma_f32_16x16x32_bf16 v[52:55], v[164:167], v[156:159], v[52:55]
	s_waitcnt lgkmcnt(3)
	v_mfma_f32_16x16x32_bf16 v[124:127], v[160:163], v[176:179], v[124:127]
	v_mfma_f32_16x16x32_bf16 v[44:47], v[164:167], v[176:179], v[44:47]
	s_waitcnt lgkmcnt(2)
	v_mfma_f32_16x16x32_bf16 v[136:139], v[168:171], v[152:155], v[136:139]
	s_waitcnt lgkmcnt(1)
	v_mfma_f32_16x16x32_bf16 v[56:59], v[172:175], v[152:155], v[56:59]
	v_add_u32_e32 v151, v149, v116
	ds_read_b128 v[152:155], v151
	v_mfma_f32_16x16x32_bf16 v[128:131], v[168:171], v[156:159], v[128:131]
	v_mfma_f32_16x16x32_bf16 v[48:51], v[172:175], v[156:159], v[48:51]
	v_add_u32_e32 v151, v149, v117
	ds_read_b128 v[156:159], v151
	v_mfma_f32_16x16x32_bf16 v[120:123], v[168:171], v[176:179], v[120:123]
	v_mfma_f32_16x16x32_bf16 v[40:43], v[172:175], v[176:179], v[40:43]
	v_add_u32_e32 v151, v149, v118
	ds_read_b128 v[176:179], v151
	s_waitcnt lgkmcnt(3)
	v_mfma_f32_16x16x32_bf16 v[100:103], v[160:163], v[180:183], v[100:103]
	v_mfma_f32_16x16x32_bf16 v[36:39], v[164:167], v[180:183], v[36:39]
	v_mfma_f32_16x16x32_bf16 v[96:99], v[168:171], v[180:183], v[96:99]
	v_mfma_f32_16x16x32_bf16 v[32:35], v[172:175], v[180:183], v[32:35]
	v_add_u32_e32 v151, v149, v119
	ds_read_b128 v[180:183], v151
	s_waitcnt lgkmcnt(3)
	v_mfma_f32_16x16x32_bf16 v[92:95], v[160:163], v[152:155], v[92:95]
	v_mfma_f32_16x16x32_bf16 v[28:31], v[164:167], v[152:155], v[28:31]
	v_mfma_f32_16x16x32_bf16 v[88:91], v[168:171], v[152:155], v[88:91]
	v_mfma_f32_16x16x32_bf16 v[24:27], v[172:175], v[152:155], v[24:27]
	s_waitcnt lgkmcnt(2)
	v_mfma_f32_16x16x32_bf16 v[84:87], v[160:163], v[156:159], v[84:87]
	v_mfma_f32_16x16x32_bf16 v[20:23], v[164:167], v[156:159], v[20:23]
	v_mfma_f32_16x16x32_bf16 v[80:83], v[168:171], v[156:159], v[80:83]
	v_mfma_f32_16x16x32_bf16 v[16:19], v[172:175], v[156:159], v[16:19]
	s_waitcnt vmcnt(0)
	s_add_u32 s2, s2, 0x100
	s_addc_u32 s3, s3, 0
	s_add_i32 s76, s76, 2
	s_cmpk_lg_i32 s2, 0x1000
	s_waitcnt lgkmcnt(0)
	s_barrier
	s_cbranch_scc1 .LBB0_87
	v_mfma_f32_16x16x32_bf16 v[76:79], v[160:163], v[176:179], v[76:79]
	v_mfma_f32_16x16x32_bf16 v[64:67], v[160:163], v[180:183], v[64:67]
	v_mfma_f32_16x16x32_bf16 v[12:15], v[164:167], v[176:179], v[12:15]
	v_mfma_f32_16x16x32_bf16 v[0:3], v[164:167], v[180:183], v[0:3]
	v_mfma_f32_16x16x32_bf16 v[72:75], v[168:171], v[176:179], v[72:75]
	v_mfma_f32_16x16x32_bf16 v[68:71], v[168:171], v[180:183], v[68:71]
	v_mfma_f32_16x16x32_bf16 v[4:7], v[172:175], v[176:179], v[4:7]
	v_mfma_f32_16x16x32_bf16 v[8:11], v[172:175], v[180:183], v[8:11]
	s_nop 15
	s_nop 15
	v_mov_b32_e32 v145, v184
	s_movk_i32 s1, 0x100
	v_and_b32_e32 v163, 15, v145
	v_cmp_gt_u32_e64 s[2:3], s1, v145
	v_cmp_lt_u32_e32 vcc, 13, v163
	s_and_b64 s[4:5], s[2:3], vcc
	s_xor_b64 s[4:5], s[4:5], -1
	v_lshlrev_b32_e32 v149, 6, v163
	s_and_saveexec_b64 s[36:37], s[4:5]
	s_xor_b64 s[4:5], exec, s[36:37]
	v_lshlrev_b32_e32 v149, 6, v163
	s_or_saveexec_b64 s[4:5], s[4:5]
	v_bfe_u32 v150, v145, 4, 2
	v_readlane_b32 s68, v253, 18
	v_readlane_b32 s75, v253, 20
	s_xor_b64 exec, exec, s[4:5]
	s_cbranch_execz .LBB0_92
	v_mov_b32_e32 v104, 0x211c0
	v_lshl_or_b32 v104, v163, 2, v104
	ds_read_b32 v108, v104
	v_and_b32_e32 v104, 0xc0, v145
	v_lshl_add_u32 v104, v104, 2, v149
	v_lshl_or_b32 v109, v150, 4, v104
	v_add_u32_e32 v110, 0x1fc80, v109
	s_waitcnt lgkmcnt(0)
	v_pk_mul_f32 v[104:105], v[64:65], v[108:109] op_sel_hi:[1,0]
	v_pk_mul_f32 v[106:107], v[66:67], v[108:109] op_sel_hi:[1,0]
	v_add_u32_e32 v109, 0x1fd00, v109
	ds_write_b128 v110, v[104:107]
	v_pk_mul_f32 v[104:105], v[0:1], v[108:109] op_sel_hi:[1,0]
	v_pk_mul_f32 v[106:107], v[2:3], v[108:109] op_sel_hi:[1,0]
	ds_write_b128 v109, v[104:107]

.LBB0_154:
	s_ashr_i32 s21, s20, 31
	s_lshl_b64 s[20:21], s[20:21], 20
	s_add_u32 s20, s26, s20
	s_addc_u32 s21, s27, s21
	s_ashr_i32 s23, s22, 31
	s_lshl_b64 s[22:23], s[22:23], 20
	s_add_u32 s22, s8, s22
	s_addc_u32 s23, s9, s23
	s_add_u32 s44, s16, 0x80
	v_and_b32_e32 v8, 48, v7
	v_lshlrev_b32_e32 v9, 6, v7
	v_lshlrev_b32_e32 v7, 2, v7
	s_addc_u32 s45, s17, 0
	v_and_b32_e32 v10, 0x3c0, v9
	v_and_b32_e32 v149, 32, v7
	s_add_u32 s46, s18, 0x80
	v_or_b32_e32 v145, v10, v8
	v_bitop3_b32 v12, v10, v149, v8 bitop3:0x36
	s_waitcnt vmcnt(0)
	s_barrier
	v_lshlrev_b32_e32 v8, 13, v6
	s_addc_u32 s47, s19, 0
	s_add_i32 s25, s1, 0x10000
	v_lshl_add_u64 v[6:7], s[44:45], 0, v[0:1]
	s_mov_b32 s39, m0
	s_mov_b32 m0, s25
	s_nop 0
	global_load_lds_dwordx4 v[6:7], off
	s_mov_b32 m0, s39
	s_add_i32 s24, s1, 0x18000
	v_lshl_add_u64 v[6:7], s[46:47], 0, v[0:1]
	s_mov_b32 s39, m0
	s_mov_b32 m0, s24
	s_nop 0
	global_load_lds_dwordx4 v[6:7], off
	s_mov_b32 m0, s39
	v_lshl_add_u64 v[6:7], s[44:45], 0, v[2:3]
	s_add_i32 s39, s1, 0x12000
	s_mov_b32 s40, m0
	s_mov_b32 m0, s39
	s_nop 0
	global_load_lds_dwordx4 v[6:7], off
	s_mov_b32 m0, s40
	v_lshl_add_u64 v[6:7], s[46:47], 0, v[2:3]
	s_add_i32 s40, s1, 0x1a000
	s_mov_b32 s41, m0
	s_mov_b32 m0, s40
	s_nop 0
	global_load_lds_dwordx4 v[6:7], off
	s_mov_b32 m0, s41
	v_lshl_add_u64 v[6:7], s[44:45], 0, v[4:5]
	s_add_i32 s41, s1, 0x14000
	s_mov_b32 s42, m0
	s_mov_b32 m0, s41
	s_nop 0
	global_load_lds_dwordx4 v[6:7], off
	s_mov_b32 m0, s42
	v_lshl_add_u64 v[6:7], s[46:47], 0, v[4:5]
	s_add_i32 s42, s1, 0x1c000
	s_mov_b32 s43, m0
	s_mov_b32 m0, s42
	s_nop 0
	global_load_lds_dwordx4 v[6:7], off
	s_mov_b32 m0, s43
	v_lshl_add_u64 v[6:7], s[44:45], 0, v[146:147]
	s_add_i32 s43, s1, 0x16000
	s_mov_b32 s44, m0
	s_mov_b32 m0, s43
	s_nop 0
	global_load_lds_dwordx4 v[6:7], off
	s_mov_b32 m0, s44
	v_lshl_add_u64 v[6:7], s[46:47], 0, v[146:147]
	s_add_i32 s44, s1, 0x1e000
	s_mov_b32 s45, m0
	s_mov_b32 m0, s44
	s_nop 0
	global_load_lds_dwordx4 v[6:7], off
	s_mov_b32 m0, s45
	v_and_b32_e32 v182, 0xffffc000, v9
	v_or_b32_e32 v183, 0x800, v182
	v_or_b32_e32 v189, 0x1000, v182
	v_or_b32_e32 v199, 0x1800, v182
	v_or_b32_e32 v200, 0x2000, v182
	v_or_b32_e32 v201, 0x2800, v182
	v_or_b32_e32 v203, 0x3000, v182
	v_or_b32_e32 v206, 0x3800, v182
	s_movk_i32 s45, 0x6000
	v_and_or_b32 v7, v8, s45, v12
	ds_read_b128 v[8:11], v7 offset:32768
	v_or_b32_e32 v6, v12, v182
	ds_read_b128 v[12:15], v7 offset:34816
	ds_read_b128 v[16:19], v7 offset:36864
	ds_read_b128 v[24:27], v7 offset:38912
	ds_read_b128 v[20:23], v6
	ds_read_b128 v[28:31], v6 offset:2048
	ds_read_b128 v[32:35], v6 offset:4096
	ds_read_b128 v[36:39], v6 offset:6144
	s_waitcnt lgkmcnt(3)
	v_mfma_f32_16x16x32_bf16 v[40:43], v[8:11], v[20:23], 0
	v_mfma_f32_16x16x32_bf16 v[44:47], v[12:15], v[20:23], 0
	v_mfma_f32_16x16x32_bf16 v[48:51], v[16:19], v[20:23], 0
	v_mfma_f32_16x16x32_bf16 v[20:23], v[24:27], v[20:23], 0
	ds_read_b128 v[52:55], v6 offset:8192
	s_waitcnt lgkmcnt(3)
	v_mfma_f32_16x16x32_bf16 v[56:59], v[8:11], v[28:31], 0
	v_mfma_f32_16x16x32_bf16 v[60:63], v[12:15], v[28:31], 0
	v_mfma_f32_16x16x32_bf16 v[64:67], v[16:19], v[28:31], 0
	v_mfma_f32_16x16x32_bf16 v[28:31], v[24:27], v[28:31], 0
	ds_read_b128 v[68:71], v6 offset:10240
	s_waitcnt lgkmcnt(3)
	v_mfma_f32_16x16x32_bf16 v[72:75], v[8:11], v[32:35], 0
	v_mfma_f32_16x16x32_bf16 v[76:79], v[12:15], v[32:35], 0
	v_mfma_f32_16x16x32_bf16 v[80:83], v[16:19], v[32:35], 0
	v_mfma_f32_16x16x32_bf16 v[32:35], v[24:27], v[32:35], 0
	ds_read_b128 v[84:87], v6 offset:12288
	s_waitcnt lgkmcnt(3)
	v_mfma_f32_16x16x32_bf16 v[88:91], v[8:11], v[36:39], 0
	v_mfma_f32_16x16x32_bf16 v[92:95], v[12:15], v[36:39], 0
	v_mfma_f32_16x16x32_bf16 v[96:99], v[16:19], v[36:39], 0
	v_mfma_f32_16x16x32_bf16 v[36:39], v[24:27], v[36:39], 0
	ds_read_b128 v[100:103], v6 offset:14336
	s_waitcnt lgkmcnt(3)
	v_mfma_f32_16x16x32_bf16 v[104:107], v[8:11], v[52:55], 0
	v_mfma_f32_16x16x32_bf16 v[108:111], v[12:15], v[52:55], 0
	v_mfma_f32_16x16x32_bf16 v[112:115], v[16:19], v[52:55], 0
	v_mfma_f32_16x16x32_bf16 v[52:55], v[24:27], v[52:55], 0
	s_waitcnt lgkmcnt(2)
	v_mfma_f32_16x16x32_bf16 v[116:119], v[8:11], v[68:71], 0
	v_mfma_f32_16x16x32_bf16 v[120:123], v[12:15], v[68:71], 0
	v_mfma_f32_16x16x32_bf16 v[124:127], v[16:19], v[68:71], 0
	v_mfma_f32_16x16x32_bf16 v[68:71], v[24:27], v[68:71], 0
	s_waitcnt lgkmcnt(1)
	v_mfma_f32_16x16x32_bf16 v[128:131], v[8:11], v[84:87], 0
	v_mfma_f32_16x16x32_bf16 v[132:135], v[12:15], v[84:87], 0
	v_mfma_f32_16x16x32_bf16 v[136:139], v[16:19], v[84:87], 0
	v_mfma_f32_16x16x32_bf16 v[84:87], v[24:27], v[84:87], 0
	s_waitcnt lgkmcnt(0)
	v_mfma_f32_16x16x32_bf16 v[8:11], v[8:11], v[100:103], 0
	v_mfma_f32_16x16x32_bf16 v[12:15], v[12:15], v[100:103], 0
	v_mfma_f32_16x16x32_bf16 v[16:19], v[16:19], v[100:103], 0
	v_mfma_f32_16x16x32_bf16 v[24:27], v[24:27], v[100:103], 0
	ds_read_b128 v[100:103], v7 offset:33792
	ds_read_b128 v[140:143], v7 offset:35840
	ds_read_b128 v[150:153], v7 offset:37888
	ds_read_b128 v[158:161], v7 offset:39936
	ds_read_b128 v[154:157], v6 offset:1024
	ds_read_b128 v[162:165], v6 offset:3072
	ds_read_b128 v[166:169], v6 offset:5120
	ds_read_b128 v[170:173], v6 offset:7168
	s_waitcnt lgkmcnt(3)
	v_mfma_f32_16x16x32_bf16 v[40:43], v[100:103], v[154:157], v[40:43]
	v_mfma_f32_16x16x32_bf16 v[44:47], v[140:143], v[154:157], v[44:47]
	v_mfma_f32_16x16x32_bf16 v[48:51], v[150:153], v[154:157], v[48:51]
	v_mfma_f32_16x16x32_bf16 v[20:23], v[158:161], v[154:157], v[20:23]
	ds_read_b128 v[154:157], v6 offset:9216
	s_waitcnt lgkmcnt(3)
	v_mfma_f32_16x16x32_bf16 v[56:59], v[100:103], v[162:165], v[56:59]
	v_mfma_f32_16x16x32_bf16 v[60:63], v[140:143], v[162:165], v[60:63]
	v_mfma_f32_16x16x32_bf16 v[64:67], v[150:153], v[162:165], v[64:67]
	v_mfma_f32_16x16x32_bf16 v[28:31], v[158:161], v[162:165], v[28:31]
	ds_read_b128 v[162:165], v6 offset:11264
	s_waitcnt lgkmcnt(3)
	v_mfma_f32_16x16x32_bf16 v[72:75], v[100:103], v[166:169], v[72:75]
	v_mfma_f32_16x16x32_bf16 v[76:79], v[140:143], v[166:169], v[76:79]
	v_mfma_f32_16x16x32_bf16 v[80:83], v[150:153], v[166:169], v[80:83]
	v_mfma_f32_16x16x32_bf16 v[32:35], v[158:161], v[166:169], v[32:35]
	ds_read_b128 v[166:169], v6 offset:13312
	s_waitcnt lgkmcnt(3)
	v_mfma_f32_16x16x32_bf16 v[88:91], v[100:103], v[170:173], v[88:91]
	v_mfma_f32_16x16x32_bf16 v[92:95], v[140:143], v[170:173], v[92:95]
	v_mfma_f32_16x16x32_bf16 v[96:99], v[150:153], v[170:173], v[96:99]
	v_mfma_f32_16x16x32_bf16 v[36:39], v[158:161], v[170:173], v[36:39]
	ds_read_b128 v[170:173], v6 offset:15360
	s_waitcnt lgkmcnt(3)
	v_mfma_f32_16x16x32_bf16 v[104:107], v[100:103], v[154:157], v[104:107]
	v_mfma_f32_16x16x32_bf16 v[108:111], v[140:143], v[154:157], v[108:111]
	v_mfma_f32_16x16x32_bf16 v[112:115], v[150:153], v[154:157], v[112:115]
	v_mfma_f32_16x16x32_bf16 v[52:55], v[158:161], v[154:157], v[52:55]
	s_waitcnt lgkmcnt(2)
	v_mfma_f32_16x16x32_bf16 v[116:119], v[100:103], v[162:165], v[116:119]
	v_mfma_f32_16x16x32_bf16 v[120:123], v[140:143], v[162:165], v[120:123]
	v_mfma_f32_16x16x32_bf16 v[124:127], v[150:153], v[162:165], v[124:127]
	v_mfma_f32_16x16x32_bf16 v[68:71], v[158:161], v[162:165], v[68:71]
	s_waitcnt lgkmcnt(1)
	v_mfma_f32_16x16x32_bf16 v[128:131], v[100:103], v[166:169], v[128:131]
	v_mfma_f32_16x16x32_bf16 v[132:135], v[140:143], v[166:169], v[132:135]
	v_mfma_f32_16x16x32_bf16 v[136:139], v[150:153], v[166:169], v[136:139]
	v_mfma_f32_16x16x32_bf16 v[84:87], v[158:161], v[166:169], v[84:87]
	s_waitcnt lgkmcnt(0)
	v_mfma_f32_16x16x32_bf16 v[100:103], v[100:103], v[170:173], v[8:11]
	v_mfma_f32_16x16x32_bf16 v[150:153], v[150:153], v[170:173], v[16:19]
	v_mfma_f32_16x16x32_bf16 v[24:27], v[158:161], v[170:173], v[24:27]
	v_mfma_f32_16x16x32_bf16 v[140:143], v[140:143], v[170:173], v[12:15]
	s_add_u32 s46, s16, 0x100
	s_addc_u32 s47, s17, 0
	s_add_u32 s48, s18, 0x100
	s_waitcnt vmcnt(0)
	s_barrier
	s_addc_u32 s49, s19, 0
	v_lshl_add_u64 v[8:9], s[46:47], 0, v[0:1]
	s_mov_b32 s45, m0
	s_mov_b32 m0, s1
	s_nop 0
	global_load_lds_dwordx4 v[8:9], off
	s_mov_b32 m0, s45
	v_lshl_add_u64 v[8:9], s[48:49], 0, v[0:1]
	s_mov_b32 s45, m0
	s_mov_b32 m0, s30
	s_nop 0
	global_load_lds_dwordx4 v[8:9], off
	s_mov_b32 m0, s45
	v_lshl_add_u64 v[8:9], s[46:47], 0, v[2:3]
	s_mov_b32 s45, m0
	s_mov_b32 m0, s31
	s_nop 0
	global_load_lds_dwordx4 v[8:9], off
	s_mov_b32 m0, s45
	v_lshl_add_u64 v[8:9], s[48:49], 0, v[2:3]
	s_mov_b32 s45, m0
	s_mov_b32 m0, s34
	s_nop 0
	global_load_lds_dwordx4 v[8:9], off
	s_mov_b32 m0, s45
	v_lshl_add_u64 v[8:9], s[46:47], 0, v[4:5]
	s_mov_b32 s45, m0
	s_mov_b32 m0, s35
	s_nop 0
	global_load_lds_dwordx4 v[8:9], off
	s_mov_b32 m0, s45
	v_lshl_add_u64 v[8:9], s[48:49], 0, v[4:5]
	s_mov_b32 s45, m0
	s_mov_b32 m0, s36
	s_nop 0
	global_load_lds_dwordx4 v[8:9], off
	s_mov_b32 m0, s45
	v_lshl_add_u64 v[8:9], s[46:47], 0, v[146:147]
	s_mov_b32 s45, m0
	s_mov_b32 m0, s37
	s_nop 0
	global_load_lds_dwordx4 v[8:9], off
	s_mov_b32 m0, s45
	v_lshl_add_u64 v[8:9], s[48:49], 0, v[146:147]
	s_mov_b32 s45, m0
	s_mov_b32 m0, s38
	s_nop 0
	global_load_lds_dwordx4 v[8:9], off
	s_mov_b32 m0, s45
	v_or_b32_e32 v8, 0x18000, v7
	v_or_b32_e32 v9, 0x18800, v7
	v_or_b32_e32 v11, 0x19000, v7
	v_or_b32_e32 v10, 0x19800, v7
	ds_read_b128 v[154:157], v8
	ds_read_b128 v[158:161], v9
	ds_read_b128 v[162:165], v11
	ds_read_b128 v[166:169], v10
	v_bitop3_b32 v207, v145, s33, v149 bitop3:0xde
	v_add_u32_e32 v12, v207, v182
	ds_read_b128 v[16:19], v12
	v_add_u32_e32 v13, v207, v183
	v_add_u32_e32 v14, v207, v189
	v_add_u32_e32 v15, v207, v199
	ds_read_b128 v[170:173], v13
	ds_read_b128 v[174:177], v14
	ds_read_b128 v[178:181], v15
	s_waitcnt lgkmcnt(3)
	v_mfma_f32_16x16x32_bf16 v[40:43], v[154:157], v[16:19], v[40:43]
	v_mfma_f32_16x16x32_bf16 v[44:47], v[158:161], v[16:19], v[44:47]
	v_mfma_f32_16x16x32_bf16 v[48:51], v[162:165], v[16:19], v[48:51]
	v_mfma_f32_16x16x32_bf16 v[214:217], v[166:169], v[16:19], v[20:23]
	v_add_u32_e32 v16, v207, v200
	v_add_u32_e32 v17, v207, v201
	v_add_u32_e32 v18, v207, v203
	v_add_u32_e32 v19, v207, v206
	ds_read_b128 v[20:23], v16
	s_waitcnt lgkmcnt(3)
	v_mfma_f32_16x16x32_bf16 v[56:59], v[154:157], v[170:173], v[56:59]
	v_mfma_f32_16x16x32_bf16 v[60:63], v[158:161], v[170:173], v[60:63]
	v_mfma_f32_16x16x32_bf16 v[64:67], v[162:165], v[170:173], v[64:67]
	v_mfma_f32_16x16x32_bf16 v[170:173], v[166:169], v[170:173], v[28:31]
	s_nop 2
	ds_read_b128 v[28:31], v17
	s_waitcnt lgkmcnt(3)
	v_mfma_f32_16x16x32_bf16 v[72:75], v[154:157], v[174:177], v[72:75]
	v_mfma_f32_16x16x32_bf16 v[76:79], v[158:161], v[174:177], v[76:79]
	v_mfma_f32_16x16x32_bf16 v[80:83], v[162:165], v[174:177], v[80:83]
	v_mfma_f32_16x16x32_bf16 v[32:35], v[166:169], v[174:177], v[32:35]
	ds_read_b128 v[174:177], v18
	s_waitcnt lgkmcnt(3)
	v_mfma_f32_16x16x32_bf16 v[88:91], v[154:157], v[178:181], v[88:91]
	v_mfma_f32_16x16x32_bf16 v[92:95], v[158:161], v[178:181], v[92:95]
	v_mfma_f32_16x16x32_bf16 v[96:99], v[162:165], v[178:181], v[96:99]
	v_mfma_f32_16x16x32_bf16 v[36:39], v[166:169], v[178:181], v[36:39]
	ds_read_b128 v[178:181], v19
	s_waitcnt lgkmcnt(3)
	v_mfma_f32_16x16x32_bf16 v[104:107], v[154:157], v[20:23], v[104:107]
	v_mfma_f32_16x16x32_bf16 v[108:111], v[158:161], v[20:23], v[108:111]
	v_mfma_f32_16x16x32_bf16 v[112:115], v[162:165], v[20:23], v[112:115]
	v_mfma_f32_16x16x32_bf16 v[52:55], v[166:169], v[20:23], v[52:55]
	s_waitcnt lgkmcnt(2)
	v_mfma_f32_16x16x32_bf16 v[116:119], v[154:157], v[28:31], v[116:119]
	v_mfma_f32_16x16x32_bf16 v[120:123], v[158:161], v[28:31], v[120:123]
	v_mfma_f32_16x16x32_bf16 v[124:127], v[162:165], v[28:31], v[124:127]
	v_mfma_f32_16x16x32_bf16 v[68:71], v[166:169], v[28:31], v[68:71]
	s_waitcnt lgkmcnt(1)
	v_mfma_f32_16x16x32_bf16 v[128:131], v[154:157], v[174:177], v[128:131]
	v_mfma_f32_16x16x32_bf16 v[132:135], v[158:161], v[174:177], v[132:135]
	v_mfma_f32_16x16x32_bf16 v[84:87], v[166:169], v[174:177], v[84:87]
	s_waitcnt lgkmcnt(0)
	v_mfma_f32_16x16x32_bf16 v[100:103], v[154:157], v[178:181], v[100:103]
	v_mfma_f32_16x16x32_bf16 v[150:153], v[162:165], v[178:181], v[150:153]
	v_mfma_f32_16x16x32_bf16 v[154:157], v[166:169], v[178:181], v[24:27]
	v_mfma_f32_16x16x32_bf16 v[136:139], v[162:165], v[174:177], v[136:139]
	v_mfma_f32_16x16x32_bf16 v[140:143], v[158:161], v[178:181], v[140:143]
	v_or_b32_e32 v20, 0x18400, v7
	v_or_b32_e32 v21, 0x18c00, v7
	v_or_b32_e32 v23, 0x19400, v7
	v_or_b32_e32 v22, 0x19c00, v7
	ds_read_b128 v[158:161], v20
	ds_read_b128 v[162:165], v21
	ds_read_b128 v[166:169], v23
	ds_read_b128 v[174:177], v22
	s_mov_b32 s45, 0x10400
	v_bitop3_b32 v145, v145, s45, v149 bitop3:0xde
	v_add_u32_e32 v24, v145, v182
	ds_read_b128 v[28:31], v24
	v_add_u32_e32 v25, v145, v183
	v_add_u32_e32 v26, v145, v189
	v_add_u32_e32 v27, v145, v199
	ds_read_b128 v[178:181], v25
	ds_read_b128 v[218:221], v26
	ds_read_b128 v[222:225], v27
	s_waitcnt lgkmcnt(3)
	v_mfma_f32_16x16x32_bf16 v[40:43], v[158:161], v[28:31], v[40:43]
	v_mfma_f32_16x16x32_bf16 v[44:47], v[162:165], v[28:31], v[44:47]
	v_mfma_f32_16x16x32_bf16 v[48:51], v[166:169], v[28:31], v[48:51]
	v_mfma_f32_16x16x32_bf16 v[214:217], v[174:177], v[28:31], v[214:217]
	v_add_u32_e32 v28, v145, v200
	v_add_u32_e32 v29, v145, v201
	v_add_u32_e32 v30, v145, v203
	v_add_u32_e32 v31, v145, v206
	ds_read_b128 v[226:229], v28
	s_waitcnt lgkmcnt(3)
	v_mfma_f32_16x16x32_bf16 v[56:59], v[158:161], v[178:181], v[56:59]
	v_mfma_f32_16x16x32_bf16 v[60:63], v[162:165], v[178:181], v[60:63]
	v_mfma_f32_16x16x32_bf16 v[64:67], v[166:169], v[178:181], v[64:67]
	v_mfma_f32_16x16x32_bf16 v[170:173], v[174:177], v[178:181], v[170:173]
	ds_read_b128 v[178:181], v29
	s_waitcnt lgkmcnt(3)
	v_mfma_f32_16x16x32_bf16 v[72:75], v[158:161], v[218:221], v[72:75]
	v_mfma_f32_16x16x32_bf16 v[76:79], v[162:165], v[218:221], v[76:79]
	v_mfma_f32_16x16x32_bf16 v[80:83], v[166:169], v[218:221], v[80:83]
	v_mfma_f32_16x16x32_bf16 v[32:35], v[174:177], v[218:221], v[32:35]
	ds_read_b128 v[218:221], v30
	s_waitcnt lgkmcnt(3)
	v_mfma_f32_16x16x32_bf16 v[88:91], v[158:161], v[222:225], v[88:91]
	v_mfma_f32_16x16x32_bf16 v[92:95], v[162:165], v[222:225], v[92:95]
	v_mfma_f32_16x16x32_bf16 v[96:99], v[166:169], v[222:225], v[96:99]
	v_mfma_f32_16x16x32_bf16 v[36:39], v[174:177], v[222:225], v[36:39]
	ds_read_b128 v[222:225], v31
	s_waitcnt lgkmcnt(3)
	v_mfma_f32_16x16x32_bf16 v[104:107], v[158:161], v[226:229], v[104:107]
	v_mfma_f32_16x16x32_bf16 v[108:111], v[162:165], v[226:229], v[108:111]
	v_mfma_f32_16x16x32_bf16 v[112:115], v[166:169], v[226:229], v[112:115]
	v_mfma_f32_16x16x32_bf16 v[52:55], v[174:177], v[226:229], v[52:55]
	s_waitcnt lgkmcnt(2)
	v_mfma_f32_16x16x32_bf16 v[116:119], v[158:161], v[178:181], v[116:119]
	v_mfma_f32_16x16x32_bf16 v[120:123], v[162:165], v[178:181], v[120:123]
	v_mfma_f32_16x16x32_bf16 v[124:127], v[166:169], v[178:181], v[124:127]
	v_mfma_f32_16x16x32_bf16 v[68:71], v[174:177], v[178:181], v[68:71]
	s_waitcnt lgkmcnt(1)
	v_mfma_f32_16x16x32_bf16 v[132:135], v[162:165], v[218:221], v[132:135]
	v_mfma_f32_16x16x32_bf16 v[84:87], v[174:177], v[218:221], v[84:87]
	s_waitcnt lgkmcnt(0)
	v_mfma_f32_16x16x32_bf16 v[100:103], v[158:161], v[222:225], v[100:103]
	v_mfma_f32_16x16x32_bf16 v[150:153], v[166:169], v[222:225], v[150:153]
	v_mfma_f32_16x16x32_bf16 v[154:157], v[174:177], v[222:225], v[154:157]
	v_mfma_f32_16x16x32_bf16 v[128:131], v[158:161], v[218:221], v[128:131]
	v_mfma_f32_16x16x32_bf16 v[136:139], v[166:169], v[218:221], v[136:139]
	v_mfma_f32_16x16x32_bf16 v[140:143], v[162:165], v[222:225], v[140:143]
	s_add_u32 s46, s16, 0x180
	s_addc_u32 s47, s17, 0
	s_add_u32 s48, s18, 0x180
	s_waitcnt vmcnt(0)
	s_barrier
	s_addc_u32 s49, s19, 0
	v_lshl_add_u64 v[158:159], s[46:47], 0, v[0:1]
	s_mov_b32 s45, m0
	s_mov_b32 m0, s25
	s_nop 0
	global_load_lds_dwordx4 v[158:159], off
	s_mov_b32 m0, s45
	v_lshl_add_u64 v[158:159], s[48:49], 0, v[0:1]
	s_mov_b32 s45, m0
	s_mov_b32 m0, s24
	s_nop 0
	global_load_lds_dwordx4 v[158:159], off
	s_mov_b32 m0, s45
	v_lshl_add_u64 v[158:159], s[46:47], 0, v[2:3]
	s_mov_b32 s45, m0
	s_mov_b32 m0, s39
	s_nop 0
	global_load_lds_dwordx4 v[158:159], off
	s_mov_b32 m0, s45
	v_lshl_add_u64 v[158:159], s[48:49], 0, v[2:3]
	s_mov_b32 s45, m0
	s_mov_b32 m0, s40
	s_nop 0
	global_load_lds_dwordx4 v[158:159], off
	s_mov_b32 m0, s45
	v_lshl_add_u64 v[158:159], s[46:47], 0, v[4:5]
	s_mov_b32 s45, m0
	s_mov_b32 m0, s41
	s_nop 0
	global_load_lds_dwordx4 v[158:159], off
	s_mov_b32 m0, s45
	v_lshl_add_u64 v[158:159], s[48:49], 0, v[4:5]
	s_mov_b32 s45, m0
	s_mov_b32 m0, s42
	s_nop 0
	global_load_lds_dwordx4 v[158:159], off
	s_mov_b32 m0, s45
	v_lshl_add_u64 v[158:159], s[46:47], 0, v[146:147]
	s_mov_b32 s45, m0
	s_mov_b32 m0, s43
	s_nop 0
	global_load_lds_dwordx4 v[158:159], off
	s_mov_b32 m0, s45
	v_lshl_add_u64 v[158:159], s[48:49], 0, v[146:147]
	s_mov_b32 s45, m0
	s_mov_b32 m0, s44
	s_nop 0
	global_load_lds_dwordx4 v[158:159], off
	s_mov_b32 m0, s45
	ds_read_b128 v[158:161], v7 offset:32768
	ds_read_b128 v[162:165], v7 offset:34816
	ds_read_b128 v[166:169], v7 offset:36864
	ds_read_b128 v[178:181], v7 offset:38912
	ds_read_b128 v[174:177], v6
	ds_read_b128 v[218:221], v6 offset:2048
	ds_read_b128 v[222:225], v6 offset:4096
	ds_read_b128 v[226:229], v6 offset:6144
	s_waitcnt lgkmcnt(3)
	v_mfma_f32_16x16x32_bf16 v[40:43], v[158:161], v[174:177], v[40:43]
	v_mfma_f32_16x16x32_bf16 v[44:47], v[162:165], v[174:177], v[44:47]
	v_mfma_f32_16x16x32_bf16 v[48:51], v[166:169], v[174:177], v[48:51]
	v_mfma_f32_16x16x32_bf16 v[174:177], v[178:181], v[174:177], v[214:217]
	s_nop 2
	ds_read_b128 v[214:217], v6 offset:8192
	s_waitcnt lgkmcnt(3)
	v_mfma_f32_16x16x32_bf16 v[56:59], v[158:161], v[218:221], v[56:59]
	v_mfma_f32_16x16x32_bf16 v[60:63], v[162:165], v[218:221], v[60:63]
	v_mfma_f32_16x16x32_bf16 v[64:67], v[166:169], v[218:221], v[64:67]
	v_mfma_f32_16x16x32_bf16 v[170:173], v[178:181], v[218:221], v[170:173]
	ds_read_b128 v[218:221], v6 offset:10240
	s_waitcnt lgkmcnt(3)
	v_mfma_f32_16x16x32_bf16 v[72:75], v[158:161], v[222:225], v[72:75]
	v_mfma_f32_16x16x32_bf16 v[76:79], v[162:165], v[222:225], v[76:79]
	v_mfma_f32_16x16x32_bf16 v[80:83], v[166:169], v[222:225], v[80:83]
	v_mfma_f32_16x16x32_bf16 v[32:35], v[178:181], v[222:225], v[32:35]
	ds_read_b128 v[222:225], v6 offset:12288
	s_waitcnt lgkmcnt(3)
	v_mfma_f32_16x16x32_bf16 v[88:91], v[158:161], v[226:229], v[88:91]
	v_mfma_f32_16x16x32_bf16 v[92:95], v[162:165], v[226:229], v[92:95]
	v_mfma_f32_16x16x32_bf16 v[96:99], v[166:169], v[226:229], v[96:99]
	v_mfma_f32_16x16x32_bf16 v[36:39], v[178:181], v[226:229], v[36:39]
	ds_read_b128 v[226:229], v6 offset:14336
	s_waitcnt lgkmcnt(3)
	v_mfma_f32_16x16x32_bf16 v[104:107], v[158:161], v[214:217], v[104:107]
	v_mfma_f32_16x16x32_bf16 v[108:111], v[162:165], v[214:217], v[108:111]
	v_mfma_f32_16x16x32_bf16 v[112:115], v[166:169], v[214:217], v[112:115]
	v_mfma_f32_16x16x32_bf16 v[52:55], v[178:181], v[214:217], v[52:55]
	s_waitcnt lgkmcnt(2)
	v_mfma_f32_16x16x32_bf16 v[116:119], v[158:161], v[218:221], v[116:119]
	v_mfma_f32_16x16x32_bf16 v[120:123], v[162:165], v[218:221], v[120:123]
	v_mfma_f32_16x16x32_bf16 v[124:127], v[166:169], v[218:221], v[124:127]
	v_mfma_f32_16x16x32_bf16 v[68:71], v[178:181], v[218:221], v[68:71]
	s_waitcnt lgkmcnt(1)
	v_mfma_f32_16x16x32_bf16 v[132:135], v[162:165], v[222:225], v[132:135]
	v_mfma_f32_16x16x32_bf16 v[84:87], v[178:181], v[222:225], v[84:87]
	s_waitcnt lgkmcnt(0)
	v_mfma_f32_16x16x32_bf16 v[100:103], v[158:161], v[226:229], v[100:103]
	v_mfma_f32_16x16x32_bf16 v[150:153], v[166:169], v[226:229], v[150:153]
	v_mfma_f32_16x16x32_bf16 v[154:157], v[178:181], v[226:229], v[154:157]
	v_mfma_f32_16x16x32_bf16 v[128:131], v[158:161], v[222:225], v[128:131]
	v_mfma_f32_16x16x32_bf16 v[136:139], v[166:169], v[222:225], v[136:139]
	v_mfma_f32_16x16x32_bf16 v[140:143], v[162:165], v[226:229], v[140:143]
	ds_read_b128 v[158:161], v7 offset:33792
	ds_read_b128 v[162:165], v7 offset:35840
	ds_read_b128 v[166:169], v7 offset:37888
	ds_read_b128 v[214:217], v7 offset:39936
	ds_read_b128 v[178:181], v6 offset:1024
	ds_read_b128 v[218:221], v6 offset:3072
	ds_read_b128 v[222:225], v6 offset:5120
	ds_read_b128 v[226:229], v6 offset:7168
	s_waitcnt lgkmcnt(3)
	v_mfma_f32_16x16x32_bf16 v[40:43], v[158:161], v[178:181], v[40:43]
	v_mfma_f32_16x16x32_bf16 v[44:47], v[162:165], v[178:181], v[44:47]
	v_mfma_f32_16x16x32_bf16 v[48:51], v[166:169], v[178:181], v[48:51]
	v_mfma_f32_16x16x32_bf16 v[174:177], v[214:217], v[178:181], v[174:177]
	ds_read_b128 v[178:181], v6 offset:9216
	s_waitcnt lgkmcnt(3)
	v_mfma_f32_16x16x32_bf16 v[56:59], v[158:161], v[218:221], v[56:59]
	v_mfma_f32_16x16x32_bf16 v[60:63], v[162:165], v[218:221], v[60:63]
	v_mfma_f32_16x16x32_bf16 v[64:67], v[166:169], v[218:221], v[64:67]
	v_mfma_f32_16x16x32_bf16 v[170:173], v[214:217], v[218:221], v[170:173]
	ds_read_b128 v[218:221], v6 offset:11264
	s_waitcnt lgkmcnt(3)
	v_mfma_f32_16x16x32_bf16 v[72:75], v[158:161], v[222:225], v[72:75]
	v_mfma_f32_16x16x32_bf16 v[76:79], v[162:165], v[222:225], v[76:79]
	v_mfma_f32_16x16x32_bf16 v[80:83], v[166:169], v[222:225], v[80:83]
	v_mfma_f32_16x16x32_bf16 v[32:35], v[214:217], v[222:225], v[32:35]
	ds_read_b128 v[222:225], v6 offset:13312
	s_waitcnt lgkmcnt(3)
	v_mfma_f32_16x16x32_bf16 v[88:91], v[158:161], v[226:229], v[88:91]
	v_mfma_f32_16x16x32_bf16 v[92:95], v[162:165], v[226:229], v[92:95]
	v_mfma_f32_16x16x32_bf16 v[96:99], v[166:169], v[226:229], v[96:99]
	v_mfma_f32_16x16x32_bf16 v[36:39], v[214:217], v[226:229], v[36:39]
	ds_read_b128 v[226:229], v6 offset:15360
	s_waitcnt lgkmcnt(3)
	v_mfma_f32_16x16x32_bf16 v[104:107], v[158:161], v[178:181], v[104:107]
	v_mfma_f32_16x16x32_bf16 v[108:111], v[162:165], v[178:181], v[108:111]
	v_mfma_f32_16x16x32_bf16 v[112:115], v[166:169], v[178:181], v[112:115]
	v_mfma_f32_16x16x32_bf16 v[52:55], v[214:217], v[178:181], v[52:55]
	s_waitcnt lgkmcnt(2)
	v_mfma_f32_16x16x32_bf16 v[116:119], v[158:161], v[218:221], v[116:119]
	v_mfma_f32_16x16x32_bf16 v[120:123], v[162:165], v[218:221], v[120:123]
	v_mfma_f32_16x16x32_bf16 v[124:127], v[166:169], v[218:221], v[124:127]
	v_mfma_f32_16x16x32_bf16 v[68:71], v[214:217], v[218:221], v[68:71]
	s_waitcnt lgkmcnt(1)
	v_mfma_f32_16x16x32_bf16 v[132:135], v[162:165], v[222:225], v[132:135]
	v_mfma_f32_16x16x32_bf16 v[84:87], v[214:217], v[222:225], v[84:87]
	s_waitcnt lgkmcnt(0)
	v_mfma_f32_16x16x32_bf16 v[100:103], v[158:161], v[226:229], v[100:103]
	v_mfma_f32_16x16x32_bf16 v[150:153], v[166:169], v[226:229], v[150:153]
	v_mfma_f32_16x16x32_bf16 v[154:157], v[214:217], v[226:229], v[154:157]
	v_mfma_f32_16x16x32_bf16 v[128:131], v[158:161], v[222:225], v[128:131]
	v_mfma_f32_16x16x32_bf16 v[136:139], v[166:169], v[222:225], v[136:139]
	v_mfma_f32_16x16x32_bf16 v[140:143], v[162:165], v[226:229], v[140:143]
	s_add_u32 s46, s16, 0x200
	s_addc_u32 s47, s17, 0
	s_add_u32 s48, s18, 0x200
	s_waitcnt vmcnt(0)
	s_barrier
	s_addc_u32 s49, s19, 0
	s_mov_b32 s45, 0x280
	ds_read_b128 v[158:161], v8
	ds_read_b128 v[162:165], v12
	s_mov_b32 m0, s30
	s_nop 0
	global_load_lds_dwordx4 v0, s[48:49]
	ds_read_b128 v[166:169], v9
	s_mov_b32 m0, s34
	s_nop 0
	global_load_lds_dwordx4 v2, s[48:49]
	ds_read_b128 v[178:181], v13
	ds_read_b128 v[214:217], v11
	s_mov_b32 m0, s36
	s_nop 0
	global_load_lds_dwordx4 v4, s[48:49]
	ds_read_b128 v[218:221], v10
	ds_read_b128 v[222:225], v14
	ds_read_b128 v[226:229], v15
	s_branch .Lmy_rot_r_r2b
.Lmy_rr_r2b:
	ds_read_b128 v[158:161], v8
	ds_read_b128 v[162:165], v12
	s_mov_b32 m0, s30
	v_mfma_f32_16x16x32_bf16 v[128:131], v[166:169], v[222:225], v[128:131]
	global_load_lds_dwordx4 v0, s[48:49]
	v_mfma_f32_16x16x32_bf16 v[100:103], v[166:169], v[226:229], v[100:103]
	ds_read_b128 v[166:169], v9
	v_mfma_f32_16x16x32_bf16 v[132:135], v[178:181], v[222:225], v[132:135]
	s_mov_b32 m0, s34
	v_mfma_f32_16x16x32_bf16 v[140:143], v[178:181], v[226:229], v[140:143]
	global_load_lds_dwordx4 v2, s[48:49]
	ds_read_b128 v[178:181], v13
	v_mfma_f32_16x16x32_bf16 v[136:139], v[214:217], v[222:225], v[136:139]
	v_mfma_f32_16x16x32_bf16 v[150:153], v[214:217], v[226:229], v[150:153]
	ds_read_b128 v[214:217], v11
	s_mov_b32 m0, s36
	v_mfma_f32_16x16x32_bf16 v[84:87], v[218:221], v[222:225], v[84:87]
	global_load_lds_dwordx4 v4, s[48:49]
	v_mfma_f32_16x16x32_bf16 v[154:157], v[218:221], v[226:229], v[154:157]
	ds_read_b128 v[218:221], v10
	ds_read_b128 v[222:225], v14
	ds_read_b128 v[226:229], v15
.Lmy_rot_r_r2b:
	s_waitcnt lgkmcnt(6)
	v_mfma_f32_16x16x32_bf16 v[40:43], v[158:161], v[162:165], v[40:43]
	s_waitcnt lgkmcnt(5)
	s_mov_b32 m0, s38
	v_mfma_f32_16x16x32_bf16 v[44:47], v[166:169], v[162:165], v[44:47]
	global_load_lds_dwordx4 v146, s[48:49]
	s_waitcnt lgkmcnt(4)
	v_mfma_f32_16x16x32_bf16 v[56:59], v[158:161], v[178:181], v[56:59]
	v_mfma_f32_16x16x32_bf16 v[60:63], v[166:169], v[178:181], v[60:63]
	s_waitcnt lgkmcnt(3)
	s_mov_b32 m0, s1
	v_mfma_f32_16x16x32_bf16 v[48:51], v[214:217], v[162:165], v[48:51]
	global_load_lds_dwordx4 v0, s[46:47]
	v_mfma_f32_16x16x32_bf16 v[64:67], v[214:217], v[178:181], v[64:67]
	s_waitcnt lgkmcnt(2)
	v_mfma_f32_16x16x32_bf16 v[174:177], v[218:221], v[162:165], v[174:177]
	ds_read_b128 v[162:165], v16
	s_mov_b32 m0, s31
	v_mfma_f32_16x16x32_bf16 v[170:173], v[218:221], v[178:181], v[170:173]
	global_load_lds_dwordx4 v2, s[46:47]
	ds_read_b128 v[178:181], v17
	s_waitcnt lgkmcnt(3)
	v_mfma_f32_16x16x32_bf16 v[72:75], v[158:161], v[222:225], v[72:75]
	v_mfma_f32_16x16x32_bf16 v[76:79], v[166:169], v[222:225], v[76:79]
	s_mov_b32 m0, s35
	v_mfma_f32_16x16x32_bf16 v[80:83], v[214:217], v[222:225], v[80:83]
	global_load_lds_dwordx4 v4, s[46:47]
	v_mfma_f32_16x16x32_bf16 v[32:35], v[218:221], v[222:225], v[32:35]
	ds_read_b128 v[222:225], v18
	s_waitcnt lgkmcnt(3)
	v_mfma_f32_16x16x32_bf16 v[88:91], v[158:161], v[226:229], v[88:91]
	s_mov_b32 m0, s37
	v_mfma_f32_16x16x32_bf16 v[92:95], v[166:169], v[226:229], v[92:95]
	global_load_lds_dwordx4 v146, s[46:47]
	v_mfma_f32_16x16x32_bf16 v[96:99], v[214:217], v[226:229], v[96:99]
	v_mfma_f32_16x16x32_bf16 v[36:39], v[218:221], v[226:229], v[36:39]
	ds_read_b128 v[226:229], v19
	s_waitcnt lgkmcnt(3)
	v_mfma_f32_16x16x32_bf16 v[108:111], v[166:169], v[162:165], v[108:111]
	s_waitcnt lgkmcnt(2)
	v_mfma_f32_16x16x32_bf16 v[120:123], v[166:169], v[178:181], v[120:123]
	s_waitcnt lgkmcnt(1)
	v_mfma_f32_16x16x32_bf16 v[132:135], v[166:169], v[222:225], v[132:135]
	s_waitcnt lgkmcnt(0)
	v_mfma_f32_16x16x32_bf16 v[140:143], v[166:169], v[226:229], v[140:143]
	ds_read_b128 v[166:169], v20
	v_mfma_f32_16x16x32_bf16 v[104:107], v[158:161], v[162:165], v[104:107]
	v_mfma_f32_16x16x32_bf16 v[116:119], v[158:161], v[178:181], v[116:119]
	v_mfma_f32_16x16x32_bf16 v[128:131], v[158:161], v[222:225], v[128:131]
	v_mfma_f32_16x16x32_bf16 v[100:103], v[158:161], v[226:229], v[100:103]
	ds_read_b128 v[158:161], v24
	v_mfma_f32_16x16x32_bf16 v[124:127], v[214:217], v[178:181], v[124:127]
	v_mfma_f32_16x16x32_bf16 v[68:71], v[218:221], v[178:181], v[68:71]
	ds_read_b128 v[178:181], v21
	v_mfma_f32_16x16x32_bf16 v[112:115], v[214:217], v[162:165], v[112:115]
	v_mfma_f32_16x16x32_bf16 v[52:55], v[218:221], v[162:165], v[52:55]
	ds_read_b128 v[162:165], v25
	v_mfma_f32_16x16x32_bf16 v[136:139], v[214:217], v[222:225], v[136:139]
	v_mfma_f32_16x16x32_bf16 v[84:87], v[218:221], v[222:225], v[84:87]
	ds_read_b128 v[222:225], v26
	v_mfma_f32_16x16x32_bf16 v[150:153], v[214:217], v[226:229], v[150:153]
	ds_read_b128 v[214:217], v23
	v_mfma_f32_16x16x32_bf16 v[154:157], v[218:221], v[226:229], v[154:157]
	ds_read_b128 v[218:221], v22
	ds_read_b128 v[226:229], v27
	s_waitcnt lgkmcnt(6)
	v_mfma_f32_16x16x32_bf16 v[40:43], v[166:169], v[158:161], v[40:43]
	s_waitcnt lgkmcnt(5)
	v_mfma_f32_16x16x32_bf16 v[44:47], v[178:181], v[158:161], v[44:47]
	s_waitcnt lgkmcnt(4)
	v_mfma_f32_16x16x32_bf16 v[56:59], v[166:169], v[162:165], v[56:59]
	v_mfma_f32_16x16x32_bf16 v[60:63], v[178:181], v[162:165], v[60:63]
	s_waitcnt lgkmcnt(3)
	v_mfma_f32_16x16x32_bf16 v[72:75], v[166:169], v[222:225], v[72:75]
	v_mfma_f32_16x16x32_bf16 v[76:79], v[178:181], v[222:225], v[76:79]
	s_waitcnt lgkmcnt(2)
	v_mfma_f32_16x16x32_bf16 v[48:51], v[214:217], v[158:161], v[48:51]
	s_waitcnt lgkmcnt(1)
	v_mfma_f32_16x16x32_bf16 v[174:177], v[218:221], v[158:161], v[174:177]
	ds_read_b128 v[158:161], v28
	v_mfma_f32_16x16x32_bf16 v[64:67], v[214:217], v[162:165], v[64:67]
	v_mfma_f32_16x16x32_bf16 v[170:173], v[218:221], v[162:165], v[170:173]
	ds_read_b128 v[162:165], v29
	v_mfma_f32_16x16x32_bf16 v[80:83], v[214:217], v[222:225], v[80:83]
	v_mfma_f32_16x16x32_bf16 v[32:35], v[218:221], v[222:225], v[32:35]
	ds_read_b128 v[222:225], v30
	s_waitcnt lgkmcnt(3)
	v_mfma_f32_16x16x32_bf16 v[88:91], v[166:169], v[226:229], v[88:91]
	v_mfma_f32_16x16x32_bf16 v[92:95], v[178:181], v[226:229], v[92:95]
	v_mfma_f32_16x16x32_bf16 v[96:99], v[214:217], v[226:229], v[96:99]
	v_mfma_f32_16x16x32_bf16 v[36:39], v[218:221], v[226:229], v[36:39]
	ds_read_b128 v[226:229], v31
	s_waitcnt lgkmcnt(3)
	v_mfma_f32_16x16x32_bf16 v[104:107], v[166:169], v[158:161], v[104:107]
	v_mfma_f32_16x16x32_bf16 v[108:111], v[178:181], v[158:161], v[108:111]
	v_mfma_f32_16x16x32_bf16 v[112:115], v[214:217], v[158:161], v[112:115]
	v_mfma_f32_16x16x32_bf16 v[52:55], v[218:221], v[158:161], v[52:55]
	s_waitcnt lgkmcnt(2)
	v_mfma_f32_16x16x32_bf16 v[116:119], v[166:169], v[162:165], v[116:119]
	v_mfma_f32_16x16x32_bf16 v[120:123], v[178:181], v[162:165], v[120:123]
	v_mfma_f32_16x16x32_bf16 v[124:127], v[214:217], v[162:165], v[124:127]
	v_mfma_f32_16x16x32_bf16 v[68:71], v[218:221], v[162:165], v[68:71]
	s_add_u32 s46, s16, s45
	s_addc_u32 s47, s17, 0
	s_add_u32 s48, s18, s45
	s_addc_u32 s49, s19, 0
	s_add_u32 s45, s45, 0x80
	s_waitcnt vmcnt(0)
	s_waitcnt lgkmcnt(0)
	s_barrier
	ds_read_b128 v[158:161], v7 offset:32768
	ds_read_b128 v[162:165], v6
	s_mov_b32 m0, s24
	v_mfma_f32_16x16x32_bf16 v[128:131], v[166:169], v[222:225], v[128:131]
	global_load_lds_dwordx4 v0, s[48:49]
	v_mfma_f32_16x16x32_bf16 v[100:103], v[166:169], v[226:229], v[100:103]
	ds_read_b128 v[166:169], v7 offset:34816
	v_mfma_f32_16x16x32_bf16 v[132:135], v[178:181], v[222:225], v[132:135]
	s_mov_b32 m0, s40
	v_mfma_f32_16x16x32_bf16 v[140:143], v[178:181], v[226:229], v[140:143]
	global_load_lds_dwordx4 v2, s[48:49]
	ds_read_b128 v[178:181], v6 offset:2048
	v_mfma_f32_16x16x32_bf16 v[136:139], v[214:217], v[222:225], v[136:139]
	v_mfma_f32_16x16x32_bf16 v[150:153], v[214:217], v[226:229], v[150:153]
	ds_read_b128 v[214:217], v7 offset:36864
	s_mov_b32 m0, s42
	v_mfma_f32_16x16x32_bf16 v[84:87], v[218:221], v[222:225], v[84:87]
	global_load_lds_dwordx4 v4, s[48:49]
	v_mfma_f32_16x16x32_bf16 v[154:157], v[218:221], v[226:229], v[154:157]
	ds_read_b128 v[218:221], v7 offset:38912
	ds_read_b128 v[222:225], v6 offset:4096
	ds_read_b128 v[226:229], v6 offset:6144
	s_waitcnt lgkmcnt(6)
	v_mfma_f32_16x16x32_bf16 v[40:43], v[158:161], v[162:165], v[40:43]
	s_waitcnt lgkmcnt(5)
	s_mov_b32 m0, s44
	v_mfma_f32_16x16x32_bf16 v[44:47], v[166:169], v[162:165], v[44:47]
	global_load_lds_dwordx4 v146, s[48:49]
	s_waitcnt lgkmcnt(4)
	v_mfma_f32_16x16x32_bf16 v[56:59], v[158:161], v[178:181], v[56:59]
	v_mfma_f32_16x16x32_bf16 v[60:63], v[166:169], v[178:181], v[60:63]
	s_waitcnt lgkmcnt(3)
	s_mov_b32 m0, s25
	v_mfma_f32_16x16x32_bf16 v[48:51], v[214:217], v[162:165], v[48:51]
	global_load_lds_dwordx4 v0, s[46:47]
	v_mfma_f32_16x16x32_bf16 v[64:67], v[214:217], v[178:181], v[64:67]
	s_waitcnt lgkmcnt(2)
	v_mfma_f32_16x16x32_bf16 v[174:177], v[218:221], v[162:165], v[174:177]
	ds_read_b128 v[162:165], v6 offset:8192
	s_mov_b32 m0, s39
	v_mfma_f32_16x16x32_bf16 v[170:173], v[218:221], v[178:181], v[170:173]
	global_load_lds_dwordx4 v2, s[46:47]
	ds_read_b128 v[178:181], v6 offset:10240
	s_waitcnt lgkmcnt(3)
	v_mfma_f32_16x16x32_bf16 v[72:75], v[158:161], v[222:225], v[72:75]
	v_mfma_f32_16x16x32_bf16 v[76:79], v[166:169], v[222:225], v[76:79]
	s_mov_b32 m0, s41
	v_mfma_f32_16x16x32_bf16 v[80:83], v[214:217], v[222:225], v[80:83]
	global_load_lds_dwordx4 v4, s[46:47]
	v_mfma_f32_16x16x32_bf16 v[32:35], v[218:221], v[222:225], v[32:35]
	ds_read_b128 v[222:225], v6 offset:12288
	s_waitcnt lgkmcnt(3)
	v_mfma_f32_16x16x32_bf16 v[88:91], v[158:161], v[226:229], v[88:91]
	s_mov_b32 m0, s43
	v_mfma_f32_16x16x32_bf16 v[92:95], v[166:169], v[226:229], v[92:95]
	global_load_lds_dwordx4 v146, s[46:47]
	v_mfma_f32_16x16x32_bf16 v[96:99], v[214:217], v[226:229], v[96:99]
	v_mfma_f32_16x16x32_bf16 v[36:39], v[218:221], v[226:229], v[36:39]
	ds_read_b128 v[226:229], v6 offset:14336
	s_waitcnt lgkmcnt(3)
	v_mfma_f32_16x16x32_bf16 v[108:111], v[166:169], v[162:165], v[108:111]
	s_waitcnt lgkmcnt(2)
	v_mfma_f32_16x16x32_bf16 v[120:123], v[166:169], v[178:181], v[120:123]
	s_waitcnt lgkmcnt(1)
	v_mfma_f32_16x16x32_bf16 v[132:135], v[166:169], v[222:225], v[132:135]
	s_waitcnt lgkmcnt(0)
	v_mfma_f32_16x16x32_bf16 v[140:143], v[166:169], v[226:229], v[140:143]
	ds_read_b128 v[166:169], v7 offset:33792
	v_mfma_f32_16x16x32_bf16 v[104:107], v[158:161], v[162:165], v[104:107]
	v_mfma_f32_16x16x32_bf16 v[116:119], v[158:161], v[178:181], v[116:119]
	v_mfma_f32_16x16x32_bf16 v[128:131], v[158:161], v[222:225], v[128:131]
	v_mfma_f32_16x16x32_bf16 v[100:103], v[158:161], v[226:229], v[100:103]
	ds_read_b128 v[158:161], v6 offset:1024
	v_mfma_f32_16x16x32_bf16 v[124:127], v[214:217], v[178:181], v[124:127]
	v_mfma_f32_16x16x32_bf16 v[68:71], v[218:221], v[178:181], v[68:71]
	ds_read_b128 v[178:181], v7 offset:35840
	v_mfma_f32_16x16x32_bf16 v[112:115], v[214:217], v[162:165], v[112:115]
	v_mfma_f32_16x16x32_bf16 v[52:55], v[218:221], v[162:165], v[52:55]
	ds_read_b128 v[162:165], v6 offset:3072
	v_mfma_f32_16x16x32_bf16 v[136:139], v[214:217], v[222:225], v[136:139]
	v_mfma_f32_16x16x32_bf16 v[84:87], v[218:221], v[222:225], v[84:87]
	ds_read_b128 v[222:225], v6 offset:5120
	v_mfma_f32_16x16x32_bf16 v[150:153], v[214:217], v[226:229], v[150:153]
	ds_read_b128 v[214:217], v7 offset:37888
	v_mfma_f32_16x16x32_bf16 v[154:157], v[218:221], v[226:229], v[154:157]
	ds_read_b128 v[218:221], v7 offset:39936
	ds_read_b128 v[226:229], v6 offset:7168
	s_waitcnt lgkmcnt(6)
	v_mfma_f32_16x16x32_bf16 v[40:43], v[166:169], v[158:161], v[40:43]
	s_waitcnt lgkmcnt(5)
	v_mfma_f32_16x16x32_bf16 v[44:47], v[178:181], v[158:161], v[44:47]
	s_waitcnt lgkmcnt(4)
	v_mfma_f32_16x16x32_bf16 v[56:59], v[166:169], v[162:165], v[56:59]
	v_mfma_f32_16x16x32_bf16 v[60:63], v[178:181], v[162:165], v[60:63]
	s_waitcnt lgkmcnt(3)
	v_mfma_f32_16x16x32_bf16 v[72:75], v[166:169], v[222:225], v[72:75]
	v_mfma_f32_16x16x32_bf16 v[76:79], v[178:181], v[222:225], v[76:79]
	s_waitcnt lgkmcnt(2)
	v_mfma_f32_16x16x32_bf16 v[48:51], v[214:217], v[158:161], v[48:51]
	s_waitcnt lgkmcnt(1)
	v_mfma_f32_16x16x32_bf16 v[174:177], v[218:221], v[158:161], v[174:177]
	ds_read_b128 v[158:161], v6 offset:9216
	v_mfma_f32_16x16x32_bf16 v[64:67], v[214:217], v[162:165], v[64:67]
	v_mfma_f32_16x16x32_bf16 v[170:173], v[218:221], v[162:165], v[170:173]
	ds_read_b128 v[162:165], v6 offset:11264
	v_mfma_f32_16x16x32_bf16 v[80:83], v[214:217], v[222:225], v[80:83]
	v_mfma_f32_16x16x32_bf16 v[32:35], v[218:221], v[222:225], v[32:35]
	ds_read_b128 v[222:225], v6 offset:13312
	s_waitcnt lgkmcnt(3)
	v_mfma_f32_16x16x32_bf16 v[88:91], v[166:169], v[226:229], v[88:91]
	v_mfma_f32_16x16x32_bf16 v[92:95], v[178:181], v[226:229], v[92:95]
	v_mfma_f32_16x16x32_bf16 v[96:99], v[214:217], v[226:229], v[96:99]
	v_mfma_f32_16x16x32_bf16 v[36:39], v[218:221], v[226:229], v[36:39]
	ds_read_b128 v[226:229], v6 offset:15360
	s_waitcnt lgkmcnt(3)
	v_mfma_f32_16x16x32_bf16 v[104:107], v[166:169], v[158:161], v[104:107]
	v_mfma_f32_16x16x32_bf16 v[108:111], v[178:181], v[158:161], v[108:111]
	v_mfma_f32_16x16x32_bf16 v[112:115], v[214:217], v[158:161], v[112:115]
	v_mfma_f32_16x16x32_bf16 v[52:55], v[218:221], v[158:161], v[52:55]
	s_waitcnt lgkmcnt(2)
	v_mfma_f32_16x16x32_bf16 v[116:119], v[166:169], v[162:165], v[116:119]
	v_mfma_f32_16x16x32_bf16 v[120:123], v[178:181], v[162:165], v[120:123]
	v_mfma_f32_16x16x32_bf16 v[124:127], v[214:217], v[162:165], v[124:127]
	v_mfma_f32_16x16x32_bf16 v[68:71], v[218:221], v[162:165], v[68:71]
	s_add_u32 s46, s16, s45
	s_addc_u32 s47, s17, 0
	s_add_u32 s48, s18, s45
	s_addc_u32 s49, s19, 0
	s_add_u32 s45, s45, 0x80
	s_cmp_lg_u32 s45, 0xf80
	s_waitcnt vmcnt(0)
	s_waitcnt lgkmcnt(0)
	s_barrier
	s_cbranch_scc1 .Lmy_rr_r2b
	v_mfma_f32_16x16x32_bf16 v[128:131], v[166:169], v[222:225], v[128:131]
	v_mfma_f32_16x16x32_bf16 v[100:103], v[166:169], v[226:229], v[100:103]
	v_mfma_f32_16x16x32_bf16 v[132:135], v[178:181], v[222:225], v[132:135]
	v_mfma_f32_16x16x32_bf16 v[140:143], v[178:181], v[226:229], v[140:143]
	v_mfma_f32_16x16x32_bf16 v[136:139], v[214:217], v[222:225], v[136:139]
	v_mfma_f32_16x16x32_bf16 v[150:153], v[214:217], v[226:229], v[150:153]
	v_mfma_f32_16x16x32_bf16 v[84:87], v[218:221], v[222:225], v[84:87]
	v_mfma_f32_16x16x32_bf16 v[154:157], v[218:221], v[226:229], v[154:157]
	s_nop 15
	s_nop 15
	v_lshl_add_u64 v[158:159], s[46:47], 0, v[0:1]
	s_mov_b32 s45, m0
	s_mov_b32 m0, s1
	s_nop 0
	global_load_lds_dwordx4 v[158:159], off
	s_mov_b32 m0, s45
	v_lshl_add_u64 v[158:159], s[48:49], 0, v[0:1]
	s_mov_b32 s45, m0
	s_mov_b32 m0, s30
	s_nop 0
	global_load_lds_dwordx4 v[158:159], off
	s_mov_b32 m0, s45
	v_lshl_add_u64 v[158:159], s[46:47], 0, v[2:3]
	s_mov_b32 s45, m0
	s_mov_b32 m0, s31
	s_nop 0
	global_load_lds_dwordx4 v[158:159], off
	s_mov_b32 m0, s45
	v_lshl_add_u64 v[158:159], s[48:49], 0, v[2:3]
	s_mov_b32 s45, m0
	s_mov_b32 m0, s34
	s_nop 0
	global_load_lds_dwordx4 v[158:159], off
	s_mov_b32 m0, s45
	v_lshl_add_u64 v[158:159], s[46:47], 0, v[4:5]
	s_mov_b32 s45, m0
	s_mov_b32 m0, s35
	s_nop 0
	global_load_lds_dwordx4 v[158:159], off
	s_mov_b32 m0, s45
	v_lshl_add_u64 v[158:159], s[48:49], 0, v[4:5]
	s_mov_b32 s45, m0
	s_mov_b32 m0, s36
	s_nop 0
	global_load_lds_dwordx4 v[158:159], off
	s_mov_b32 m0, s45
	v_lshl_add_u64 v[158:159], s[46:47], 0, v[146:147]
	s_mov_b32 s45, m0
	s_mov_b32 m0, s37
	s_nop 0
	global_load_lds_dwordx4 v[158:159], off
	s_mov_b32 m0, s45
	v_lshl_add_u64 v[158:159], s[48:49], 0, v[146:147]
	s_mov_b32 s45, m0
	s_mov_b32 m0, s38
	s_nop 0
	global_load_lds_dwordx4 v[158:159], off
	s_mov_b32 m0, s45
	ds_read_b128 v[158:161], v8
	ds_read_b128 v[162:165], v9
	ds_read_b128 v[166:169], v11
	ds_read_b128 v[214:217], v10
	ds_read_b128 v[178:181], v12
	ds_read_b128 v[218:221], v13
	ds_read_b128 v[222:225], v14
	ds_read_b128 v[226:229], v15
	s_waitcnt lgkmcnt(3)
	v_mfma_f32_16x16x32_bf16 v[40:43], v[158:161], v[178:181], v[40:43]
	v_mfma_f32_16x16x32_bf16 v[44:47], v[162:165], v[178:181], v[44:47]
	v_mfma_f32_16x16x32_bf16 v[48:51], v[166:169], v[178:181], v[48:51]
	v_mfma_f32_16x16x32_bf16 v[174:177], v[214:217], v[178:181], v[174:177]
	ds_read_b128 v[178:181], v16
	s_waitcnt lgkmcnt(3)
	v_mfma_f32_16x16x32_bf16 v[56:59], v[158:161], v[218:221], v[56:59]
	v_mfma_f32_16x16x32_bf16 v[60:63], v[162:165], v[218:221], v[60:63]
	v_mfma_f32_16x16x32_bf16 v[64:67], v[166:169], v[218:221], v[64:67]
	v_mfma_f32_16x16x32_bf16 v[170:173], v[214:217], v[218:221], v[170:173]
	ds_read_b128 v[218:221], v17
	s_waitcnt lgkmcnt(3)
	v_mfma_f32_16x16x32_bf16 v[72:75], v[158:161], v[222:225], v[72:75]
	v_mfma_f32_16x16x32_bf16 v[76:79], v[162:165], v[222:225], v[76:79]
	v_mfma_f32_16x16x32_bf16 v[80:83], v[166:169], v[222:225], v[80:83]
	v_mfma_f32_16x16x32_bf16 v[32:35], v[214:217], v[222:225], v[32:35]
	ds_read_b128 v[222:225], v18
	s_waitcnt lgkmcnt(3)
	v_mfma_f32_16x16x32_bf16 v[88:91], v[158:161], v[226:229], v[88:91]
	v_mfma_f32_16x16x32_bf16 v[92:95], v[162:165], v[226:229], v[92:95]
	v_mfma_f32_16x16x32_bf16 v[96:99], v[166:169], v[226:229], v[96:99]
	v_mfma_f32_16x16x32_bf16 v[36:39], v[214:217], v[226:229], v[36:39]
	ds_read_b128 v[226:229], v19
	s_waitcnt lgkmcnt(3)
	v_mfma_f32_16x16x32_bf16 v[104:107], v[158:161], v[178:181], v[104:107]
	v_mfma_f32_16x16x32_bf16 v[108:111], v[162:165], v[178:181], v[108:111]
	v_mfma_f32_16x16x32_bf16 v[112:115], v[166:169], v[178:181], v[112:115]
	v_mfma_f32_16x16x32_bf16 v[52:55], v[214:217], v[178:181], v[52:55]
	s_waitcnt lgkmcnt(2)
	v_mfma_f32_16x16x32_bf16 v[116:119], v[158:161], v[218:221], v[116:119]
	v_mfma_f32_16x16x32_bf16 v[120:123], v[162:165], v[218:221], v[120:123]
	v_mfma_f32_16x16x32_bf16 v[124:127], v[166:169], v[218:221], v[124:127]
	v_mfma_f32_16x16x32_bf16 v[68:71], v[214:217], v[218:221], v[68:71]
	s_waitcnt lgkmcnt(1)
	v_mfma_f32_16x16x32_bf16 v[132:135], v[162:165], v[222:225], v[132:135]
	v_mfma_f32_16x16x32_bf16 v[84:87], v[214:217], v[222:225], v[84:87]
	s_waitcnt lgkmcnt(0)
	v_mfma_f32_16x16x32_bf16 v[100:103], v[158:161], v[226:229], v[100:103]
	v_mfma_f32_16x16x32_bf16 v[150:153], v[166:169], v[226:229], v[150:153]
	v_mfma_f32_16x16x32_bf16 v[154:157], v[214:217], v[226:229], v[154:157]
	v_mfma_f32_16x16x32_bf16 v[128:131], v[158:161], v[222:225], v[128:131]
	v_mfma_f32_16x16x32_bf16 v[136:139], v[166:169], v[222:225], v[136:139]
	v_mfma_f32_16x16x32_bf16 v[140:143], v[162:165], v[226:229], v[140:143]
	ds_read_b128 v[158:161], v20
	ds_read_b128 v[162:165], v21
	ds_read_b128 v[166:169], v23
	ds_read_b128 v[214:217], v22
	ds_read_b128 v[178:181], v24
	ds_read_b128 v[218:221], v25
	ds_read_b128 v[222:225], v26
	ds_read_b128 v[226:229], v27
	s_waitcnt lgkmcnt(3)
	v_mfma_f32_16x16x32_bf16 v[40:43], v[158:161], v[178:181], v[40:43]
	v_mfma_f32_16x16x32_bf16 v[44:47], v[162:165], v[178:181], v[44:47]
	v_mfma_f32_16x16x32_bf16 v[48:51], v[166:169], v[178:181], v[48:51]
	v_mfma_f32_16x16x32_bf16 v[174:177], v[214:217], v[178:181], v[174:177]
	ds_read_b128 v[178:181], v28
	s_waitcnt lgkmcnt(3)
	v_mfma_f32_16x16x32_bf16 v[56:59], v[158:161], v[218:221], v[56:59]
	v_mfma_f32_16x16x32_bf16 v[60:63], v[162:165], v[218:221], v[60:63]
	v_mfma_f32_16x16x32_bf16 v[64:67], v[166:169], v[218:221], v[64:67]
	v_mfma_f32_16x16x32_bf16 v[170:173], v[214:217], v[218:221], v[170:173]
	ds_read_b128 v[218:221], v29
	s_waitcnt lgkmcnt(3)
	v_mfma_f32_16x16x32_bf16 v[72:75], v[158:161], v[222:225], v[72:75]
	v_mfma_f32_16x16x32_bf16 v[76:79], v[162:165], v[222:225], v[76:79]
	v_mfma_f32_16x16x32_bf16 v[80:83], v[166:169], v[222:225], v[80:83]
	v_mfma_f32_16x16x32_bf16 v[32:35], v[214:217], v[222:225], v[32:35]
	ds_read_b128 v[222:225], v30
	s_waitcnt lgkmcnt(3)
	v_mfma_f32_16x16x32_bf16 v[88:91], v[158:161], v[226:229], v[88:91]
	v_mfma_f32_16x16x32_bf16 v[92:95], v[162:165], v[226:229], v[92:95]
	v_mfma_f32_16x16x32_bf16 v[96:99], v[166:169], v[226:229], v[96:99]
	v_mfma_f32_16x16x32_bf16 v[36:39], v[214:217], v[226:229], v[36:39]
	ds_read_b128 v[226:229], v31
	s_waitcnt lgkmcnt(3)
	v_mfma_f32_16x16x32_bf16 v[104:107], v[158:161], v[178:181], v[104:107]
	v_mfma_f32_16x16x32_bf16 v[108:111], v[162:165], v[178:181], v[108:111]
	v_mfma_f32_16x16x32_bf16 v[112:115], v[166:169], v[178:181], v[112:115]
	v_mfma_f32_16x16x32_bf16 v[52:55], v[214:217], v[178:181], v[52:55]
	s_waitcnt lgkmcnt(2)
	v_mfma_f32_16x16x32_bf16 v[116:119], v[158:161], v[218:221], v[116:119]
	v_mfma_f32_16x16x32_bf16 v[120:123], v[162:165], v[218:221], v[120:123]
	v_mfma_f32_16x16x32_bf16 v[124:127], v[166:169], v[218:221], v[124:127]
	v_mfma_f32_16x16x32_bf16 v[68:71], v[214:217], v[218:221], v[68:71]
	s_waitcnt lgkmcnt(1)
	v_mfma_f32_16x16x32_bf16 v[132:135], v[162:165], v[222:225], v[132:135]
	v_mfma_f32_16x16x32_bf16 v[84:87], v[214:217], v[222:225], v[84:87]
	s_waitcnt lgkmcnt(0)
	v_mfma_f32_16x16x32_bf16 v[100:103], v[158:161], v[226:229], v[100:103]
	v_mfma_f32_16x16x32_bf16 v[150:153], v[166:169], v[226:229], v[150:153]
	v_mfma_f32_16x16x32_bf16 v[154:157], v[214:217], v[226:229], v[154:157]
	v_mfma_f32_16x16x32_bf16 v[128:131], v[158:161], v[222:225], v[128:131]
	v_mfma_f32_16x16x32_bf16 v[136:139], v[166:169], v[222:225], v[136:139]
	v_mfma_f32_16x16x32_bf16 v[140:143], v[162:165], v[226:229], v[140:143]
	s_add_u32 s16, s16, 0xf80
	s_addc_u32 s17, s17, 0
	s_add_u32 s18, s18, 0xf80
	s_waitcnt vmcnt(0)
	s_barrier
	s_addc_u32 s19, s19, 0
	v_lshl_add_u64 v[158:159], s[16:17], 0, v[0:1]
	s_mov_b32 s45, m0
	s_mov_b32 m0, s25
	s_nop 0
	global_load_lds_dwordx4 v[158:159], off
	s_mov_b32 m0, s45
	v_lshl_add_u64 v[158:159], s[18:19], 0, v[0:1]
	s_mov_b32 s25, m0
	s_mov_b32 m0, s24
	s_nop 0
	global_load_lds_dwordx4 v[158:159], off
	s_mov_b32 m0, s25
	v_lshl_add_u64 v[158:159], s[16:17], 0, v[2:3]
	s_mov_b32 s24, m0
	s_mov_b32 m0, s39
	s_nop 0
	global_load_lds_dwordx4 v[158:159], off
	s_mov_b32 m0, s24
	v_lshl_add_u64 v[158:159], s[18:19], 0, v[2:3]
	s_mov_b32 s24, m0
	s_mov_b32 m0, s40
	s_nop 0
	global_load_lds_dwordx4 v[158:159], off
	s_mov_b32 m0, s24
	v_lshl_add_u64 v[158:159], s[16:17], 0, v[4:5]
	s_mov_b32 s24, m0
	s_mov_b32 m0, s41
	s_nop 0
	global_load_lds_dwordx4 v[158:159], off
	s_mov_b32 m0, s24
	v_lshl_add_u64 v[158:159], s[18:19], 0, v[4:5]
	s_mov_b32 s24, m0
	s_mov_b32 m0, s42
	s_nop 0
	global_load_lds_dwordx4 v[158:159], off
	s_mov_b32 m0, s24
	v_lshl_add_u64 v[158:159], s[16:17], 0, v[146:147]
	s_mov_b32 s16, m0
	s_mov_b32 m0, s43
	s_nop 0
	global_load_lds_dwordx4 v[158:159], off
	s_mov_b32 m0, s16
	v_lshl_add_u64 v[158:159], s[18:19], 0, v[146:147]
	s_mov_b32 s16, m0
	s_mov_b32 m0, s44
	s_nop 0
	global_load_lds_dwordx4 v[158:159], off
	s_mov_b32 m0, s16
	ds_read_b128 v[158:161], v7 offset:32768
	ds_read_b128 v[162:165], v7 offset:34816
	ds_read_b128 v[166:169], v7 offset:36864
	ds_read_b128 v[214:217], v7 offset:38912
	ds_read_b128 v[178:181], v6
	ds_read_b128 v[218:221], v6 offset:2048
	ds_read_b128 v[222:225], v6 offset:4096
	ds_read_b128 v[226:229], v6 offset:6144
	s_waitcnt lgkmcnt(3)
	v_mfma_f32_16x16x32_bf16 v[40:43], v[158:161], v[178:181], v[40:43]
	v_mfma_f32_16x16x32_bf16 v[44:47], v[162:165], v[178:181], v[44:47]
	v_mfma_f32_16x16x32_bf16 v[48:51], v[166:169], v[178:181], v[48:51]
	v_mfma_f32_16x16x32_bf16 v[174:177], v[214:217], v[178:181], v[174:177]
	ds_read_b128 v[178:181], v6 offset:8192
	s_waitcnt lgkmcnt(3)
	v_mfma_f32_16x16x32_bf16 v[56:59], v[158:161], v[218:221], v[56:59]
	v_mfma_f32_16x16x32_bf16 v[60:63], v[162:165], v[218:221], v[60:63]
	v_mfma_f32_16x16x32_bf16 v[64:67], v[166:169], v[218:221], v[64:67]
	v_mfma_f32_16x16x32_bf16 v[170:173], v[214:217], v[218:221], v[170:173]
	ds_read_b128 v[218:221], v6 offset:10240
	s_waitcnt lgkmcnt(3)
	v_mfma_f32_16x16x32_bf16 v[72:75], v[158:161], v[222:225], v[72:75]
	v_mfma_f32_16x16x32_bf16 v[76:79], v[162:165], v[222:225], v[76:79]
	v_mfma_f32_16x16x32_bf16 v[80:83], v[166:169], v[222:225], v[80:83]
	v_mfma_f32_16x16x32_bf16 v[32:35], v[214:217], v[222:225], v[32:35]
	ds_read_b128 v[222:225], v6 offset:12288
	s_waitcnt lgkmcnt(3)
	v_mfma_f32_16x16x32_bf16 v[88:91], v[158:161], v[226:229], v[88:91]
	v_mfma_f32_16x16x32_bf16 v[92:95], v[162:165], v[226:229], v[92:95]
	v_mfma_f32_16x16x32_bf16 v[96:99], v[166:169], v[226:229], v[96:99]
	v_mfma_f32_16x16x32_bf16 v[36:39], v[214:217], v[226:229], v[36:39]
	ds_read_b128 v[226:229], v6 offset:14336
	s_waitcnt lgkmcnt(3)
	v_mfma_f32_16x16x32_bf16 v[104:107], v[158:161], v[178:181], v[104:107]
	v_mfma_f32_16x16x32_bf16 v[108:111], v[162:165], v[178:181], v[108:111]
	v_mfma_f32_16x16x32_bf16 v[112:115], v[166:169], v[178:181], v[112:115]
	v_mfma_f32_16x16x32_bf16 v[52:55], v[214:217], v[178:181], v[52:55]
	s_waitcnt lgkmcnt(2)
	v_mfma_f32_16x16x32_bf16 v[116:119], v[158:161], v[218:221], v[116:119]
	v_mfma_f32_16x16x32_bf16 v[120:123], v[162:165], v[218:221], v[120:123]
	v_mfma_f32_16x16x32_bf16 v[124:127], v[166:169], v[218:221], v[124:127]
	v_mfma_f32_16x16x32_bf16 v[68:71], v[214:217], v[218:221], v[68:71]
	s_waitcnt lgkmcnt(1)
	v_mfma_f32_16x16x32_bf16 v[132:135], v[162:165], v[222:225], v[132:135]
	v_mfma_f32_16x16x32_bf16 v[84:87], v[214:217], v[222:225], v[84:87]
	s_waitcnt lgkmcnt(0)
	v_mfma_f32_16x16x32_bf16 v[100:103], v[158:161], v[226:229], v[100:103]
	v_mfma_f32_16x16x32_bf16 v[150:153], v[166:169], v[226:229], v[150:153]
	v_mfma_f32_16x16x32_bf16 v[154:157], v[214:217], v[226:229], v[154:157]
	v_mfma_f32_16x16x32_bf16 v[128:131], v[158:161], v[222:225], v[128:131]
	v_mfma_f32_16x16x32_bf16 v[136:139], v[166:169], v[222:225], v[136:139]
	v_mfma_f32_16x16x32_bf16 v[140:143], v[162:165], v[226:229], v[140:143]
	ds_read_b128 v[158:161], v7 offset:33792
	ds_read_b128 v[162:165], v7 offset:35840
	ds_read_b128 v[166:169], v7 offset:37888
	ds_read_b128 v[214:217], v7 offset:39936
	ds_read_b128 v[178:181], v6 offset:1024
	ds_read_b128 v[218:221], v6 offset:3072
	ds_read_b128 v[222:225], v6 offset:5120
	ds_read_b128 v[226:229], v6 offset:7168
	s_waitcnt lgkmcnt(3)
	v_mfma_f32_16x16x32_bf16 v[40:43], v[158:161], v[178:181], v[40:43]
	v_mfma_f32_16x16x32_bf16 v[44:47], v[162:165], v[178:181], v[44:47]
	v_mfma_f32_16x16x32_bf16 v[48:51], v[166:169], v[178:181], v[48:51]
	v_mfma_f32_16x16x32_bf16 v[174:177], v[214:217], v[178:181], v[174:177]
	ds_read_b128 v[178:181], v6 offset:9216
	s_waitcnt lgkmcnt(3)
	v_mfma_f32_16x16x32_bf16 v[56:59], v[158:161], v[218:221], v[56:59]
	v_mfma_f32_16x16x32_bf16 v[60:63], v[162:165], v[218:221], v[60:63]
	v_mfma_f32_16x16x32_bf16 v[64:67], v[166:169], v[218:221], v[64:67]
	v_mfma_f32_16x16x32_bf16 v[170:173], v[214:217], v[218:221], v[170:173]
	ds_read_b128 v[218:221], v6 offset:11264
	s_waitcnt lgkmcnt(3)
	v_mfma_f32_16x16x32_bf16 v[72:75], v[158:161], v[222:225], v[72:75]
	v_mfma_f32_16x16x32_bf16 v[76:79], v[162:165], v[222:225], v[76:79]
	v_mfma_f32_16x16x32_bf16 v[80:83], v[166:169], v[222:225], v[80:83]
	v_mfma_f32_16x16x32_bf16 v[32:35], v[214:217], v[222:225], v[32:35]
	ds_read_b128 v[222:225], v6 offset:13312
	s_waitcnt lgkmcnt(3)
	v_mfma_f32_16x16x32_bf16 v[88:91], v[158:161], v[226:229], v[88:91]
	v_mfma_f32_16x16x32_bf16 v[92:95], v[162:165], v[226:229], v[92:95]
	v_mfma_f32_16x16x32_bf16 v[96:99], v[166:169], v[226:229], v[96:99]
	v_mfma_f32_16x16x32_bf16 v[36:39], v[214:217], v[226:229], v[36:39]
	ds_read_b128 v[226:229], v6 offset:15360
	s_waitcnt lgkmcnt(3)
	v_mfma_f32_16x16x32_bf16 v[104:107], v[158:161], v[178:181], v[104:107]
	v_mfma_f32_16x16x32_bf16 v[108:111], v[162:165], v[178:181], v[108:111]
	v_mfma_f32_16x16x32_bf16 v[112:115], v[166:169], v[178:181], v[112:115]
	v_mfma_f32_16x16x32_bf16 v[52:55], v[214:217], v[178:181], v[52:55]
	s_waitcnt lgkmcnt(2)
	v_mfma_f32_16x16x32_bf16 v[116:119], v[158:161], v[218:221], v[116:119]
	v_mfma_f32_16x16x32_bf16 v[120:123], v[162:165], v[218:221], v[120:123]
	v_mfma_f32_16x16x32_bf16 v[124:127], v[166:169], v[218:221], v[124:127]
	v_mfma_f32_16x16x32_bf16 v[68:71], v[214:217], v[218:221], v[68:71]
	s_waitcnt lgkmcnt(1)
	v_mfma_f32_16x16x32_bf16 v[132:135], v[162:165], v[222:225], v[132:135]
	v_mfma_f32_16x16x32_bf16 v[84:87], v[214:217], v[222:225], v[84:87]
	s_waitcnt lgkmcnt(0)
	v_mfma_f32_16x16x32_bf16 v[100:103], v[158:161], v[226:229], v[100:103]
	v_mfma_f32_16x16x32_bf16 v[150:153], v[166:169], v[226:229], v[150:153]
	v_mfma_f32_16x16x32_bf16 v[154:157], v[214:217], v[226:229], v[154:157]
	v_mfma_f32_16x16x32_bf16 v[128:131], v[158:161], v[222:225], v[128:131]
	v_mfma_f32_16x16x32_bf16 v[136:139], v[166:169], v[222:225], v[136:139]
	v_mfma_f32_16x16x32_bf16 v[140:143], v[162:165], v[226:229], v[140:143]
	s_waitcnt vmcnt(0)
	s_barrier
	v_lshl_add_u64 v[6:7], s[20:21], 0, v[0:1]
	s_mov_b32 s16, m0
	s_mov_b32 m0, s1
	s_nop 0
	global_load_lds_dwordx4 v[6:7], off
	s_mov_b32 m0, s16
	v_lshl_add_u64 v[0:1], s[22:23], 0, v[0:1]
	s_mov_b32 s1, m0
	s_mov_b32 m0, s30
	s_nop 0
	global_load_lds_dwordx4 v[0:1], off
	s_mov_b32 m0, s1
	v_lshl_add_u64 v[0:1], s[20:21], 0, v[2:3]
	s_mov_b32 s1, m0
	s_mov_b32 m0, s31
	s_nop 0
	global_load_lds_dwordx4 v[0:1], off
	s_mov_b32 m0, s1
	v_lshl_add_u64 v[0:1], s[22:23], 0, v[2:3]
	s_mov_b32 s1, m0
	s_mov_b32 m0, s34
	s_nop 0
	global_load_lds_dwordx4 v[0:1], off
	s_mov_b32 m0, s1
	v_lshl_add_u64 v[0:1], s[20:21], 0, v[4:5]
	s_mov_b32 s1, m0
	s_mov_b32 m0, s35
	s_nop 0
	global_load_lds_dwordx4 v[0:1], off
	s_mov_b32 m0, s1
	v_lshl_add_u64 v[0:1], s[22:23], 0, v[4:5]
	s_mov_b32 s1, m0
	s_mov_b32 m0, s36
	s_nop 0
	global_load_lds_dwordx4 v[0:1], off
	s_mov_b32 m0, s1
	v_lshl_add_u64 v[0:1], s[20:21], 0, v[146:147]
	s_mov_b32 s1, m0
	s_mov_b32 m0, s37
	s_nop 0
	global_load_lds_dwordx4 v[0:1], off
	s_mov_b32 m0, s1
	v_lshl_add_u64 v[0:1], s[22:23], 0, v[146:147]
	s_mov_b32 s1, m0
	s_mov_b32 m0, s38
	s_nop 0
	global_load_lds_dwordx4 v[0:1], off
	s_mov_b32 m0, s1
	ds_read_b128 v[0:3], v8
	ds_read_b128 v[4:7], v9
	ds_read_b128 v[158:161], v11
	ds_read_b128 v[8:11], v10
	ds_read_b128 v[162:165], v12
	ds_read_b128 v[166:169], v13
	ds_read_b128 v[178:181], v14
	ds_read_b128 v[12:15], v15
	s_waitcnt lgkmcnt(3)
	v_mfma_f32_16x16x32_bf16 v[40:43], v[0:3], v[162:165], v[40:43]
	v_mfma_f32_16x16x32_bf16 v[44:47], v[4:7], v[162:165], v[44:47]
	v_mfma_f32_16x16x32_bf16 v[48:51], v[158:161], v[162:165], v[48:51]
	v_mfma_f32_16x16x32_bf16 v[162:165], v[8:11], v[162:165], v[174:177]
	s_nop 2
	ds_read_b128 v[174:177], v16
	s_waitcnt lgkmcnt(3)
	v_mfma_f32_16x16x32_bf16 v[56:59], v[0:3], v[166:169], v[56:59]
	v_mfma_f32_16x16x32_bf16 v[60:63], v[4:7], v[166:169], v[60:63]
	v_mfma_f32_16x16x32_bf16 v[64:67], v[158:161], v[166:169], v[64:67]
	v_mfma_f32_16x16x32_bf16 v[166:169], v[8:11], v[166:169], v[170:173]
	s_nop 2
	ds_read_b128 v[170:173], v17
	s_waitcnt lgkmcnt(3)
	v_mfma_f32_16x16x32_bf16 v[72:75], v[0:3], v[178:181], v[72:75]
	v_mfma_f32_16x16x32_bf16 v[76:79], v[4:7], v[178:181], v[76:79]
	v_mfma_f32_16x16x32_bf16 v[80:83], v[158:161], v[178:181], v[80:83]
	v_mfma_f32_16x16x32_bf16 v[32:35], v[8:11], v[178:181], v[32:35]
	ds_read_b128 v[178:181], v18
	s_waitcnt lgkmcnt(3)
	v_mfma_f32_16x16x32_bf16 v[214:217], v[0:3], v[12:15], v[88:91]
	v_mfma_f32_16x16x32_bf16 v[218:221], v[4:7], v[12:15], v[92:95]
	v_mfma_f32_16x16x32_bf16 v[222:225], v[158:161], v[12:15], v[96:99]
	v_mfma_f32_16x16x32_bf16 v[12:15], v[8:11], v[12:15], v[36:39]
	ds_read_b128 v[16:19], v19
	s_waitcnt lgkmcnt(3)
	v_mfma_f32_16x16x32_bf16 v[36:39], v[0:3], v[174:177], v[104:107]
	v_mfma_f32_16x16x32_bf16 v[226:229], v[4:7], v[174:177], v[108:111]
	v_mfma_f32_16x16x32_bf16 v[112:115], v[158:161], v[174:177], v[112:115]
	s_waitcnt lgkmcnt(2)
	v_mfma_f32_16x16x32_bf16 v[116:119], v[0:3], v[170:173], v[116:119]
	v_mfma_f32_16x16x32_bf16 v[120:123], v[4:7], v[170:173], v[120:123]
	v_mfma_f32_16x16x32_bf16 v[124:127], v[158:161], v[170:173], v[124:127]
	s_waitcnt lgkmcnt(1)
	v_mfma_f32_16x16x32_bf16 v[128:131], v[0:3], v[178:181], v[128:131]
	v_mfma_f32_16x16x32_bf16 v[132:135], v[4:7], v[178:181], v[132:135]
	s_waitcnt lgkmcnt(0)
	v_mfma_f32_16x16x32_bf16 v[0:3], v[0:3], v[16:19], v[100:103]
	v_mfma_f32_16x16x32_bf16 v[4:7], v[4:7], v[16:19], v[140:143]
	v_mfma_f32_16x16x32_bf16 v[140:143], v[158:161], v[16:19], v[150:153]
	v_mfma_f32_16x16x32_bf16 v[150:153], v[8:11], v[16:19], v[154:157]
	v_mfma_f32_16x16x32_bf16 v[174:177], v[8:11], v[174:177], v[52:55]
	v_mfma_f32_16x16x32_bf16 v[170:173], v[8:11], v[170:173], v[68:71]
	v_mfma_f32_16x16x32_bf16 v[136:139], v[158:161], v[178:181], v[136:139]
	v_mfma_f32_16x16x32_bf16 v[178:181], v[8:11], v[178:181], v[84:87]
	ds_read_b128 v[8:11], v20
	ds_read_b128 v[154:157], v21
	ds_read_b128 v[158:161], v23
	ds_read_b128 v[230:233], v22
	ds_read_b128 v[16:19], v24
	ds_read_b128 v[20:23], v25
	ds_read_b128 v[52:55], v26
	ds_read_b128 v[24:27], v27
	s_waitcnt lgkmcnt(3)
	v_mfma_f32_16x16x32_bf16 v[234:237], v[8:11], v[16:19], v[40:43]
	v_mfma_f32_16x16x32_bf16 v[238:241], v[154:157], v[16:19], v[44:47]
	v_mfma_f32_16x16x32_bf16 v[242:245], v[158:161], v[16:19], v[48:51]
	v_mfma_f32_16x16x32_bf16 v[162:165], v[230:233], v[16:19], v[162:165]
	ds_read_b128 v[16:19], v28
	s_waitcnt lgkmcnt(3)
	v_mfma_f32_16x16x32_bf16 v[108:111], v[8:11], v[20:23], v[56:59]
	v_mfma_f32_16x16x32_bf16 v[104:107], v[154:157], v[20:23], v[60:63]
	v_mfma_f32_16x16x32_bf16 v[100:103], v[158:161], v[20:23], v[64:67]
	v_mfma_f32_16x16x32_bf16 v[96:99], v[230:233], v[20:23], v[166:169]
	ds_read_b128 v[20:23], v29
	s_waitcnt lgkmcnt(3)
	v_mfma_f32_16x16x32_bf16 v[92:95], v[8:11], v[52:55], v[72:75]
	v_mfma_f32_16x16x32_bf16 v[88:91], v[154:157], v[52:55], v[76:79]
	v_mfma_f32_16x16x32_bf16 v[84:87], v[158:161], v[52:55], v[80:83]
	v_mfma_f32_16x16x32_bf16 v[80:83], v[230:233], v[52:55], v[32:35]
	ds_read_b128 v[166:169], v30
	s_waitcnt lgkmcnt(3)
	v_mfma_f32_16x16x32_bf16 v[76:79], v[8:11], v[24:27], v[214:217]
	v_mfma_f32_16x16x32_bf16 v[72:75], v[154:157], v[24:27], v[218:221]
	v_mfma_f32_16x16x32_bf16 v[68:71], v[158:161], v[24:27], v[222:225]
	v_mfma_f32_16x16x32_bf16 v[64:67], v[230:233], v[24:27], v[12:15]
	ds_read_b128 v[214:217], v31
	s_waitcnt lgkmcnt(3)
	v_mfma_f32_16x16x32_bf16 v[60:63], v[8:11], v[16:19], v[36:39]
	v_mfma_f32_16x16x32_bf16 v[56:59], v[154:157], v[16:19], v[226:229]
	v_mfma_f32_16x16x32_bf16 v[52:55], v[158:161], v[16:19], v[112:115]
	v_mfma_f32_16x16x32_bf16 v[48:51], v[230:233], v[16:19], v[174:177]
	s_waitcnt lgkmcnt(2)
	v_mfma_f32_16x16x32_bf16 v[44:47], v[8:11], v[20:23], v[116:119]
	v_mfma_f32_16x16x32_bf16 v[40:43], v[154:157], v[20:23], v[120:123]
	v_mfma_f32_16x16x32_bf16 v[36:39], v[158:161], v[20:23], v[124:127]
	v_mfma_f32_16x16x32_bf16 v[32:35], v[230:233], v[20:23], v[170:173]
	s_waitcnt lgkmcnt(1)
	v_mfma_f32_16x16x32_bf16 v[28:31], v[8:11], v[166:169], v[128:131]
	v_mfma_f32_16x16x32_bf16 v[24:27], v[154:157], v[166:169], v[132:135]
	v_mfma_f32_16x16x32_bf16 v[20:23], v[158:161], v[166:169], v[136:139]
	v_mfma_f32_16x16x32_bf16 v[16:19], v[230:233], v[166:169], v[178:181]
	s_waitcnt lgkmcnt(0)
	v_mfma_f32_16x16x32_bf16 v[12:15], v[8:11], v[214:217], v[0:3]
	v_mfma_f32_16x16x32_bf16 v[8:11], v[154:157], v[214:217], v[4:7]
	v_mfma_f32_16x16x32_bf16 v[4:7], v[158:161], v[214:217], v[140:143]
	v_mfma_f32_16x16x32_bf16 v[0:3], v[230:233], v[214:217], v[150:153]
	v_mov_b32_e32 v145, v184
	s_waitcnt vmcnt(0)
	s_barrier
	s_lshl_b32 s18, s0, 8
	s_lshl_b32 s16, s14, 8
	v_and_b32_e32 v151, 15, v145
	v_ashrrev_i32_e32 v112, 1, v145
	v_and_b32_e32 v153, 0xffffff80, v112
	v_or_b32_e32 v112, s18, v151
	v_add_u32_e32 v112, v112, v153
	v_ashrrev_i32_e32 v113, 31, v112
	v_lshlrev_b64 v[112:113], 13, v[112:113]
	v_bfe_u32 v150, v145, 6, 2
	v_lshl_add_u64 v[112:113], s[2:3], 0, v[112:113]
	s_ashr_i32 s17, s16, 31
	v_bfe_u32 v152, v145, 4, 2
	v_lshl_add_u64 v[112:113], s[16:17], 2, v[112:113]
	v_lshlrev_b32_e32 v146, 8, v150
	v_lshl_add_u64 v[112:113], v[112:113], 0, v[146:147]
	v_lshlrev_b32_e32 v146, 4, v152
	v_lshl_add_u64 v[154:155], v[112:113], 0, v[146:147]
	global_load_dwordx4 v[120:123], v[154:155], off offset:192
	global_load_dwordx4 v[128:131], v[154:155], off offset:128
	global_load_dwordx4 v[136:139], v[154:155], off offset:64
	global_load_dwordx4 v[140:143], v[154:155], off
	v_add_co_u32_e32 v112, vcc, s66, v154
	v_lshlrev_b32_e32 v158, 2, v152
	s_nop 0
	v_addc_co_u32_e32 v113, vcc, 0, v155, vcc
	global_load_dwordx4 v[132:135], v[112:113], off
	global_load_dwordx4 v[124:127], v[112:113], off offset:64
	global_load_dwordx4 v[116:119], v[112:113], off offset:128
	v_cmp_lt_i32_e32 vcc, v188, v186
	global_load_dwordx4 v[112:115], v[112:113], off offset:192
	v_cmp_eq_u32_e64 s[0:1], 0, v152
	v_cndmask_b32_e32 v146, v185, v188, vcc
	v_cmp_lt_i32_e32 vcc, v187, v186
	v_lshlrev_b32_e32 v149, 2, v146
	v_lshlrev_b32_e32 v157, 6, v150
	v_cndmask_b32_e32 v156, v185, v187, vcc
	v_lshlrev_b32_e32 v146, 2, v156
	v_or_b32_e32 v156, v153, v151
	v_add_u32_e32 v152, s18, v156
	v_ashrrev_i32_e32 v153, 31, v152
	v_lshl_or_b32 v182, v150, 10, v204
	v_or3_b32 v150, v157, s16, v158
	v_lshlrev_b64 v[158:159], 13, v[152:153]
	v_ashrrev_i32_e32 v151, 31, v150
	v_lshlrev_b64 v[160:161], 12, v[152:153]
	v_lshl_add_u64 v[158:159], s[2:3], 0, v[158:159]
	v_lshl_add_u64 v[160:161], s[4:5], 0, v[160:161]
	v_lshl_add_u64 v[166:167], v[150:151], 2, v[158:159]
	v_lshl_add_u64 v[168:169], v[150:151], 1, v[160:161]
	s_waitcnt vmcnt(7)
	v_pk_add_f32 v[158:159], v[162:163], v[120:121]
	s_waitcnt vmcnt(6)
	v_pk_add_f32 v[120:121], v[242:243], v[128:129]
	s_waitcnt vmcnt(5)
	v_pk_add_f32 v[128:129], v[238:239], v[136:137]
	s_waitcnt vmcnt(4)
	v_pk_add_f32 v[136:137], v[234:235], v[140:141]
	v_pk_add_f32 v[160:161], v[164:165], v[122:123]
	v_pk_add_f32 v[122:123], v[244:245], v[130:131]
	v_pk_add_f32 v[130:131], v[240:241], v[138:139]
	v_pk_add_f32 v[138:139], v[236:237], v[142:143]
	v_pk_mul_f32 v[172:173], v[128:129], v[128:129]
	v_pk_mul_f32 v[178:179], v[136:137], v[136:137]
	v_pk_mul_f32 v[162:163], v[120:121], v[120:121]
	v_pk_mul_f32 v[174:175], v[130:131], v[130:131]
	v_cvt_pk_bf16_f32 v176, v136, v137
	v_pk_mul_f32 v[180:181], v[138:139], v[138:139]
	global_store_dwordx4 v[166:167], v[136:139], off
	v_add_f32_e32 v153, v172, v173
	v_add_f32_e32 v157, v178, v179
	v_pk_mul_f32 v[136:137], v[158:159], v[158:159]
	v_pk_mul_f32 v[164:165], v[122:123], v[122:123]
	v_cvt_pk_bf16_f32 v177, v138, v139
	v_pk_mul_f32 v[138:139], v[160:161], v[160:161]
	v_add_f32_e32 v162, v162, v163
	v_add_f32_e32 v136, v136, v137
	v_add_f32_e32 v137, v174, v153
	v_add_f32_e32 v153, v180, v157
	v_add_f32_e32 v157, v164, v162
	v_add_f32_e32 v136, v138, v136
	v_add_f32_e32 v137, v175, v137
	v_add_f32_e32 v138, v181, v153
	v_add_f32_e32 v153, v165, v157
	v_add_f32_e32 v137, v138, v137
	v_add_f32_e32 v137, v137, v153
	v_add_f32_e32 v136, v139, v136
	v_add_f32_e32 v136, v137, v136
	ds_bpermute_b32 v137, v149, v136
	v_cvt_pk_bf16_f32 v170, v128, v129
	v_cvt_pk_bf16_f32 v171, v130, v131
	v_cvt_pk_bf16_f32 v142, v120, v121
	global_store_dwordx2 v[168:169], v[176:177], off
	global_store_dwordx4 v[166:167], v[128:131], off offset:64
	global_store_dwordx2 v[168:169], v[170:171], off offset:32
	global_store_dwordx4 v[166:167], v[120:123], off offset:128
	v_cvt_pk_bf16_f32 v140, v158, v159
	v_cvt_pk_bf16_f32 v141, v160, v161
	s_waitcnt lgkmcnt(0)
	v_add_f32_e32 v120, v136, v137
	ds_bpermute_b32 v121, v146, v120
	v_cvt_pk_bf16_f32 v143, v122, v123
	v_lshl_add_u32 v153, v156, 2, v182
	global_store_dwordx2 v[168:169], v[142:143], off offset:64
	global_store_dwordx4 v[166:167], v[158:161], off offset:192
	global_store_dwordx2 v[168:169], v[140:141], off offset:96
	s_and_saveexec_b64 s[16:17], s[0:1]
	s_cbranch_execz .LBB0_156
	s_waitcnt lgkmcnt(0)
	v_add_f32_e32 v120, v120, v121
	ds_write_b32 v153, v120

.LBB0_252:
	s_mul_i32 s16, s19, 0x300000
	s_mul_hi_i32 s17, s19, 0x300000
	s_add_u32 s16, s22, s16
	s_addc_u32 s17, s23, s17
	s_mul_hi_i32 s19, s18, 0x300000
	s_mul_i32 s18, s18, 0x300000
	s_add_u32 s18, s24, s18
	s_addc_u32 s19, s25, s19
	s_add_u32 s44, s0, 0x80
	v_and_b32_e32 v8, 48, v7
	v_lshlrev_b32_e32 v9, 6, v7
	v_lshlrev_b32_e32 v7, 2, v7
	s_addc_u32 s45, s1, 0
	v_and_b32_e32 v10, 0x3c0, v9
	v_and_b32_e32 v149, 32, v7
	s_add_u32 s46, s14, 0x80
	v_or_b32_e32 v145, v10, v8
	v_bitop3_b32 v12, v10, v149, v8 bitop3:0x36
	s_waitcnt vmcnt(0)
	s_barrier
	v_lshlrev_b32_e32 v8, 13, v6
	s_addc_u32 s47, s15, 0
	s_add_i32 s38, s27, 0x10000
	v_lshl_add_u64 v[6:7], s[44:45], 0, v[0:1]
	s_mov_b32 s39, m0
	s_mov_b32 m0, s38
	s_nop 0
	global_load_lds_dwordx4 v[6:7], off
	s_mov_b32 m0, s39
	s_add_i32 s37, s27, 0x18000
	v_lshl_add_u64 v[6:7], s[46:47], 0, v[0:1]
	s_mov_b32 s39, m0
	s_mov_b32 m0, s37
	s_nop 0
	global_load_lds_dwordx4 v[6:7], off
	s_mov_b32 m0, s39
	v_lshl_add_u64 v[6:7], s[44:45], 0, v[2:3]
	s_add_i32 s39, s27, 0x12000
	s_mov_b32 s40, m0
	s_mov_b32 m0, s39
	s_nop 0
	global_load_lds_dwordx4 v[6:7], off
	s_mov_b32 m0, s40
	v_lshl_add_u64 v[6:7], s[46:47], 0, v[2:3]
	s_add_i32 s40, s27, 0x1a000
	s_mov_b32 s41, m0
	s_mov_b32 m0, s40
	s_nop 0
	global_load_lds_dwordx4 v[6:7], off
	s_mov_b32 m0, s41
	v_lshl_add_u64 v[6:7], s[44:45], 0, v[4:5]
	s_add_i32 s41, s27, 0x14000
	s_mov_b32 s42, m0
	s_mov_b32 m0, s41
	s_nop 0
	global_load_lds_dwordx4 v[6:7], off
	s_mov_b32 m0, s42
	v_lshl_add_u64 v[6:7], s[46:47], 0, v[4:5]
	s_add_i32 s42, s27, 0x1c000
	s_mov_b32 s43, m0
	s_mov_b32 m0, s42
	s_nop 0
	global_load_lds_dwordx4 v[6:7], off
	s_mov_b32 m0, s43
	v_lshl_add_u64 v[6:7], s[44:45], 0, v[146:147]
	s_add_i32 s43, s27, 0x16000
	s_mov_b32 s44, m0
	s_mov_b32 m0, s43
	s_nop 0
	global_load_lds_dwordx4 v[6:7], off
	s_mov_b32 m0, s44
	v_lshl_add_u64 v[6:7], s[46:47], 0, v[146:147]
	s_add_i32 s44, s27, 0x1e000
	s_mov_b32 s45, m0
	s_mov_b32 m0, s44
	s_nop 0
	global_load_lds_dwordx4 v[6:7], off
	s_mov_b32 m0, s45
	v_and_b32_e32 v182, 0xffffc000, v9
	v_or_b32_e32 v183, 0x800, v182
	v_or_b32_e32 v189, 0x1000, v182
	v_or_b32_e32 v199, 0x1800, v182
	v_or_b32_e32 v200, 0x2000, v182
	v_or_b32_e32 v201, 0x2800, v182
	v_or_b32_e32 v203, 0x3000, v182
	v_or_b32_e32 v206, 0x3800, v182
	s_movk_i32 s45, 0x6000
	v_and_or_b32 v7, v8, s45, v12
	ds_read_b128 v[8:11], v7 offset:32768
	v_or_b32_e32 v6, v12, v182
	ds_read_b128 v[12:15], v7 offset:34816
	ds_read_b128 v[16:19], v7 offset:36864
	ds_read_b128 v[24:27], v7 offset:38912
	ds_read_b128 v[20:23], v6
	ds_read_b128 v[28:31], v6 offset:2048
	ds_read_b128 v[32:35], v6 offset:4096
	ds_read_b128 v[36:39], v6 offset:6144
	s_waitcnt lgkmcnt(3)
	v_mfma_f32_16x16x32_bf16 v[40:43], v[8:11], v[20:23], 0
	v_mfma_f32_16x16x32_bf16 v[44:47], v[12:15], v[20:23], 0
	v_mfma_f32_16x16x32_bf16 v[48:51], v[16:19], v[20:23], 0
	v_mfma_f32_16x16x32_bf16 v[20:23], v[24:27], v[20:23], 0
	ds_read_b128 v[52:55], v6 offset:8192
	s_waitcnt lgkmcnt(3)
	v_mfma_f32_16x16x32_bf16 v[56:59], v[8:11], v[28:31], 0
	v_mfma_f32_16x16x32_bf16 v[60:63], v[12:15], v[28:31], 0
	v_mfma_f32_16x16x32_bf16 v[64:67], v[16:19], v[28:31], 0
	v_mfma_f32_16x16x32_bf16 v[28:31], v[24:27], v[28:31], 0
	ds_read_b128 v[68:71], v6 offset:10240
	s_waitcnt lgkmcnt(3)
	v_mfma_f32_16x16x32_bf16 v[72:75], v[8:11], v[32:35], 0
	v_mfma_f32_16x16x32_bf16 v[76:79], v[12:15], v[32:35], 0
	v_mfma_f32_16x16x32_bf16 v[80:83], v[16:19], v[32:35], 0
	v_mfma_f32_16x16x32_bf16 v[32:35], v[24:27], v[32:35], 0
	ds_read_b128 v[84:87], v6 offset:12288
	s_waitcnt lgkmcnt(3)
	v_mfma_f32_16x16x32_bf16 v[88:91], v[8:11], v[36:39], 0
	v_mfma_f32_16x16x32_bf16 v[92:95], v[12:15], v[36:39], 0
	v_mfma_f32_16x16x32_bf16 v[96:99], v[16:19], v[36:39], 0
	v_mfma_f32_16x16x32_bf16 v[36:39], v[24:27], v[36:39], 0
	ds_read_b128 v[100:103], v6 offset:14336
	s_waitcnt lgkmcnt(3)
	v_mfma_f32_16x16x32_bf16 v[104:107], v[8:11], v[52:55], 0
	v_mfma_f32_16x16x32_bf16 v[108:111], v[12:15], v[52:55], 0
	v_mfma_f32_16x16x32_bf16 v[112:115], v[16:19], v[52:55], 0
	v_mfma_f32_16x16x32_bf16 v[52:55], v[24:27], v[52:55], 0
	s_waitcnt lgkmcnt(2)
	v_mfma_f32_16x16x32_bf16 v[116:119], v[8:11], v[68:71], 0
	v_mfma_f32_16x16x32_bf16 v[120:123], v[12:15], v[68:71], 0
	v_mfma_f32_16x16x32_bf16 v[124:127], v[16:19], v[68:71], 0
	v_mfma_f32_16x16x32_bf16 v[68:71], v[24:27], v[68:71], 0
	s_waitcnt lgkmcnt(1)
	v_mfma_f32_16x16x32_bf16 v[128:131], v[8:11], v[84:87], 0
	v_mfma_f32_16x16x32_bf16 v[132:135], v[12:15], v[84:87], 0
	v_mfma_f32_16x16x32_bf16 v[136:139], v[16:19], v[84:87], 0
	v_mfma_f32_16x16x32_bf16 v[84:87], v[24:27], v[84:87], 0
	s_waitcnt lgkmcnt(0)
	v_mfma_f32_16x16x32_bf16 v[8:11], v[8:11], v[100:103], 0
	v_mfma_f32_16x16x32_bf16 v[12:15], v[12:15], v[100:103], 0
	v_mfma_f32_16x16x32_bf16 v[16:19], v[16:19], v[100:103], 0
	v_mfma_f32_16x16x32_bf16 v[24:27], v[24:27], v[100:103], 0
	ds_read_b128 v[100:103], v7 offset:33792
	ds_read_b128 v[140:143], v7 offset:35840
	ds_read_b128 v[150:153], v7 offset:37888
	ds_read_b128 v[158:161], v7 offset:39936
	ds_read_b128 v[154:157], v6 offset:1024
	ds_read_b128 v[162:165], v6 offset:3072
	ds_read_b128 v[166:169], v6 offset:5120
	ds_read_b128 v[170:173], v6 offset:7168
	s_waitcnt lgkmcnt(3)
	v_mfma_f32_16x16x32_bf16 v[40:43], v[100:103], v[154:157], v[40:43]
	v_mfma_f32_16x16x32_bf16 v[44:47], v[140:143], v[154:157], v[44:47]
	v_mfma_f32_16x16x32_bf16 v[48:51], v[150:153], v[154:157], v[48:51]
	v_mfma_f32_16x16x32_bf16 v[20:23], v[158:161], v[154:157], v[20:23]
	ds_read_b128 v[154:157], v6 offset:9216
	s_waitcnt lgkmcnt(3)
	v_mfma_f32_16x16x32_bf16 v[56:59], v[100:103], v[162:165], v[56:59]
	v_mfma_f32_16x16x32_bf16 v[60:63], v[140:143], v[162:165], v[60:63]
	v_mfma_f32_16x16x32_bf16 v[64:67], v[150:153], v[162:165], v[64:67]
	v_mfma_f32_16x16x32_bf16 v[28:31], v[158:161], v[162:165], v[28:31]
	ds_read_b128 v[162:165], v6 offset:11264
	s_waitcnt lgkmcnt(3)
	v_mfma_f32_16x16x32_bf16 v[72:75], v[100:103], v[166:169], v[72:75]
	v_mfma_f32_16x16x32_bf16 v[76:79], v[140:143], v[166:169], v[76:79]
	v_mfma_f32_16x16x32_bf16 v[80:83], v[150:153], v[166:169], v[80:83]
	v_mfma_f32_16x16x32_bf16 v[32:35], v[158:161], v[166:169], v[32:35]
	ds_read_b128 v[166:169], v6 offset:13312
	s_waitcnt lgkmcnt(3)
	v_mfma_f32_16x16x32_bf16 v[88:91], v[100:103], v[170:173], v[88:91]
	v_mfma_f32_16x16x32_bf16 v[92:95], v[140:143], v[170:173], v[92:95]
	v_mfma_f32_16x16x32_bf16 v[96:99], v[150:153], v[170:173], v[96:99]
	v_mfma_f32_16x16x32_bf16 v[36:39], v[158:161], v[170:173], v[36:39]
	ds_read_b128 v[170:173], v6 offset:15360
	s_waitcnt lgkmcnt(3)
	v_mfma_f32_16x16x32_bf16 v[104:107], v[100:103], v[154:157], v[104:107]
	v_mfma_f32_16x16x32_bf16 v[108:111], v[140:143], v[154:157], v[108:111]
	v_mfma_f32_16x16x32_bf16 v[112:115], v[150:153], v[154:157], v[112:115]
	v_mfma_f32_16x16x32_bf16 v[52:55], v[158:161], v[154:157], v[52:55]
	s_waitcnt lgkmcnt(2)
	v_mfma_f32_16x16x32_bf16 v[116:119], v[100:103], v[162:165], v[116:119]
	v_mfma_f32_16x16x32_bf16 v[120:123], v[140:143], v[162:165], v[120:123]
	v_mfma_f32_16x16x32_bf16 v[124:127], v[150:153], v[162:165], v[124:127]
	v_mfma_f32_16x16x32_bf16 v[68:71], v[158:161], v[162:165], v[68:71]
	s_waitcnt lgkmcnt(1)
	v_mfma_f32_16x16x32_bf16 v[128:131], v[100:103], v[166:169], v[128:131]
	v_mfma_f32_16x16x32_bf16 v[132:135], v[140:143], v[166:169], v[132:135]
	v_mfma_f32_16x16x32_bf16 v[136:139], v[150:153], v[166:169], v[136:139]
	v_mfma_f32_16x16x32_bf16 v[84:87], v[158:161], v[166:169], v[84:87]
	s_waitcnt lgkmcnt(0)
	v_mfma_f32_16x16x32_bf16 v[100:103], v[100:103], v[170:173], v[8:11]
	v_mfma_f32_16x16x32_bf16 v[150:153], v[150:153], v[170:173], v[16:19]
	v_mfma_f32_16x16x32_bf16 v[24:27], v[158:161], v[170:173], v[24:27]
	v_mfma_f32_16x16x32_bf16 v[140:143], v[140:143], v[170:173], v[12:15]
	s_add_u32 s46, s0, 0x100
	s_addc_u32 s47, s1, 0
	s_add_u32 s48, s14, 0x100
	s_waitcnt vmcnt(0)
	s_barrier
	s_addc_u32 s49, s15, 0
	v_lshl_add_u64 v[8:9], s[46:47], 0, v[0:1]
	s_mov_b32 s45, m0
	s_mov_b32 m0, s27
	s_nop 0
	global_load_lds_dwordx4 v[8:9], off
	s_mov_b32 m0, s45
	v_lshl_add_u64 v[8:9], s[48:49], 0, v[0:1]
	s_mov_b32 s45, m0
	s_mov_b32 m0, s28
	s_nop 0
	global_load_lds_dwordx4 v[8:9], off
	s_mov_b32 m0, s45
	v_lshl_add_u64 v[8:9], s[46:47], 0, v[2:3]
	s_mov_b32 s45, m0
	s_mov_b32 m0, s29
	s_nop 0
	global_load_lds_dwordx4 v[8:9], off
	s_mov_b32 m0, s45
	v_lshl_add_u64 v[8:9], s[48:49], 0, v[2:3]
	s_mov_b32 s45, m0
	s_mov_b32 m0, s30
	s_nop 0
	global_load_lds_dwordx4 v[8:9], off
	s_mov_b32 m0, s45
	v_lshl_add_u64 v[8:9], s[46:47], 0, v[4:5]
	s_mov_b32 s45, m0
	s_mov_b32 m0, s31
	s_nop 0
	global_load_lds_dwordx4 v[8:9], off
	s_mov_b32 m0, s45
	v_lshl_add_u64 v[8:9], s[48:49], 0, v[4:5]
	s_mov_b32 s45, m0
	s_mov_b32 m0, s34
	s_nop 0
	global_load_lds_dwordx4 v[8:9], off
	s_mov_b32 m0, s45
	v_lshl_add_u64 v[8:9], s[46:47], 0, v[146:147]
	s_mov_b32 s45, m0
	s_mov_b32 m0, s35
	s_nop 0
	global_load_lds_dwordx4 v[8:9], off
	s_mov_b32 m0, s45
	v_lshl_add_u64 v[8:9], s[48:49], 0, v[146:147]
	s_mov_b32 s45, m0
	s_mov_b32 m0, s36
	s_nop 0
	global_load_lds_dwordx4 v[8:9], off
	s_mov_b32 m0, s45
	v_or_b32_e32 v8, 0x18000, v7
	v_or_b32_e32 v9, 0x18800, v7
	v_or_b32_e32 v11, 0x19000, v7
	v_or_b32_e32 v10, 0x19800, v7
	ds_read_b128 v[154:157], v8
	ds_read_b128 v[158:161], v9
	ds_read_b128 v[162:165], v11
	ds_read_b128 v[166:169], v10
	v_bitop3_b32 v207, v145, s33, v149 bitop3:0xde
	v_add_u32_e32 v12, v207, v182
	ds_read_b128 v[16:19], v12
	v_add_u32_e32 v13, v207, v183
	v_add_u32_e32 v14, v207, v189
	v_add_u32_e32 v15, v207, v199
	ds_read_b128 v[170:173], v13
	ds_read_b128 v[174:177], v14
	ds_read_b128 v[178:181], v15
	s_waitcnt lgkmcnt(3)
	v_mfma_f32_16x16x32_bf16 v[40:43], v[154:157], v[16:19], v[40:43]
	v_mfma_f32_16x16x32_bf16 v[44:47], v[158:161], v[16:19], v[44:47]
	v_mfma_f32_16x16x32_bf16 v[48:51], v[162:165], v[16:19], v[48:51]
	v_mfma_f32_16x16x32_bf16 v[214:217], v[166:169], v[16:19], v[20:23]
	v_add_u32_e32 v16, v207, v200
	v_add_u32_e32 v17, v207, v201
	v_add_u32_e32 v18, v207, v203
	v_add_u32_e32 v19, v207, v206
	ds_read_b128 v[20:23], v16
	s_waitcnt lgkmcnt(3)
	v_mfma_f32_16x16x32_bf16 v[56:59], v[154:157], v[170:173], v[56:59]
	v_mfma_f32_16x16x32_bf16 v[60:63], v[158:161], v[170:173], v[60:63]
	v_mfma_f32_16x16x32_bf16 v[64:67], v[162:165], v[170:173], v[64:67]
	v_mfma_f32_16x16x32_bf16 v[170:173], v[166:169], v[170:173], v[28:31]
	s_nop 2
	ds_read_b128 v[28:31], v17
	s_waitcnt lgkmcnt(3)
	v_mfma_f32_16x16x32_bf16 v[72:75], v[154:157], v[174:177], v[72:75]
	v_mfma_f32_16x16x32_bf16 v[76:79], v[158:161], v[174:177], v[76:79]
	v_mfma_f32_16x16x32_bf16 v[80:83], v[162:165], v[174:177], v[80:83]
	v_mfma_f32_16x16x32_bf16 v[32:35], v[166:169], v[174:177], v[32:35]
	ds_read_b128 v[174:177], v18
	s_waitcnt lgkmcnt(3)
	v_mfma_f32_16x16x32_bf16 v[88:91], v[154:157], v[178:181], v[88:91]
	v_mfma_f32_16x16x32_bf16 v[92:95], v[158:161], v[178:181], v[92:95]
	v_mfma_f32_16x16x32_bf16 v[96:99], v[162:165], v[178:181], v[96:99]
	v_mfma_f32_16x16x32_bf16 v[36:39], v[166:169], v[178:181], v[36:39]
	ds_read_b128 v[178:181], v19
	s_waitcnt lgkmcnt(3)
	v_mfma_f32_16x16x32_bf16 v[104:107], v[154:157], v[20:23], v[104:107]
	v_mfma_f32_16x16x32_bf16 v[108:111], v[158:161], v[20:23], v[108:111]
	v_mfma_f32_16x16x32_bf16 v[112:115], v[162:165], v[20:23], v[112:115]
	v_mfma_f32_16x16x32_bf16 v[52:55], v[166:169], v[20:23], v[52:55]
	s_waitcnt lgkmcnt(2)
	v_mfma_f32_16x16x32_bf16 v[116:119], v[154:157], v[28:31], v[116:119]
	v_mfma_f32_16x16x32_bf16 v[120:123], v[158:161], v[28:31], v[120:123]
	v_mfma_f32_16x16x32_bf16 v[124:127], v[162:165], v[28:31], v[124:127]
	v_mfma_f32_16x16x32_bf16 v[68:71], v[166:169], v[28:31], v[68:71]
	s_waitcnt lgkmcnt(1)
	v_mfma_f32_16x16x32_bf16 v[128:131], v[154:157], v[174:177], v[128:131]
	v_mfma_f32_16x16x32_bf16 v[132:135], v[158:161], v[174:177], v[132:135]
	v_mfma_f32_16x16x32_bf16 v[84:87], v[166:169], v[174:177], v[84:87]
	s_waitcnt lgkmcnt(0)
	v_mfma_f32_16x16x32_bf16 v[100:103], v[154:157], v[178:181], v[100:103]
	v_mfma_f32_16x16x32_bf16 v[150:153], v[162:165], v[178:181], v[150:153]
	v_mfma_f32_16x16x32_bf16 v[154:157], v[166:169], v[178:181], v[24:27]
	v_mfma_f32_16x16x32_bf16 v[136:139], v[162:165], v[174:177], v[136:139]
	v_mfma_f32_16x16x32_bf16 v[140:143], v[158:161], v[178:181], v[140:143]
	v_or_b32_e32 v20, 0x18400, v7
	v_or_b32_e32 v21, 0x18c00, v7
	v_or_b32_e32 v23, 0x19400, v7
	v_or_b32_e32 v22, 0x19c00, v7
	ds_read_b128 v[158:161], v20
	ds_read_b128 v[162:165], v21
	ds_read_b128 v[166:169], v23
	ds_read_b128 v[174:177], v22
	s_mov_b32 s45, 0x10400
	v_bitop3_b32 v145, v145, s45, v149 bitop3:0xde
	v_add_u32_e32 v24, v145, v182
	ds_read_b128 v[28:31], v24
	v_add_u32_e32 v25, v145, v183
	v_add_u32_e32 v26, v145, v189
	v_add_u32_e32 v27, v145, v199
	ds_read_b128 v[178:181], v25
	ds_read_b128 v[218:221], v26
	ds_read_b128 v[222:225], v27
	s_waitcnt lgkmcnt(3)
	v_mfma_f32_16x16x32_bf16 v[40:43], v[158:161], v[28:31], v[40:43]
	v_mfma_f32_16x16x32_bf16 v[44:47], v[162:165], v[28:31], v[44:47]
	v_mfma_f32_16x16x32_bf16 v[48:51], v[166:169], v[28:31], v[48:51]
	v_mfma_f32_16x16x32_bf16 v[214:217], v[174:177], v[28:31], v[214:217]
	v_add_u32_e32 v28, v145, v200
	v_add_u32_e32 v29, v145, v201
	v_add_u32_e32 v30, v145, v203
	v_add_u32_e32 v31, v145, v206
	ds_read_b128 v[226:229], v28
	s_waitcnt lgkmcnt(3)
	v_mfma_f32_16x16x32_bf16 v[56:59], v[158:161], v[178:181], v[56:59]
	v_mfma_f32_16x16x32_bf16 v[60:63], v[162:165], v[178:181], v[60:63]
	v_mfma_f32_16x16x32_bf16 v[64:67], v[166:169], v[178:181], v[64:67]
	v_mfma_f32_16x16x32_bf16 v[170:173], v[174:177], v[178:181], v[170:173]
	ds_read_b128 v[178:181], v29
	s_waitcnt lgkmcnt(3)
	v_mfma_f32_16x16x32_bf16 v[72:75], v[158:161], v[218:221], v[72:75]
	v_mfma_f32_16x16x32_bf16 v[76:79], v[162:165], v[218:221], v[76:79]
	v_mfma_f32_16x16x32_bf16 v[80:83], v[166:169], v[218:221], v[80:83]
	v_mfma_f32_16x16x32_bf16 v[32:35], v[174:177], v[218:221], v[32:35]
	ds_read_b128 v[218:221], v30
	s_waitcnt lgkmcnt(3)
	v_mfma_f32_16x16x32_bf16 v[88:91], v[158:161], v[222:225], v[88:91]
	v_mfma_f32_16x16x32_bf16 v[92:95], v[162:165], v[222:225], v[92:95]
	v_mfma_f32_16x16x32_bf16 v[96:99], v[166:169], v[222:225], v[96:99]
	v_mfma_f32_16x16x32_bf16 v[36:39], v[174:177], v[222:225], v[36:39]
	ds_read_b128 v[222:225], v31
	s_waitcnt lgkmcnt(3)
	v_mfma_f32_16x16x32_bf16 v[104:107], v[158:161], v[226:229], v[104:107]
	v_mfma_f32_16x16x32_bf16 v[108:111], v[162:165], v[226:229], v[108:111]
	v_mfma_f32_16x16x32_bf16 v[112:115], v[166:169], v[226:229], v[112:115]
	v_mfma_f32_16x16x32_bf16 v[52:55], v[174:177], v[226:229], v[52:55]
	s_waitcnt lgkmcnt(2)
	v_mfma_f32_16x16x32_bf16 v[116:119], v[158:161], v[178:181], v[116:119]
	v_mfma_f32_16x16x32_bf16 v[120:123], v[162:165], v[178:181], v[120:123]
	v_mfma_f32_16x16x32_bf16 v[124:127], v[166:169], v[178:181], v[124:127]
	v_mfma_f32_16x16x32_bf16 v[68:71], v[174:177], v[178:181], v[68:71]
	s_waitcnt lgkmcnt(1)
	v_mfma_f32_16x16x32_bf16 v[132:135], v[162:165], v[218:221], v[132:135]
	v_mfma_f32_16x16x32_bf16 v[84:87], v[174:177], v[218:221], v[84:87]
	s_waitcnt lgkmcnt(0)
	v_mfma_f32_16x16x32_bf16 v[100:103], v[158:161], v[222:225], v[100:103]
	v_mfma_f32_16x16x32_bf16 v[150:153], v[166:169], v[222:225], v[150:153]
	v_mfma_f32_16x16x32_bf16 v[154:157], v[174:177], v[222:225], v[154:157]
	v_mfma_f32_16x16x32_bf16 v[128:131], v[158:161], v[218:221], v[128:131]
	v_mfma_f32_16x16x32_bf16 v[136:139], v[166:169], v[218:221], v[136:139]
	v_mfma_f32_16x16x32_bf16 v[140:143], v[162:165], v[222:225], v[140:143]
	s_add_u32 s46, s0, 0x180
	s_addc_u32 s47, s1, 0
	s_add_u32 s48, s14, 0x180
	s_waitcnt vmcnt(0)
	s_barrier
	s_addc_u32 s49, s15, 0
	v_lshl_add_u64 v[158:159], s[46:47], 0, v[0:1]
	s_mov_b32 s45, m0
	s_mov_b32 m0, s38
	s_nop 0
	global_load_lds_dwordx4 v[158:159], off
	s_mov_b32 m0, s45
	v_lshl_add_u64 v[158:159], s[48:49], 0, v[0:1]
	s_mov_b32 s45, m0
	s_mov_b32 m0, s37
	s_nop 0
	global_load_lds_dwordx4 v[158:159], off
	s_mov_b32 m0, s45
	v_lshl_add_u64 v[158:159], s[46:47], 0, v[2:3]
	s_mov_b32 s45, m0
	s_mov_b32 m0, s39
	s_nop 0
	global_load_lds_dwordx4 v[158:159], off
	s_mov_b32 m0, s45
	v_lshl_add_u64 v[158:159], s[48:49], 0, v[2:3]
	s_mov_b32 s45, m0
	s_mov_b32 m0, s40
	s_nop 0
	global_load_lds_dwordx4 v[158:159], off
	s_mov_b32 m0, s45
	v_lshl_add_u64 v[158:159], s[46:47], 0, v[4:5]
	s_mov_b32 s45, m0
	s_mov_b32 m0, s41
	s_nop 0
	global_load_lds_dwordx4 v[158:159], off
	s_mov_b32 m0, s45
	v_lshl_add_u64 v[158:159], s[48:49], 0, v[4:5]
	s_mov_b32 s45, m0
	s_mov_b32 m0, s42
	s_nop 0
	global_load_lds_dwordx4 v[158:159], off
	s_mov_b32 m0, s45
	v_lshl_add_u64 v[158:159], s[46:47], 0, v[146:147]
	s_mov_b32 s45, m0
	s_mov_b32 m0, s43
	s_nop 0
	global_load_lds_dwordx4 v[158:159], off
	s_mov_b32 m0, s45
	v_lshl_add_u64 v[158:159], s[48:49], 0, v[146:147]
	s_mov_b32 s45, m0
	s_mov_b32 m0, s44
	s_nop 0
	global_load_lds_dwordx4 v[158:159], off
	s_mov_b32 m0, s45
	ds_read_b128 v[158:161], v7 offset:32768
	ds_read_b128 v[162:165], v7 offset:34816
	ds_read_b128 v[166:169], v7 offset:36864
	ds_read_b128 v[178:181], v7 offset:38912
	ds_read_b128 v[174:177], v6
	ds_read_b128 v[218:221], v6 offset:2048
	ds_read_b128 v[222:225], v6 offset:4096
	ds_read_b128 v[226:229], v6 offset:6144
	s_waitcnt lgkmcnt(3)
	v_mfma_f32_16x16x32_bf16 v[40:43], v[158:161], v[174:177], v[40:43]
	v_mfma_f32_16x16x32_bf16 v[44:47], v[162:165], v[174:177], v[44:47]
	v_mfma_f32_16x16x32_bf16 v[48:51], v[166:169], v[174:177], v[48:51]
	v_mfma_f32_16x16x32_bf16 v[174:177], v[178:181], v[174:177], v[214:217]
	s_nop 2
	ds_read_b128 v[214:217], v6 offset:8192
	s_waitcnt lgkmcnt(3)
	v_mfma_f32_16x16x32_bf16 v[56:59], v[158:161], v[218:221], v[56:59]
	v_mfma_f32_16x16x32_bf16 v[60:63], v[162:165], v[218:221], v[60:63]
	v_mfma_f32_16x16x32_bf16 v[64:67], v[166:169], v[218:221], v[64:67]
	v_mfma_f32_16x16x32_bf16 v[170:173], v[178:181], v[218:221], v[170:173]
	ds_read_b128 v[218:221], v6 offset:10240
	s_waitcnt lgkmcnt(3)
	v_mfma_f32_16x16x32_bf16 v[72:75], v[158:161], v[222:225], v[72:75]
	v_mfma_f32_16x16x32_bf16 v[76:79], v[162:165], v[222:225], v[76:79]
	v_mfma_f32_16x16x32_bf16 v[80:83], v[166:169], v[222:225], v[80:83]
	v_mfma_f32_16x16x32_bf16 v[32:35], v[178:181], v[222:225], v[32:35]
	ds_read_b128 v[222:225], v6 offset:12288
	s_waitcnt lgkmcnt(3)
	v_mfma_f32_16x16x32_bf16 v[88:91], v[158:161], v[226:229], v[88:91]
	v_mfma_f32_16x16x32_bf16 v[92:95], v[162:165], v[226:229], v[92:95]
	v_mfma_f32_16x16x32_bf16 v[96:99], v[166:169], v[226:229], v[96:99]
	v_mfma_f32_16x16x32_bf16 v[36:39], v[178:181], v[226:229], v[36:39]
	ds_read_b128 v[226:229], v6 offset:14336
	s_waitcnt lgkmcnt(3)
	v_mfma_f32_16x16x32_bf16 v[104:107], v[158:161], v[214:217], v[104:107]
	v_mfma_f32_16x16x32_bf16 v[108:111], v[162:165], v[214:217], v[108:111]
	v_mfma_f32_16x16x32_bf16 v[112:115], v[166:169], v[214:217], v[112:115]
	v_mfma_f32_16x16x32_bf16 v[52:55], v[178:181], v[214:217], v[52:55]
	s_waitcnt lgkmcnt(2)
	v_mfma_f32_16x16x32_bf16 v[116:119], v[158:161], v[218:221], v[116:119]
	v_mfma_f32_16x16x32_bf16 v[120:123], v[162:165], v[218:221], v[120:123]
	v_mfma_f32_16x16x32_bf16 v[124:127], v[166:169], v[218:221], v[124:127]
	v_mfma_f32_16x16x32_bf16 v[68:71], v[178:181], v[218:221], v[68:71]
	s_waitcnt lgkmcnt(1)
	v_mfma_f32_16x16x32_bf16 v[132:135], v[162:165], v[222:225], v[132:135]
	v_mfma_f32_16x16x32_bf16 v[84:87], v[178:181], v[222:225], v[84:87]
	s_waitcnt lgkmcnt(0)
	v_mfma_f32_16x16x32_bf16 v[100:103], v[158:161], v[226:229], v[100:103]
	v_mfma_f32_16x16x32_bf16 v[150:153], v[166:169], v[226:229], v[150:153]
	v_mfma_f32_16x16x32_bf16 v[154:157], v[178:181], v[226:229], v[154:157]
	v_mfma_f32_16x16x32_bf16 v[128:131], v[158:161], v[222:225], v[128:131]
	v_mfma_f32_16x16x32_bf16 v[136:139], v[166:169], v[222:225], v[136:139]
	v_mfma_f32_16x16x32_bf16 v[140:143], v[162:165], v[226:229], v[140:143]
	ds_read_b128 v[158:161], v7 offset:33792
	ds_read_b128 v[162:165], v7 offset:35840
	ds_read_b128 v[166:169], v7 offset:37888
	ds_read_b128 v[214:217], v7 offset:39936
	ds_read_b128 v[178:181], v6 offset:1024
	ds_read_b128 v[218:221], v6 offset:3072
	ds_read_b128 v[222:225], v6 offset:5120
	ds_read_b128 v[226:229], v6 offset:7168
	s_waitcnt lgkmcnt(3)
	v_mfma_f32_16x16x32_bf16 v[40:43], v[158:161], v[178:181], v[40:43]
	v_mfma_f32_16x16x32_bf16 v[44:47], v[162:165], v[178:181], v[44:47]
	v_mfma_f32_16x16x32_bf16 v[48:51], v[166:169], v[178:181], v[48:51]
	v_mfma_f32_16x16x32_bf16 v[174:177], v[214:217], v[178:181], v[174:177]
	ds_read_b128 v[178:181], v6 offset:9216
	s_waitcnt lgkmcnt(3)
	v_mfma_f32_16x16x32_bf16 v[56:59], v[158:161], v[218:221], v[56:59]
	v_mfma_f32_16x16x32_bf16 v[60:63], v[162:165], v[218:221], v[60:63]
	v_mfma_f32_16x16x32_bf16 v[64:67], v[166:169], v[218:221], v[64:67]
	v_mfma_f32_16x16x32_bf16 v[170:173], v[214:217], v[218:221], v[170:173]
	ds_read_b128 v[218:221], v6 offset:11264
	s_waitcnt lgkmcnt(3)
	v_mfma_f32_16x16x32_bf16 v[72:75], v[158:161], v[222:225], v[72:75]
	v_mfma_f32_16x16x32_bf16 v[76:79], v[162:165], v[222:225], v[76:79]
	v_mfma_f32_16x16x32_bf16 v[80:83], v[166:169], v[222:225], v[80:83]
	v_mfma_f32_16x16x32_bf16 v[32:35], v[214:217], v[222:225], v[32:35]
	ds_read_b128 v[222:225], v6 offset:13312
	s_waitcnt lgkmcnt(3)
	v_mfma_f32_16x16x32_bf16 v[88:91], v[158:161], v[226:229], v[88:91]
	v_mfma_f32_16x16x32_bf16 v[92:95], v[162:165], v[226:229], v[92:95]
	v_mfma_f32_16x16x32_bf16 v[96:99], v[166:169], v[226:229], v[96:99]
	v_mfma_f32_16x16x32_bf16 v[36:39], v[214:217], v[226:229], v[36:39]
	ds_read_b128 v[226:229], v6 offset:15360
	s_waitcnt lgkmcnt(3)
	v_mfma_f32_16x16x32_bf16 v[104:107], v[158:161], v[178:181], v[104:107]
	v_mfma_f32_16x16x32_bf16 v[108:111], v[162:165], v[178:181], v[108:111]
	v_mfma_f32_16x16x32_bf16 v[112:115], v[166:169], v[178:181], v[112:115]
	v_mfma_f32_16x16x32_bf16 v[52:55], v[214:217], v[178:181], v[52:55]
	s_waitcnt lgkmcnt(2)
	v_mfma_f32_16x16x32_bf16 v[116:119], v[158:161], v[218:221], v[116:119]
	v_mfma_f32_16x16x32_bf16 v[120:123], v[162:165], v[218:221], v[120:123]
	v_mfma_f32_16x16x32_bf16 v[124:127], v[166:169], v[218:221], v[124:127]
	v_mfma_f32_16x16x32_bf16 v[68:71], v[214:217], v[218:221], v[68:71]
	s_waitcnt lgkmcnt(1)
	v_mfma_f32_16x16x32_bf16 v[132:135], v[162:165], v[222:225], v[132:135]
	v_mfma_f32_16x16x32_bf16 v[84:87], v[214:217], v[222:225], v[84:87]
	s_waitcnt lgkmcnt(0)
	v_mfma_f32_16x16x32_bf16 v[100:103], v[158:161], v[226:229], v[100:103]
	v_mfma_f32_16x16x32_bf16 v[150:153], v[166:169], v[226:229], v[150:153]
	v_mfma_f32_16x16x32_bf16 v[154:157], v[214:217], v[226:229], v[154:157]
	v_mfma_f32_16x16x32_bf16 v[128:131], v[158:161], v[222:225], v[128:131]
	v_mfma_f32_16x16x32_bf16 v[136:139], v[166:169], v[222:225], v[136:139]
	v_mfma_f32_16x16x32_bf16 v[140:143], v[162:165], v[226:229], v[140:143]
	s_add_u32 s46, s0, 0x200
	s_addc_u32 s47, s1, 0
	s_add_u32 s48, s14, 0x200
	s_waitcnt vmcnt(0)
	s_barrier
	s_addc_u32 s49, s15, 0
	s_mov_b32 s45, 0x280
	ds_read_b128 v[158:161], v8
	ds_read_b128 v[162:165], v12
	s_mov_b32 m0, s28
	s_nop 0
	global_load_lds_dwordx4 v0, s[48:49]
	ds_read_b128 v[166:169], v9
	s_mov_b32 m0, s30
	s_nop 0
	global_load_lds_dwordx4 v2, s[48:49]
	ds_read_b128 v[178:181], v13
	ds_read_b128 v[214:217], v11
	s_mov_b32 m0, s34
	s_nop 0
	global_load_lds_dwordx4 v4, s[48:49]
	ds_read_b128 v[218:221], v10
	ds_read_b128 v[222:225], v14
	ds_read_b128 v[226:229], v15
	s_branch .Lmy_rot_r_r6b
.Lmy_rr_r6b:
	ds_read_b128 v[158:161], v8
	ds_read_b128 v[162:165], v12
	s_mov_b32 m0, s28
	v_mfma_f32_16x16x32_bf16 v[128:131], v[166:169], v[222:225], v[128:131]
	global_load_lds_dwordx4 v0, s[48:49]
	v_mfma_f32_16x16x32_bf16 v[100:103], v[166:169], v[226:229], v[100:103]
	ds_read_b128 v[166:169], v9
	v_mfma_f32_16x16x32_bf16 v[132:135], v[178:181], v[222:225], v[132:135]
	s_mov_b32 m0, s30
	v_mfma_f32_16x16x32_bf16 v[140:143], v[178:181], v[226:229], v[140:143]
	global_load_lds_dwordx4 v2, s[48:49]
	ds_read_b128 v[178:181], v13
	v_mfma_f32_16x16x32_bf16 v[136:139], v[214:217], v[222:225], v[136:139]
	v_mfma_f32_16x16x32_bf16 v[150:153], v[214:217], v[226:229], v[150:153]
	ds_read_b128 v[214:217], v11
	s_mov_b32 m0, s34
	v_mfma_f32_16x16x32_bf16 v[84:87], v[218:221], v[222:225], v[84:87]
	global_load_lds_dwordx4 v4, s[48:49]
	v_mfma_f32_16x16x32_bf16 v[154:157], v[218:221], v[226:229], v[154:157]
	ds_read_b128 v[218:221], v10
	ds_read_b128 v[222:225], v14
	ds_read_b128 v[226:229], v15
.Lmy_rot_r_r6b:
	s_waitcnt lgkmcnt(6)
	v_mfma_f32_16x16x32_bf16 v[40:43], v[158:161], v[162:165], v[40:43]
	s_waitcnt lgkmcnt(5)
	s_mov_b32 m0, s36
	v_mfma_f32_16x16x32_bf16 v[44:47], v[166:169], v[162:165], v[44:47]
	global_load_lds_dwordx4 v146, s[48:49]
	s_waitcnt lgkmcnt(4)
	v_mfma_f32_16x16x32_bf16 v[56:59], v[158:161], v[178:181], v[56:59]
	v_mfma_f32_16x16x32_bf16 v[60:63], v[166:169], v[178:181], v[60:63]
	s_waitcnt lgkmcnt(3)
	s_mov_b32 m0, s27
	v_mfma_f32_16x16x32_bf16 v[48:51], v[214:217], v[162:165], v[48:51]
	global_load_lds_dwordx4 v0, s[46:47]
	v_mfma_f32_16x16x32_bf16 v[64:67], v[214:217], v[178:181], v[64:67]
	s_waitcnt lgkmcnt(2)
	v_mfma_f32_16x16x32_bf16 v[174:177], v[218:221], v[162:165], v[174:177]
	ds_read_b128 v[162:165], v16
	s_mov_b32 m0, s29
	v_mfma_f32_16x16x32_bf16 v[170:173], v[218:221], v[178:181], v[170:173]
	global_load_lds_dwordx4 v2, s[46:47]
	ds_read_b128 v[178:181], v17
	s_waitcnt lgkmcnt(3)
	v_mfma_f32_16x16x32_bf16 v[72:75], v[158:161], v[222:225], v[72:75]
	v_mfma_f32_16x16x32_bf16 v[76:79], v[166:169], v[222:225], v[76:79]
	s_mov_b32 m0, s31
	v_mfma_f32_16x16x32_bf16 v[80:83], v[214:217], v[222:225], v[80:83]
	global_load_lds_dwordx4 v4, s[46:47]
	v_mfma_f32_16x16x32_bf16 v[32:35], v[218:221], v[222:225], v[32:35]
	ds_read_b128 v[222:225], v18
	s_waitcnt lgkmcnt(3)
	v_mfma_f32_16x16x32_bf16 v[88:91], v[158:161], v[226:229], v[88:91]
	s_mov_b32 m0, s35
	v_mfma_f32_16x16x32_bf16 v[92:95], v[166:169], v[226:229], v[92:95]
	global_load_lds_dwordx4 v146, s[46:47]
	v_mfma_f32_16x16x32_bf16 v[96:99], v[214:217], v[226:229], v[96:99]
	v_mfma_f32_16x16x32_bf16 v[36:39], v[218:221], v[226:229], v[36:39]
	ds_read_b128 v[226:229], v19
	s_waitcnt lgkmcnt(3)
	v_mfma_f32_16x16x32_bf16 v[108:111], v[166:169], v[162:165], v[108:111]
	s_waitcnt lgkmcnt(2)
	v_mfma_f32_16x16x32_bf16 v[120:123], v[166:169], v[178:181], v[120:123]
	s_waitcnt lgkmcnt(1)
	v_mfma_f32_16x16x32_bf16 v[132:135], v[166:169], v[222:225], v[132:135]
	s_waitcnt lgkmcnt(0)
	v_mfma_f32_16x16x32_bf16 v[140:143], v[166:169], v[226:229], v[140:143]
	ds_read_b128 v[166:169], v20
	v_mfma_f32_16x16x32_bf16 v[104:107], v[158:161], v[162:165], v[104:107]
	v_mfma_f32_16x16x32_bf16 v[116:119], v[158:161], v[178:181], v[116:119]
	v_mfma_f32_16x16x32_bf16 v[128:131], v[158:161], v[222:225], v[128:131]
	v_mfma_f32_16x16x32_bf16 v[100:103], v[158:161], v[226:229], v[100:103]
	ds_read_b128 v[158:161], v24
	v_mfma_f32_16x16x32_bf16 v[124:127], v[214:217], v[178:181], v[124:127]
	v_mfma_f32_16x16x32_bf16 v[68:71], v[218:221], v[178:181], v[68:71]
	ds_read_b128 v[178:181], v21
	v_mfma_f32_16x16x32_bf16 v[112:115], v[214:217], v[162:165], v[112:115]
	v_mfma_f32_16x16x32_bf16 v[52:55], v[218:221], v[162:165], v[52:55]
	ds_read_b128 v[162:165], v25
	v_mfma_f32_16x16x32_bf16 v[136:139], v[214:217], v[222:225], v[136:139]
	v_mfma_f32_16x16x32_bf16 v[84:87], v[218:221], v[222:225], v[84:87]
	ds_read_b128 v[222:225], v26
	v_mfma_f32_16x16x32_bf16 v[150:153], v[214:217], v[226:229], v[150:153]
	ds_read_b128 v[214:217], v23
	v_mfma_f32_16x16x32_bf16 v[154:157], v[218:221], v[226:229], v[154:157]
	ds_read_b128 v[218:221], v22
	ds_read_b128 v[226:229], v27
	s_waitcnt lgkmcnt(6)
	v_mfma_f32_16x16x32_bf16 v[40:43], v[166:169], v[158:161], v[40:43]
	s_waitcnt lgkmcnt(5)
	v_mfma_f32_16x16x32_bf16 v[44:47], v[178:181], v[158:161], v[44:47]
	s_waitcnt lgkmcnt(4)
	v_mfma_f32_16x16x32_bf16 v[56:59], v[166:169], v[162:165], v[56:59]
	v_mfma_f32_16x16x32_bf16 v[60:63], v[178:181], v[162:165], v[60:63]
	s_waitcnt lgkmcnt(3)
	v_mfma_f32_16x16x32_bf16 v[72:75], v[166:169], v[222:225], v[72:75]
	v_mfma_f32_16x16x32_bf16 v[76:79], v[178:181], v[222:225], v[76:79]
	s_waitcnt lgkmcnt(2)
	v_mfma_f32_16x16x32_bf16 v[48:51], v[214:217], v[158:161], v[48:51]
	s_waitcnt lgkmcnt(1)
	v_mfma_f32_16x16x32_bf16 v[174:177], v[218:221], v[158:161], v[174:177]
	ds_read_b128 v[158:161], v28
	v_mfma_f32_16x16x32_bf16 v[64:67], v[214:217], v[162:165], v[64:67]
	v_mfma_f32_16x16x32_bf16 v[170:173], v[218:221], v[162:165], v[170:173]
	ds_read_b128 v[162:165], v29
	v_mfma_f32_16x16x32_bf16 v[80:83], v[214:217], v[222:225], v[80:83]
	v_mfma_f32_16x16x32_bf16 v[32:35], v[218:221], v[222:225], v[32:35]
	ds_read_b128 v[222:225], v30
	s_waitcnt lgkmcnt(3)
	v_mfma_f32_16x16x32_bf16 v[88:91], v[166:169], v[226:229], v[88:91]
	v_mfma_f32_16x16x32_bf16 v[92:95], v[178:181], v[226:229], v[92:95]
	v_mfma_f32_16x16x32_bf16 v[96:99], v[214:217], v[226:229], v[96:99]
	v_mfma_f32_16x16x32_bf16 v[36:39], v[218:221], v[226:229], v[36:39]
	ds_read_b128 v[226:229], v31
	s_waitcnt lgkmcnt(3)
	v_mfma_f32_16x16x32_bf16 v[104:107], v[166:169], v[158:161], v[104:107]
	v_mfma_f32_16x16x32_bf16 v[108:111], v[178:181], v[158:161], v[108:111]
	v_mfma_f32_16x16x32_bf16 v[112:115], v[214:217], v[158:161], v[112:115]
	v_mfma_f32_16x16x32_bf16 v[52:55], v[218:221], v[158:161], v[52:55]
	s_waitcnt lgkmcnt(2)
	v_mfma_f32_16x16x32_bf16 v[116:119], v[166:169], v[162:165], v[116:119]
	v_mfma_f32_16x16x32_bf16 v[120:123], v[178:181], v[162:165], v[120:123]
	v_mfma_f32_16x16x32_bf16 v[124:127], v[214:217], v[162:165], v[124:127]
	v_mfma_f32_16x16x32_bf16 v[68:71], v[218:221], v[162:165], v[68:71]
	s_add_u32 s46, s0, s45
	s_addc_u32 s47, s1, 0
	s_add_u32 s48, s14, s45
	s_addc_u32 s49, s15, 0
	s_add_u32 s45, s45, 0x80
	s_waitcnt vmcnt(0)
	s_waitcnt lgkmcnt(0)
	s_barrier
	ds_read_b128 v[158:161], v7 offset:32768
	ds_read_b128 v[162:165], v6
	s_mov_b32 m0, s37
	v_mfma_f32_16x16x32_bf16 v[128:131], v[166:169], v[222:225], v[128:131]
	global_load_lds_dwordx4 v0, s[48:49]
	v_mfma_f32_16x16x32_bf16 v[100:103], v[166:169], v[226:229], v[100:103]
	ds_read_b128 v[166:169], v7 offset:34816
	v_mfma_f32_16x16x32_bf16 v[132:135], v[178:181], v[222:225], v[132:135]
	s_mov_b32 m0, s40
	v_mfma_f32_16x16x32_bf16 v[140:143], v[178:181], v[226:229], v[140:143]
	global_load_lds_dwordx4 v2, s[48:49]
	ds_read_b128 v[178:181], v6 offset:2048
	v_mfma_f32_16x16x32_bf16 v[136:139], v[214:217], v[222:225], v[136:139]
	v_mfma_f32_16x16x32_bf16 v[150:153], v[214:217], v[226:229], v[150:153]
	ds_read_b128 v[214:217], v7 offset:36864
	s_mov_b32 m0, s42
	v_mfma_f32_16x16x32_bf16 v[84:87], v[218:221], v[222:225], v[84:87]
	global_load_lds_dwordx4 v4, s[48:49]
	v_mfma_f32_16x16x32_bf16 v[154:157], v[218:221], v[226:229], v[154:157]
	ds_read_b128 v[218:221], v7 offset:38912
	ds_read_b128 v[222:225], v6 offset:4096
	ds_read_b128 v[226:229], v6 offset:6144
	s_waitcnt lgkmcnt(6)
	v_mfma_f32_16x16x32_bf16 v[40:43], v[158:161], v[162:165], v[40:43]
	s_waitcnt lgkmcnt(5)
	s_mov_b32 m0, s44
	v_mfma_f32_16x16x32_bf16 v[44:47], v[166:169], v[162:165], v[44:47]
	global_load_lds_dwordx4 v146, s[48:49]
	s_waitcnt lgkmcnt(4)
	v_mfma_f32_16x16x32_bf16 v[56:59], v[158:161], v[178:181], v[56:59]
	v_mfma_f32_16x16x32_bf16 v[60:63], v[166:169], v[178:181], v[60:63]
	s_waitcnt lgkmcnt(3)
	s_mov_b32 m0, s38
	v_mfma_f32_16x16x32_bf16 v[48:51], v[214:217], v[162:165], v[48:51]
	global_load_lds_dwordx4 v0, s[46:47]
	v_mfma_f32_16x16x32_bf16 v[64:67], v[214:217], v[178:181], v[64:67]
	s_waitcnt lgkmcnt(2)
	v_mfma_f32_16x16x32_bf16 v[174:177], v[218:221], v[162:165], v[174:177]
	ds_read_b128 v[162:165], v6 offset:8192
	s_mov_b32 m0, s39
	v_mfma_f32_16x16x32_bf16 v[170:173], v[218:221], v[178:181], v[170:173]
	global_load_lds_dwordx4 v2, s[46:47]
	ds_read_b128 v[178:181], v6 offset:10240
	s_waitcnt lgkmcnt(3)
	v_mfma_f32_16x16x32_bf16 v[72:75], v[158:161], v[222:225], v[72:75]
	v_mfma_f32_16x16x32_bf16 v[76:79], v[166:169], v[222:225], v[76:79]
	s_mov_b32 m0, s41
	v_mfma_f32_16x16x32_bf16 v[80:83], v[214:217], v[222:225], v[80:83]
	global_load_lds_dwordx4 v4, s[46:47]
	v_mfma_f32_16x16x32_bf16 v[32:35], v[218:221], v[222:225], v[32:35]
	ds_read_b128 v[222:225], v6 offset:12288
	s_waitcnt lgkmcnt(3)
	v_mfma_f32_16x16x32_bf16 v[88:91], v[158:161], v[226:229], v[88:91]
	s_mov_b32 m0, s43
	v_mfma_f32_16x16x32_bf16 v[92:95], v[166:169], v[226:229], v[92:95]
	global_load_lds_dwordx4 v146, s[46:47]
	v_mfma_f32_16x16x32_bf16 v[96:99], v[214:217], v[226:229], v[96:99]
	v_mfma_f32_16x16x32_bf16 v[36:39], v[218:221], v[226:229], v[36:39]
	ds_read_b128 v[226:229], v6 offset:14336
	s_waitcnt lgkmcnt(3)
	v_mfma_f32_16x16x32_bf16 v[108:111], v[166:169], v[162:165], v[108:111]
	s_waitcnt lgkmcnt(2)
	v_mfma_f32_16x16x32_bf16 v[120:123], v[166:169], v[178:181], v[120:123]
	s_waitcnt lgkmcnt(1)
	v_mfma_f32_16x16x32_bf16 v[132:135], v[166:169], v[222:225], v[132:135]
	s_waitcnt lgkmcnt(0)
	v_mfma_f32_16x16x32_bf16 v[140:143], v[166:169], v[226:229], v[140:143]
	ds_read_b128 v[166:169], v7 offset:33792
	v_mfma_f32_16x16x32_bf16 v[104:107], v[158:161], v[162:165], v[104:107]
	v_mfma_f32_16x16x32_bf16 v[116:119], v[158:161], v[178:181], v[116:119]
	v_mfma_f32_16x16x32_bf16 v[128:131], v[158:161], v[222:225], v[128:131]
	v_mfma_f32_16x16x32_bf16 v[100:103], v[158:161], v[226:229], v[100:103]
	ds_read_b128 v[158:161], v6 offset:1024
	v_mfma_f32_16x16x32_bf16 v[124:127], v[214:217], v[178:181], v[124:127]
	v_mfma_f32_16x16x32_bf16 v[68:71], v[218:221], v[178:181], v[68:71]
	ds_read_b128 v[178:181], v7 offset:35840
	v_mfma_f32_16x16x32_bf16 v[112:115], v[214:217], v[162:165], v[112:115]
	v_mfma_f32_16x16x32_bf16 v[52:55], v[218:221], v[162:165], v[52:55]
	ds_read_b128 v[162:165], v6 offset:3072
	v_mfma_f32_16x16x32_bf16 v[136:139], v[214:217], v[222:225], v[136:139]
	v_mfma_f32_16x16x32_bf16 v[84:87], v[218:221], v[222:225], v[84:87]
	ds_read_b128 v[222:225], v6 offset:5120
	v_mfma_f32_16x16x32_bf16 v[150:153], v[214:217], v[226:229], v[150:153]
	ds_read_b128 v[214:217], v7 offset:37888
	v_mfma_f32_16x16x32_bf16 v[154:157], v[218:221], v[226:229], v[154:157]
	ds_read_b128 v[218:221], v7 offset:39936
	ds_read_b128 v[226:229], v6 offset:7168
	s_waitcnt lgkmcnt(6)
	v_mfma_f32_16x16x32_bf16 v[40:43], v[166:169], v[158:161], v[40:43]
	s_waitcnt lgkmcnt(5)
	v_mfma_f32_16x16x32_bf16 v[44:47], v[178:181], v[158:161], v[44:47]
	s_waitcnt lgkmcnt(4)
	v_mfma_f32_16x16x32_bf16 v[56:59], v[166:169], v[162:165], v[56:59]
	v_mfma_f32_16x16x32_bf16 v[60:63], v[178:181], v[162:165], v[60:63]
	s_waitcnt lgkmcnt(3)
	v_mfma_f32_16x16x32_bf16 v[72:75], v[166:169], v[222:225], v[72:75]
	v_mfma_f32_16x16x32_bf16 v[76:79], v[178:181], v[222:225], v[76:79]
	s_waitcnt lgkmcnt(2)
	v_mfma_f32_16x16x32_bf16 v[48:51], v[214:217], v[158:161], v[48:51]
	s_waitcnt lgkmcnt(1)
	v_mfma_f32_16x16x32_bf16 v[174:177], v[218:221], v[158:161], v[174:177]
	ds_read_b128 v[158:161], v6 offset:9216
	v_mfma_f32_16x16x32_bf16 v[64:67], v[214:217], v[162:165], v[64:67]
	v_mfma_f32_16x16x32_bf16 v[170:173], v[218:221], v[162:165], v[170:173]
	ds_read_b128 v[162:165], v6 offset:11264
	v_mfma_f32_16x16x32_bf16 v[80:83], v[214:217], v[222:225], v[80:83]
	v_mfma_f32_16x16x32_bf16 v[32:35], v[218:221], v[222:225], v[32:35]
	ds_read_b128 v[222:225], v6 offset:13312
	s_waitcnt lgkmcnt(3)
	v_mfma_f32_16x16x32_bf16 v[88:91], v[166:169], v[226:229], v[88:91]
	v_mfma_f32_16x16x32_bf16 v[92:95], v[178:181], v[226:229], v[92:95]
	v_mfma_f32_16x16x32_bf16 v[96:99], v[214:217], v[226:229], v[96:99]
	v_mfma_f32_16x16x32_bf16 v[36:39], v[218:221], v[226:229], v[36:39]
	ds_read_b128 v[226:229], v6 offset:15360
	s_waitcnt lgkmcnt(3)
	v_mfma_f32_16x16x32_bf16 v[104:107], v[166:169], v[158:161], v[104:107]
	v_mfma_f32_16x16x32_bf16 v[108:111], v[178:181], v[158:161], v[108:111]
	v_mfma_f32_16x16x32_bf16 v[112:115], v[214:217], v[158:161], v[112:115]
	v_mfma_f32_16x16x32_bf16 v[52:55], v[218:221], v[158:161], v[52:55]
	s_waitcnt lgkmcnt(2)
	v_mfma_f32_16x16x32_bf16 v[116:119], v[166:169], v[162:165], v[116:119]
	v_mfma_f32_16x16x32_bf16 v[120:123], v[178:181], v[162:165], v[120:123]
	v_mfma_f32_16x16x32_bf16 v[124:127], v[214:217], v[162:165], v[124:127]
	v_mfma_f32_16x16x32_bf16 v[68:71], v[218:221], v[162:165], v[68:71]
	s_add_u32 s46, s0, s45
	s_addc_u32 s47, s1, 0
	s_add_u32 s48, s14, s45
	s_addc_u32 s49, s15, 0
	s_add_u32 s45, s45, 0x80
	s_cmp_lg_u32 s45, 0x2f80
	s_waitcnt vmcnt(0)
	s_waitcnt lgkmcnt(0)
	s_barrier
	s_cbranch_scc1 .Lmy_rr_r6b
	v_mfma_f32_16x16x32_bf16 v[128:131], v[166:169], v[222:225], v[128:131]
	v_mfma_f32_16x16x32_bf16 v[100:103], v[166:169], v[226:229], v[100:103]
	v_mfma_f32_16x16x32_bf16 v[132:135], v[178:181], v[222:225], v[132:135]
	v_mfma_f32_16x16x32_bf16 v[140:143], v[178:181], v[226:229], v[140:143]
	v_mfma_f32_16x16x32_bf16 v[136:139], v[214:217], v[222:225], v[136:139]
	v_mfma_f32_16x16x32_bf16 v[150:153], v[214:217], v[226:229], v[150:153]
	v_mfma_f32_16x16x32_bf16 v[84:87], v[218:221], v[222:225], v[84:87]
	v_mfma_f32_16x16x32_bf16 v[154:157], v[218:221], v[226:229], v[154:157]
	s_nop 15
	s_nop 15
	v_lshl_add_u64 v[158:159], s[46:47], 0, v[0:1]
	s_mov_b32 s45, m0
	s_mov_b32 m0, s27
	s_nop 0
	global_load_lds_dwordx4 v[158:159], off
	s_mov_b32 m0, s45
	v_lshl_add_u64 v[158:159], s[48:49], 0, v[0:1]
	s_mov_b32 s45, m0
	s_mov_b32 m0, s28
	s_nop 0
	global_load_lds_dwordx4 v[158:159], off
	s_mov_b32 m0, s45
	v_lshl_add_u64 v[158:159], s[46:47], 0, v[2:3]
	s_mov_b32 s45, m0
	s_mov_b32 m0, s29
	s_nop 0
	global_load_lds_dwordx4 v[158:159], off
	s_mov_b32 m0, s45
	v_lshl_add_u64 v[158:159], s[48:49], 0, v[2:3]
	s_mov_b32 s45, m0
	s_mov_b32 m0, s30
	s_nop 0
	global_load_lds_dwordx4 v[158:159], off
	s_mov_b32 m0, s45
	v_lshl_add_u64 v[158:159], s[46:47], 0, v[4:5]
	s_mov_b32 s45, m0
	s_mov_b32 m0, s31
	s_nop 0
	global_load_lds_dwordx4 v[158:159], off
	s_mov_b32 m0, s45
	v_lshl_add_u64 v[158:159], s[48:49], 0, v[4:5]
	s_mov_b32 s45, m0
	s_mov_b32 m0, s34
	s_nop 0
	global_load_lds_dwordx4 v[158:159], off
	s_mov_b32 m0, s45
	v_lshl_add_u64 v[158:159], s[46:47], 0, v[146:147]
	s_mov_b32 s45, m0
	s_mov_b32 m0, s35
	s_nop 0
	global_load_lds_dwordx4 v[158:159], off
	s_mov_b32 m0, s45
	v_lshl_add_u64 v[158:159], s[48:49], 0, v[146:147]
	s_mov_b32 s45, m0
	s_mov_b32 m0, s36
	s_nop 0
	global_load_lds_dwordx4 v[158:159], off
	s_mov_b32 m0, s45
	ds_read_b128 v[158:161], v8
	ds_read_b128 v[162:165], v9
	ds_read_b128 v[166:169], v11
	ds_read_b128 v[214:217], v10
	ds_read_b128 v[178:181], v12
	ds_read_b128 v[218:221], v13
	ds_read_b128 v[222:225], v14
	ds_read_b128 v[226:229], v15
	s_waitcnt lgkmcnt(3)
	v_mfma_f32_16x16x32_bf16 v[40:43], v[158:161], v[178:181], v[40:43]
	v_mfma_f32_16x16x32_bf16 v[44:47], v[162:165], v[178:181], v[44:47]
	v_mfma_f32_16x16x32_bf16 v[48:51], v[166:169], v[178:181], v[48:51]
	v_mfma_f32_16x16x32_bf16 v[174:177], v[214:217], v[178:181], v[174:177]
	ds_read_b128 v[178:181], v16
	s_waitcnt lgkmcnt(3)
	v_mfma_f32_16x16x32_bf16 v[56:59], v[158:161], v[218:221], v[56:59]
	v_mfma_f32_16x16x32_bf16 v[60:63], v[162:165], v[218:221], v[60:63]
	v_mfma_f32_16x16x32_bf16 v[64:67], v[166:169], v[218:221], v[64:67]
	v_mfma_f32_16x16x32_bf16 v[170:173], v[214:217], v[218:221], v[170:173]
	ds_read_b128 v[218:221], v17
	s_waitcnt lgkmcnt(3)
	v_mfma_f32_16x16x32_bf16 v[72:75], v[158:161], v[222:225], v[72:75]
	v_mfma_f32_16x16x32_bf16 v[76:79], v[162:165], v[222:225], v[76:79]
	v_mfma_f32_16x16x32_bf16 v[80:83], v[166:169], v[222:225], v[80:83]
	v_mfma_f32_16x16x32_bf16 v[32:35], v[214:217], v[222:225], v[32:35]
	ds_read_b128 v[222:225], v18
	s_waitcnt lgkmcnt(3)
	v_mfma_f32_16x16x32_bf16 v[88:91], v[158:161], v[226:229], v[88:91]
	v_mfma_f32_16x16x32_bf16 v[92:95], v[162:165], v[226:229], v[92:95]
	v_mfma_f32_16x16x32_bf16 v[96:99], v[166:169], v[226:229], v[96:99]
	v_mfma_f32_16x16x32_bf16 v[36:39], v[214:217], v[226:229], v[36:39]
	ds_read_b128 v[226:229], v19
	s_waitcnt lgkmcnt(3)
	v_mfma_f32_16x16x32_bf16 v[104:107], v[158:161], v[178:181], v[104:107]
	v_mfma_f32_16x16x32_bf16 v[108:111], v[162:165], v[178:181], v[108:111]
	v_mfma_f32_16x16x32_bf16 v[112:115], v[166:169], v[178:181], v[112:115]
	v_mfma_f32_16x16x32_bf16 v[52:55], v[214:217], v[178:181], v[52:55]
	s_waitcnt lgkmcnt(2)
	v_mfma_f32_16x16x32_bf16 v[116:119], v[158:161], v[218:221], v[116:119]
	v_mfma_f32_16x16x32_bf16 v[120:123], v[162:165], v[218:221], v[120:123]
	v_mfma_f32_16x16x32_bf16 v[124:127], v[166:169], v[218:221], v[124:127]
	v_mfma_f32_16x16x32_bf16 v[68:71], v[214:217], v[218:221], v[68:71]
	s_waitcnt lgkmcnt(1)
	v_mfma_f32_16x16x32_bf16 v[132:135], v[162:165], v[222:225], v[132:135]
	v_mfma_f32_16x16x32_bf16 v[84:87], v[214:217], v[222:225], v[84:87]
	s_waitcnt lgkmcnt(0)
	v_mfma_f32_16x16x32_bf16 v[100:103], v[158:161], v[226:229], v[100:103]
	v_mfma_f32_16x16x32_bf16 v[150:153], v[166:169], v[226:229], v[150:153]
	v_mfma_f32_16x16x32_bf16 v[154:157], v[214:217], v[226:229], v[154:157]
	v_mfma_f32_16x16x32_bf16 v[128:131], v[158:161], v[222:225], v[128:131]
	v_mfma_f32_16x16x32_bf16 v[136:139], v[166:169], v[222:225], v[136:139]
	v_mfma_f32_16x16x32_bf16 v[140:143], v[162:165], v[226:229], v[140:143]
	ds_read_b128 v[158:161], v20
	ds_read_b128 v[162:165], v21
	ds_read_b128 v[166:169], v23
	ds_read_b128 v[214:217], v22
	ds_read_b128 v[178:181], v24
	ds_read_b128 v[218:221], v25
	ds_read_b128 v[222:225], v26
	ds_read_b128 v[226:229], v27
	s_waitcnt lgkmcnt(3)
	v_mfma_f32_16x16x32_bf16 v[40:43], v[158:161], v[178:181], v[40:43]
	v_mfma_f32_16x16x32_bf16 v[44:47], v[162:165], v[178:181], v[44:47]
	v_mfma_f32_16x16x32_bf16 v[48:51], v[166:169], v[178:181], v[48:51]
	v_mfma_f32_16x16x32_bf16 v[174:177], v[214:217], v[178:181], v[174:177]
	ds_read_b128 v[178:181], v28
	s_waitcnt lgkmcnt(3)
	v_mfma_f32_16x16x32_bf16 v[56:59], v[158:161], v[218:221], v[56:59]
	v_mfma_f32_16x16x32_bf16 v[60:63], v[162:165], v[218:221], v[60:63]
	v_mfma_f32_16x16x32_bf16 v[64:67], v[166:169], v[218:221], v[64:67]
	v_mfma_f32_16x16x32_bf16 v[170:173], v[214:217], v[218:221], v[170:173]
	ds_read_b128 v[218:221], v29
	s_waitcnt lgkmcnt(3)
	v_mfma_f32_16x16x32_bf16 v[72:75], v[158:161], v[222:225], v[72:75]
	v_mfma_f32_16x16x32_bf16 v[76:79], v[162:165], v[222:225], v[76:79]
	v_mfma_f32_16x16x32_bf16 v[80:83], v[166:169], v[222:225], v[80:83]
	v_mfma_f32_16x16x32_bf16 v[32:35], v[214:217], v[222:225], v[32:35]
	ds_read_b128 v[222:225], v30
	s_waitcnt lgkmcnt(3)
	v_mfma_f32_16x16x32_bf16 v[88:91], v[158:161], v[226:229], v[88:91]
	v_mfma_f32_16x16x32_bf16 v[92:95], v[162:165], v[226:229], v[92:95]
	v_mfma_f32_16x16x32_bf16 v[96:99], v[166:169], v[226:229], v[96:99]
	v_mfma_f32_16x16x32_bf16 v[36:39], v[214:217], v[226:229], v[36:39]
	ds_read_b128 v[226:229], v31
	s_waitcnt lgkmcnt(3)
	v_mfma_f32_16x16x32_bf16 v[104:107], v[158:161], v[178:181], v[104:107]
	v_mfma_f32_16x16x32_bf16 v[108:111], v[162:165], v[178:181], v[108:111]
	v_mfma_f32_16x16x32_bf16 v[112:115], v[166:169], v[178:181], v[112:115]
	v_mfma_f32_16x16x32_bf16 v[52:55], v[214:217], v[178:181], v[52:55]
	s_waitcnt lgkmcnt(2)
	v_mfma_f32_16x16x32_bf16 v[116:119], v[158:161], v[218:221], v[116:119]
	v_mfma_f32_16x16x32_bf16 v[120:123], v[162:165], v[218:221], v[120:123]
	v_mfma_f32_16x16x32_bf16 v[124:127], v[166:169], v[218:221], v[124:127]
	v_mfma_f32_16x16x32_bf16 v[68:71], v[214:217], v[218:221], v[68:71]
	s_waitcnt lgkmcnt(1)
	v_mfma_f32_16x16x32_bf16 v[132:135], v[162:165], v[222:225], v[132:135]
	v_mfma_f32_16x16x32_bf16 v[84:87], v[214:217], v[222:225], v[84:87]
	s_waitcnt lgkmcnt(0)
	v_mfma_f32_16x16x32_bf16 v[100:103], v[158:161], v[226:229], v[100:103]
	v_mfma_f32_16x16x32_bf16 v[150:153], v[166:169], v[226:229], v[150:153]
	v_mfma_f32_16x16x32_bf16 v[154:157], v[214:217], v[226:229], v[154:157]
	v_mfma_f32_16x16x32_bf16 v[128:131], v[158:161], v[222:225], v[128:131]
	v_mfma_f32_16x16x32_bf16 v[136:139], v[166:169], v[222:225], v[136:139]
	v_mfma_f32_16x16x32_bf16 v[140:143], v[162:165], v[226:229], v[140:143]
	s_add_u32 s0, s0, 0x2f80
	s_addc_u32 s1, s1, 0
	s_add_u32 s14, s14, 0x2f80
	s_waitcnt vmcnt(0)
	s_barrier
	s_addc_u32 s15, s15, 0
	v_lshl_add_u64 v[158:159], s[0:1], 0, v[0:1]
	s_mov_b32 s45, m0
	s_mov_b32 m0, s38
	s_nop 0
	global_load_lds_dwordx4 v[158:159], off
	s_mov_b32 m0, s45
	v_lshl_add_u64 v[158:159], s[14:15], 0, v[0:1]
	s_mov_b32 s38, m0
	s_mov_b32 m0, s37
	s_nop 0
	global_load_lds_dwordx4 v[158:159], off
	s_mov_b32 m0, s38
	v_lshl_add_u64 v[158:159], s[0:1], 0, v[2:3]
	s_mov_b32 s37, m0
	s_mov_b32 m0, s39
	s_nop 0
	global_load_lds_dwordx4 v[158:159], off
	s_mov_b32 m0, s37
	v_lshl_add_u64 v[158:159], s[14:15], 0, v[2:3]
	s_mov_b32 s37, m0
	s_mov_b32 m0, s40
	s_nop 0
	global_load_lds_dwordx4 v[158:159], off
	s_mov_b32 m0, s37
	v_lshl_add_u64 v[158:159], s[0:1], 0, v[4:5]
	s_mov_b32 s37, m0
	s_mov_b32 m0, s41
	s_nop 0
	global_load_lds_dwordx4 v[158:159], off
	s_mov_b32 m0, s37
	v_lshl_add_u64 v[158:159], s[14:15], 0, v[4:5]
	s_mov_b32 s37, m0
	s_mov_b32 m0, s42
	s_nop 0
	global_load_lds_dwordx4 v[158:159], off
	s_mov_b32 m0, s37
	v_lshl_add_u64 v[158:159], s[0:1], 0, v[146:147]
	s_mov_b32 s0, m0
	s_mov_b32 m0, s43
	s_nop 0
	global_load_lds_dwordx4 v[158:159], off
	s_mov_b32 m0, s0
	v_lshl_add_u64 v[158:159], s[14:15], 0, v[146:147]
	s_mov_b32 s0, m0
	s_mov_b32 m0, s44
	s_nop 0
	global_load_lds_dwordx4 v[158:159], off
	s_mov_b32 m0, s0
	ds_read_b128 v[158:161], v7 offset:32768
	ds_read_b128 v[162:165], v7 offset:34816
	ds_read_b128 v[166:169], v7 offset:36864
	ds_read_b128 v[214:217], v7 offset:38912
	ds_read_b128 v[178:181], v6
	ds_read_b128 v[218:221], v6 offset:2048
	ds_read_b128 v[222:225], v6 offset:4096
	ds_read_b128 v[226:229], v6 offset:6144
	s_waitcnt lgkmcnt(3)
	v_mfma_f32_16x16x32_bf16 v[40:43], v[158:161], v[178:181], v[40:43]
	v_mfma_f32_16x16x32_bf16 v[44:47], v[162:165], v[178:181], v[44:47]
	v_mfma_f32_16x16x32_bf16 v[48:51], v[166:169], v[178:181], v[48:51]
	v_mfma_f32_16x16x32_bf16 v[174:177], v[214:217], v[178:181], v[174:177]
	ds_read_b128 v[178:181], v6 offset:8192
	s_waitcnt lgkmcnt(3)
	v_mfma_f32_16x16x32_bf16 v[56:59], v[158:161], v[218:221], v[56:59]
	v_mfma_f32_16x16x32_bf16 v[60:63], v[162:165], v[218:221], v[60:63]
	v_mfma_f32_16x16x32_bf16 v[64:67], v[166:169], v[218:221], v[64:67]
	v_mfma_f32_16x16x32_bf16 v[170:173], v[214:217], v[218:221], v[170:173]
	ds_read_b128 v[218:221], v6 offset:10240
	s_waitcnt lgkmcnt(3)
	v_mfma_f32_16x16x32_bf16 v[72:75], v[158:161], v[222:225], v[72:75]
	v_mfma_f32_16x16x32_bf16 v[76:79], v[162:165], v[222:225], v[76:79]
	v_mfma_f32_16x16x32_bf16 v[80:83], v[166:169], v[222:225], v[80:83]
	v_mfma_f32_16x16x32_bf16 v[32:35], v[214:217], v[222:225], v[32:35]
	ds_read_b128 v[222:225], v6 offset:12288
	s_waitcnt lgkmcnt(3)
	v_mfma_f32_16x16x32_bf16 v[88:91], v[158:161], v[226:229], v[88:91]
	v_mfma_f32_16x16x32_bf16 v[92:95], v[162:165], v[226:229], v[92:95]
	v_mfma_f32_16x16x32_bf16 v[96:99], v[166:169], v[226:229], v[96:99]
	v_mfma_f32_16x16x32_bf16 v[36:39], v[214:217], v[226:229], v[36:39]
	ds_read_b128 v[226:229], v6 offset:14336
	s_waitcnt lgkmcnt(3)
	v_mfma_f32_16x16x32_bf16 v[104:107], v[158:161], v[178:181], v[104:107]
	v_mfma_f32_16x16x32_bf16 v[108:111], v[162:165], v[178:181], v[108:111]
	v_mfma_f32_16x16x32_bf16 v[112:115], v[166:169], v[178:181], v[112:115]
	v_mfma_f32_16x16x32_bf16 v[52:55], v[214:217], v[178:181], v[52:55]
	s_waitcnt lgkmcnt(2)
	v_mfma_f32_16x16x32_bf16 v[116:119], v[158:161], v[218:221], v[116:119]
	v_mfma_f32_16x16x32_bf16 v[120:123], v[162:165], v[218:221], v[120:123]
	v_mfma_f32_16x16x32_bf16 v[124:127], v[166:169], v[218:221], v[124:127]
	v_mfma_f32_16x16x32_bf16 v[68:71], v[214:217], v[218:221], v[68:71]
	s_waitcnt lgkmcnt(1)
	v_mfma_f32_16x16x32_bf16 v[132:135], v[162:165], v[222:225], v[132:135]
	v_mfma_f32_16x16x32_bf16 v[84:87], v[214:217], v[222:225], v[84:87]
	s_waitcnt lgkmcnt(0)
	v_mfma_f32_16x16x32_bf16 v[100:103], v[158:161], v[226:229], v[100:103]
	v_mfma_f32_16x16x32_bf16 v[150:153], v[166:169], v[226:229], v[150:153]
	v_mfma_f32_16x16x32_bf16 v[154:157], v[214:217], v[226:229], v[154:157]
	v_mfma_f32_16x16x32_bf16 v[128:131], v[158:161], v[222:225], v[128:131]
	v_mfma_f32_16x16x32_bf16 v[136:139], v[166:169], v[222:225], v[136:139]
	v_mfma_f32_16x16x32_bf16 v[140:143], v[162:165], v[226:229], v[140:143]
	ds_read_b128 v[158:161], v7 offset:33792
	ds_read_b128 v[162:165], v7 offset:35840
	ds_read_b128 v[166:169], v7 offset:37888
	ds_read_b128 v[214:217], v7 offset:39936
	ds_read_b128 v[178:181], v6 offset:1024
	ds_read_b128 v[218:221], v6 offset:3072
	ds_read_b128 v[222:225], v6 offset:5120
	ds_read_b128 v[226:229], v6 offset:7168
	s_waitcnt lgkmcnt(3)
	v_mfma_f32_16x16x32_bf16 v[40:43], v[158:161], v[178:181], v[40:43]
	v_mfma_f32_16x16x32_bf16 v[44:47], v[162:165], v[178:181], v[44:47]
	v_mfma_f32_16x16x32_bf16 v[48:51], v[166:169], v[178:181], v[48:51]
	v_mfma_f32_16x16x32_bf16 v[174:177], v[214:217], v[178:181], v[174:177]
	ds_read_b128 v[178:181], v6 offset:9216
	s_waitcnt lgkmcnt(3)
	v_mfma_f32_16x16x32_bf16 v[56:59], v[158:161], v[218:221], v[56:59]
	v_mfma_f32_16x16x32_bf16 v[60:63], v[162:165], v[218:221], v[60:63]
	v_mfma_f32_16x16x32_bf16 v[64:67], v[166:169], v[218:221], v[64:67]
	v_mfma_f32_16x16x32_bf16 v[170:173], v[214:217], v[218:221], v[170:173]
	ds_read_b128 v[218:221], v6 offset:11264
	s_waitcnt lgkmcnt(3)
	v_mfma_f32_16x16x32_bf16 v[72:75], v[158:161], v[222:225], v[72:75]
	v_mfma_f32_16x16x32_bf16 v[76:79], v[162:165], v[222:225], v[76:79]
	v_mfma_f32_16x16x32_bf16 v[80:83], v[166:169], v[222:225], v[80:83]
	v_mfma_f32_16x16x32_bf16 v[32:35], v[214:217], v[222:225], v[32:35]
	ds_read_b128 v[222:225], v6 offset:13312
	s_waitcnt lgkmcnt(3)
	v_mfma_f32_16x16x32_bf16 v[88:91], v[158:161], v[226:229], v[88:91]
	v_mfma_f32_16x16x32_bf16 v[92:95], v[162:165], v[226:229], v[92:95]
	v_mfma_f32_16x16x32_bf16 v[96:99], v[166:169], v[226:229], v[96:99]
	v_mfma_f32_16x16x32_bf16 v[36:39], v[214:217], v[226:229], v[36:39]
	ds_read_b128 v[226:229], v6 offset:15360
	s_waitcnt lgkmcnt(3)
	v_mfma_f32_16x16x32_bf16 v[104:107], v[158:161], v[178:181], v[104:107]
	v_mfma_f32_16x16x32_bf16 v[108:111], v[162:165], v[178:181], v[108:111]
	v_mfma_f32_16x16x32_bf16 v[112:115], v[166:169], v[178:181], v[112:115]
	v_mfma_f32_16x16x32_bf16 v[52:55], v[214:217], v[178:181], v[52:55]
	s_waitcnt lgkmcnt(2)
	v_mfma_f32_16x16x32_bf16 v[116:119], v[158:161], v[218:221], v[116:119]
	v_mfma_f32_16x16x32_bf16 v[120:123], v[162:165], v[218:221], v[120:123]
	v_mfma_f32_16x16x32_bf16 v[124:127], v[166:169], v[218:221], v[124:127]
	v_mfma_f32_16x16x32_bf16 v[68:71], v[214:217], v[218:221], v[68:71]
	s_waitcnt lgkmcnt(1)
	v_mfma_f32_16x16x32_bf16 v[132:135], v[162:165], v[222:225], v[132:135]
	v_mfma_f32_16x16x32_bf16 v[84:87], v[214:217], v[222:225], v[84:87]
	s_waitcnt lgkmcnt(0)
	v_mfma_f32_16x16x32_bf16 v[100:103], v[158:161], v[226:229], v[100:103]
	v_mfma_f32_16x16x32_bf16 v[150:153], v[166:169], v[226:229], v[150:153]
	v_mfma_f32_16x16x32_bf16 v[154:157], v[214:217], v[226:229], v[154:157]
	v_mfma_f32_16x16x32_bf16 v[128:131], v[158:161], v[222:225], v[128:131]
	v_mfma_f32_16x16x32_bf16 v[136:139], v[166:169], v[222:225], v[136:139]
	v_mfma_f32_16x16x32_bf16 v[140:143], v[162:165], v[226:229], v[140:143]
	s_waitcnt vmcnt(0)
	s_barrier
	v_lshl_add_u64 v[6:7], s[16:17], 0, v[0:1]
	s_mov_b32 s0, m0
	s_mov_b32 m0, s27
	s_nop 0
	global_load_lds_dwordx4 v[6:7], off
	s_mov_b32 m0, s0
	v_lshl_add_u64 v[0:1], s[18:19], 0, v[0:1]
	s_mov_b32 s0, m0
	s_mov_b32 m0, s28
	s_nop 0
	global_load_lds_dwordx4 v[0:1], off
	s_mov_b32 m0, s0
	v_lshl_add_u64 v[0:1], s[16:17], 0, v[2:3]
	s_mov_b32 s0, m0
	s_mov_b32 m0, s29
	s_nop 0
	global_load_lds_dwordx4 v[0:1], off
	s_mov_b32 m0, s0
	v_lshl_add_u64 v[0:1], s[18:19], 0, v[2:3]
	s_mov_b32 s0, m0
	s_mov_b32 m0, s30
	s_nop 0
	global_load_lds_dwordx4 v[0:1], off
	s_mov_b32 m0, s0
	v_lshl_add_u64 v[0:1], s[16:17], 0, v[4:5]
	s_mov_b32 s0, m0
	s_mov_b32 m0, s31
	s_nop 0
	global_load_lds_dwordx4 v[0:1], off
	s_mov_b32 m0, s0
	v_lshl_add_u64 v[0:1], s[18:19], 0, v[4:5]
	s_mov_b32 s0, m0
	s_mov_b32 m0, s34
	s_nop 0
	global_load_lds_dwordx4 v[0:1], off
	s_mov_b32 m0, s0
	v_lshl_add_u64 v[0:1], s[16:17], 0, v[146:147]
	s_mov_b32 s0, m0
	s_mov_b32 m0, s35
	s_nop 0
	global_load_lds_dwordx4 v[0:1], off
	s_mov_b32 m0, s0
	v_lshl_add_u64 v[0:1], s[18:19], 0, v[146:147]
	s_mov_b32 s0, m0
	s_mov_b32 m0, s36
	s_nop 0
	global_load_lds_dwordx4 v[0:1], off
	s_mov_b32 m0, s0
	ds_read_b128 v[0:3], v8
	ds_read_b128 v[4:7], v9
	ds_read_b128 v[158:161], v11
	ds_read_b128 v[8:11], v10
	ds_read_b128 v[162:165], v12
	ds_read_b128 v[166:169], v13
	ds_read_b128 v[178:181], v14
	ds_read_b128 v[12:15], v15
	s_waitcnt lgkmcnt(3)
	v_mfma_f32_16x16x32_bf16 v[40:43], v[0:3], v[162:165], v[40:43]
	v_mfma_f32_16x16x32_bf16 v[44:47], v[4:7], v[162:165], v[44:47]
	v_mfma_f32_16x16x32_bf16 v[48:51], v[158:161], v[162:165], v[48:51]
	v_mfma_f32_16x16x32_bf16 v[162:165], v[8:11], v[162:165], v[174:177]
	s_nop 2
	ds_read_b128 v[174:177], v16
	s_waitcnt lgkmcnt(3)
	v_mfma_f32_16x16x32_bf16 v[56:59], v[0:3], v[166:169], v[56:59]
	v_mfma_f32_16x16x32_bf16 v[60:63], v[4:7], v[166:169], v[60:63]
	v_mfma_f32_16x16x32_bf16 v[64:67], v[158:161], v[166:169], v[64:67]
	v_mfma_f32_16x16x32_bf16 v[166:169], v[8:11], v[166:169], v[170:173]
	s_nop 2
	ds_read_b128 v[170:173], v17
	s_waitcnt lgkmcnt(3)
	v_mfma_f32_16x16x32_bf16 v[72:75], v[0:3], v[178:181], v[72:75]
	v_mfma_f32_16x16x32_bf16 v[76:79], v[4:7], v[178:181], v[76:79]
	v_mfma_f32_16x16x32_bf16 v[80:83], v[158:161], v[178:181], v[80:83]
	v_mfma_f32_16x16x32_bf16 v[32:35], v[8:11], v[178:181], v[32:35]
	ds_read_b128 v[178:181], v18
	s_waitcnt lgkmcnt(3)
	v_mfma_f32_16x16x32_bf16 v[214:217], v[0:3], v[12:15], v[88:91]
	v_mfma_f32_16x16x32_bf16 v[218:221], v[4:7], v[12:15], v[92:95]
	v_mfma_f32_16x16x32_bf16 v[222:225], v[158:161], v[12:15], v[96:99]
	v_mfma_f32_16x16x32_bf16 v[12:15], v[8:11], v[12:15], v[36:39]
	ds_read_b128 v[16:19], v19
	s_waitcnt lgkmcnt(3)
	v_mfma_f32_16x16x32_bf16 v[36:39], v[0:3], v[174:177], v[104:107]
	v_mfma_f32_16x16x32_bf16 v[226:229], v[4:7], v[174:177], v[108:111]
	v_mfma_f32_16x16x32_bf16 v[112:115], v[158:161], v[174:177], v[112:115]
	s_waitcnt lgkmcnt(2)
	v_mfma_f32_16x16x32_bf16 v[116:119], v[0:3], v[170:173], v[116:119]
	v_mfma_f32_16x16x32_bf16 v[120:123], v[4:7], v[170:173], v[120:123]
	v_mfma_f32_16x16x32_bf16 v[124:127], v[158:161], v[170:173], v[124:127]
	s_waitcnt lgkmcnt(1)
	v_mfma_f32_16x16x32_bf16 v[128:131], v[0:3], v[178:181], v[128:131]
	v_mfma_f32_16x16x32_bf16 v[132:135], v[4:7], v[178:181], v[132:135]
	s_waitcnt lgkmcnt(0)
	v_mfma_f32_16x16x32_bf16 v[0:3], v[0:3], v[16:19], v[100:103]
	v_mfma_f32_16x16x32_bf16 v[4:7], v[4:7], v[16:19], v[140:143]
	v_mfma_f32_16x16x32_bf16 v[140:143], v[158:161], v[16:19], v[150:153]
	v_mfma_f32_16x16x32_bf16 v[150:153], v[8:11], v[16:19], v[154:157]
	v_mfma_f32_16x16x32_bf16 v[174:177], v[8:11], v[174:177], v[52:55]
	v_mfma_f32_16x16x32_bf16 v[170:173], v[8:11], v[170:173], v[68:71]
	v_mfma_f32_16x16x32_bf16 v[136:139], v[158:161], v[178:181], v[136:139]
	v_mfma_f32_16x16x32_bf16 v[178:181], v[8:11], v[178:181], v[84:87]
	ds_read_b128 v[8:11], v20
	ds_read_b128 v[154:157], v21
	ds_read_b128 v[158:161], v23
	ds_read_b128 v[230:233], v22
	ds_read_b128 v[16:19], v24
	ds_read_b128 v[20:23], v25
	ds_read_b128 v[52:55], v26
	ds_read_b128 v[24:27], v27
	s_waitcnt lgkmcnt(3)
	v_mfma_f32_16x16x32_bf16 v[234:237], v[8:11], v[16:19], v[40:43]
	v_mfma_f32_16x16x32_bf16 v[238:241], v[154:157], v[16:19], v[44:47]
	v_mfma_f32_16x16x32_bf16 v[242:245], v[158:161], v[16:19], v[48:51]
	v_mfma_f32_16x16x32_bf16 v[162:165], v[230:233], v[16:19], v[162:165]
	ds_read_b128 v[16:19], v28
	s_waitcnt lgkmcnt(3)
	v_mfma_f32_16x16x32_bf16 v[108:111], v[8:11], v[20:23], v[56:59]
	v_mfma_f32_16x16x32_bf16 v[104:107], v[154:157], v[20:23], v[60:63]
	v_mfma_f32_16x16x32_bf16 v[100:103], v[158:161], v[20:23], v[64:67]
	v_mfma_f32_16x16x32_bf16 v[96:99], v[230:233], v[20:23], v[166:169]
	ds_read_b128 v[20:23], v29
	s_waitcnt lgkmcnt(3)
	v_mfma_f32_16x16x32_bf16 v[92:95], v[8:11], v[52:55], v[72:75]
	v_mfma_f32_16x16x32_bf16 v[88:91], v[154:157], v[52:55], v[76:79]
	v_mfma_f32_16x16x32_bf16 v[84:87], v[158:161], v[52:55], v[80:83]
	v_mfma_f32_16x16x32_bf16 v[80:83], v[230:233], v[52:55], v[32:35]
	ds_read_b128 v[166:169], v30
	s_waitcnt lgkmcnt(3)
	v_mfma_f32_16x16x32_bf16 v[76:79], v[8:11], v[24:27], v[214:217]
	v_mfma_f32_16x16x32_bf16 v[72:75], v[154:157], v[24:27], v[218:221]
	v_mfma_f32_16x16x32_bf16 v[68:71], v[158:161], v[24:27], v[222:225]
	v_mfma_f32_16x16x32_bf16 v[64:67], v[230:233], v[24:27], v[12:15]
	ds_read_b128 v[214:217], v31
	s_waitcnt lgkmcnt(3)
	v_mfma_f32_16x16x32_bf16 v[60:63], v[8:11], v[16:19], v[36:39]
	v_mfma_f32_16x16x32_bf16 v[56:59], v[154:157], v[16:19], v[226:229]
	v_mfma_f32_16x16x32_bf16 v[52:55], v[158:161], v[16:19], v[112:115]
	v_mfma_f32_16x16x32_bf16 v[48:51], v[230:233], v[16:19], v[174:177]
	s_waitcnt lgkmcnt(2)
	v_mfma_f32_16x16x32_bf16 v[44:47], v[8:11], v[20:23], v[116:119]
	v_mfma_f32_16x16x32_bf16 v[40:43], v[154:157], v[20:23], v[120:123]
	v_mfma_f32_16x16x32_bf16 v[36:39], v[158:161], v[20:23], v[124:127]
	v_mfma_f32_16x16x32_bf16 v[32:35], v[230:233], v[20:23], v[170:173]
	s_waitcnt lgkmcnt(1)
	v_mfma_f32_16x16x32_bf16 v[28:31], v[8:11], v[166:169], v[128:131]
	v_mfma_f32_16x16x32_bf16 v[24:27], v[154:157], v[166:169], v[132:135]
	v_mfma_f32_16x16x32_bf16 v[20:23], v[158:161], v[166:169], v[136:139]
	v_mfma_f32_16x16x32_bf16 v[16:19], v[230:233], v[166:169], v[178:181]
	s_waitcnt lgkmcnt(0)
	v_mfma_f32_16x16x32_bf16 v[12:15], v[8:11], v[214:217], v[0:3]
	v_mfma_f32_16x16x32_bf16 v[8:11], v[154:157], v[214:217], v[4:7]
	v_mfma_f32_16x16x32_bf16 v[4:7], v[158:161], v[214:217], v[140:143]
	v_mfma_f32_16x16x32_bf16 v[0:3], v[230:233], v[214:217], v[150:153]
	v_mov_b32_e32 v145, v184
	s_waitcnt vmcnt(0)
	s_barrier
	s_lshl_b32 s16, s13, 8
	s_lshl_b32 s14, s12, 8
	v_and_b32_e32 v151, 15, v145
	v_ashrrev_i32_e32 v112, 1, v145
	v_and_b32_e32 v153, 0xffffff80, v112
	v_or_b32_e32 v112, s16, v151
	v_add_u32_e32 v112, v112, v153
	v_ashrrev_i32_e32 v113, 31, v112
	v_lshlrev_b64 v[112:113], 13, v[112:113]
	v_bfe_u32 v150, v145, 6, 2
	v_lshl_add_u64 v[112:113], s[4:5], 0, v[112:113]
	s_ashr_i32 s15, s14, 31
	v_bfe_u32 v152, v145, 4, 2
	v_lshl_add_u64 v[112:113], s[14:15], 2, v[112:113]
	v_lshlrev_b32_e32 v146, 8, v150
	v_lshl_add_u64 v[112:113], v[112:113], 0, v[146:147]
	v_lshlrev_b32_e32 v146, 4, v152
	v_lshl_add_u64 v[154:155], v[112:113], 0, v[146:147]
	global_load_dwordx4 v[120:123], v[154:155], off offset:192
	global_load_dwordx4 v[128:131], v[154:155], off offset:128
	global_load_dwordx4 v[136:139], v[154:155], off offset:64
	global_load_dwordx4 v[140:143], v[154:155], off
	v_add_co_u32_e32 v112, vcc, s66, v154
	v_lshlrev_b32_e32 v158, 2, v152
	s_nop 0
	v_addc_co_u32_e32 v113, vcc, 0, v155, vcc
	global_load_dwordx4 v[132:135], v[112:113], off
	global_load_dwordx4 v[124:127], v[112:113], off offset:64
	global_load_dwordx4 v[116:119], v[112:113], off offset:128
	v_cmp_lt_i32_e32 vcc, v188, v186
	global_load_dwordx4 v[112:115], v[112:113], off offset:192
	v_cmp_eq_u32_e64 s[0:1], 0, v152
	v_cndmask_b32_e32 v146, v185, v188, vcc
	v_cmp_lt_i32_e32 vcc, v187, v186
	v_lshlrev_b32_e32 v149, 2, v146
	v_lshlrev_b32_e32 v157, 6, v150
	v_cndmask_b32_e32 v156, v185, v187, vcc
	v_lshlrev_b32_e32 v146, 2, v156
	v_or_b32_e32 v156, v153, v151
	v_add_u32_e32 v152, s16, v156
	v_ashrrev_i32_e32 v153, 31, v152
	v_lshl_or_b32 v182, v150, 10, v204
	v_or3_b32 v150, v157, s14, v158
	v_lshlrev_b64 v[158:159], 13, v[152:153]
	v_ashrrev_i32_e32 v151, 31, v150
	v_lshlrev_b64 v[160:161], 12, v[152:153]
	v_lshl_add_u64 v[158:159], s[4:5], 0, v[158:159]
	v_lshl_add_u64 v[160:161], s[6:7], 0, v[160:161]
	v_lshl_add_u64 v[166:167], v[150:151], 2, v[158:159]
	v_lshl_add_u64 v[168:169], v[150:151], 1, v[160:161]
	s_waitcnt vmcnt(7)
	v_pk_add_f32 v[158:159], v[162:163], v[120:121]
	s_waitcnt vmcnt(6)
	v_pk_add_f32 v[120:121], v[242:243], v[128:129]
	s_waitcnt vmcnt(5)
	v_pk_add_f32 v[128:129], v[238:239], v[136:137]
	s_waitcnt vmcnt(4)
	v_pk_add_f32 v[136:137], v[234:235], v[140:141]
	v_pk_add_f32 v[160:161], v[164:165], v[122:123]
	v_pk_add_f32 v[122:123], v[244:245], v[130:131]
	v_pk_add_f32 v[130:131], v[240:241], v[138:139]
	v_pk_add_f32 v[138:139], v[236:237], v[142:143]
	v_pk_mul_f32 v[172:173], v[128:129], v[128:129]
	v_pk_mul_f32 v[178:179], v[136:137], v[136:137]
	v_pk_mul_f32 v[162:163], v[120:121], v[120:121]
	v_pk_mul_f32 v[174:175], v[130:131], v[130:131]
	v_cvt_pk_bf16_f32 v176, v136, v137
	v_pk_mul_f32 v[180:181], v[138:139], v[138:139]
	global_store_dwordx4 v[166:167], v[136:139], off
	v_add_f32_e32 v153, v172, v173
	v_add_f32_e32 v157, v178, v179
	v_pk_mul_f32 v[136:137], v[158:159], v[158:159]
	v_pk_mul_f32 v[164:165], v[122:123], v[122:123]
	v_cvt_pk_bf16_f32 v177, v138, v139
	v_pk_mul_f32 v[138:139], v[160:161], v[160:161]
	v_add_f32_e32 v162, v162, v163
	v_add_f32_e32 v136, v136, v137
	v_add_f32_e32 v137, v174, v153
	v_add_f32_e32 v153, v180, v157
	v_add_f32_e32 v157, v164, v162
	v_add_f32_e32 v136, v138, v136
	v_add_f32_e32 v137, v175, v137
	v_add_f32_e32 v138, v181, v153
	v_add_f32_e32 v153, v165, v157
	v_add_f32_e32 v137, v138, v137
	v_add_f32_e32 v137, v137, v153
	v_add_f32_e32 v136, v139, v136
	v_add_f32_e32 v136, v137, v136
	ds_bpermute_b32 v137, v149, v136
	v_cvt_pk_bf16_f32 v170, v128, v129
	v_cvt_pk_bf16_f32 v171, v130, v131
	v_cvt_pk_bf16_f32 v142, v120, v121
	global_store_dwordx2 v[168:169], v[176:177], off
	global_store_dwordx4 v[166:167], v[128:131], off offset:64
	global_store_dwordx2 v[168:169], v[170:171], off offset:32
	global_store_dwordx4 v[166:167], v[120:123], off offset:128
	v_cvt_pk_bf16_f32 v140, v158, v159
	v_cvt_pk_bf16_f32 v141, v160, v161
	s_waitcnt lgkmcnt(0)
	v_add_f32_e32 v120, v136, v137
	ds_bpermute_b32 v121, v146, v120
	v_cvt_pk_bf16_f32 v143, v122, v123
	v_lshl_add_u32 v153, v156, 2, v182
	global_store_dwordx2 v[168:169], v[142:143], off offset:64
	global_store_dwordx4 v[166:167], v[158:161], off offset:192
	global_store_dwordx2 v[168:169], v[140:141], off offset:96
	s_and_saveexec_b64 s[14:15], s[0:1]
	s_cbranch_execz .LBB0_254
	s_waitcnt lgkmcnt(0)
	v_add_f32_e32 v120, v120, v121
	ds_write_b32 v153, v120

.LBB0_300:
	s_ashr_i32 s31, s30, 31
	s_lshl_b64 s[30:31], s[30:31], 20
	s_add_u32 s30, s38, s30
	s_addc_u32 s31, s39, s31
	s_ashr_i32 s5, s4, 31
	v_lshlrev_b32_e32 v3, 6, v1
	s_lshl_b64 s[4:5], s[4:5], 20
	v_and_b32_e32 v2, 48, v1
	v_and_b32_e32 v4, 0x3c0, v3
	v_lshlrev_b32_e32 v1, 2, v1
	s_add_u32 s34, s14, s4
	v_or_b32_e32 v5, v4, v2
	v_and_b32_e32 v1, 32, v1
	v_lshlrev_b32_e32 v0, 13, v0
	s_mov_b32 s4, 0x18000
	v_and_b32_e32 v135, 0x6000, v0
	v_bitop3_b32 v0, v5, s4, v1 bitop3:0xde
	s_mov_b32 s4, 0x10400
	s_addc_u32 s35, s15, s5
	v_bitop3_b32 v149, v5, s4, v1 bitop3:0xde
	s_lshl_b32 s4, s65, 2
	s_or_b32 s4, s4, s68
	s_lshl_b32 s5, s64, 2
	s_sub_i32 s4, s4, s5
	s_ashr_i32 s5, s4, 31
	s_waitcnt vmcnt(0)
	s_add_i32 s51, s1, 0x10000
	s_add_i32 s52, s1, 0x18000
	s_add_i32 s53, s1, 0x12000
	s_add_i32 s54, s1, 0x1a000
	s_add_i32 s55, s1, 0x14000
	s_add_i32 s58, s1, 0x1c000
	s_add_i32 s62, s1, 0x16000
	s_add_i32 s63, s1, 0x1e000
	s_lshl_b64 s[4:5], s[4:5], 20
	v_and_b32_e32 v136, 0xffffc000, v3
	s_add_u32 s64, s10, s4
	v_mov_b32_e32 v16, 0
	v_bitop3_b32 v134, v4, v1, v2 bitop3:0x36
	v_or_b32_e32 v137, 0x800, v136
	v_or_b32_e32 v138, 0x1000, v136
	v_or_b32_e32 v139, 0x1800, v136
	v_or_b32_e32 v140, 0x2000, v136
	v_or_b32_e32 v141, 0x2800, v136
	v_or_b32_e32 v142, 0x3000, v136
	v_or_b32_e32 v143, 0x3800, v136
	v_bitop3_b32 v145, v5, s33, v1 bitop3:0xde
	s_addc_u32 s65, s11, s5
	s_mov_b64 s[4:5], 0
	s_mov_b32 s68, 1
	v_add_u32_e32 v150, v0, v135
	v_mov_b32_e32 v17, v16
	v_mov_b32_e32 v18, v16
	v_mov_b32_e32 v19, v16
	v_mov_b32_e32 v20, v16
	v_mov_b32_e32 v21, v16
	v_mov_b32_e32 v22, v16
	v_mov_b32_e32 v23, v16
	v_mov_b32_e32 v24, v16
	v_mov_b32_e32 v25, v16
	v_mov_b32_e32 v26, v16
	v_mov_b32_e32 v27, v16
	v_mov_b32_e32 v28, v16
	v_mov_b32_e32 v29, v16
	v_mov_b32_e32 v30, v16
	v_mov_b32_e32 v31, v16
	v_mov_b32_e32 v32, v16
	v_mov_b32_e32 v33, v16
	v_mov_b32_e32 v34, v16
	v_mov_b32_e32 v35, v16
	v_mov_b32_e32 v36, v16
	v_mov_b32_e32 v37, v16
	v_mov_b32_e32 v38, v16
	v_mov_b32_e32 v39, v16
	v_mov_b32_e32 v40, v16
	v_mov_b32_e32 v41, v16
	v_mov_b32_e32 v42, v16
	v_mov_b32_e32 v43, v16
	v_mov_b32_e32 v44, v16
	v_mov_b32_e32 v45, v16
	v_mov_b32_e32 v46, v16
	v_mov_b32_e32 v47, v16
	v_mov_b32_e32 v48, v16
	v_mov_b32_e32 v49, v16
	v_mov_b32_e32 v50, v16
	v_mov_b32_e32 v51, v16
	v_mov_b32_e32 v52, v16
	v_mov_b32_e32 v53, v16
	v_mov_b32_e32 v54, v16
	v_mov_b32_e32 v55, v16
	v_mov_b32_e32 v56, v16
	v_mov_b32_e32 v57, v16
	v_mov_b32_e32 v58, v16
	v_mov_b32_e32 v59, v16
	v_mov_b32_e32 v60, v16
	v_mov_b32_e32 v61, v16
	v_mov_b32_e32 v62, v16
	v_mov_b32_e32 v63, v16
	v_mov_b32_e32 v64, v16
	v_mov_b32_e32 v65, v16
	v_mov_b32_e32 v66, v16
	v_mov_b32_e32 v67, v16
	v_mov_b32_e32 v68, v16
	v_mov_b32_e32 v69, v16
	v_mov_b32_e32 v70, v16
	v_mov_b32_e32 v71, v16
	v_mov_b32_e32 v72, v16
	v_mov_b32_e32 v73, v16
	v_mov_b32_e32 v74, v16
	v_mov_b32_e32 v75, v16
	v_mov_b32_e32 v76, v16
	v_mov_b32_e32 v77, v16
	v_mov_b32_e32 v78, v16
	v_mov_b32_e32 v79, v16
	v_mov_b32_e32 v80, v16
	v_mov_b32_e32 v81, v16
	v_mov_b32_e32 v82, v16
	v_mov_b32_e32 v83, v16
	v_mov_b32_e32 v84, v16
	v_mov_b32_e32 v85, v16
	v_mov_b32_e32 v86, v16
	v_mov_b32_e32 v87, v16
	v_mov_b32_e32 v88, v16
	v_mov_b32_e32 v89, v16
	v_mov_b32_e32 v90, v16
	v_mov_b32_e32 v91, v16
	v_mov_b32_e32 v92, v16
	v_mov_b32_e32 v93, v16
	v_mov_b32_e32 v94, v16
	v_mov_b32_e32 v95, v16
	v_mov_b32_e32 v96, v16
	v_mov_b32_e32 v97, v16
	v_mov_b32_e32 v98, v16
	v_mov_b32_e32 v99, v16
	v_mov_b32_e32 v100, v16
	v_mov_b32_e32 v101, v16
	v_mov_b32_e32 v102, v16
	v_mov_b32_e32 v103, v16
	v_mov_b32_e32 v104, v16
	v_mov_b32_e32 v105, v16
	v_mov_b32_e32 v106, v16
	v_mov_b32_e32 v107, v16
	v_mov_b32_e32 v108, v16
	v_mov_b32_e32 v109, v16
	v_mov_b32_e32 v110, v16
	v_mov_b32_e32 v111, v16
	v_mov_b32_e32 v112, v16
	v_mov_b32_e32 v113, v16
	v_mov_b32_e32 v114, v16
	v_mov_b32_e32 v115, v16
	v_mov_b32_e32 v116, v16
	v_mov_b32_e32 v117, v16
	v_mov_b32_e32 v118, v16
	v_mov_b32_e32 v119, v16
	v_mov_b32_e32 v120, v16
	v_mov_b32_e32 v121, v16
	v_mov_b32_e32 v122, v16
	v_mov_b32_e32 v123, v16
	v_mov_b32_e32 v124, v16
	v_mov_b32_e32 v125, v16
	v_mov_b32_e32 v126, v16
	v_mov_b32_e32 v127, v16
	v_mov_b32_e32 v12, v16
	v_mov_b32_e32 v13, v16
	v_mov_b32_e32 v14, v16
	v_mov_b32_e32 v15, v16
	v_mov_b32_e32 v8, v16
	v_mov_b32_e32 v9, v16
	v_mov_b32_e32 v10, v16
	v_mov_b32_e32 v11, v16
	v_mov_b32_e32 v4, v16
	v_mov_b32_e32 v5, v16
	v_mov_b32_e32 v6, v16
	v_mov_b32_e32 v7, v16
	v_mov_b32_e32 v0, v16
	v_mov_b32_e32 v1, v16
	v_mov_b32_e32 v2, v16
	v_mov_b32_e32 v3, v16
	s_waitcnt lgkmcnt(0)
	s_barrier
	s_add_u32 s69, s64, s4
	s_addc_u32 s74, s65, s5
	s_add_u32 s70, s69, 0x1b900080
	s_addc_u32 s71, s74, 0
	s_add_u32 s75, s2, s4
	s_addc_u32 s76, s3, s5
	s_add_u32 s72, s75, 0x80
	s_addc_u32 s73, s76, 0
	v_add_u32_e32 v151, v134, v135
	v_add_u32_e32 v189, v134, v136
	ds_read_b128 v[152:155], v151 offset:32768
	ds_read_b128 v[156:159], v189
	s_mov_b32 m0, s52
	s_nop 0
	global_load_lds_dwordx4 v128, s[72:73]
	ds_read_b128 v[160:163], v151 offset:34816
	s_mov_b32 m0, s54
	s_nop 0
	global_load_lds_dwordx4 v130, s[72:73]
	ds_read_b128 v[164:167], v189 offset:2048
	ds_read_b128 v[168:171], v151 offset:36864
	s_mov_b32 m0, s58
	s_nop 0
	global_load_lds_dwordx4 v132, s[72:73]
	ds_read_b128 v[172:175], v151 offset:38912
	ds_read_b128 v[176:179], v189 offset:4096
	ds_read_b128 v[180:183], v189 offset:6144
	s_branch .Lmy_rot_301
.LBB0_301:
	s_add_u32 s69, s64, s4
	s_addc_u32 s74, s65, s5
	s_add_u32 s70, s69, 0x1b900080
	s_addc_u32 s71, s74, 0
	s_add_u32 s75, s2, s4
	s_addc_u32 s76, s3, s5
	s_add_u32 s72, s75, 0x80
	s_addc_u32 s73, s76, 0
	v_add_u32_e32 v151, v134, v135
	v_add_u32_e32 v189, v134, v136
	ds_read_b128 v[152:155], v151 offset:32768
	ds_read_b128 v[156:159], v189
	s_mov_b32 m0, s52
	v_mfma_f32_16x16x32_bf16 v[28:31], v[160:163], v[176:179], v[28:31]
	global_load_lds_dwordx4 v128, s[72:73]
	v_mfma_f32_16x16x32_bf16 v[12:15], v[160:163], v[180:183], v[12:15]
	ds_read_b128 v[160:163], v151 offset:34816
	v_mfma_f32_16x16x32_bf16 v[24:27], v[164:167], v[176:179], v[24:27]
	s_mov_b32 m0, s54
	v_mfma_f32_16x16x32_bf16 v[8:11], v[164:167], v[180:183], v[8:11]
	global_load_lds_dwordx4 v130, s[72:73]
	ds_read_b128 v[164:167], v189 offset:2048
	v_mfma_f32_16x16x32_bf16 v[20:23], v[168:171], v[176:179], v[20:23]
	v_mfma_f32_16x16x32_bf16 v[4:7], v[168:171], v[180:183], v[4:7]
	ds_read_b128 v[168:171], v151 offset:36864
	s_mov_b32 m0, s58
	v_mfma_f32_16x16x32_bf16 v[16:19], v[172:175], v[176:179], v[16:19]
	global_load_lds_dwordx4 v132, s[72:73]
	v_mfma_f32_16x16x32_bf16 v[0:3], v[172:175], v[180:183], v[0:3]
	ds_read_b128 v[172:175], v151 offset:38912
	ds_read_b128 v[176:179], v189 offset:4096
	ds_read_b128 v[180:183], v189 offset:6144
.Lmy_rot_301:
	s_waitcnt lgkmcnt(6)
	v_mfma_f32_16x16x32_bf16 v[124:127], v[152:155], v[156:159], v[124:127]
	s_waitcnt lgkmcnt(5)
	s_mov_b32 m0, s63
	v_mfma_f32_16x16x32_bf16 v[120:123], v[160:163], v[156:159], v[120:123]
	global_load_lds_dwordx4 v146, s[72:73]
	s_waitcnt lgkmcnt(4)
	v_mfma_f32_16x16x32_bf16 v[108:111], v[152:155], v[164:167], v[108:111]
	v_mfma_f32_16x16x32_bf16 v[104:107], v[160:163], v[164:167], v[104:107]
	s_waitcnt lgkmcnt(3)
	s_mov_b32 m0, s51
	v_mfma_f32_16x16x32_bf16 v[116:119], v[168:171], v[156:159], v[116:119]
	global_load_lds_dwordx4 v128, s[70:71]
	v_mfma_f32_16x16x32_bf16 v[100:103], v[168:171], v[164:167], v[100:103]
	s_waitcnt lgkmcnt(2)
	v_mfma_f32_16x16x32_bf16 v[112:115], v[172:175], v[156:159], v[112:115]
	ds_read_b128 v[156:159], v189 offset:8192
	s_mov_b32 m0, s53
	v_mfma_f32_16x16x32_bf16 v[96:99], v[172:175], v[164:167], v[96:99]
	global_load_lds_dwordx4 v130, s[70:71]
	ds_read_b128 v[164:167], v189 offset:10240
	s_waitcnt lgkmcnt(3)
	v_mfma_f32_16x16x32_bf16 v[92:95], v[152:155], v[176:179], v[92:95]
	v_mfma_f32_16x16x32_bf16 v[88:91], v[160:163], v[176:179], v[88:91]
	s_mov_b32 m0, s55
	v_mfma_f32_16x16x32_bf16 v[84:87], v[168:171], v[176:179], v[84:87]
	global_load_lds_dwordx4 v132, s[70:71]
	v_mfma_f32_16x16x32_bf16 v[80:83], v[172:175], v[176:179], v[80:83]
	ds_read_b128 v[176:179], v189 offset:12288
	s_waitcnt lgkmcnt(3)
	v_mfma_f32_16x16x32_bf16 v[76:79], v[152:155], v[180:183], v[76:79]
	s_mov_b32 m0, s62
	v_mfma_f32_16x16x32_bf16 v[72:75], v[160:163], v[180:183], v[72:75]
	global_load_lds_dwordx4 v146, s[70:71]
	v_mfma_f32_16x16x32_bf16 v[68:71], v[168:171], v[180:183], v[68:71]
	v_mfma_f32_16x16x32_bf16 v[64:67], v[172:175], v[180:183], v[64:67]
	ds_read_b128 v[180:183], v189 offset:14336
	s_waitcnt lgkmcnt(3)
	v_mfma_f32_16x16x32_bf16 v[56:59], v[160:163], v[156:159], v[56:59]
	s_waitcnt lgkmcnt(2)
	v_mfma_f32_16x16x32_bf16 v[40:43], v[160:163], v[164:167], v[40:43]
	s_waitcnt lgkmcnt(1)
	v_mfma_f32_16x16x32_bf16 v[24:27], v[160:163], v[176:179], v[24:27]
	s_waitcnt lgkmcnt(0)
	v_mfma_f32_16x16x32_bf16 v[8:11], v[160:163], v[180:183], v[8:11]
	ds_read_b128 v[160:163], v151 offset:33792
	v_mfma_f32_16x16x32_bf16 v[60:63], v[152:155], v[156:159], v[60:63]
	v_mfma_f32_16x16x32_bf16 v[44:47], v[152:155], v[164:167], v[44:47]
	v_mfma_f32_16x16x32_bf16 v[28:31], v[152:155], v[176:179], v[28:31]
	v_mfma_f32_16x16x32_bf16 v[12:15], v[152:155], v[180:183], v[12:15]
	ds_read_b128 v[152:155], v189 offset:1024
	v_mfma_f32_16x16x32_bf16 v[36:39], v[168:171], v[164:167], v[36:39]
	v_mfma_f32_16x16x32_bf16 v[32:35], v[172:175], v[164:167], v[32:35]
	ds_read_b128 v[164:167], v151 offset:35840
	v_mfma_f32_16x16x32_bf16 v[52:55], v[168:171], v[156:159], v[52:55]
	v_mfma_f32_16x16x32_bf16 v[48:51], v[172:175], v[156:159], v[48:51]
	ds_read_b128 v[156:159], v189 offset:3072
	v_mfma_f32_16x16x32_bf16 v[20:23], v[168:171], v[176:179], v[20:23]
	v_mfma_f32_16x16x32_bf16 v[16:19], v[172:175], v[176:179], v[16:19]
	ds_read_b128 v[176:179], v189 offset:5120
	v_mfma_f32_16x16x32_bf16 v[4:7], v[168:171], v[180:183], v[4:7]
	ds_read_b128 v[168:171], v151 offset:37888
	v_mfma_f32_16x16x32_bf16 v[0:3], v[172:175], v[180:183], v[0:3]
	ds_read_b128 v[172:175], v151 offset:39936
	ds_read_b128 v[180:183], v189 offset:7168
	s_waitcnt lgkmcnt(6)
	v_mfma_f32_16x16x32_bf16 v[124:127], v[160:163], v[152:155], v[124:127]
	s_waitcnt lgkmcnt(5)
	v_mfma_f32_16x16x32_bf16 v[120:123], v[164:167], v[152:155], v[120:123]
	s_waitcnt lgkmcnt(4)
	v_mfma_f32_16x16x32_bf16 v[108:111], v[160:163], v[156:159], v[108:111]
	v_mfma_f32_16x16x32_bf16 v[104:107], v[164:167], v[156:159], v[104:107]
	s_waitcnt lgkmcnt(3)
	v_mfma_f32_16x16x32_bf16 v[92:95], v[160:163], v[176:179], v[92:95]
	v_mfma_f32_16x16x32_bf16 v[88:91], v[164:167], v[176:179], v[88:91]
	s_waitcnt lgkmcnt(2)
	v_mfma_f32_16x16x32_bf16 v[116:119], v[168:171], v[152:155], v[116:119]
	s_waitcnt lgkmcnt(1)
	v_mfma_f32_16x16x32_bf16 v[112:115], v[172:175], v[152:155], v[112:115]
	ds_read_b128 v[152:155], v189 offset:9216
	v_mfma_f32_16x16x32_bf16 v[100:103], v[168:171], v[156:159], v[100:103]
	v_mfma_f32_16x16x32_bf16 v[96:99], v[172:175], v[156:159], v[96:99]
	ds_read_b128 v[156:159], v189 offset:11264
	v_mfma_f32_16x16x32_bf16 v[84:87], v[168:171], v[176:179], v[84:87]
	v_mfma_f32_16x16x32_bf16 v[80:83], v[172:175], v[176:179], v[80:83]
	ds_read_b128 v[176:179], v189 offset:13312
	s_waitcnt lgkmcnt(3)
	v_mfma_f32_16x16x32_bf16 v[76:79], v[160:163], v[180:183], v[76:79]
	v_mfma_f32_16x16x32_bf16 v[72:75], v[164:167], v[180:183], v[72:75]
	v_mfma_f32_16x16x32_bf16 v[68:71], v[168:171], v[180:183], v[68:71]
	v_mfma_f32_16x16x32_bf16 v[64:67], v[172:175], v[180:183], v[64:67]
	ds_read_b128 v[180:183], v189 offset:15360
	s_waitcnt lgkmcnt(3)
	v_mfma_f32_16x16x32_bf16 v[60:63], v[160:163], v[152:155], v[60:63]
	v_mfma_f32_16x16x32_bf16 v[56:59], v[164:167], v[152:155], v[56:59]
	v_mfma_f32_16x16x32_bf16 v[52:55], v[168:171], v[152:155], v[52:55]
	v_mfma_f32_16x16x32_bf16 v[48:51], v[172:175], v[152:155], v[48:51]
	s_waitcnt lgkmcnt(2)
	v_mfma_f32_16x16x32_bf16 v[44:47], v[160:163], v[156:159], v[44:47]
	v_mfma_f32_16x16x32_bf16 v[40:43], v[164:167], v[156:159], v[40:43]
	v_mfma_f32_16x16x32_bf16 v[36:39], v[168:171], v[156:159], v[36:39]
	v_mfma_f32_16x16x32_bf16 v[32:35], v[172:175], v[156:159], v[32:35]
	s_add_u32 s69, s69, 0x1b900100
	s_addc_u32 s70, s74, 0
	s_add_u32 s72, s75, 0x100
	s_addc_u32 s73, s76, 0
	s_cmp_lt_u32 s68, 31
	s_cselect_b32 s71, s70, s31
	s_cselect_b32 s70, s69, s30
	s_waitcnt vmcnt(0)
	s_waitcnt lgkmcnt(0)
	s_barrier
	s_cselect_b32 s73, s73, s35
	s_cselect_b32 s72, s72, s34
	ds_read_b128 v[152:155], v150
	v_add_u32_e32 v151, v145, v136
	ds_read_b128 v[156:159], v151
	s_mov_b32 m0, s44
	v_mfma_f32_16x16x32_bf16 v[28:31], v[160:163], v[176:179], v[28:31]
	global_load_lds_dwordx4 v128, s[72:73]
	v_mfma_f32_16x16x32_bf16 v[12:15], v[160:163], v[180:183], v[12:15]
	ds_read_b128 v[160:163], v150 offset:2048
	v_mfma_f32_16x16x32_bf16 v[24:27], v[164:167], v[176:179], v[24:27]
	s_mov_b32 m0, s46
	v_mfma_f32_16x16x32_bf16 v[8:11], v[164:167], v[180:183], v[8:11]
	global_load_lds_dwordx4 v130, s[72:73]
	v_add_u32_e32 v151, v145, v137
	ds_read_b128 v[164:167], v151
	v_mfma_f32_16x16x32_bf16 v[20:23], v[168:171], v[176:179], v[20:23]
	v_mfma_f32_16x16x32_bf16 v[4:7], v[168:171], v[180:183], v[4:7]
	ds_read_b128 v[168:171], v150 offset:4096
	s_mov_b32 m0, s48
	v_mfma_f32_16x16x32_bf16 v[16:19], v[172:175], v[176:179], v[16:19]
	global_load_lds_dwordx4 v132, s[72:73]
	v_mfma_f32_16x16x32_bf16 v[0:3], v[172:175], v[180:183], v[0:3]
	ds_read_b128 v[172:175], v150 offset:6144
	v_add_u32_e32 v151, v145, v138
	ds_read_b128 v[176:179], v151
	v_add_u32_e32 v151, v145, v139
	ds_read_b128 v[180:183], v151
	s_waitcnt lgkmcnt(6)
	v_mfma_f32_16x16x32_bf16 v[124:127], v[152:155], v[156:159], v[124:127]
	s_waitcnt lgkmcnt(5)
	s_mov_b32 m0, s50
	v_mfma_f32_16x16x32_bf16 v[120:123], v[160:163], v[156:159], v[120:123]
	global_load_lds_dwordx4 v146, s[72:73]
	s_waitcnt lgkmcnt(4)
	v_mfma_f32_16x16x32_bf16 v[108:111], v[152:155], v[164:167], v[108:111]
	v_mfma_f32_16x16x32_bf16 v[104:107], v[160:163], v[164:167], v[104:107]
	s_waitcnt lgkmcnt(3)
	s_mov_b32 m0, s1
	v_mfma_f32_16x16x32_bf16 v[116:119], v[168:171], v[156:159], v[116:119]
	global_load_lds_dwordx4 v128, s[70:71]
	v_mfma_f32_16x16x32_bf16 v[100:103], v[168:171], v[164:167], v[100:103]
	s_waitcnt lgkmcnt(2)
	v_mfma_f32_16x16x32_bf16 v[112:115], v[172:175], v[156:159], v[112:115]
	v_add_u32_e32 v151, v145, v140
	ds_read_b128 v[156:159], v151
	s_mov_b32 m0, s45
	v_mfma_f32_16x16x32_bf16 v[96:99], v[172:175], v[164:167], v[96:99]
	global_load_lds_dwordx4 v130, s[70:71]
	v_add_u32_e32 v151, v145, v141
	ds_read_b128 v[164:167], v151
	s_waitcnt lgkmcnt(3)
	v_mfma_f32_16x16x32_bf16 v[92:95], v[152:155], v[176:179], v[92:95]
	v_mfma_f32_16x16x32_bf16 v[88:91], v[160:163], v[176:179], v[88:91]
	s_mov_b32 m0, s47
	v_mfma_f32_16x16x32_bf16 v[84:87], v[168:171], v[176:179], v[84:87]
	global_load_lds_dwordx4 v132, s[70:71]
	v_mfma_f32_16x16x32_bf16 v[80:83], v[172:175], v[176:179], v[80:83]
	v_add_u32_e32 v151, v145, v142
	ds_read_b128 v[176:179], v151
	s_waitcnt lgkmcnt(3)
	v_mfma_f32_16x16x32_bf16 v[76:79], v[152:155], v[180:183], v[76:79]
	s_mov_b32 m0, s49
	v_mfma_f32_16x16x32_bf16 v[72:75], v[160:163], v[180:183], v[72:75]
	global_load_lds_dwordx4 v146, s[70:71]
	v_mfma_f32_16x16x32_bf16 v[68:71], v[168:171], v[180:183], v[68:71]
	v_mfma_f32_16x16x32_bf16 v[64:67], v[172:175], v[180:183], v[64:67]
	v_add_u32_e32 v151, v145, v143
	ds_read_b128 v[180:183], v151
	s_waitcnt lgkmcnt(3)
	v_mfma_f32_16x16x32_bf16 v[56:59], v[160:163], v[156:159], v[56:59]
	s_waitcnt lgkmcnt(2)
	v_mfma_f32_16x16x32_bf16 v[40:43], v[160:163], v[164:167], v[40:43]
	s_waitcnt lgkmcnt(1)
	v_mfma_f32_16x16x32_bf16 v[24:27], v[160:163], v[176:179], v[24:27]
	s_waitcnt lgkmcnt(0)
	v_mfma_f32_16x16x32_bf16 v[8:11], v[160:163], v[180:183], v[8:11]
	ds_read_b128 v[160:163], v150 offset:1024
	v_mfma_f32_16x16x32_bf16 v[60:63], v[152:155], v[156:159], v[60:63]
	v_mfma_f32_16x16x32_bf16 v[44:47], v[152:155], v[164:167], v[44:47]
	v_mfma_f32_16x16x32_bf16 v[28:31], v[152:155], v[176:179], v[28:31]
	v_mfma_f32_16x16x32_bf16 v[12:15], v[152:155], v[180:183], v[12:15]
	v_add_u32_e32 v151, v149, v136
	ds_read_b128 v[152:155], v151
	v_mfma_f32_16x16x32_bf16 v[36:39], v[168:171], v[164:167], v[36:39]
	v_mfma_f32_16x16x32_bf16 v[32:35], v[172:175], v[164:167], v[32:35]
	ds_read_b128 v[164:167], v150 offset:3072
	v_mfma_f32_16x16x32_bf16 v[52:55], v[168:171], v[156:159], v[52:55]
	v_mfma_f32_16x16x32_bf16 v[48:51], v[172:175], v[156:159], v[48:51]
	v_add_u32_e32 v151, v149, v137
	ds_read_b128 v[156:159], v151
	v_mfma_f32_16x16x32_bf16 v[20:23], v[168:171], v[176:179], v[20:23]
	v_mfma_f32_16x16x32_bf16 v[16:19], v[172:175], v[176:179], v[16:19]
	v_add_u32_e32 v151, v149, v138
	ds_read_b128 v[176:179], v151
	v_mfma_f32_16x16x32_bf16 v[4:7], v[168:171], v[180:183], v[4:7]
	ds_read_b128 v[168:171], v150 offset:5120
	v_mfma_f32_16x16x32_bf16 v[0:3], v[172:175], v[180:183], v[0:3]
	ds_read_b128 v[172:175], v150 offset:7168
	v_add_u32_e32 v151, v149, v139
	ds_read_b128 v[180:183], v151
	s_waitcnt lgkmcnt(6)
	v_mfma_f32_16x16x32_bf16 v[124:127], v[160:163], v[152:155], v[124:127]
	s_waitcnt lgkmcnt(5)
	v_mfma_f32_16x16x32_bf16 v[120:123], v[164:167], v[152:155], v[120:123]
	s_waitcnt lgkmcnt(4)
	v_mfma_f32_16x16x32_bf16 v[108:111], v[160:163], v[156:159], v[108:111]
	v_mfma_f32_16x16x32_bf16 v[104:107], v[164:167], v[156:159], v[104:107]
	s_waitcnt lgkmcnt(3)
	v_mfma_f32_16x16x32_bf16 v[92:95], v[160:163], v[176:179], v[92:95]
	v_mfma_f32_16x16x32_bf16 v[88:91], v[164:167], v[176:179], v[88:91]
	s_waitcnt lgkmcnt(2)
	v_mfma_f32_16x16x32_bf16 v[116:119], v[168:171], v[152:155], v[116:119]
	s_waitcnt lgkmcnt(1)
	v_mfma_f32_16x16x32_bf16 v[112:115], v[172:175], v[152:155], v[112:115]
	v_add_u32_e32 v151, v149, v140
	ds_read_b128 v[152:155], v151
	v_mfma_f32_16x16x32_bf16 v[100:103], v[168:171], v[156:159], v[100:103]
	v_mfma_f32_16x16x32_bf16 v[96:99], v[172:175], v[156:159], v[96:99]
	v_add_u32_e32 v151, v149, v141
	ds_read_b128 v[156:159], v151
	v_mfma_f32_16x16x32_bf16 v[84:87], v[168:171], v[176:179], v[84:87]
	v_mfma_f32_16x16x32_bf16 v[80:83], v[172:175], v[176:179], v[80:83]
	v_add_u32_e32 v151, v149, v142
	ds_read_b128 v[176:179], v151
	s_waitcnt lgkmcnt(3)
	v_mfma_f32_16x16x32_bf16 v[76:79], v[160:163], v[180:183], v[76:79]
	v_mfma_f32_16x16x32_bf16 v[72:75], v[164:167], v[180:183], v[72:75]
	v_mfma_f32_16x16x32_bf16 v[68:71], v[168:171], v[180:183], v[68:71]
	v_mfma_f32_16x16x32_bf16 v[64:67], v[172:175], v[180:183], v[64:67]
	v_add_u32_e32 v151, v149, v143
	ds_read_b128 v[180:183], v151
	s_waitcnt lgkmcnt(3)
	v_mfma_f32_16x16x32_bf16 v[60:63], v[160:163], v[152:155], v[60:63]
	v_mfma_f32_16x16x32_bf16 v[56:59], v[164:167], v[152:155], v[56:59]
	v_mfma_f32_16x16x32_bf16 v[52:55], v[168:171], v[152:155], v[52:55]
	v_mfma_f32_16x16x32_bf16 v[48:51], v[172:175], v[152:155], v[48:51]
	s_waitcnt lgkmcnt(2)
	v_mfma_f32_16x16x32_bf16 v[44:47], v[160:163], v[156:159], v[44:47]
	v_mfma_f32_16x16x32_bf16 v[40:43], v[164:167], v[156:159], v[40:43]
	v_mfma_f32_16x16x32_bf16 v[36:39], v[168:171], v[156:159], v[36:39]
	v_mfma_f32_16x16x32_bf16 v[32:35], v[172:175], v[156:159], v[32:35]
	s_waitcnt vmcnt(0)
	s_add_u32 s4, s4, 0x100
	s_addc_u32 s5, s5, 0
	s_add_i32 s68, s68, 2
	s_cmpk_lg_i32 s4, 0x1000
	s_waitcnt lgkmcnt(0)
	s_barrier
	s_cbranch_scc1 .LBB0_301
	v_mfma_f32_16x16x32_bf16 v[28:31], v[160:163], v[176:179], v[28:31]
	v_mfma_f32_16x16x32_bf16 v[12:15], v[160:163], v[180:183], v[12:15]
	v_mfma_f32_16x16x32_bf16 v[24:27], v[164:167], v[176:179], v[24:27]
	v_mfma_f32_16x16x32_bf16 v[8:11], v[164:167], v[180:183], v[8:11]
	v_mfma_f32_16x16x32_bf16 v[20:23], v[168:171], v[176:179], v[20:23]
	v_mfma_f32_16x16x32_bf16 v[4:7], v[168:171], v[180:183], v[4:7]
	v_mfma_f32_16x16x32_bf16 v[16:19], v[172:175], v[176:179], v[16:19]
	v_mfma_f32_16x16x32_bf16 v[0:3], v[172:175], v[180:183], v[0:3]
	s_nop 15
	s_nop 15
	v_mov_b32_e32 v128, v184
	s_movk_i32 s1, 0xff80
	v_and_b32_e32 v129, 15, v128
	v_ashrrev_i32_e32 v130, 1, v128
	s_lshl_b32 s34, s0, 8
	v_and_or_b32 v163, v130, s1, v129
	s_cmp_lt_i32 s0, 8
	v_lshl_add_u32 v162, v163, 2, v202
	v_and_b32_e32 v164, 0xc0, v128
	s_cselect_b64 s[2:3], -1, 0
	s_cmp_lt_i32 s0, 10
	v_lshrrev_b32_e32 v128, 2, v128
	ds_read_b32 v150, v162
	s_cselect_b64 s[30:31], -1, 0
	s_add_i32 s1, s34, 0xfffff800
	v_and_b32_e32 v145, 12, v128
	v_or_b32_e32 v128, s34, v164
	v_ashrrev_i32_e32 v129, 31, v128
	v_or_b32_e32 v138, s1, v164
	v_add_u32_e32 v142, s43, v163
	s_cmp_gt_i32 s0, 9
	v_lshl_add_u64 v[140:141], v[128:129], 1, s[18:19]
	v_ashrrev_i32_e32 v128, 6, v138
	v_and_b32_e32 v165, 0xf8f, v142
	v_ashrrev_i32_e32 v168, 12, v142
	s_movk_i32 s0, 0xf7f
	v_ashrrev_i32_e32 v139, 31, v138
	v_add_u32_e32 v149, 0xffff8400, v128
	s_mov_b64 s[4:5], -1
	v_cmp_lt_u32_e64 s[0:1], s0, v165
	v_lshlrev_b32_e32 v166, 10, v168
	v_lshlrev_b32_e32 v167, 3, v165
	v_lshlrev_b32_e32 v136, 2, v145
	v_readlane_b32 s68, v253, 18
	s_cbranch_scc1 .LBB0_316
	v_lshlrev_b32_e32 v146, 7, v165
	v_lshl_add_u64 v[128:129], s[6:7], 0, v[146:147]
	v_mov_b32_e32 v137, v147
	v_lshl_add_u64 v[130:131], s[12:13], 0, v[146:147]
	v_lshl_add_u64 v[154:155], v[128:129], 0, v[136:137]
	v_lshl_add_u64 v[156:157], v[130:131], 0, v[136:137]
	global_load_dwordx4 v[128:131], v[154:155], off
	global_load_dwordx4 v[158:161], v[156:157], off
	v_ashrrev_i32_e32 v143, 31, v142
	v_lshlrev_b64 v[132:133], 12, v[142:143]
	s_waitcnt lgkmcnt(0)
	v_pk_mul_f32 v[170:171], v[116:117], v[150:151] op_sel_hi:[1,0]
	v_lshl_add_u64 v[152:153], v[140:141], 0, v[132:133]
	v_pk_mul_f32 v[134:135], v[124:125], v[150:151] op_sel_hi:[1,0]
	s_and_b64 vcc, exec, s[2:3]
	s_waitcnt vmcnt(0)
	v_pk_mul_f32 v[132:133], v[170:171], v[158:159]
	s_nop 0
	v_pk_fma_f32 v[132:133], v[134:135], v[128:129], v[132:133] neg_lo:[0,0,1] neg_hi:[0,0,1]
	v_pk_mul_f32 v[134:135], v[134:135], v[158:159]
	v_pk_mul_f32 v[158:159], v[126:127], v[150:151] op_sel_hi:[1,0]
	v_pk_fma_f32 v[128:129], v[170:171], v[128:129], v[134:135]
	v_pk_mul_f32 v[170:171], v[118:119], v[150:151] op_sel_hi:[1,0]
	s_nop 0
	v_pk_mul_f32 v[134:135], v[170:171], v[160:161]
	s_nop 0
	v_pk_fma_f32 v[134:135], v[158:159], v[130:131], v[134:135] neg_lo:[0,0,1] neg_hi:[0,0,1]
	v_pk_mul_f32 v[158:159], v[158:159], v[160:161]
	s_nop 0
	v_pk_fma_f32 v[130:131], v[170:171], v[130:131], v[158:159]
	s_cbranch_vccz .LBB0_305
	s_mov_b32 s4, 0x3e000000
	v_lshlrev_b32_e32 v146, 1, v145
	v_pk_mul_f32 v[160:161], v[132:133], s[4:5] op_sel_hi:[1,0]
	v_pk_mul_f32 v[170:171], v[134:135], s[4:5] op_sel_hi:[1,0]
	v_lshl_add_u64 v[158:159], v[152:153], 0, v[146:147]
	v_cvt_pk_bf16_f32 v160, v160, v161
	v_cvt_pk_bf16_f32 v161, v170, v171
	global_store_dwordx2 v[158:159], v[160:161], off
	v_pk_mul_f32 v[160:161], v[128:129], s[4:5] op_sel_hi:[1,0]
	v_pk_mul_f32 v[170:171], v[130:131], s[4:5] op_sel_hi:[1,0]
	v_cvt_pk_bf16_f32 v160, v160, v161
	v_cvt_pk_bf16_f32 v161, v170, v171
	s_mov_b64 s[4:5], 0
	global_store_dwordx2 v[158:159], v[160:161], off offset:64

.LBB0_565:
	s_mul_i32 s20, s23, 0x300000
	s_mul_hi_i32 s21, s23, 0x300000
	s_add_u32 s20, s26, s20
	s_addc_u32 s21, s27, s21
	s_mul_hi_i32 s23, s22, 0x300000
	s_mul_i32 s22, s22, 0x300000
	s_add_u32 s22, s38, s22
	s_addc_u32 s23, s39, s23
	s_add_u32 s62, s0, 0x80
	v_and_b32_e32 v8, 48, v7
	v_lshlrev_b32_e32 v9, 6, v7
	v_lshlrev_b32_e32 v7, 2, v7
	s_addc_u32 s63, s1, 0
	v_and_b32_e32 v10, 0x3c0, v9
	v_and_b32_e32 v149, 32, v7
	s_add_u32 s64, s14, 0x80
	v_or_b32_e32 v145, v10, v8
	v_bitop3_b32 v12, v10, v149, v8 bitop3:0x36
	s_waitcnt vmcnt(0)
	s_barrier
	v_lshlrev_b32_e32 v8, 13, v6
	s_addc_u32 s65, s15, 0
	s_add_i32 s52, s42, 0x10000
	v_lshl_add_u64 v[6:7], s[62:63], 0, v[0:1]
	s_mov_b32 s53, m0
	s_mov_b32 m0, s52
	s_nop 0
	global_load_lds_dwordx4 v[6:7], off
	s_mov_b32 m0, s53
	s_add_i32 s51, s42, 0x18000
	v_lshl_add_u64 v[6:7], s[64:65], 0, v[0:1]
	s_mov_b32 s53, m0
	s_mov_b32 m0, s51
	s_nop 0
	global_load_lds_dwordx4 v[6:7], off
	s_mov_b32 m0, s53
	v_lshl_add_u64 v[6:7], s[62:63], 0, v[2:3]
	s_add_i32 s53, s42, 0x12000
	s_mov_b32 s54, m0
	s_mov_b32 m0, s53
	s_nop 0
	global_load_lds_dwordx4 v[6:7], off
	s_mov_b32 m0, s54
	v_lshl_add_u64 v[6:7], s[64:65], 0, v[2:3]
	s_add_i32 s54, s42, 0x1a000
	s_mov_b32 s55, m0
	s_mov_b32 m0, s54
	s_nop 0
	global_load_lds_dwordx4 v[6:7], off
	s_mov_b32 m0, s55
	v_lshl_add_u64 v[6:7], s[62:63], 0, v[4:5]
	s_add_i32 s55, s42, 0x14000
	s_mov_b32 s58, m0
	s_mov_b32 m0, s55
	s_nop 0
	global_load_lds_dwordx4 v[6:7], off
	s_mov_b32 m0, s58
	v_lshl_add_u64 v[6:7], s[64:65], 0, v[4:5]
	s_add_i32 s58, s42, 0x1c000
	s_mov_b32 s68, m0
	s_mov_b32 m0, s58
	s_nop 0
	global_load_lds_dwordx4 v[6:7], off
	s_mov_b32 m0, s68
	v_lshl_add_u64 v[6:7], s[62:63], 0, v[146:147]
	s_add_i32 s62, s42, 0x16000
	s_mov_b32 s63, m0
	s_mov_b32 m0, s62
	s_nop 0
	global_load_lds_dwordx4 v[6:7], off
	s_mov_b32 m0, s63
	v_lshl_add_u64 v[6:7], s[64:65], 0, v[146:147]
	s_add_i32 s63, s42, 0x1e000
	s_mov_b32 s64, m0
	s_mov_b32 m0, s63
	s_nop 0
	global_load_lds_dwordx4 v[6:7], off
	s_mov_b32 m0, s64
	v_and_b32_e32 v182, 0xffffc000, v9
	v_or_b32_e32 v183, 0x800, v182
	v_or_b32_e32 v189, 0x1000, v182
	v_or_b32_e32 v199, 0x1800, v182
	v_or_b32_e32 v200, 0x2000, v182
	v_or_b32_e32 v201, 0x2800, v182
	v_or_b32_e32 v203, 0x3000, v182
	v_or_b32_e32 v206, 0x3800, v182
	s_movk_i32 s64, 0x6000
	v_and_or_b32 v7, v8, s64, v12
	ds_read_b128 v[8:11], v7 offset:32768
	v_or_b32_e32 v6, v12, v182
	ds_read_b128 v[12:15], v7 offset:34816
	ds_read_b128 v[16:19], v7 offset:36864
	ds_read_b128 v[24:27], v7 offset:38912
	ds_read_b128 v[20:23], v6
	ds_read_b128 v[28:31], v6 offset:2048
	ds_read_b128 v[32:35], v6 offset:4096
	ds_read_b128 v[36:39], v6 offset:6144
	s_waitcnt lgkmcnt(3)
	v_mfma_f32_16x16x32_bf16 v[40:43], v[8:11], v[20:23], 0
	v_mfma_f32_16x16x32_bf16 v[44:47], v[12:15], v[20:23], 0
	v_mfma_f32_16x16x32_bf16 v[48:51], v[16:19], v[20:23], 0
	v_mfma_f32_16x16x32_bf16 v[20:23], v[24:27], v[20:23], 0
	ds_read_b128 v[52:55], v6 offset:8192
	s_waitcnt lgkmcnt(3)
	v_mfma_f32_16x16x32_bf16 v[56:59], v[8:11], v[28:31], 0
	v_mfma_f32_16x16x32_bf16 v[60:63], v[12:15], v[28:31], 0
	v_mfma_f32_16x16x32_bf16 v[64:67], v[16:19], v[28:31], 0
	v_mfma_f32_16x16x32_bf16 v[28:31], v[24:27], v[28:31], 0
	ds_read_b128 v[68:71], v6 offset:10240
	s_waitcnt lgkmcnt(3)
	v_mfma_f32_16x16x32_bf16 v[72:75], v[8:11], v[32:35], 0
	v_mfma_f32_16x16x32_bf16 v[76:79], v[12:15], v[32:35], 0
	v_mfma_f32_16x16x32_bf16 v[80:83], v[16:19], v[32:35], 0
	v_mfma_f32_16x16x32_bf16 v[32:35], v[24:27], v[32:35], 0
	ds_read_b128 v[84:87], v6 offset:12288
	s_waitcnt lgkmcnt(3)
	v_mfma_f32_16x16x32_bf16 v[88:91], v[8:11], v[36:39], 0
	v_mfma_f32_16x16x32_bf16 v[92:95], v[12:15], v[36:39], 0
	v_mfma_f32_16x16x32_bf16 v[96:99], v[16:19], v[36:39], 0
	v_mfma_f32_16x16x32_bf16 v[36:39], v[24:27], v[36:39], 0
	ds_read_b128 v[100:103], v6 offset:14336
	s_waitcnt lgkmcnt(3)
	v_mfma_f32_16x16x32_bf16 v[104:107], v[8:11], v[52:55], 0
	v_mfma_f32_16x16x32_bf16 v[108:111], v[12:15], v[52:55], 0
	v_mfma_f32_16x16x32_bf16 v[112:115], v[16:19], v[52:55], 0
	v_mfma_f32_16x16x32_bf16 v[52:55], v[24:27], v[52:55], 0
	s_waitcnt lgkmcnt(2)
	v_mfma_f32_16x16x32_bf16 v[116:119], v[8:11], v[68:71], 0
	v_mfma_f32_16x16x32_bf16 v[120:123], v[12:15], v[68:71], 0
	v_mfma_f32_16x16x32_bf16 v[124:127], v[16:19], v[68:71], 0
	v_mfma_f32_16x16x32_bf16 v[68:71], v[24:27], v[68:71], 0
	s_waitcnt lgkmcnt(1)
	v_mfma_f32_16x16x32_bf16 v[128:131], v[8:11], v[84:87], 0
	v_mfma_f32_16x16x32_bf16 v[132:135], v[12:15], v[84:87], 0
	v_mfma_f32_16x16x32_bf16 v[136:139], v[16:19], v[84:87], 0
	v_mfma_f32_16x16x32_bf16 v[84:87], v[24:27], v[84:87], 0
	s_waitcnt lgkmcnt(0)
	v_mfma_f32_16x16x32_bf16 v[8:11], v[8:11], v[100:103], 0
	v_mfma_f32_16x16x32_bf16 v[12:15], v[12:15], v[100:103], 0
	v_mfma_f32_16x16x32_bf16 v[16:19], v[16:19], v[100:103], 0
	v_mfma_f32_16x16x32_bf16 v[24:27], v[24:27], v[100:103], 0
	ds_read_b128 v[100:103], v7 offset:33792
	ds_read_b128 v[140:143], v7 offset:35840
	ds_read_b128 v[150:153], v7 offset:37888
	ds_read_b128 v[158:161], v7 offset:39936
	ds_read_b128 v[154:157], v6 offset:1024
	ds_read_b128 v[162:165], v6 offset:3072
	ds_read_b128 v[166:169], v6 offset:5120
	ds_read_b128 v[170:173], v6 offset:7168
	s_waitcnt lgkmcnt(3)
	v_mfma_f32_16x16x32_bf16 v[40:43], v[100:103], v[154:157], v[40:43]
	v_mfma_f32_16x16x32_bf16 v[44:47], v[140:143], v[154:157], v[44:47]
	v_mfma_f32_16x16x32_bf16 v[48:51], v[150:153], v[154:157], v[48:51]
	v_mfma_f32_16x16x32_bf16 v[20:23], v[158:161], v[154:157], v[20:23]
	ds_read_b128 v[154:157], v6 offset:9216
	s_waitcnt lgkmcnt(3)
	v_mfma_f32_16x16x32_bf16 v[56:59], v[100:103], v[162:165], v[56:59]
	v_mfma_f32_16x16x32_bf16 v[60:63], v[140:143], v[162:165], v[60:63]
	v_mfma_f32_16x16x32_bf16 v[64:67], v[150:153], v[162:165], v[64:67]
	v_mfma_f32_16x16x32_bf16 v[28:31], v[158:161], v[162:165], v[28:31]
	ds_read_b128 v[162:165], v6 offset:11264
	s_waitcnt lgkmcnt(3)
	v_mfma_f32_16x16x32_bf16 v[72:75], v[100:103], v[166:169], v[72:75]
	v_mfma_f32_16x16x32_bf16 v[76:79], v[140:143], v[166:169], v[76:79]
	v_mfma_f32_16x16x32_bf16 v[80:83], v[150:153], v[166:169], v[80:83]
	v_mfma_f32_16x16x32_bf16 v[32:35], v[158:161], v[166:169], v[32:35]
	ds_read_b128 v[166:169], v6 offset:13312
	s_waitcnt lgkmcnt(3)
	v_mfma_f32_16x16x32_bf16 v[88:91], v[100:103], v[170:173], v[88:91]
	v_mfma_f32_16x16x32_bf16 v[92:95], v[140:143], v[170:173], v[92:95]
	v_mfma_f32_16x16x32_bf16 v[96:99], v[150:153], v[170:173], v[96:99]
	v_mfma_f32_16x16x32_bf16 v[36:39], v[158:161], v[170:173], v[36:39]
	ds_read_b128 v[170:173], v6 offset:15360
	s_waitcnt lgkmcnt(3)
	v_mfma_f32_16x16x32_bf16 v[104:107], v[100:103], v[154:157], v[104:107]
	v_mfma_f32_16x16x32_bf16 v[108:111], v[140:143], v[154:157], v[108:111]
	v_mfma_f32_16x16x32_bf16 v[112:115], v[150:153], v[154:157], v[112:115]
	v_mfma_f32_16x16x32_bf16 v[52:55], v[158:161], v[154:157], v[52:55]
	s_waitcnt lgkmcnt(2)
	v_mfma_f32_16x16x32_bf16 v[116:119], v[100:103], v[162:165], v[116:119]
	v_mfma_f32_16x16x32_bf16 v[120:123], v[140:143], v[162:165], v[120:123]
	v_mfma_f32_16x16x32_bf16 v[124:127], v[150:153], v[162:165], v[124:127]
	v_mfma_f32_16x16x32_bf16 v[68:71], v[158:161], v[162:165], v[68:71]
	s_waitcnt lgkmcnt(1)
	v_mfma_f32_16x16x32_bf16 v[128:131], v[100:103], v[166:169], v[128:131]
	v_mfma_f32_16x16x32_bf16 v[132:135], v[140:143], v[166:169], v[132:135]
	v_mfma_f32_16x16x32_bf16 v[136:139], v[150:153], v[166:169], v[136:139]
	v_mfma_f32_16x16x32_bf16 v[84:87], v[158:161], v[166:169], v[84:87]
	s_waitcnt lgkmcnt(0)
	v_mfma_f32_16x16x32_bf16 v[100:103], v[100:103], v[170:173], v[8:11]
	v_mfma_f32_16x16x32_bf16 v[150:153], v[150:153], v[170:173], v[16:19]
	v_mfma_f32_16x16x32_bf16 v[24:27], v[158:161], v[170:173], v[24:27]
	v_mfma_f32_16x16x32_bf16 v[140:143], v[140:143], v[170:173], v[12:15]
	s_add_u32 s64, s0, 0x100
	s_addc_u32 s65, s1, 0
	s_add_u32 s68, s14, 0x100
	s_waitcnt vmcnt(0)
	s_barrier
	s_addc_u32 s69, s15, 0
	v_lshl_add_u64 v[8:9], s[64:65], 0, v[0:1]
	s_mov_b32 s70, m0
	s_mov_b32 m0, s42
	s_nop 0
	global_load_lds_dwordx4 v[8:9], off
	s_mov_b32 m0, s70
	v_lshl_add_u64 v[8:9], s[68:69], 0, v[0:1]
	s_mov_b32 s70, m0
	s_mov_b32 m0, s43
	s_nop 0
	global_load_lds_dwordx4 v[8:9], off
	s_mov_b32 m0, s70
	v_lshl_add_u64 v[8:9], s[64:65], 0, v[2:3]
	s_mov_b32 s70, m0
	s_mov_b32 m0, s44
	s_nop 0
	global_load_lds_dwordx4 v[8:9], off
	s_mov_b32 m0, s70
	v_lshl_add_u64 v[8:9], s[68:69], 0, v[2:3]
	s_mov_b32 s70, m0
	s_mov_b32 m0, s45
	s_nop 0
	global_load_lds_dwordx4 v[8:9], off
	s_mov_b32 m0, s70
	v_lshl_add_u64 v[8:9], s[64:65], 0, v[4:5]
	s_mov_b32 s70, m0
	s_mov_b32 m0, s46
	s_nop 0
	global_load_lds_dwordx4 v[8:9], off
	s_mov_b32 m0, s70
	v_lshl_add_u64 v[8:9], s[68:69], 0, v[4:5]
	s_mov_b32 s70, m0
	s_mov_b32 m0, s47
	s_nop 0
	global_load_lds_dwordx4 v[8:9], off
	s_mov_b32 m0, s70
	v_lshl_add_u64 v[8:9], s[64:65], 0, v[146:147]
	s_mov_b32 s64, m0
	s_mov_b32 m0, s49
	s_nop 0
	global_load_lds_dwordx4 v[8:9], off
	s_mov_b32 m0, s64
	v_lshl_add_u64 v[8:9], s[68:69], 0, v[146:147]
	s_mov_b32 s64, m0
	s_mov_b32 m0, s50
	s_nop 0
	global_load_lds_dwordx4 v[8:9], off
	s_mov_b32 m0, s64
	v_or_b32_e32 v8, 0x18000, v7
	v_or_b32_e32 v9, 0x18800, v7
	v_or_b32_e32 v11, 0x19000, v7
	v_or_b32_e32 v10, 0x19800, v7
	ds_read_b128 v[154:157], v8
	ds_read_b128 v[158:161], v9
	ds_read_b128 v[162:165], v11
	ds_read_b128 v[166:169], v10
	v_bitop3_b32 v207, v145, s33, v149 bitop3:0xde
	v_add_u32_e32 v12, v207, v182
	ds_read_b128 v[16:19], v12
	v_add_u32_e32 v13, v207, v183
	v_add_u32_e32 v14, v207, v189
	v_add_u32_e32 v15, v207, v199
	ds_read_b128 v[170:173], v13
	ds_read_b128 v[174:177], v14
	ds_read_b128 v[178:181], v15
	s_waitcnt lgkmcnt(3)
	v_mfma_f32_16x16x32_bf16 v[40:43], v[154:157], v[16:19], v[40:43]
	v_mfma_f32_16x16x32_bf16 v[44:47], v[158:161], v[16:19], v[44:47]
	v_mfma_f32_16x16x32_bf16 v[48:51], v[162:165], v[16:19], v[48:51]
	v_mfma_f32_16x16x32_bf16 v[214:217], v[166:169], v[16:19], v[20:23]
	v_add_u32_e32 v16, v207, v200
	v_add_u32_e32 v17, v207, v201
	v_add_u32_e32 v18, v207, v203
	v_add_u32_e32 v19, v207, v206
	ds_read_b128 v[20:23], v16
	s_waitcnt lgkmcnt(3)
	v_mfma_f32_16x16x32_bf16 v[56:59], v[154:157], v[170:173], v[56:59]
	v_mfma_f32_16x16x32_bf16 v[60:63], v[158:161], v[170:173], v[60:63]
	v_mfma_f32_16x16x32_bf16 v[64:67], v[162:165], v[170:173], v[64:67]
	v_mfma_f32_16x16x32_bf16 v[170:173], v[166:169], v[170:173], v[28:31]
	s_nop 2
	ds_read_b128 v[28:31], v17
	s_waitcnt lgkmcnt(3)
	v_mfma_f32_16x16x32_bf16 v[72:75], v[154:157], v[174:177], v[72:75]
	v_mfma_f32_16x16x32_bf16 v[76:79], v[158:161], v[174:177], v[76:79]
	v_mfma_f32_16x16x32_bf16 v[80:83], v[162:165], v[174:177], v[80:83]
	v_mfma_f32_16x16x32_bf16 v[32:35], v[166:169], v[174:177], v[32:35]
	ds_read_b128 v[174:177], v18
	s_waitcnt lgkmcnt(3)
	v_mfma_f32_16x16x32_bf16 v[88:91], v[154:157], v[178:181], v[88:91]
	v_mfma_f32_16x16x32_bf16 v[92:95], v[158:161], v[178:181], v[92:95]
	v_mfma_f32_16x16x32_bf16 v[96:99], v[162:165], v[178:181], v[96:99]
	v_mfma_f32_16x16x32_bf16 v[36:39], v[166:169], v[178:181], v[36:39]
	ds_read_b128 v[178:181], v19
	s_waitcnt lgkmcnt(3)
	v_mfma_f32_16x16x32_bf16 v[104:107], v[154:157], v[20:23], v[104:107]
	v_mfma_f32_16x16x32_bf16 v[108:111], v[158:161], v[20:23], v[108:111]
	v_mfma_f32_16x16x32_bf16 v[112:115], v[162:165], v[20:23], v[112:115]
	v_mfma_f32_16x16x32_bf16 v[52:55], v[166:169], v[20:23], v[52:55]
	s_waitcnt lgkmcnt(2)
	v_mfma_f32_16x16x32_bf16 v[116:119], v[154:157], v[28:31], v[116:119]
	v_mfma_f32_16x16x32_bf16 v[120:123], v[158:161], v[28:31], v[120:123]
	v_mfma_f32_16x16x32_bf16 v[124:127], v[162:165], v[28:31], v[124:127]
	v_mfma_f32_16x16x32_bf16 v[68:71], v[166:169], v[28:31], v[68:71]
	s_waitcnt lgkmcnt(1)
	v_mfma_f32_16x16x32_bf16 v[128:131], v[154:157], v[174:177], v[128:131]
	v_mfma_f32_16x16x32_bf16 v[132:135], v[158:161], v[174:177], v[132:135]
	v_mfma_f32_16x16x32_bf16 v[84:87], v[166:169], v[174:177], v[84:87]
	s_waitcnt lgkmcnt(0)
	v_mfma_f32_16x16x32_bf16 v[100:103], v[154:157], v[178:181], v[100:103]
	v_mfma_f32_16x16x32_bf16 v[150:153], v[162:165], v[178:181], v[150:153]
	v_mfma_f32_16x16x32_bf16 v[154:157], v[166:169], v[178:181], v[24:27]
	v_mfma_f32_16x16x32_bf16 v[136:139], v[162:165], v[174:177], v[136:139]
	v_mfma_f32_16x16x32_bf16 v[140:143], v[158:161], v[178:181], v[140:143]
	v_or_b32_e32 v20, 0x18400, v7
	v_or_b32_e32 v21, 0x18c00, v7
	v_or_b32_e32 v23, 0x19400, v7
	v_or_b32_e32 v22, 0x19c00, v7
	ds_read_b128 v[158:161], v20
	ds_read_b128 v[162:165], v21
	ds_read_b128 v[166:169], v23
	ds_read_b128 v[174:177], v22
	s_mov_b32 s64, 0x10400
	v_bitop3_b32 v145, v145, s64, v149 bitop3:0xde
	v_add_u32_e32 v24, v145, v182
	ds_read_b128 v[28:31], v24
	v_add_u32_e32 v25, v145, v183
	v_add_u32_e32 v26, v145, v189
	v_add_u32_e32 v27, v145, v199
	ds_read_b128 v[178:181], v25
	ds_read_b128 v[218:221], v26
	ds_read_b128 v[222:225], v27
	s_waitcnt lgkmcnt(3)
	v_mfma_f32_16x16x32_bf16 v[40:43], v[158:161], v[28:31], v[40:43]
	v_mfma_f32_16x16x32_bf16 v[44:47], v[162:165], v[28:31], v[44:47]
	v_mfma_f32_16x16x32_bf16 v[48:51], v[166:169], v[28:31], v[48:51]
	v_mfma_f32_16x16x32_bf16 v[214:217], v[174:177], v[28:31], v[214:217]
	v_add_u32_e32 v28, v145, v200
	v_add_u32_e32 v29, v145, v201
	v_add_u32_e32 v30, v145, v203
	v_add_u32_e32 v31, v145, v206
	ds_read_b128 v[226:229], v28
	s_waitcnt lgkmcnt(3)
	v_mfma_f32_16x16x32_bf16 v[56:59], v[158:161], v[178:181], v[56:59]
	v_mfma_f32_16x16x32_bf16 v[60:63], v[162:165], v[178:181], v[60:63]
	v_mfma_f32_16x16x32_bf16 v[64:67], v[166:169], v[178:181], v[64:67]
	v_mfma_f32_16x16x32_bf16 v[170:173], v[174:177], v[178:181], v[170:173]
	ds_read_b128 v[178:181], v29
	s_waitcnt lgkmcnt(3)
	v_mfma_f32_16x16x32_bf16 v[72:75], v[158:161], v[218:221], v[72:75]
	v_mfma_f32_16x16x32_bf16 v[76:79], v[162:165], v[218:221], v[76:79]
	v_mfma_f32_16x16x32_bf16 v[80:83], v[166:169], v[218:221], v[80:83]
	v_mfma_f32_16x16x32_bf16 v[32:35], v[174:177], v[218:221], v[32:35]
	ds_read_b128 v[218:221], v30
	s_waitcnt lgkmcnt(3)
	v_mfma_f32_16x16x32_bf16 v[88:91], v[158:161], v[222:225], v[88:91]
	v_mfma_f32_16x16x32_bf16 v[92:95], v[162:165], v[222:225], v[92:95]
	v_mfma_f32_16x16x32_bf16 v[96:99], v[166:169], v[222:225], v[96:99]
	v_mfma_f32_16x16x32_bf16 v[36:39], v[174:177], v[222:225], v[36:39]
	ds_read_b128 v[222:225], v31
	s_waitcnt lgkmcnt(3)
	v_mfma_f32_16x16x32_bf16 v[104:107], v[158:161], v[226:229], v[104:107]
	v_mfma_f32_16x16x32_bf16 v[108:111], v[162:165], v[226:229], v[108:111]
	v_mfma_f32_16x16x32_bf16 v[112:115], v[166:169], v[226:229], v[112:115]
	v_mfma_f32_16x16x32_bf16 v[52:55], v[174:177], v[226:229], v[52:55]
	s_waitcnt lgkmcnt(2)
	v_mfma_f32_16x16x32_bf16 v[116:119], v[158:161], v[178:181], v[116:119]
	v_mfma_f32_16x16x32_bf16 v[120:123], v[162:165], v[178:181], v[120:123]
	v_mfma_f32_16x16x32_bf16 v[124:127], v[166:169], v[178:181], v[124:127]
	v_mfma_f32_16x16x32_bf16 v[68:71], v[174:177], v[178:181], v[68:71]
	s_waitcnt lgkmcnt(1)
	v_mfma_f32_16x16x32_bf16 v[132:135], v[162:165], v[218:221], v[132:135]
	v_mfma_f32_16x16x32_bf16 v[84:87], v[174:177], v[218:221], v[84:87]
	s_waitcnt lgkmcnt(0)
	v_mfma_f32_16x16x32_bf16 v[100:103], v[158:161], v[222:225], v[100:103]
	v_mfma_f32_16x16x32_bf16 v[150:153], v[166:169], v[222:225], v[150:153]
	v_mfma_f32_16x16x32_bf16 v[154:157], v[174:177], v[222:225], v[154:157]
	v_mfma_f32_16x16x32_bf16 v[128:131], v[158:161], v[218:221], v[128:131]
	v_mfma_f32_16x16x32_bf16 v[136:139], v[166:169], v[218:221], v[136:139]
	v_mfma_f32_16x16x32_bf16 v[140:143], v[162:165], v[222:225], v[140:143]
	s_add_u32 s64, s0, 0x180
	s_addc_u32 s65, s1, 0
	s_add_u32 s68, s14, 0x180
	s_waitcnt vmcnt(0)
	s_barrier
	s_addc_u32 s69, s15, 0
	v_lshl_add_u64 v[158:159], s[64:65], 0, v[0:1]
	s_mov_b32 s70, m0
	s_mov_b32 m0, s52
	s_nop 0
	global_load_lds_dwordx4 v[158:159], off
	s_mov_b32 m0, s70
	v_lshl_add_u64 v[158:159], s[68:69], 0, v[0:1]
	s_mov_b32 s70, m0
	s_mov_b32 m0, s51
	s_nop 0
	global_load_lds_dwordx4 v[158:159], off
	s_mov_b32 m0, s70
	v_lshl_add_u64 v[158:159], s[64:65], 0, v[2:3]
	s_mov_b32 s70, m0
	s_mov_b32 m0, s53
	s_nop 0
	global_load_lds_dwordx4 v[158:159], off
	s_mov_b32 m0, s70
	v_lshl_add_u64 v[158:159], s[68:69], 0, v[2:3]
	s_mov_b32 s70, m0
	s_mov_b32 m0, s54
	s_nop 0
	global_load_lds_dwordx4 v[158:159], off
	s_mov_b32 m0, s70
	v_lshl_add_u64 v[158:159], s[64:65], 0, v[4:5]
	s_mov_b32 s70, m0
	s_mov_b32 m0, s55
	s_nop 0
	global_load_lds_dwordx4 v[158:159], off
	s_mov_b32 m0, s70
	v_lshl_add_u64 v[158:159], s[68:69], 0, v[4:5]
	s_mov_b32 s70, m0
	s_mov_b32 m0, s58
	s_nop 0
	global_load_lds_dwordx4 v[158:159], off
	s_mov_b32 m0, s70
	v_lshl_add_u64 v[158:159], s[64:65], 0, v[146:147]
	s_mov_b32 s64, m0
	s_mov_b32 m0, s62
	s_nop 0
	global_load_lds_dwordx4 v[158:159], off
	s_mov_b32 m0, s64
	v_lshl_add_u64 v[158:159], s[68:69], 0, v[146:147]
	s_mov_b32 s64, m0
	s_mov_b32 m0, s63
	s_nop 0
	global_load_lds_dwordx4 v[158:159], off
	s_mov_b32 m0, s64
	ds_read_b128 v[158:161], v7 offset:32768
	ds_read_b128 v[162:165], v7 offset:34816
	ds_read_b128 v[166:169], v7 offset:36864
	ds_read_b128 v[178:181], v7 offset:38912
	ds_read_b128 v[174:177], v6
	ds_read_b128 v[218:221], v6 offset:2048
	ds_read_b128 v[222:225], v6 offset:4096
	ds_read_b128 v[226:229], v6 offset:6144
	s_waitcnt lgkmcnt(3)
	v_mfma_f32_16x16x32_bf16 v[40:43], v[158:161], v[174:177], v[40:43]
	v_mfma_f32_16x16x32_bf16 v[44:47], v[162:165], v[174:177], v[44:47]
	v_mfma_f32_16x16x32_bf16 v[48:51], v[166:169], v[174:177], v[48:51]
	v_mfma_f32_16x16x32_bf16 v[174:177], v[178:181], v[174:177], v[214:217]
	s_nop 2
	ds_read_b128 v[214:217], v6 offset:8192
	s_waitcnt lgkmcnt(3)
	v_mfma_f32_16x16x32_bf16 v[56:59], v[158:161], v[218:221], v[56:59]
	v_mfma_f32_16x16x32_bf16 v[60:63], v[162:165], v[218:221], v[60:63]
	v_mfma_f32_16x16x32_bf16 v[64:67], v[166:169], v[218:221], v[64:67]
	v_mfma_f32_16x16x32_bf16 v[170:173], v[178:181], v[218:221], v[170:173]
	ds_read_b128 v[218:221], v6 offset:10240
	s_waitcnt lgkmcnt(3)
	v_mfma_f32_16x16x32_bf16 v[72:75], v[158:161], v[222:225], v[72:75]
	v_mfma_f32_16x16x32_bf16 v[76:79], v[162:165], v[222:225], v[76:79]
	v_mfma_f32_16x16x32_bf16 v[80:83], v[166:169], v[222:225], v[80:83]
	v_mfma_f32_16x16x32_bf16 v[32:35], v[178:181], v[222:225], v[32:35]
	ds_read_b128 v[222:225], v6 offset:12288
	s_waitcnt lgkmcnt(3)
	v_mfma_f32_16x16x32_bf16 v[88:91], v[158:161], v[226:229], v[88:91]
	v_mfma_f32_16x16x32_bf16 v[92:95], v[162:165], v[226:229], v[92:95]
	v_mfma_f32_16x16x32_bf16 v[96:99], v[166:169], v[226:229], v[96:99]
	v_mfma_f32_16x16x32_bf16 v[36:39], v[178:181], v[226:229], v[36:39]
	ds_read_b128 v[226:229], v6 offset:14336
	s_waitcnt lgkmcnt(3)
	v_mfma_f32_16x16x32_bf16 v[104:107], v[158:161], v[214:217], v[104:107]
	v_mfma_f32_16x16x32_bf16 v[108:111], v[162:165], v[214:217], v[108:111]
	v_mfma_f32_16x16x32_bf16 v[112:115], v[166:169], v[214:217], v[112:115]
	v_mfma_f32_16x16x32_bf16 v[52:55], v[178:181], v[214:217], v[52:55]
	s_waitcnt lgkmcnt(2)
	v_mfma_f32_16x16x32_bf16 v[116:119], v[158:161], v[218:221], v[116:119]
	v_mfma_f32_16x16x32_bf16 v[120:123], v[162:165], v[218:221], v[120:123]
	v_mfma_f32_16x16x32_bf16 v[124:127], v[166:169], v[218:221], v[124:127]
	v_mfma_f32_16x16x32_bf16 v[68:71], v[178:181], v[218:221], v[68:71]
	s_waitcnt lgkmcnt(1)
	v_mfma_f32_16x16x32_bf16 v[132:135], v[162:165], v[222:225], v[132:135]
	v_mfma_f32_16x16x32_bf16 v[84:87], v[178:181], v[222:225], v[84:87]
	s_waitcnt lgkmcnt(0)
	v_mfma_f32_16x16x32_bf16 v[100:103], v[158:161], v[226:229], v[100:103]
	v_mfma_f32_16x16x32_bf16 v[150:153], v[166:169], v[226:229], v[150:153]
	v_mfma_f32_16x16x32_bf16 v[154:157], v[178:181], v[226:229], v[154:157]
	v_mfma_f32_16x16x32_bf16 v[128:131], v[158:161], v[222:225], v[128:131]
	v_mfma_f32_16x16x32_bf16 v[136:139], v[166:169], v[222:225], v[136:139]
	v_mfma_f32_16x16x32_bf16 v[140:143], v[162:165], v[226:229], v[140:143]
	ds_read_b128 v[158:161], v7 offset:33792
	ds_read_b128 v[162:165], v7 offset:35840
	ds_read_b128 v[166:169], v7 offset:37888
	ds_read_b128 v[214:217], v7 offset:39936
	ds_read_b128 v[178:181], v6 offset:1024
	ds_read_b128 v[218:221], v6 offset:3072
	ds_read_b128 v[222:225], v6 offset:5120
	ds_read_b128 v[226:229], v6 offset:7168
	s_waitcnt lgkmcnt(3)
	v_mfma_f32_16x16x32_bf16 v[40:43], v[158:161], v[178:181], v[40:43]
	v_mfma_f32_16x16x32_bf16 v[44:47], v[162:165], v[178:181], v[44:47]
	v_mfma_f32_16x16x32_bf16 v[48:51], v[166:169], v[178:181], v[48:51]
	v_mfma_f32_16x16x32_bf16 v[174:177], v[214:217], v[178:181], v[174:177]
	ds_read_b128 v[178:181], v6 offset:9216
	s_waitcnt lgkmcnt(3)
	v_mfma_f32_16x16x32_bf16 v[56:59], v[158:161], v[218:221], v[56:59]
	v_mfma_f32_16x16x32_bf16 v[60:63], v[162:165], v[218:221], v[60:63]
	v_mfma_f32_16x16x32_bf16 v[64:67], v[166:169], v[218:221], v[64:67]
	v_mfma_f32_16x16x32_bf16 v[170:173], v[214:217], v[218:221], v[170:173]
	ds_read_b128 v[218:221], v6 offset:11264
	s_waitcnt lgkmcnt(3)
	v_mfma_f32_16x16x32_bf16 v[72:75], v[158:161], v[222:225], v[72:75]
	v_mfma_f32_16x16x32_bf16 v[76:79], v[162:165], v[222:225], v[76:79]
	v_mfma_f32_16x16x32_bf16 v[80:83], v[166:169], v[222:225], v[80:83]
	v_mfma_f32_16x16x32_bf16 v[32:35], v[214:217], v[222:225], v[32:35]
	ds_read_b128 v[222:225], v6 offset:13312
	s_waitcnt lgkmcnt(3)
	v_mfma_f32_16x16x32_bf16 v[88:91], v[158:161], v[226:229], v[88:91]
	v_mfma_f32_16x16x32_bf16 v[92:95], v[162:165], v[226:229], v[92:95]
	v_mfma_f32_16x16x32_bf16 v[96:99], v[166:169], v[226:229], v[96:99]
	v_mfma_f32_16x16x32_bf16 v[36:39], v[214:217], v[226:229], v[36:39]
	ds_read_b128 v[226:229], v6 offset:15360
	s_waitcnt lgkmcnt(3)
	v_mfma_f32_16x16x32_bf16 v[104:107], v[158:161], v[178:181], v[104:107]
	v_mfma_f32_16x16x32_bf16 v[108:111], v[162:165], v[178:181], v[108:111]
	v_mfma_f32_16x16x32_bf16 v[112:115], v[166:169], v[178:181], v[112:115]
	v_mfma_f32_16x16x32_bf16 v[52:55], v[214:217], v[178:181], v[52:55]
	s_waitcnt lgkmcnt(2)
	v_mfma_f32_16x16x32_bf16 v[116:119], v[158:161], v[218:221], v[116:119]
	v_mfma_f32_16x16x32_bf16 v[120:123], v[162:165], v[218:221], v[120:123]
	v_mfma_f32_16x16x32_bf16 v[124:127], v[166:169], v[218:221], v[124:127]
	v_mfma_f32_16x16x32_bf16 v[68:71], v[214:217], v[218:221], v[68:71]
	s_waitcnt lgkmcnt(1)
	v_mfma_f32_16x16x32_bf16 v[132:135], v[162:165], v[222:225], v[132:135]
	v_mfma_f32_16x16x32_bf16 v[84:87], v[214:217], v[222:225], v[84:87]
	s_waitcnt lgkmcnt(0)
	v_mfma_f32_16x16x32_bf16 v[100:103], v[158:161], v[226:229], v[100:103]
	v_mfma_f32_16x16x32_bf16 v[150:153], v[166:169], v[226:229], v[150:153]
	v_mfma_f32_16x16x32_bf16 v[154:157], v[214:217], v[226:229], v[154:157]
	v_mfma_f32_16x16x32_bf16 v[128:131], v[158:161], v[222:225], v[128:131]
	v_mfma_f32_16x16x32_bf16 v[136:139], v[166:169], v[222:225], v[136:139]
	v_mfma_f32_16x16x32_bf16 v[140:143], v[162:165], v[226:229], v[140:143]
	s_add_u32 s64, s0, 0x200
	s_addc_u32 s65, s1, 0
	s_add_u32 s68, s14, 0x200
	s_waitcnt vmcnt(0)
	s_barrier
	s_addc_u32 s69, s15, 0
	s_mov_b32 s70, 0x280
	ds_read_b128 v[158:161], v8
	ds_read_b128 v[162:165], v12
	s_mov_b32 m0, s43
	s_nop 0
	global_load_lds_dwordx4 v0, s[68:69]
	ds_read_b128 v[166:169], v9
	s_mov_b32 m0, s45
	s_nop 0
	global_load_lds_dwordx4 v2, s[68:69]
	ds_read_b128 v[178:181], v13
	ds_read_b128 v[214:217], v11
	s_mov_b32 m0, s47
	s_nop 0
	global_load_lds_dwordx4 v4, s[68:69]
	ds_read_b128 v[218:221], v10
	ds_read_b128 v[222:225], v14
	ds_read_b128 v[226:229], v15
	s_branch .Lmy_rot_r_r6a
.Lmy_rr_r6a:
	ds_read_b128 v[158:161], v8
	ds_read_b128 v[162:165], v12
	s_mov_b32 m0, s43
	v_mfma_f32_16x16x32_bf16 v[128:131], v[166:169], v[222:225], v[128:131]
	global_load_lds_dwordx4 v0, s[68:69]
	v_mfma_f32_16x16x32_bf16 v[100:103], v[166:169], v[226:229], v[100:103]
	ds_read_b128 v[166:169], v9
	v_mfma_f32_16x16x32_bf16 v[132:135], v[178:181], v[222:225], v[132:135]
	s_mov_b32 m0, s45
	v_mfma_f32_16x16x32_bf16 v[140:143], v[178:181], v[226:229], v[140:143]
	global_load_lds_dwordx4 v2, s[68:69]
	ds_read_b128 v[178:181], v13
	v_mfma_f32_16x16x32_bf16 v[136:139], v[214:217], v[222:225], v[136:139]
	v_mfma_f32_16x16x32_bf16 v[150:153], v[214:217], v[226:229], v[150:153]
	ds_read_b128 v[214:217], v11
	s_mov_b32 m0, s47
	v_mfma_f32_16x16x32_bf16 v[84:87], v[218:221], v[222:225], v[84:87]
	global_load_lds_dwordx4 v4, s[68:69]
	v_mfma_f32_16x16x32_bf16 v[154:157], v[218:221], v[226:229], v[154:157]
	ds_read_b128 v[218:221], v10
	ds_read_b128 v[222:225], v14
	ds_read_b128 v[226:229], v15
.Lmy_rot_r_r6a:
	s_waitcnt lgkmcnt(6)
	v_mfma_f32_16x16x32_bf16 v[40:43], v[158:161], v[162:165], v[40:43]
	s_waitcnt lgkmcnt(5)
	s_mov_b32 m0, s50
	v_mfma_f32_16x16x32_bf16 v[44:47], v[166:169], v[162:165], v[44:47]
	global_load_lds_dwordx4 v146, s[68:69]
	s_waitcnt lgkmcnt(4)
	v_mfma_f32_16x16x32_bf16 v[56:59], v[158:161], v[178:181], v[56:59]
	v_mfma_f32_16x16x32_bf16 v[60:63], v[166:169], v[178:181], v[60:63]
	s_waitcnt lgkmcnt(3)
	s_mov_b32 m0, s42
	v_mfma_f32_16x16x32_bf16 v[48:51], v[214:217], v[162:165], v[48:51]
	global_load_lds_dwordx4 v0, s[64:65]
	v_mfma_f32_16x16x32_bf16 v[64:67], v[214:217], v[178:181], v[64:67]
	s_waitcnt lgkmcnt(2)
	v_mfma_f32_16x16x32_bf16 v[174:177], v[218:221], v[162:165], v[174:177]
	ds_read_b128 v[162:165], v16
	s_mov_b32 m0, s44
	v_mfma_f32_16x16x32_bf16 v[170:173], v[218:221], v[178:181], v[170:173]
	global_load_lds_dwordx4 v2, s[64:65]
	ds_read_b128 v[178:181], v17
	s_waitcnt lgkmcnt(3)
	v_mfma_f32_16x16x32_bf16 v[72:75], v[158:161], v[222:225], v[72:75]
	v_mfma_f32_16x16x32_bf16 v[76:79], v[166:169], v[222:225], v[76:79]
	s_mov_b32 m0, s46
	v_mfma_f32_16x16x32_bf16 v[80:83], v[214:217], v[222:225], v[80:83]
	global_load_lds_dwordx4 v4, s[64:65]
	v_mfma_f32_16x16x32_bf16 v[32:35], v[218:221], v[222:225], v[32:35]
	ds_read_b128 v[222:225], v18
	s_waitcnt lgkmcnt(3)
	v_mfma_f32_16x16x32_bf16 v[88:91], v[158:161], v[226:229], v[88:91]
	s_mov_b32 m0, s49
	v_mfma_f32_16x16x32_bf16 v[92:95], v[166:169], v[226:229], v[92:95]
	global_load_lds_dwordx4 v146, s[64:65]
	v_mfma_f32_16x16x32_bf16 v[96:99], v[214:217], v[226:229], v[96:99]
	v_mfma_f32_16x16x32_bf16 v[36:39], v[218:221], v[226:229], v[36:39]
	ds_read_b128 v[226:229], v19
	s_waitcnt lgkmcnt(3)
	v_mfma_f32_16x16x32_bf16 v[108:111], v[166:169], v[162:165], v[108:111]
	s_waitcnt lgkmcnt(2)
	v_mfma_f32_16x16x32_bf16 v[120:123], v[166:169], v[178:181], v[120:123]
	s_waitcnt lgkmcnt(1)
	v_mfma_f32_16x16x32_bf16 v[132:135], v[166:169], v[222:225], v[132:135]
	s_waitcnt lgkmcnt(0)
	v_mfma_f32_16x16x32_bf16 v[140:143], v[166:169], v[226:229], v[140:143]
	ds_read_b128 v[166:169], v20
	v_mfma_f32_16x16x32_bf16 v[104:107], v[158:161], v[162:165], v[104:107]
	v_mfma_f32_16x16x32_bf16 v[116:119], v[158:161], v[178:181], v[116:119]
	v_mfma_f32_16x16x32_bf16 v[128:131], v[158:161], v[222:225], v[128:131]
	v_mfma_f32_16x16x32_bf16 v[100:103], v[158:161], v[226:229], v[100:103]
	ds_read_b128 v[158:161], v24
	v_mfma_f32_16x16x32_bf16 v[124:127], v[214:217], v[178:181], v[124:127]
	v_mfma_f32_16x16x32_bf16 v[68:71], v[218:221], v[178:181], v[68:71]
	ds_read_b128 v[178:181], v21
	v_mfma_f32_16x16x32_bf16 v[112:115], v[214:217], v[162:165], v[112:115]
	v_mfma_f32_16x16x32_bf16 v[52:55], v[218:221], v[162:165], v[52:55]
	ds_read_b128 v[162:165], v25
	v_mfma_f32_16x16x32_bf16 v[136:139], v[214:217], v[222:225], v[136:139]
	v_mfma_f32_16x16x32_bf16 v[84:87], v[218:221], v[222:225], v[84:87]
	ds_read_b128 v[222:225], v26
	v_mfma_f32_16x16x32_bf16 v[150:153], v[214:217], v[226:229], v[150:153]
	ds_read_b128 v[214:217], v23
	v_mfma_f32_16x16x32_bf16 v[154:157], v[218:221], v[226:229], v[154:157]
	ds_read_b128 v[218:221], v22
	ds_read_b128 v[226:229], v27
	s_waitcnt lgkmcnt(6)
	v_mfma_f32_16x16x32_bf16 v[40:43], v[166:169], v[158:161], v[40:43]
	s_waitcnt lgkmcnt(5)
	v_mfma_f32_16x16x32_bf16 v[44:47], v[178:181], v[158:161], v[44:47]
	s_waitcnt lgkmcnt(4)
	v_mfma_f32_16x16x32_bf16 v[56:59], v[166:169], v[162:165], v[56:59]
	v_mfma_f32_16x16x32_bf16 v[60:63], v[178:181], v[162:165], v[60:63]
	s_waitcnt lgkmcnt(3)
	v_mfma_f32_16x16x32_bf16 v[72:75], v[166:169], v[222:225], v[72:75]
	v_mfma_f32_16x16x32_bf16 v[76:79], v[178:181], v[222:225], v[76:79]
	s_waitcnt lgkmcnt(2)
	v_mfma_f32_16x16x32_bf16 v[48:51], v[214:217], v[158:161], v[48:51]
	s_waitcnt lgkmcnt(1)
	v_mfma_f32_16x16x32_bf16 v[174:177], v[218:221], v[158:161], v[174:177]
	ds_read_b128 v[158:161], v28
	v_mfma_f32_16x16x32_bf16 v[64:67], v[214:217], v[162:165], v[64:67]
	v_mfma_f32_16x16x32_bf16 v[170:173], v[218:221], v[162:165], v[170:173]
	ds_read_b128 v[162:165], v29
	v_mfma_f32_16x16x32_bf16 v[80:83], v[214:217], v[222:225], v[80:83]
	v_mfma_f32_16x16x32_bf16 v[32:35], v[218:221], v[222:225], v[32:35]
	ds_read_b128 v[222:225], v30
	s_waitcnt lgkmcnt(3)
	v_mfma_f32_16x16x32_bf16 v[88:91], v[166:169], v[226:229], v[88:91]
	v_mfma_f32_16x16x32_bf16 v[92:95], v[178:181], v[226:229], v[92:95]
	v_mfma_f32_16x16x32_bf16 v[96:99], v[214:217], v[226:229], v[96:99]
	v_mfma_f32_16x16x32_bf16 v[36:39], v[218:221], v[226:229], v[36:39]
	ds_read_b128 v[226:229], v31
	s_waitcnt lgkmcnt(3)
	v_mfma_f32_16x16x32_bf16 v[104:107], v[166:169], v[158:161], v[104:107]
	v_mfma_f32_16x16x32_bf16 v[108:111], v[178:181], v[158:161], v[108:111]
	v_mfma_f32_16x16x32_bf16 v[112:115], v[214:217], v[158:161], v[112:115]
	v_mfma_f32_16x16x32_bf16 v[52:55], v[218:221], v[158:161], v[52:55]
	s_waitcnt lgkmcnt(2)
	v_mfma_f32_16x16x32_bf16 v[116:119], v[166:169], v[162:165], v[116:119]
	v_mfma_f32_16x16x32_bf16 v[120:123], v[178:181], v[162:165], v[120:123]
	v_mfma_f32_16x16x32_bf16 v[124:127], v[214:217], v[162:165], v[124:127]
	v_mfma_f32_16x16x32_bf16 v[68:71], v[218:221], v[162:165], v[68:71]
	s_add_u32 s64, s0, s70
	s_addc_u32 s65, s1, 0
	s_add_u32 s68, s14, s70
	s_addc_u32 s69, s15, 0
	s_add_u32 s70, s70, 0x80
	s_waitcnt vmcnt(0)
	s_waitcnt lgkmcnt(0)
	s_barrier
	ds_read_b128 v[158:161], v7 offset:32768
	ds_read_b128 v[162:165], v6
	s_mov_b32 m0, s51
	v_mfma_f32_16x16x32_bf16 v[128:131], v[166:169], v[222:225], v[128:131]
	global_load_lds_dwordx4 v0, s[68:69]
	v_mfma_f32_16x16x32_bf16 v[100:103], v[166:169], v[226:229], v[100:103]
	ds_read_b128 v[166:169], v7 offset:34816
	v_mfma_f32_16x16x32_bf16 v[132:135], v[178:181], v[222:225], v[132:135]
	s_mov_b32 m0, s54
	v_mfma_f32_16x16x32_bf16 v[140:143], v[178:181], v[226:229], v[140:143]
	global_load_lds_dwordx4 v2, s[68:69]
	ds_read_b128 v[178:181], v6 offset:2048
	v_mfma_f32_16x16x32_bf16 v[136:139], v[214:217], v[222:225], v[136:139]
	v_mfma_f32_16x16x32_bf16 v[150:153], v[214:217], v[226:229], v[150:153]
	ds_read_b128 v[214:217], v7 offset:36864
	s_mov_b32 m0, s58
	v_mfma_f32_16x16x32_bf16 v[84:87], v[218:221], v[222:225], v[84:87]
	global_load_lds_dwordx4 v4, s[68:69]
	v_mfma_f32_16x16x32_bf16 v[154:157], v[218:221], v[226:229], v[154:157]
	ds_read_b128 v[218:221], v7 offset:38912
	ds_read_b128 v[222:225], v6 offset:4096
	ds_read_b128 v[226:229], v6 offset:6144
	s_waitcnt lgkmcnt(6)
	v_mfma_f32_16x16x32_bf16 v[40:43], v[158:161], v[162:165], v[40:43]
	s_waitcnt lgkmcnt(5)
	s_mov_b32 m0, s63
	v_mfma_f32_16x16x32_bf16 v[44:47], v[166:169], v[162:165], v[44:47]
	global_load_lds_dwordx4 v146, s[68:69]
	s_waitcnt lgkmcnt(4)
	v_mfma_f32_16x16x32_bf16 v[56:59], v[158:161], v[178:181], v[56:59]
	v_mfma_f32_16x16x32_bf16 v[60:63], v[166:169], v[178:181], v[60:63]
	s_waitcnt lgkmcnt(3)
	s_mov_b32 m0, s52
	v_mfma_f32_16x16x32_bf16 v[48:51], v[214:217], v[162:165], v[48:51]
	global_load_lds_dwordx4 v0, s[64:65]
	v_mfma_f32_16x16x32_bf16 v[64:67], v[214:217], v[178:181], v[64:67]
	s_waitcnt lgkmcnt(2)
	v_mfma_f32_16x16x32_bf16 v[174:177], v[218:221], v[162:165], v[174:177]
	ds_read_b128 v[162:165], v6 offset:8192
	s_mov_b32 m0, s53
	v_mfma_f32_16x16x32_bf16 v[170:173], v[218:221], v[178:181], v[170:173]
	global_load_lds_dwordx4 v2, s[64:65]
	ds_read_b128 v[178:181], v6 offset:10240
	s_waitcnt lgkmcnt(3)
	v_mfma_f32_16x16x32_bf16 v[72:75], v[158:161], v[222:225], v[72:75]
	v_mfma_f32_16x16x32_bf16 v[76:79], v[166:169], v[222:225], v[76:79]
	s_mov_b32 m0, s55
	v_mfma_f32_16x16x32_bf16 v[80:83], v[214:217], v[222:225], v[80:83]
	global_load_lds_dwordx4 v4, s[64:65]
	v_mfma_f32_16x16x32_bf16 v[32:35], v[218:221], v[222:225], v[32:35]
	ds_read_b128 v[222:225], v6 offset:12288
	s_waitcnt lgkmcnt(3)
	v_mfma_f32_16x16x32_bf16 v[88:91], v[158:161], v[226:229], v[88:91]
	s_mov_b32 m0, s62
	v_mfma_f32_16x16x32_bf16 v[92:95], v[166:169], v[226:229], v[92:95]
	global_load_lds_dwordx4 v146, s[64:65]
	v_mfma_f32_16x16x32_bf16 v[96:99], v[214:217], v[226:229], v[96:99]
	v_mfma_f32_16x16x32_bf16 v[36:39], v[218:221], v[226:229], v[36:39]
	ds_read_b128 v[226:229], v6 offset:14336
	s_waitcnt lgkmcnt(3)
	v_mfma_f32_16x16x32_bf16 v[108:111], v[166:169], v[162:165], v[108:111]
	s_waitcnt lgkmcnt(2)
	v_mfma_f32_16x16x32_bf16 v[120:123], v[166:169], v[178:181], v[120:123]
	s_waitcnt lgkmcnt(1)
	v_mfma_f32_16x16x32_bf16 v[132:135], v[166:169], v[222:225], v[132:135]
	s_waitcnt lgkmcnt(0)
	v_mfma_f32_16x16x32_bf16 v[140:143], v[166:169], v[226:229], v[140:143]
	ds_read_b128 v[166:169], v7 offset:33792
	v_mfma_f32_16x16x32_bf16 v[104:107], v[158:161], v[162:165], v[104:107]
	v_mfma_f32_16x16x32_bf16 v[116:119], v[158:161], v[178:181], v[116:119]
	v_mfma_f32_16x16x32_bf16 v[128:131], v[158:161], v[222:225], v[128:131]
	v_mfma_f32_16x16x32_bf16 v[100:103], v[158:161], v[226:229], v[100:103]
	ds_read_b128 v[158:161], v6 offset:1024
	v_mfma_f32_16x16x32_bf16 v[124:127], v[214:217], v[178:181], v[124:127]
	v_mfma_f32_16x16x32_bf16 v[68:71], v[218:221], v[178:181], v[68:71]
	ds_read_b128 v[178:181], v7 offset:35840
	v_mfma_f32_16x16x32_bf16 v[112:115], v[214:217], v[162:165], v[112:115]
	v_mfma_f32_16x16x32_bf16 v[52:55], v[218:221], v[162:165], v[52:55]
	ds_read_b128 v[162:165], v6 offset:3072
	v_mfma_f32_16x16x32_bf16 v[136:139], v[214:217], v[222:225], v[136:139]
	v_mfma_f32_16x16x32_bf16 v[84:87], v[218:221], v[222:225], v[84:87]
	ds_read_b128 v[222:225], v6 offset:5120
	v_mfma_f32_16x16x32_bf16 v[150:153], v[214:217], v[226:229], v[150:153]
	ds_read_b128 v[214:217], v7 offset:37888
	v_mfma_f32_16x16x32_bf16 v[154:157], v[218:221], v[226:229], v[154:157]
	ds_read_b128 v[218:221], v7 offset:39936
	ds_read_b128 v[226:229], v6 offset:7168
	s_waitcnt lgkmcnt(6)
	v_mfma_f32_16x16x32_bf16 v[40:43], v[166:169], v[158:161], v[40:43]
	s_waitcnt lgkmcnt(5)
	v_mfma_f32_16x16x32_bf16 v[44:47], v[178:181], v[158:161], v[44:47]
	s_waitcnt lgkmcnt(4)
	v_mfma_f32_16x16x32_bf16 v[56:59], v[166:169], v[162:165], v[56:59]
	v_mfma_f32_16x16x32_bf16 v[60:63], v[178:181], v[162:165], v[60:63]
	s_waitcnt lgkmcnt(3)
	v_mfma_f32_16x16x32_bf16 v[72:75], v[166:169], v[222:225], v[72:75]
	v_mfma_f32_16x16x32_bf16 v[76:79], v[178:181], v[222:225], v[76:79]
	s_waitcnt lgkmcnt(2)
	v_mfma_f32_16x16x32_bf16 v[48:51], v[214:217], v[158:161], v[48:51]
	s_waitcnt lgkmcnt(1)
	v_mfma_f32_16x16x32_bf16 v[174:177], v[218:221], v[158:161], v[174:177]
	ds_read_b128 v[158:161], v6 offset:9216
	v_mfma_f32_16x16x32_bf16 v[64:67], v[214:217], v[162:165], v[64:67]
	v_mfma_f32_16x16x32_bf16 v[170:173], v[218:221], v[162:165], v[170:173]
	ds_read_b128 v[162:165], v6 offset:11264
	v_mfma_f32_16x16x32_bf16 v[80:83], v[214:217], v[222:225], v[80:83]
	v_mfma_f32_16x16x32_bf16 v[32:35], v[218:221], v[222:225], v[32:35]
	ds_read_b128 v[222:225], v6 offset:13312
	s_waitcnt lgkmcnt(3)
	v_mfma_f32_16x16x32_bf16 v[88:91], v[166:169], v[226:229], v[88:91]
	v_mfma_f32_16x16x32_bf16 v[92:95], v[178:181], v[226:229], v[92:95]
	v_mfma_f32_16x16x32_bf16 v[96:99], v[214:217], v[226:229], v[96:99]
	v_mfma_f32_16x16x32_bf16 v[36:39], v[218:221], v[226:229], v[36:39]
	ds_read_b128 v[226:229], v6 offset:15360
	s_waitcnt lgkmcnt(3)
	v_mfma_f32_16x16x32_bf16 v[104:107], v[166:169], v[158:161], v[104:107]
	v_mfma_f32_16x16x32_bf16 v[108:111], v[178:181], v[158:161], v[108:111]
	v_mfma_f32_16x16x32_bf16 v[112:115], v[214:217], v[158:161], v[112:115]
	v_mfma_f32_16x16x32_bf16 v[52:55], v[218:221], v[158:161], v[52:55]
	s_waitcnt lgkmcnt(2)
	v_mfma_f32_16x16x32_bf16 v[116:119], v[166:169], v[162:165], v[116:119]
	v_mfma_f32_16x16x32_bf16 v[120:123], v[178:181], v[162:165], v[120:123]
	v_mfma_f32_16x16x32_bf16 v[124:127], v[214:217], v[162:165], v[124:127]
	v_mfma_f32_16x16x32_bf16 v[68:71], v[218:221], v[162:165], v[68:71]
	s_add_u32 s64, s0, s70
	s_addc_u32 s65, s1, 0
	s_add_u32 s68, s14, s70
	s_addc_u32 s69, s15, 0
	s_add_u32 s70, s70, 0x80
	s_cmp_lg_u32 s70, 0x2f80
	s_waitcnt vmcnt(0)
	s_waitcnt lgkmcnt(0)
	s_barrier
	s_cbranch_scc1 .Lmy_rr_r6a
	v_mfma_f32_16x16x32_bf16 v[128:131], v[166:169], v[222:225], v[128:131]
	v_mfma_f32_16x16x32_bf16 v[100:103], v[166:169], v[226:229], v[100:103]
	v_mfma_f32_16x16x32_bf16 v[132:135], v[178:181], v[222:225], v[132:135]
	v_mfma_f32_16x16x32_bf16 v[140:143], v[178:181], v[226:229], v[140:143]
	v_mfma_f32_16x16x32_bf16 v[136:139], v[214:217], v[222:225], v[136:139]
	v_mfma_f32_16x16x32_bf16 v[150:153], v[214:217], v[226:229], v[150:153]
	v_mfma_f32_16x16x32_bf16 v[84:87], v[218:221], v[222:225], v[84:87]
	v_mfma_f32_16x16x32_bf16 v[154:157], v[218:221], v[226:229], v[154:157]
	s_nop 15
	s_nop 15
	v_lshl_add_u64 v[158:159], s[64:65], 0, v[0:1]
	s_mov_b32 s70, m0
	s_mov_b32 m0, s42
	s_nop 0
	global_load_lds_dwordx4 v[158:159], off
	s_mov_b32 m0, s70
	v_lshl_add_u64 v[158:159], s[68:69], 0, v[0:1]
	s_mov_b32 s70, m0
	s_mov_b32 m0, s43
	s_nop 0
	global_load_lds_dwordx4 v[158:159], off
	s_mov_b32 m0, s70
	v_lshl_add_u64 v[158:159], s[64:65], 0, v[2:3]
	s_mov_b32 s70, m0
	s_mov_b32 m0, s44
	s_nop 0
	global_load_lds_dwordx4 v[158:159], off
	s_mov_b32 m0, s70
	v_lshl_add_u64 v[158:159], s[68:69], 0, v[2:3]
	s_mov_b32 s70, m0
	s_mov_b32 m0, s45
	s_nop 0
	global_load_lds_dwordx4 v[158:159], off
	s_mov_b32 m0, s70
	v_lshl_add_u64 v[158:159], s[64:65], 0, v[4:5]
	s_mov_b32 s70, m0
	s_mov_b32 m0, s46
	s_nop 0
	global_load_lds_dwordx4 v[158:159], off
	s_mov_b32 m0, s70
	v_lshl_add_u64 v[158:159], s[68:69], 0, v[4:5]
	s_mov_b32 s70, m0
	s_mov_b32 m0, s47
	s_nop 0
	global_load_lds_dwordx4 v[158:159], off
	s_mov_b32 m0, s70
	v_lshl_add_u64 v[158:159], s[64:65], 0, v[146:147]
	s_mov_b32 s64, m0
	s_mov_b32 m0, s49
	s_nop 0
	global_load_lds_dwordx4 v[158:159], off
	s_mov_b32 m0, s64
	v_lshl_add_u64 v[158:159], s[68:69], 0, v[146:147]
	s_mov_b32 s64, m0
	s_mov_b32 m0, s50
	s_nop 0
	global_load_lds_dwordx4 v[158:159], off
	s_mov_b32 m0, s64
	ds_read_b128 v[158:161], v8
	ds_read_b128 v[162:165], v9
	ds_read_b128 v[166:169], v11
	ds_read_b128 v[214:217], v10
	ds_read_b128 v[178:181], v12
	ds_read_b128 v[218:221], v13
	ds_read_b128 v[222:225], v14
	ds_read_b128 v[226:229], v15
	s_waitcnt lgkmcnt(3)
	v_mfma_f32_16x16x32_bf16 v[40:43], v[158:161], v[178:181], v[40:43]
	v_mfma_f32_16x16x32_bf16 v[44:47], v[162:165], v[178:181], v[44:47]
	v_mfma_f32_16x16x32_bf16 v[48:51], v[166:169], v[178:181], v[48:51]
	v_mfma_f32_16x16x32_bf16 v[174:177], v[214:217], v[178:181], v[174:177]
	ds_read_b128 v[178:181], v16
	s_waitcnt lgkmcnt(3)
	v_mfma_f32_16x16x32_bf16 v[56:59], v[158:161], v[218:221], v[56:59]
	v_mfma_f32_16x16x32_bf16 v[60:63], v[162:165], v[218:221], v[60:63]
	v_mfma_f32_16x16x32_bf16 v[64:67], v[166:169], v[218:221], v[64:67]
	v_mfma_f32_16x16x32_bf16 v[170:173], v[214:217], v[218:221], v[170:173]
	ds_read_b128 v[218:221], v17
	s_waitcnt lgkmcnt(3)
	v_mfma_f32_16x16x32_bf16 v[72:75], v[158:161], v[222:225], v[72:75]
	v_mfma_f32_16x16x32_bf16 v[76:79], v[162:165], v[222:225], v[76:79]
	v_mfma_f32_16x16x32_bf16 v[80:83], v[166:169], v[222:225], v[80:83]
	v_mfma_f32_16x16x32_bf16 v[32:35], v[214:217], v[222:225], v[32:35]
	ds_read_b128 v[222:225], v18
	s_waitcnt lgkmcnt(3)
	v_mfma_f32_16x16x32_bf16 v[88:91], v[158:161], v[226:229], v[88:91]
	v_mfma_f32_16x16x32_bf16 v[92:95], v[162:165], v[226:229], v[92:95]
	v_mfma_f32_16x16x32_bf16 v[96:99], v[166:169], v[226:229], v[96:99]
	v_mfma_f32_16x16x32_bf16 v[36:39], v[214:217], v[226:229], v[36:39]
	ds_read_b128 v[226:229], v19
	s_waitcnt lgkmcnt(3)
	v_mfma_f32_16x16x32_bf16 v[104:107], v[158:161], v[178:181], v[104:107]
	v_mfma_f32_16x16x32_bf16 v[108:111], v[162:165], v[178:181], v[108:111]
	v_mfma_f32_16x16x32_bf16 v[112:115], v[166:169], v[178:181], v[112:115]
	v_mfma_f32_16x16x32_bf16 v[52:55], v[214:217], v[178:181], v[52:55]
	s_waitcnt lgkmcnt(2)
	v_mfma_f32_16x16x32_bf16 v[116:119], v[158:161], v[218:221], v[116:119]
	v_mfma_f32_16x16x32_bf16 v[120:123], v[162:165], v[218:221], v[120:123]
	v_mfma_f32_16x16x32_bf16 v[124:127], v[166:169], v[218:221], v[124:127]
	v_mfma_f32_16x16x32_bf16 v[68:71], v[214:217], v[218:221], v[68:71]
	s_waitcnt lgkmcnt(1)
	v_mfma_f32_16x16x32_bf16 v[132:135], v[162:165], v[222:225], v[132:135]
	v_mfma_f32_16x16x32_bf16 v[84:87], v[214:217], v[222:225], v[84:87]
	s_waitcnt lgkmcnt(0)
	v_mfma_f32_16x16x32_bf16 v[100:103], v[158:161], v[226:229], v[100:103]
	v_mfma_f32_16x16x32_bf16 v[150:153], v[166:169], v[226:229], v[150:153]
	v_mfma_f32_16x16x32_bf16 v[154:157], v[214:217], v[226:229], v[154:157]
	v_mfma_f32_16x16x32_bf16 v[128:131], v[158:161], v[222:225], v[128:131]
	v_mfma_f32_16x16x32_bf16 v[136:139], v[166:169], v[222:225], v[136:139]
	v_mfma_f32_16x16x32_bf16 v[140:143], v[162:165], v[226:229], v[140:143]
	ds_read_b128 v[158:161], v20
	ds_read_b128 v[162:165], v21
	ds_read_b128 v[166:169], v23
	ds_read_b128 v[214:217], v22
	ds_read_b128 v[178:181], v24
	ds_read_b128 v[218:221], v25
	ds_read_b128 v[222:225], v26
	ds_read_b128 v[226:229], v27
	s_waitcnt lgkmcnt(3)
	v_mfma_f32_16x16x32_bf16 v[40:43], v[158:161], v[178:181], v[40:43]
	v_mfma_f32_16x16x32_bf16 v[44:47], v[162:165], v[178:181], v[44:47]
	v_mfma_f32_16x16x32_bf16 v[48:51], v[166:169], v[178:181], v[48:51]
	v_mfma_f32_16x16x32_bf16 v[174:177], v[214:217], v[178:181], v[174:177]
	ds_read_b128 v[178:181], v28
	s_waitcnt lgkmcnt(3)
	v_mfma_f32_16x16x32_bf16 v[56:59], v[158:161], v[218:221], v[56:59]
	v_mfma_f32_16x16x32_bf16 v[60:63], v[162:165], v[218:221], v[60:63]
	v_mfma_f32_16x16x32_bf16 v[64:67], v[166:169], v[218:221], v[64:67]
	v_mfma_f32_16x16x32_bf16 v[170:173], v[214:217], v[218:221], v[170:173]
	ds_read_b128 v[218:221], v29
	s_waitcnt lgkmcnt(3)
	v_mfma_f32_16x16x32_bf16 v[72:75], v[158:161], v[222:225], v[72:75]
	v_mfma_f32_16x16x32_bf16 v[76:79], v[162:165], v[222:225], v[76:79]
	v_mfma_f32_16x16x32_bf16 v[80:83], v[166:169], v[222:225], v[80:83]
	v_mfma_f32_16x16x32_bf16 v[32:35], v[214:217], v[222:225], v[32:35]
	ds_read_b128 v[222:225], v30
	s_waitcnt lgkmcnt(3)
	v_mfma_f32_16x16x32_bf16 v[88:91], v[158:161], v[226:229], v[88:91]
	v_mfma_f32_16x16x32_bf16 v[92:95], v[162:165], v[226:229], v[92:95]
	v_mfma_f32_16x16x32_bf16 v[96:99], v[166:169], v[226:229], v[96:99]
	v_mfma_f32_16x16x32_bf16 v[36:39], v[214:217], v[226:229], v[36:39]
	ds_read_b128 v[226:229], v31
	s_waitcnt lgkmcnt(3)
	v_mfma_f32_16x16x32_bf16 v[104:107], v[158:161], v[178:181], v[104:107]
	v_mfma_f32_16x16x32_bf16 v[108:111], v[162:165], v[178:181], v[108:111]
	v_mfma_f32_16x16x32_bf16 v[112:115], v[166:169], v[178:181], v[112:115]
	v_mfma_f32_16x16x32_bf16 v[52:55], v[214:217], v[178:181], v[52:55]
	s_waitcnt lgkmcnt(2)
	v_mfma_f32_16x16x32_bf16 v[116:119], v[158:161], v[218:221], v[116:119]
	v_mfma_f32_16x16x32_bf16 v[120:123], v[162:165], v[218:221], v[120:123]
	v_mfma_f32_16x16x32_bf16 v[124:127], v[166:169], v[218:221], v[124:127]
	v_mfma_f32_16x16x32_bf16 v[68:71], v[214:217], v[218:221], v[68:71]
	s_waitcnt lgkmcnt(1)
	v_mfma_f32_16x16x32_bf16 v[132:135], v[162:165], v[222:225], v[132:135]
	v_mfma_f32_16x16x32_bf16 v[84:87], v[214:217], v[222:225], v[84:87]
	s_waitcnt lgkmcnt(0)
	v_mfma_f32_16x16x32_bf16 v[100:103], v[158:161], v[226:229], v[100:103]
	v_mfma_f32_16x16x32_bf16 v[150:153], v[166:169], v[226:229], v[150:153]
	v_mfma_f32_16x16x32_bf16 v[154:157], v[214:217], v[226:229], v[154:157]
	v_mfma_f32_16x16x32_bf16 v[128:131], v[158:161], v[222:225], v[128:131]
	v_mfma_f32_16x16x32_bf16 v[136:139], v[166:169], v[222:225], v[136:139]
	v_mfma_f32_16x16x32_bf16 v[140:143], v[162:165], v[226:229], v[140:143]
	s_add_u32 s0, s0, 0x2f80
	s_addc_u32 s1, s1, 0
	s_add_u32 s14, s14, 0x2f80
	s_waitcnt vmcnt(0)
	s_barrier
	s_addc_u32 s15, s15, 0
	v_lshl_add_u64 v[158:159], s[0:1], 0, v[0:1]
	s_mov_b32 s64, m0
	s_mov_b32 m0, s52
	s_nop 0
	global_load_lds_dwordx4 v[158:159], off
	s_mov_b32 m0, s64
	v_lshl_add_u64 v[158:159], s[14:15], 0, v[0:1]
	s_mov_b32 s52, m0
	s_mov_b32 m0, s51
	s_nop 0
	global_load_lds_dwordx4 v[158:159], off
	s_mov_b32 m0, s52
	v_lshl_add_u64 v[158:159], s[0:1], 0, v[2:3]
	s_mov_b32 s51, m0
	s_mov_b32 m0, s53
	s_nop 0
	global_load_lds_dwordx4 v[158:159], off
	s_mov_b32 m0, s51
	v_lshl_add_u64 v[158:159], s[14:15], 0, v[2:3]
	s_mov_b32 s51, m0
	s_mov_b32 m0, s54
	s_nop 0
	global_load_lds_dwordx4 v[158:159], off
	s_mov_b32 m0, s51
	v_lshl_add_u64 v[158:159], s[0:1], 0, v[4:5]
	s_mov_b32 s51, m0
	s_mov_b32 m0, s55
	s_nop 0
	global_load_lds_dwordx4 v[158:159], off
	s_mov_b32 m0, s51
	v_lshl_add_u64 v[158:159], s[14:15], 0, v[4:5]
	s_mov_b32 s51, m0
	s_mov_b32 m0, s58
	s_nop 0
	global_load_lds_dwordx4 v[158:159], off
	s_mov_b32 m0, s51
	v_lshl_add_u64 v[158:159], s[0:1], 0, v[146:147]
	s_mov_b32 s0, m0
	s_mov_b32 m0, s62
	s_nop 0
	global_load_lds_dwordx4 v[158:159], off
	s_mov_b32 m0, s0
	v_lshl_add_u64 v[158:159], s[14:15], 0, v[146:147]
	s_mov_b32 s0, m0
	s_mov_b32 m0, s63
	s_nop 0
	global_load_lds_dwordx4 v[158:159], off
	s_mov_b32 m0, s0
	ds_read_b128 v[158:161], v7 offset:32768
	ds_read_b128 v[162:165], v7 offset:34816
	ds_read_b128 v[166:169], v7 offset:36864
	ds_read_b128 v[214:217], v7 offset:38912
	ds_read_b128 v[178:181], v6
	ds_read_b128 v[218:221], v6 offset:2048
	ds_read_b128 v[222:225], v6 offset:4096
	ds_read_b128 v[226:229], v6 offset:6144
	s_waitcnt lgkmcnt(3)
	v_mfma_f32_16x16x32_bf16 v[40:43], v[158:161], v[178:181], v[40:43]
	v_mfma_f32_16x16x32_bf16 v[44:47], v[162:165], v[178:181], v[44:47]
	v_mfma_f32_16x16x32_bf16 v[48:51], v[166:169], v[178:181], v[48:51]
	v_mfma_f32_16x16x32_bf16 v[174:177], v[214:217], v[178:181], v[174:177]
	ds_read_b128 v[178:181], v6 offset:8192
	s_waitcnt lgkmcnt(3)
	v_mfma_f32_16x16x32_bf16 v[56:59], v[158:161], v[218:221], v[56:59]
	v_mfma_f32_16x16x32_bf16 v[60:63], v[162:165], v[218:221], v[60:63]
	v_mfma_f32_16x16x32_bf16 v[64:67], v[166:169], v[218:221], v[64:67]
	v_mfma_f32_16x16x32_bf16 v[170:173], v[214:217], v[218:221], v[170:173]
	ds_read_b128 v[218:221], v6 offset:10240
	s_waitcnt lgkmcnt(3)
	v_mfma_f32_16x16x32_bf16 v[72:75], v[158:161], v[222:225], v[72:75]
	v_mfma_f32_16x16x32_bf16 v[76:79], v[162:165], v[222:225], v[76:79]
	v_mfma_f32_16x16x32_bf16 v[80:83], v[166:169], v[222:225], v[80:83]
	v_mfma_f32_16x16x32_bf16 v[32:35], v[214:217], v[222:225], v[32:35]
	ds_read_b128 v[222:225], v6 offset:12288
	s_waitcnt lgkmcnt(3)
	v_mfma_f32_16x16x32_bf16 v[88:91], v[158:161], v[226:229], v[88:91]
	v_mfma_f32_16x16x32_bf16 v[92:95], v[162:165], v[226:229], v[92:95]
	v_mfma_f32_16x16x32_bf16 v[96:99], v[166:169], v[226:229], v[96:99]
	v_mfma_f32_16x16x32_bf16 v[36:39], v[214:217], v[226:229], v[36:39]
	ds_read_b128 v[226:229], v6 offset:14336
	s_waitcnt lgkmcnt(3)
	v_mfma_f32_16x16x32_bf16 v[104:107], v[158:161], v[178:181], v[104:107]
	v_mfma_f32_16x16x32_bf16 v[108:111], v[162:165], v[178:181], v[108:111]
	v_mfma_f32_16x16x32_bf16 v[112:115], v[166:169], v[178:181], v[112:115]
	v_mfma_f32_16x16x32_bf16 v[52:55], v[214:217], v[178:181], v[52:55]
	s_waitcnt lgkmcnt(2)
	v_mfma_f32_16x16x32_bf16 v[116:119], v[158:161], v[218:221], v[116:119]
	v_mfma_f32_16x16x32_bf16 v[120:123], v[162:165], v[218:221], v[120:123]
	v_mfma_f32_16x16x32_bf16 v[124:127], v[166:169], v[218:221], v[124:127]
	v_mfma_f32_16x16x32_bf16 v[68:71], v[214:217], v[218:221], v[68:71]
	s_waitcnt lgkmcnt(1)
	v_mfma_f32_16x16x32_bf16 v[132:135], v[162:165], v[222:225], v[132:135]
	v_mfma_f32_16x16x32_bf16 v[84:87], v[214:217], v[222:225], v[84:87]
	s_waitcnt lgkmcnt(0)
	v_mfma_f32_16x16x32_bf16 v[100:103], v[158:161], v[226:229], v[100:103]
	v_mfma_f32_16x16x32_bf16 v[150:153], v[166:169], v[226:229], v[150:153]
	v_mfma_f32_16x16x32_bf16 v[154:157], v[214:217], v[226:229], v[154:157]
	v_mfma_f32_16x16x32_bf16 v[128:131], v[158:161], v[222:225], v[128:131]
	v_mfma_f32_16x16x32_bf16 v[136:139], v[166:169], v[222:225], v[136:139]
	v_mfma_f32_16x16x32_bf16 v[140:143], v[162:165], v[226:229], v[140:143]
	ds_read_b128 v[158:161], v7 offset:33792
	ds_read_b128 v[162:165], v7 offset:35840
	ds_read_b128 v[166:169], v7 offset:37888
	ds_read_b128 v[214:217], v7 offset:39936
	ds_read_b128 v[178:181], v6 offset:1024
	ds_read_b128 v[218:221], v6 offset:3072
	ds_read_b128 v[222:225], v6 offset:5120
	ds_read_b128 v[226:229], v6 offset:7168
	s_waitcnt lgkmcnt(3)
	v_mfma_f32_16x16x32_bf16 v[40:43], v[158:161], v[178:181], v[40:43]
	v_mfma_f32_16x16x32_bf16 v[44:47], v[162:165], v[178:181], v[44:47]
	v_mfma_f32_16x16x32_bf16 v[48:51], v[166:169], v[178:181], v[48:51]
	v_mfma_f32_16x16x32_bf16 v[174:177], v[214:217], v[178:181], v[174:177]
	ds_read_b128 v[178:181], v6 offset:9216
	s_waitcnt lgkmcnt(3)
	v_mfma_f32_16x16x32_bf16 v[56:59], v[158:161], v[218:221], v[56:59]
	v_mfma_f32_16x16x32_bf16 v[60:63], v[162:165], v[218:221], v[60:63]
	v_mfma_f32_16x16x32_bf16 v[64:67], v[166:169], v[218:221], v[64:67]
	v_mfma_f32_16x16x32_bf16 v[170:173], v[214:217], v[218:221], v[170:173]
	ds_read_b128 v[218:221], v6 offset:11264
	s_waitcnt lgkmcnt(3)
	v_mfma_f32_16x16x32_bf16 v[72:75], v[158:161], v[222:225], v[72:75]
	v_mfma_f32_16x16x32_bf16 v[76:79], v[162:165], v[222:225], v[76:79]
	v_mfma_f32_16x16x32_bf16 v[80:83], v[166:169], v[222:225], v[80:83]
	v_mfma_f32_16x16x32_bf16 v[32:35], v[214:217], v[222:225], v[32:35]
	ds_read_b128 v[222:225], v6 offset:13312
	s_waitcnt lgkmcnt(3)
	v_mfma_f32_16x16x32_bf16 v[88:91], v[158:161], v[226:229], v[88:91]
	v_mfma_f32_16x16x32_bf16 v[92:95], v[162:165], v[226:229], v[92:95]
	v_mfma_f32_16x16x32_bf16 v[96:99], v[166:169], v[226:229], v[96:99]
	v_mfma_f32_16x16x32_bf16 v[36:39], v[214:217], v[226:229], v[36:39]
	ds_read_b128 v[226:229], v6 offset:15360
	s_waitcnt lgkmcnt(3)
	v_mfma_f32_16x16x32_bf16 v[104:107], v[158:161], v[178:181], v[104:107]
	v_mfma_f32_16x16x32_bf16 v[108:111], v[162:165], v[178:181], v[108:111]
	v_mfma_f32_16x16x32_bf16 v[112:115], v[166:169], v[178:181], v[112:115]
	v_mfma_f32_16x16x32_bf16 v[52:55], v[214:217], v[178:181], v[52:55]
	s_waitcnt lgkmcnt(2)
	v_mfma_f32_16x16x32_bf16 v[116:119], v[158:161], v[218:221], v[116:119]
	v_mfma_f32_16x16x32_bf16 v[120:123], v[162:165], v[218:221], v[120:123]
	v_mfma_f32_16x16x32_bf16 v[124:127], v[166:169], v[218:221], v[124:127]
	v_mfma_f32_16x16x32_bf16 v[68:71], v[214:217], v[218:221], v[68:71]
	s_waitcnt lgkmcnt(1)
	v_mfma_f32_16x16x32_bf16 v[132:135], v[162:165], v[222:225], v[132:135]
	v_mfma_f32_16x16x32_bf16 v[84:87], v[214:217], v[222:225], v[84:87]
	s_waitcnt lgkmcnt(0)
	v_mfma_f32_16x16x32_bf16 v[100:103], v[158:161], v[226:229], v[100:103]
	v_mfma_f32_16x16x32_bf16 v[150:153], v[166:169], v[226:229], v[150:153]
	v_mfma_f32_16x16x32_bf16 v[154:157], v[214:217], v[226:229], v[154:157]
	v_mfma_f32_16x16x32_bf16 v[128:131], v[158:161], v[222:225], v[128:131]
	v_mfma_f32_16x16x32_bf16 v[136:139], v[166:169], v[222:225], v[136:139]
	v_mfma_f32_16x16x32_bf16 v[140:143], v[162:165], v[226:229], v[140:143]
	s_waitcnt vmcnt(0)
	s_barrier
	v_lshl_add_u64 v[6:7], s[20:21], 0, v[0:1]
	s_mov_b32 s0, m0
	s_mov_b32 m0, s42
	s_nop 0
	global_load_lds_dwordx4 v[6:7], off
	s_mov_b32 m0, s0
	v_lshl_add_u64 v[0:1], s[22:23], 0, v[0:1]
	s_mov_b32 s0, m0
	s_mov_b32 m0, s43
	s_nop 0
	global_load_lds_dwordx4 v[0:1], off
	s_mov_b32 m0, s0
	v_lshl_add_u64 v[0:1], s[20:21], 0, v[2:3]
	s_mov_b32 s0, m0
	s_mov_b32 m0, s44
	s_nop 0
	global_load_lds_dwordx4 v[0:1], off
	s_mov_b32 m0, s0
	v_lshl_add_u64 v[0:1], s[22:23], 0, v[2:3]
	s_mov_b32 s0, m0
	s_mov_b32 m0, s45
	s_nop 0
	global_load_lds_dwordx4 v[0:1], off
	s_mov_b32 m0, s0
	v_lshl_add_u64 v[0:1], s[20:21], 0, v[4:5]
	s_mov_b32 s0, m0
	s_mov_b32 m0, s46
	s_nop 0
	global_load_lds_dwordx4 v[0:1], off
	s_mov_b32 m0, s0
	v_lshl_add_u64 v[0:1], s[22:23], 0, v[4:5]
	s_mov_b32 s0, m0
	s_mov_b32 m0, s47
	s_nop 0
	global_load_lds_dwordx4 v[0:1], off
	s_mov_b32 m0, s0
	v_lshl_add_u64 v[0:1], s[20:21], 0, v[146:147]
	s_mov_b32 s0, m0
	s_mov_b32 m0, s49
	s_nop 0
	global_load_lds_dwordx4 v[0:1], off
	s_mov_b32 m0, s0
	v_lshl_add_u64 v[0:1], s[22:23], 0, v[146:147]
	s_mov_b32 s0, m0
	s_mov_b32 m0, s50
	s_nop 0
	global_load_lds_dwordx4 v[0:1], off
	s_mov_b32 m0, s0
	ds_read_b128 v[0:3], v8
	ds_read_b128 v[4:7], v9
	ds_read_b128 v[158:161], v11
	ds_read_b128 v[8:11], v10
	ds_read_b128 v[162:165], v12
	ds_read_b128 v[166:169], v13
	ds_read_b128 v[178:181], v14
	ds_read_b128 v[12:15], v15
	s_waitcnt lgkmcnt(3)
	v_mfma_f32_16x16x32_bf16 v[40:43], v[0:3], v[162:165], v[40:43]
	v_mfma_f32_16x16x32_bf16 v[44:47], v[4:7], v[162:165], v[44:47]
	v_mfma_f32_16x16x32_bf16 v[48:51], v[158:161], v[162:165], v[48:51]
	v_mfma_f32_16x16x32_bf16 v[162:165], v[8:11], v[162:165], v[174:177]
	s_nop 2
	ds_read_b128 v[174:177], v16
	s_waitcnt lgkmcnt(3)
	v_mfma_f32_16x16x32_bf16 v[56:59], v[0:3], v[166:169], v[56:59]
	v_mfma_f32_16x16x32_bf16 v[60:63], v[4:7], v[166:169], v[60:63]
	v_mfma_f32_16x16x32_bf16 v[64:67], v[158:161], v[166:169], v[64:67]
	v_mfma_f32_16x16x32_bf16 v[166:169], v[8:11], v[166:169], v[170:173]
	s_nop 2
	ds_read_b128 v[170:173], v17
	s_waitcnt lgkmcnt(3)
	v_mfma_f32_16x16x32_bf16 v[72:75], v[0:3], v[178:181], v[72:75]
	v_mfma_f32_16x16x32_bf16 v[76:79], v[4:7], v[178:181], v[76:79]
	v_mfma_f32_16x16x32_bf16 v[80:83], v[158:161], v[178:181], v[80:83]
	v_mfma_f32_16x16x32_bf16 v[32:35], v[8:11], v[178:181], v[32:35]
	ds_read_b128 v[178:181], v18
	s_waitcnt lgkmcnt(3)
	v_mfma_f32_16x16x32_bf16 v[214:217], v[0:3], v[12:15], v[88:91]
	v_mfma_f32_16x16x32_bf16 v[218:221], v[4:7], v[12:15], v[92:95]
	v_mfma_f32_16x16x32_bf16 v[222:225], v[158:161], v[12:15], v[96:99]
	v_mfma_f32_16x16x32_bf16 v[12:15], v[8:11], v[12:15], v[36:39]
	ds_read_b128 v[16:19], v19
	s_waitcnt lgkmcnt(3)
	v_mfma_f32_16x16x32_bf16 v[36:39], v[0:3], v[174:177], v[104:107]
	v_mfma_f32_16x16x32_bf16 v[226:229], v[4:7], v[174:177], v[108:111]
	v_mfma_f32_16x16x32_bf16 v[112:115], v[158:161], v[174:177], v[112:115]
	s_waitcnt lgkmcnt(2)
	v_mfma_f32_16x16x32_bf16 v[116:119], v[0:3], v[170:173], v[116:119]
	v_mfma_f32_16x16x32_bf16 v[120:123], v[4:7], v[170:173], v[120:123]
	v_mfma_f32_16x16x32_bf16 v[124:127], v[158:161], v[170:173], v[124:127]
	s_waitcnt lgkmcnt(1)
	v_mfma_f32_16x16x32_bf16 v[128:131], v[0:3], v[178:181], v[128:131]
	v_mfma_f32_16x16x32_bf16 v[132:135], v[4:7], v[178:181], v[132:135]
	s_waitcnt lgkmcnt(0)
	v_mfma_f32_16x16x32_bf16 v[0:3], v[0:3], v[16:19], v[100:103]
	v_mfma_f32_16x16x32_bf16 v[4:7], v[4:7], v[16:19], v[140:143]
	v_mfma_f32_16x16x32_bf16 v[140:143], v[158:161], v[16:19], v[150:153]
	v_mfma_f32_16x16x32_bf16 v[150:153], v[8:11], v[16:19], v[154:157]
	v_mfma_f32_16x16x32_bf16 v[174:177], v[8:11], v[174:177], v[52:55]
	v_mfma_f32_16x16x32_bf16 v[170:173], v[8:11], v[170:173], v[68:71]
	v_mfma_f32_16x16x32_bf16 v[136:139], v[158:161], v[178:181], v[136:139]
	v_mfma_f32_16x16x32_bf16 v[178:181], v[8:11], v[178:181], v[84:87]
	ds_read_b128 v[8:11], v20
	ds_read_b128 v[154:157], v21
	ds_read_b128 v[158:161], v23
	ds_read_b128 v[230:233], v22
	ds_read_b128 v[16:19], v24
	ds_read_b128 v[20:23], v25
	ds_read_b128 v[52:55], v26
	ds_read_b128 v[24:27], v27
	s_waitcnt lgkmcnt(3)
	v_mfma_f32_16x16x32_bf16 v[234:237], v[8:11], v[16:19], v[40:43]
	v_mfma_f32_16x16x32_bf16 v[238:241], v[154:157], v[16:19], v[44:47]
	v_mfma_f32_16x16x32_bf16 v[242:245], v[158:161], v[16:19], v[48:51]
	v_mfma_f32_16x16x32_bf16 v[162:165], v[230:233], v[16:19], v[162:165]
	ds_read_b128 v[16:19], v28
	s_waitcnt lgkmcnt(3)
	v_mfma_f32_16x16x32_bf16 v[108:111], v[8:11], v[20:23], v[56:59]
	v_mfma_f32_16x16x32_bf16 v[104:107], v[154:157], v[20:23], v[60:63]
	v_mfma_f32_16x16x32_bf16 v[100:103], v[158:161], v[20:23], v[64:67]
	v_mfma_f32_16x16x32_bf16 v[96:99], v[230:233], v[20:23], v[166:169]
	ds_read_b128 v[20:23], v29
	s_waitcnt lgkmcnt(3)
	v_mfma_f32_16x16x32_bf16 v[92:95], v[8:11], v[52:55], v[72:75]
	v_mfma_f32_16x16x32_bf16 v[88:91], v[154:157], v[52:55], v[76:79]
	v_mfma_f32_16x16x32_bf16 v[84:87], v[158:161], v[52:55], v[80:83]
	v_mfma_f32_16x16x32_bf16 v[80:83], v[230:233], v[52:55], v[32:35]
	ds_read_b128 v[166:169], v30
	s_waitcnt lgkmcnt(3)
	v_mfma_f32_16x16x32_bf16 v[76:79], v[8:11], v[24:27], v[214:217]
	v_mfma_f32_16x16x32_bf16 v[72:75], v[154:157], v[24:27], v[218:221]
	v_mfma_f32_16x16x32_bf16 v[68:71], v[158:161], v[24:27], v[222:225]
	v_mfma_f32_16x16x32_bf16 v[64:67], v[230:233], v[24:27], v[12:15]
	ds_read_b128 v[214:217], v31
	s_waitcnt lgkmcnt(3)
	v_mfma_f32_16x16x32_bf16 v[60:63], v[8:11], v[16:19], v[36:39]
	v_mfma_f32_16x16x32_bf16 v[56:59], v[154:157], v[16:19], v[226:229]
	v_mfma_f32_16x16x32_bf16 v[52:55], v[158:161], v[16:19], v[112:115]
	v_mfma_f32_16x16x32_bf16 v[48:51], v[230:233], v[16:19], v[174:177]
	s_waitcnt lgkmcnt(2)
	v_mfma_f32_16x16x32_bf16 v[44:47], v[8:11], v[20:23], v[116:119]
	v_mfma_f32_16x16x32_bf16 v[40:43], v[154:157], v[20:23], v[120:123]
	v_mfma_f32_16x16x32_bf16 v[36:39], v[158:161], v[20:23], v[124:127]
	v_mfma_f32_16x16x32_bf16 v[32:35], v[230:233], v[20:23], v[170:173]
	s_waitcnt lgkmcnt(1)
	v_mfma_f32_16x16x32_bf16 v[28:31], v[8:11], v[166:169], v[128:131]
	v_mfma_f32_16x16x32_bf16 v[24:27], v[154:157], v[166:169], v[132:135]
	v_mfma_f32_16x16x32_bf16 v[20:23], v[158:161], v[166:169], v[136:139]
	v_mfma_f32_16x16x32_bf16 v[16:19], v[230:233], v[166:169], v[178:181]
	s_waitcnt lgkmcnt(0)
	v_mfma_f32_16x16x32_bf16 v[12:15], v[8:11], v[214:217], v[0:3]
	v_mfma_f32_16x16x32_bf16 v[8:11], v[154:157], v[214:217], v[4:7]
	v_mfma_f32_16x16x32_bf16 v[4:7], v[158:161], v[214:217], v[140:143]
	v_mfma_f32_16x16x32_bf16 v[0:3], v[230:233], v[214:217], v[150:153]
	v_mov_b32_e32 v145, v184
	s_waitcnt vmcnt(0)
	s_barrier
	s_lshl_b32 s20, s13, 8
	s_lshl_b32 s14, s12, 8
	v_and_b32_e32 v151, 15, v145
	v_ashrrev_i32_e32 v112, 1, v145
	v_and_b32_e32 v153, 0xffffff80, v112
	v_or_b32_e32 v112, s20, v151
	v_add_u32_e32 v112, v112, v153
	v_ashrrev_i32_e32 v113, 31, v112
	v_lshlrev_b64 v[112:113], 13, v[112:113]
	v_bfe_u32 v150, v145, 6, 2
	v_lshl_add_u64 v[112:113], s[4:5], 0, v[112:113]
	s_ashr_i32 s15, s14, 31
	v_bfe_u32 v152, v145, 4, 2
	v_lshl_add_u64 v[112:113], s[14:15], 2, v[112:113]
	v_lshlrev_b32_e32 v146, 8, v150
	v_lshl_add_u64 v[112:113], v[112:113], 0, v[146:147]
	v_lshlrev_b32_e32 v146, 4, v152
	v_lshl_add_u64 v[154:155], v[112:113], 0, v[146:147]
	global_load_dwordx4 v[120:123], v[154:155], off offset:192
	global_load_dwordx4 v[128:131], v[154:155], off offset:128
	global_load_dwordx4 v[136:139], v[154:155], off offset:64
	global_load_dwordx4 v[140:143], v[154:155], off
	v_add_co_u32_e32 v112, vcc, s66, v154
	v_lshlrev_b32_e32 v158, 2, v152
	s_nop 0
	v_addc_co_u32_e32 v113, vcc, 0, v155, vcc
	global_load_dwordx4 v[132:135], v[112:113], off
	global_load_dwordx4 v[124:127], v[112:113], off offset:64
	global_load_dwordx4 v[116:119], v[112:113], off offset:128
	v_cmp_lt_i32_e32 vcc, v188, v186
	global_load_dwordx4 v[112:115], v[112:113], off offset:192
	v_cmp_eq_u32_e64 s[0:1], 0, v152
	v_cndmask_b32_e32 v146, v185, v188, vcc
	v_cmp_lt_i32_e32 vcc, v187, v186
	v_lshlrev_b32_e32 v149, 2, v146
	v_lshlrev_b32_e32 v157, 6, v150
	v_cndmask_b32_e32 v156, v185, v187, vcc
	v_lshlrev_b32_e32 v146, 2, v156
	v_or_b32_e32 v156, v153, v151
	v_add_u32_e32 v152, s20, v156
	v_ashrrev_i32_e32 v153, 31, v152
	v_lshl_or_b32 v182, v150, 10, v204
	v_or3_b32 v150, v157, s14, v158
	v_lshlrev_b64 v[158:159], 13, v[152:153]
	v_ashrrev_i32_e32 v151, 31, v150
	v_lshlrev_b64 v[160:161], 12, v[152:153]
	v_lshl_add_u64 v[158:159], s[4:5], 0, v[158:159]
	v_lshl_add_u64 v[160:161], s[6:7], 0, v[160:161]
	v_lshl_add_u64 v[166:167], v[150:151], 2, v[158:159]
	v_lshl_add_u64 v[168:169], v[150:151], 1, v[160:161]
	s_waitcnt vmcnt(7)
	v_pk_add_f32 v[158:159], v[162:163], v[120:121]
	s_waitcnt vmcnt(6)
	v_pk_add_f32 v[120:121], v[242:243], v[128:129]
	s_waitcnt vmcnt(5)
	v_pk_add_f32 v[128:129], v[238:239], v[136:137]
	s_waitcnt vmcnt(4)
	v_pk_add_f32 v[136:137], v[234:235], v[140:141]
	v_pk_add_f32 v[160:161], v[164:165], v[122:123]
	v_pk_add_f32 v[122:123], v[244:245], v[130:131]
	v_pk_add_f32 v[130:131], v[240:241], v[138:139]
	v_pk_add_f32 v[138:139], v[236:237], v[142:143]
	v_pk_mul_f32 v[172:173], v[128:129], v[128:129]
	v_pk_mul_f32 v[178:179], v[136:137], v[136:137]
	v_pk_mul_f32 v[162:163], v[120:121], v[120:121]
	v_pk_mul_f32 v[174:175], v[130:131], v[130:131]
	v_cvt_pk_bf16_f32 v176, v136, v137
	v_pk_mul_f32 v[180:181], v[138:139], v[138:139]
	global_store_dwordx4 v[166:167], v[136:139], off
	v_add_f32_e32 v153, v172, v173
	v_add_f32_e32 v157, v178, v179
	v_pk_mul_f32 v[136:137], v[158:159], v[158:159]
	v_pk_mul_f32 v[164:165], v[122:123], v[122:123]
	v_cvt_pk_bf16_f32 v177, v138, v139
	v_pk_mul_f32 v[138:139], v[160:161], v[160:161]
	v_add_f32_e32 v162, v162, v163
	v_add_f32_e32 v136, v136, v137
	v_add_f32_e32 v137, v174, v153
	v_add_f32_e32 v153, v180, v157
	v_add_f32_e32 v157, v164, v162
	v_add_f32_e32 v136, v138, v136
	v_add_f32_e32 v137, v175, v137
	v_add_f32_e32 v138, v181, v153
	v_add_f32_e32 v153, v165, v157
	v_add_f32_e32 v137, v138, v137
	v_add_f32_e32 v137, v137, v153
	v_add_f32_e32 v136, v139, v136
	v_add_f32_e32 v136, v137, v136
	ds_bpermute_b32 v137, v149, v136
	v_cvt_pk_bf16_f32 v170, v128, v129
	v_cvt_pk_bf16_f32 v171, v130, v131
	v_cvt_pk_bf16_f32 v142, v120, v121
	global_store_dwordx2 v[168:169], v[176:177], off
	global_store_dwordx4 v[166:167], v[128:131], off offset:64
	global_store_dwordx2 v[168:169], v[170:171], off offset:32
	global_store_dwordx4 v[166:167], v[120:123], off offset:128
	v_cvt_pk_bf16_f32 v140, v158, v159
	v_cvt_pk_bf16_f32 v141, v160, v161
	s_waitcnt lgkmcnt(0)
	v_add_f32_e32 v120, v136, v137
	ds_bpermute_b32 v121, v146, v120
	v_cvt_pk_bf16_f32 v143, v122, v123
	v_lshl_add_u32 v153, v156, 2, v182
	global_store_dwordx2 v[168:169], v[142:143], off offset:64
	global_store_dwordx4 v[166:167], v[158:161], off offset:192
	global_store_dwordx2 v[168:169], v[140:141], off offset:96
	s_and_saveexec_b64 s[14:15], s[0:1]
	s_cbranch_execz .LBB0_567
	s_waitcnt lgkmcnt(0)
	v_add_f32_e32 v120, v120, v121
	ds_write_b32 v153, v120

.LBB0_626:
	s_ashr_i32 s43, s42, 31
	s_lshl_b64 s[42:43], s[42:43], 20
	s_add_u32 s42, s58, s42
	s_addc_u32 s43, s62, s43
	s_ashr_i32 s5, s4, 31
	v_lshlrev_b32_e32 v3, 6, v1
	s_lshl_b64 s[4:5], s[4:5], 20
	v_and_b32_e32 v2, 48, v1
	v_and_b32_e32 v4, 0x3c0, v3
	v_lshlrev_b32_e32 v1, 2, v1
	s_add_u32 s4, s54, s4
	v_or_b32_e32 v5, v4, v2
	v_and_b32_e32 v1, 32, v1
	v_lshlrev_b32_e32 v0, 13, v0
	s_mov_b32 s80, 0x18000
	s_addc_u32 s5, s55, s5
	v_and_b32_e32 v111, 0x6000, v0
	s_add_i32 s46, s1, 0x10000
	s_add_i32 s47, s1, 0x18000
	s_add_i32 s74, s1, 0x12000
	s_add_i32 s75, s1, 0x1a000
	s_add_i32 s76, s1, 0x14000
	s_add_i32 s77, s1, 0x1c000
	s_add_i32 s78, s1, 0x16000
	s_add_i32 s79, s1, 0x1e000
	v_bitop3_b32 v0, v5, s80, v1 bitop3:0xde
	s_mov_b32 s80, 0x10400
	v_bitop3_b32 v149, v5, s80, v1 bitop3:0xde
	s_add_u32 s80, s52, s2
	s_addc_u32 s81, s53, s3
	s_add_i32 s2, s82, s83
	s_ashr_i32 s3, s2, 31
	s_waitcnt vmcnt(0)
	s_lshl_b64 s[2:3], s[2:3], 20
	v_bitop3_b32 v110, v4, v1, v2 bitop3:0x36
	v_and_b32_e32 v112, 0xffffc000, v3
	s_add_u32 s82, s10, s2
	v_mov_b32_e32 v4, 0
	v_or_b32_e32 v113, 0x800, v112
	v_or_b32_e32 v114, 0x1000, v112
	v_or_b32_e32 v115, 0x1800, v112
	v_or_b32_e32 v116, 0x2000, v112
	v_or_b32_e32 v117, 0x2800, v112
	v_or_b32_e32 v118, 0x3000, v112
	v_or_b32_e32 v119, 0x3800, v112
	v_bitop3_b32 v145, v5, s33, v1 bitop3:0xde
	s_addc_u32 s83, s11, s3
	s_mov_b64 s[2:3], 0
	s_mov_b32 s84, 1
	v_add_u32_e32 v150, v0, v111
	v_mov_b32_e32 v5, v4
	v_mov_b32_e32 v6, v4
	v_mov_b32_e32 v7, v4
	v_mov_b32_e32 v72, v4
	v_mov_b32_e32 v73, v4
	v_mov_b32_e32 v74, v4
	v_mov_b32_e32 v75, v4
	v_mov_b32_e32 v12, v4
	v_mov_b32_e32 v13, v4
	v_mov_b32_e32 v14, v4
	v_mov_b32_e32 v15, v4
	v_mov_b32_e32 v76, v4
	v_mov_b32_e32 v77, v4
	v_mov_b32_e32 v78, v4
	v_mov_b32_e32 v79, v4
	v_mov_b32_e32 v16, v4
	v_mov_b32_e32 v17, v4
	v_mov_b32_e32 v18, v4
	v_mov_b32_e32 v19, v4
	v_mov_b32_e32 v80, v4
	v_mov_b32_e32 v81, v4
	v_mov_b32_e32 v82, v4
	v_mov_b32_e32 v83, v4
	v_mov_b32_e32 v20, v4
	v_mov_b32_e32 v21, v4
	v_mov_b32_e32 v22, v4
	v_mov_b32_e32 v23, v4
	v_mov_b32_e32 v84, v4
	v_mov_b32_e32 v85, v4
	v_mov_b32_e32 v86, v4
	v_mov_b32_e32 v87, v4
	v_mov_b32_e32 v24, v4
	v_mov_b32_e32 v25, v4
	v_mov_b32_e32 v26, v4
	v_mov_b32_e32 v27, v4
	v_mov_b32_e32 v88, v4
	v_mov_b32_e32 v89, v4
	v_mov_b32_e32 v90, v4
	v_mov_b32_e32 v91, v4
	v_mov_b32_e32 v28, v4
	v_mov_b32_e32 v29, v4
	v_mov_b32_e32 v30, v4
	v_mov_b32_e32 v31, v4
	v_mov_b32_e32 v92, v4
	v_mov_b32_e32 v93, v4
	v_mov_b32_e32 v94, v4
	v_mov_b32_e32 v95, v4
	v_mov_b32_e32 v32, v4
	v_mov_b32_e32 v33, v4
	v_mov_b32_e32 v34, v4
	v_mov_b32_e32 v35, v4
	v_mov_b32_e32 v96, v4
	v_mov_b32_e32 v97, v4
	v_mov_b32_e32 v98, v4
	v_mov_b32_e32 v99, v4
	v_mov_b32_e32 v36, v4
	v_mov_b32_e32 v37, v4
	v_mov_b32_e32 v38, v4
	v_mov_b32_e32 v39, v4
	v_mov_b32_e32 v100, v4
	v_mov_b32_e32 v101, v4
	v_mov_b32_e32 v102, v4
	v_mov_b32_e32 v103, v4
	v_mov_b32_e32 v40, v4
	v_mov_b32_e32 v41, v4
	v_mov_b32_e32 v42, v4
	v_mov_b32_e32 v43, v4
	v_mov_b32_e32 v120, v4
	v_mov_b32_e32 v121, v4
	v_mov_b32_e32 v122, v4
	v_mov_b32_e32 v123, v4
	v_mov_b32_e32 v44, v4
	v_mov_b32_e32 v45, v4
	v_mov_b32_e32 v46, v4
	v_mov_b32_e32 v47, v4
	v_mov_b32_e32 v124, v4
	v_mov_b32_e32 v125, v4
	v_mov_b32_e32 v126, v4
	v_mov_b32_e32 v127, v4
	v_mov_b32_e32 v48, v4
	v_mov_b32_e32 v49, v4
	v_mov_b32_e32 v50, v4
	v_mov_b32_e32 v51, v4
	v_mov_b32_e32 v128, v4
	v_mov_b32_e32 v129, v4
	v_mov_b32_e32 v130, v4
	v_mov_b32_e32 v131, v4
	v_mov_b32_e32 v52, v4
	v_mov_b32_e32 v53, v4
	v_mov_b32_e32 v54, v4
	v_mov_b32_e32 v55, v4
	v_mov_b32_e32 v132, v4
	v_mov_b32_e32 v133, v4
	v_mov_b32_e32 v134, v4
	v_mov_b32_e32 v135, v4
	v_mov_b32_e32 v56, v4
	v_mov_b32_e32 v57, v4
	v_mov_b32_e32 v58, v4
	v_mov_b32_e32 v59, v4
	v_mov_b32_e32 v136, v4
	v_mov_b32_e32 v137, v4
	v_mov_b32_e32 v138, v4
	v_mov_b32_e32 v139, v4
	v_mov_b32_e32 v60, v4
	v_mov_b32_e32 v61, v4
	v_mov_b32_e32 v62, v4
	v_mov_b32_e32 v63, v4
	v_mov_b32_e32 v140, v4
	v_mov_b32_e32 v141, v4
	v_mov_b32_e32 v142, v4
	v_mov_b32_e32 v143, v4
	v_mov_b32_e32 v64, v4
	v_mov_b32_e32 v65, v4
	v_mov_b32_e32 v66, v4
	v_mov_b32_e32 v67, v4
	v_mov_b32_e32 v0, v4
	v_mov_b32_e32 v1, v4
	v_mov_b32_e32 v2, v4
	v_mov_b32_e32 v3, v4
	v_mov_b32_e32 v68, v4
	v_mov_b32_e32 v69, v4
	v_mov_b32_e32 v70, v4
	v_mov_b32_e32 v71, v4
	v_mov_b32_e32 v8, v4
	v_mov_b32_e32 v9, v4
	v_mov_b32_e32 v10, v4
	v_mov_b32_e32 v11, v4
	s_waitcnt lgkmcnt(0)
	s_barrier
	s_add_u32 s85, s82, s2
	s_addc_u32 s90, s83, s3
	s_add_u32 s86, s85, 0x1b900080
	s_addc_u32 s87, s90, 0
	s_add_u32 s91, s80, s2
	s_addc_u32 s92, s81, s3
	s_add_u32 s88, s91, 0x3400080
	s_addc_u32 s89, s92, 0
	v_add_u32_e32 v151, v110, v111
	v_add_u32_e32 v189, v110, v112
	ds_read_b128 v[152:155], v151 offset:32768
	ds_read_b128 v[156:159], v189
	s_mov_b32 m0, s47
	s_nop 0
	global_load_lds_dwordx4 v104, s[88:89]
	ds_read_b128 v[160:163], v151 offset:34816
	s_mov_b32 m0, s75
	s_nop 0
	global_load_lds_dwordx4 v106, s[88:89]
	ds_read_b128 v[164:167], v189 offset:2048
	ds_read_b128 v[168:171], v151 offset:36864
	s_mov_b32 m0, s77
	s_nop 0
	global_load_lds_dwordx4 v108, s[88:89]
	ds_read_b128 v[172:175], v151 offset:38912
	ds_read_b128 v[176:179], v189 offset:4096
	ds_read_b128 v[180:183], v189 offset:6144
	s_branch .Lmy_rot_627
.LBB0_627:
	s_add_u32 s85, s82, s2
	s_addc_u32 s90, s83, s3
	s_add_u32 s86, s85, 0x1b900080
	s_addc_u32 s87, s90, 0
	s_add_u32 s91, s80, s2
	s_addc_u32 s92, s81, s3
	s_add_u32 s88, s91, 0x3400080
	s_addc_u32 s89, s92, 0
	v_add_u32_e32 v151, v110, v111
	v_add_u32_e32 v189, v110, v112
	ds_read_b128 v[152:155], v151 offset:32768
	ds_read_b128 v[156:159], v189
	s_mov_b32 m0, s47
	v_mfma_f32_16x16x32_bf16 v[76:79], v[160:163], v[176:179], v[76:79]
	global_load_lds_dwordx4 v104, s[88:89]
	v_mfma_f32_16x16x32_bf16 v[64:67], v[160:163], v[180:183], v[64:67]
	ds_read_b128 v[160:163], v151 offset:34816
	v_mfma_f32_16x16x32_bf16 v[12:15], v[164:167], v[176:179], v[12:15]
	s_mov_b32 m0, s75
	v_mfma_f32_16x16x32_bf16 v[0:3], v[164:167], v[180:183], v[0:3]
	global_load_lds_dwordx4 v106, s[88:89]
	ds_read_b128 v[164:167], v189 offset:2048
	v_mfma_f32_16x16x32_bf16 v[72:75], v[168:171], v[176:179], v[72:75]
	v_mfma_f32_16x16x32_bf16 v[68:71], v[168:171], v[180:183], v[68:71]
	ds_read_b128 v[168:171], v151 offset:36864
	s_mov_b32 m0, s77
	v_mfma_f32_16x16x32_bf16 v[4:7], v[172:175], v[176:179], v[4:7]
	global_load_lds_dwordx4 v108, s[88:89]
	v_mfma_f32_16x16x32_bf16 v[8:11], v[172:175], v[180:183], v[8:11]
	ds_read_b128 v[172:175], v151 offset:38912
	ds_read_b128 v[176:179], v189 offset:4096
	ds_read_b128 v[180:183], v189 offset:6144
.Lmy_rot_627:
	s_waitcnt lgkmcnt(6)
	v_mfma_f32_16x16x32_bf16 v[140:143], v[152:155], v[156:159], v[140:143]
	s_waitcnt lgkmcnt(5)
	s_mov_b32 m0, s79
	v_mfma_f32_16x16x32_bf16 v[60:63], v[160:163], v[156:159], v[60:63]
	global_load_lds_dwordx4 v146, s[88:89]
	s_waitcnt lgkmcnt(4)
	v_mfma_f32_16x16x32_bf16 v[132:135], v[152:155], v[164:167], v[132:135]
	v_mfma_f32_16x16x32_bf16 v[52:55], v[160:163], v[164:167], v[52:55]
	s_waitcnt lgkmcnt(3)
	s_mov_b32 m0, s46
	v_mfma_f32_16x16x32_bf16 v[136:139], v[168:171], v[156:159], v[136:139]
	global_load_lds_dwordx4 v104, s[86:87]
	v_mfma_f32_16x16x32_bf16 v[128:131], v[168:171], v[164:167], v[128:131]
	s_waitcnt lgkmcnt(2)
	v_mfma_f32_16x16x32_bf16 v[56:59], v[172:175], v[156:159], v[56:59]
	ds_read_b128 v[156:159], v189 offset:8192
	s_mov_b32 m0, s74
	v_mfma_f32_16x16x32_bf16 v[48:51], v[172:175], v[164:167], v[48:51]
	global_load_lds_dwordx4 v106, s[86:87]
	ds_read_b128 v[164:167], v189 offset:10240
	s_waitcnt lgkmcnt(3)
	v_mfma_f32_16x16x32_bf16 v[124:127], v[152:155], v[176:179], v[124:127]
	v_mfma_f32_16x16x32_bf16 v[44:47], v[160:163], v[176:179], v[44:47]
	s_mov_b32 m0, s76
	v_mfma_f32_16x16x32_bf16 v[120:123], v[168:171], v[176:179], v[120:123]
	global_load_lds_dwordx4 v108, s[86:87]
	v_mfma_f32_16x16x32_bf16 v[40:43], v[172:175], v[176:179], v[40:43]
	ds_read_b128 v[176:179], v189 offset:12288
	s_waitcnt lgkmcnt(3)
	v_mfma_f32_16x16x32_bf16 v[100:103], v[152:155], v[180:183], v[100:103]
	s_mov_b32 m0, s78
	v_mfma_f32_16x16x32_bf16 v[36:39], v[160:163], v[180:183], v[36:39]
	global_load_lds_dwordx4 v146, s[86:87]
	v_mfma_f32_16x16x32_bf16 v[96:99], v[168:171], v[180:183], v[96:99]
	v_mfma_f32_16x16x32_bf16 v[32:35], v[172:175], v[180:183], v[32:35]
	ds_read_b128 v[180:183], v189 offset:14336
	s_waitcnt lgkmcnt(3)
	v_mfma_f32_16x16x32_bf16 v[28:31], v[160:163], v[156:159], v[28:31]
	s_waitcnt lgkmcnt(2)
	v_mfma_f32_16x16x32_bf16 v[20:23], v[160:163], v[164:167], v[20:23]
	s_waitcnt lgkmcnt(1)
	v_mfma_f32_16x16x32_bf16 v[12:15], v[160:163], v[176:179], v[12:15]
	s_waitcnt lgkmcnt(0)
	v_mfma_f32_16x16x32_bf16 v[0:3], v[160:163], v[180:183], v[0:3]
	ds_read_b128 v[160:163], v151 offset:33792
	v_mfma_f32_16x16x32_bf16 v[92:95], v[152:155], v[156:159], v[92:95]
	v_mfma_f32_16x16x32_bf16 v[84:87], v[152:155], v[164:167], v[84:87]
	v_mfma_f32_16x16x32_bf16 v[76:79], v[152:155], v[176:179], v[76:79]
	v_mfma_f32_16x16x32_bf16 v[64:67], v[152:155], v[180:183], v[64:67]
	ds_read_b128 v[152:155], v189 offset:1024
	v_mfma_f32_16x16x32_bf16 v[80:83], v[168:171], v[164:167], v[80:83]
	v_mfma_f32_16x16x32_bf16 v[16:19], v[172:175], v[164:167], v[16:19]
	ds_read_b128 v[164:167], v151 offset:35840
	v_mfma_f32_16x16x32_bf16 v[88:91], v[168:171], v[156:159], v[88:91]
	v_mfma_f32_16x16x32_bf16 v[24:27], v[172:175], v[156:159], v[24:27]
	ds_read_b128 v[156:159], v189 offset:3072
	v_mfma_f32_16x16x32_bf16 v[72:75], v[168:171], v[176:179], v[72:75]
	v_mfma_f32_16x16x32_bf16 v[4:7], v[172:175], v[176:179], v[4:7]
	ds_read_b128 v[176:179], v189 offset:5120
	v_mfma_f32_16x16x32_bf16 v[68:71], v[168:171], v[180:183], v[68:71]
	ds_read_b128 v[168:171], v151 offset:37888
	v_mfma_f32_16x16x32_bf16 v[8:11], v[172:175], v[180:183], v[8:11]
	ds_read_b128 v[172:175], v151 offset:39936
	ds_read_b128 v[180:183], v189 offset:7168
	s_waitcnt lgkmcnt(6)
	v_mfma_f32_16x16x32_bf16 v[140:143], v[160:163], v[152:155], v[140:143]
	s_waitcnt lgkmcnt(5)
	v_mfma_f32_16x16x32_bf16 v[60:63], v[164:167], v[152:155], v[60:63]
	s_waitcnt lgkmcnt(4)
	v_mfma_f32_16x16x32_bf16 v[132:135], v[160:163], v[156:159], v[132:135]
	v_mfma_f32_16x16x32_bf16 v[52:55], v[164:167], v[156:159], v[52:55]
	s_waitcnt lgkmcnt(3)
	v_mfma_f32_16x16x32_bf16 v[124:127], v[160:163], v[176:179], v[124:127]
	v_mfma_f32_16x16x32_bf16 v[44:47], v[164:167], v[176:179], v[44:47]
	s_waitcnt lgkmcnt(2)
	v_mfma_f32_16x16x32_bf16 v[136:139], v[168:171], v[152:155], v[136:139]
	s_waitcnt lgkmcnt(1)
	v_mfma_f32_16x16x32_bf16 v[56:59], v[172:175], v[152:155], v[56:59]
	ds_read_b128 v[152:155], v189 offset:9216
	v_mfma_f32_16x16x32_bf16 v[128:131], v[168:171], v[156:159], v[128:131]
	v_mfma_f32_16x16x32_bf16 v[48:51], v[172:175], v[156:159], v[48:51]
	ds_read_b128 v[156:159], v189 offset:11264
	v_mfma_f32_16x16x32_bf16 v[120:123], v[168:171], v[176:179], v[120:123]
	v_mfma_f32_16x16x32_bf16 v[40:43], v[172:175], v[176:179], v[40:43]
	ds_read_b128 v[176:179], v189 offset:13312
	s_waitcnt lgkmcnt(3)
	v_mfma_f32_16x16x32_bf16 v[100:103], v[160:163], v[180:183], v[100:103]
	v_mfma_f32_16x16x32_bf16 v[36:39], v[164:167], v[180:183], v[36:39]
	v_mfma_f32_16x16x32_bf16 v[96:99], v[168:171], v[180:183], v[96:99]
	v_mfma_f32_16x16x32_bf16 v[32:35], v[172:175], v[180:183], v[32:35]
	ds_read_b128 v[180:183], v189 offset:15360
	s_waitcnt lgkmcnt(3)
	v_mfma_f32_16x16x32_bf16 v[92:95], v[160:163], v[152:155], v[92:95]
	v_mfma_f32_16x16x32_bf16 v[28:31], v[164:167], v[152:155], v[28:31]
	v_mfma_f32_16x16x32_bf16 v[88:91], v[168:171], v[152:155], v[88:91]
	v_mfma_f32_16x16x32_bf16 v[24:27], v[172:175], v[152:155], v[24:27]
	s_waitcnt lgkmcnt(2)
	v_mfma_f32_16x16x32_bf16 v[84:87], v[160:163], v[156:159], v[84:87]
	v_mfma_f32_16x16x32_bf16 v[20:23], v[164:167], v[156:159], v[20:23]
	v_mfma_f32_16x16x32_bf16 v[80:83], v[168:171], v[156:159], v[80:83]
	v_mfma_f32_16x16x32_bf16 v[16:19], v[172:175], v[156:159], v[16:19]
	s_add_u32 s85, s85, 0x1b900100
	s_addc_u32 s86, s90, 0
	s_add_u32 s88, s91, 0x3400100
	s_addc_u32 s89, s92, 0
	s_cmp_lt_u32 s84, 31
	s_cselect_b32 s87, s86, s43
	s_cselect_b32 s86, s85, s42
	s_waitcnt vmcnt(0)
	s_waitcnt lgkmcnt(0)
	s_barrier
	s_cselect_b32 s89, s89, s5
	s_cselect_b32 s88, s88, s4
	ds_read_b128 v[152:155], v150
	v_add_u32_e32 v151, v145, v112
	ds_read_b128 v[156:159], v151
	s_mov_b32 m0, s45
	v_mfma_f32_16x16x32_bf16 v[76:79], v[160:163], v[176:179], v[76:79]
	global_load_lds_dwordx4 v104, s[88:89]
	v_mfma_f32_16x16x32_bf16 v[64:67], v[160:163], v[180:183], v[64:67]
	ds_read_b128 v[160:163], v150 offset:2048
	v_mfma_f32_16x16x32_bf16 v[12:15], v[164:167], v[176:179], v[12:15]
	s_mov_b32 m0, s69
	v_mfma_f32_16x16x32_bf16 v[0:3], v[164:167], v[180:183], v[0:3]
	global_load_lds_dwordx4 v106, s[88:89]
	v_add_u32_e32 v151, v145, v113
	ds_read_b128 v[164:167], v151
	v_mfma_f32_16x16x32_bf16 v[72:75], v[168:171], v[176:179], v[72:75]
	v_mfma_f32_16x16x32_bf16 v[68:71], v[168:171], v[180:183], v[68:71]
	ds_read_b128 v[168:171], v150 offset:4096
	s_mov_b32 m0, s71
	v_mfma_f32_16x16x32_bf16 v[4:7], v[172:175], v[176:179], v[4:7]
	global_load_lds_dwordx4 v108, s[88:89]
	v_mfma_f32_16x16x32_bf16 v[8:11], v[172:175], v[180:183], v[8:11]
	ds_read_b128 v[172:175], v150 offset:6144
	v_add_u32_e32 v151, v145, v114
	ds_read_b128 v[176:179], v151
	v_add_u32_e32 v151, v145, v115
	ds_read_b128 v[180:183], v151
	s_waitcnt lgkmcnt(6)
	v_mfma_f32_16x16x32_bf16 v[140:143], v[152:155], v[156:159], v[140:143]
	s_waitcnt lgkmcnt(5)
	s_mov_b32 m0, s73
	v_mfma_f32_16x16x32_bf16 v[60:63], v[160:163], v[156:159], v[60:63]
	global_load_lds_dwordx4 v146, s[88:89]
	s_waitcnt lgkmcnt(4)
	v_mfma_f32_16x16x32_bf16 v[132:135], v[152:155], v[164:167], v[132:135]
	v_mfma_f32_16x16x32_bf16 v[52:55], v[160:163], v[164:167], v[52:55]
	s_waitcnt lgkmcnt(3)
	s_mov_b32 m0, s1
	v_mfma_f32_16x16x32_bf16 v[136:139], v[168:171], v[156:159], v[136:139]
	global_load_lds_dwordx4 v104, s[86:87]
	v_mfma_f32_16x16x32_bf16 v[128:131], v[168:171], v[164:167], v[128:131]
	s_waitcnt lgkmcnt(2)
	v_mfma_f32_16x16x32_bf16 v[56:59], v[172:175], v[156:159], v[56:59]
	v_add_u32_e32 v151, v145, v116
	ds_read_b128 v[156:159], v151
	s_mov_b32 m0, s68
	v_mfma_f32_16x16x32_bf16 v[48:51], v[172:175], v[164:167], v[48:51]
	global_load_lds_dwordx4 v106, s[86:87]
	v_add_u32_e32 v151, v145, v117
	ds_read_b128 v[164:167], v151
	s_waitcnt lgkmcnt(3)
	v_mfma_f32_16x16x32_bf16 v[124:127], v[152:155], v[176:179], v[124:127]
	v_mfma_f32_16x16x32_bf16 v[44:47], v[160:163], v[176:179], v[44:47]
	s_mov_b32 m0, s70
	v_mfma_f32_16x16x32_bf16 v[120:123], v[168:171], v[176:179], v[120:123]
	global_load_lds_dwordx4 v108, s[86:87]
	v_mfma_f32_16x16x32_bf16 v[40:43], v[172:175], v[176:179], v[40:43]
	v_add_u32_e32 v151, v145, v118
	ds_read_b128 v[176:179], v151
	s_waitcnt lgkmcnt(3)
	v_mfma_f32_16x16x32_bf16 v[100:103], v[152:155], v[180:183], v[100:103]
	s_mov_b32 m0, s72
	v_mfma_f32_16x16x32_bf16 v[36:39], v[160:163], v[180:183], v[36:39]
	global_load_lds_dwordx4 v146, s[86:87]
	v_mfma_f32_16x16x32_bf16 v[96:99], v[168:171], v[180:183], v[96:99]
	v_mfma_f32_16x16x32_bf16 v[32:35], v[172:175], v[180:183], v[32:35]
	v_add_u32_e32 v151, v145, v119
	ds_read_b128 v[180:183], v151
	s_waitcnt lgkmcnt(3)
	v_mfma_f32_16x16x32_bf16 v[28:31], v[160:163], v[156:159], v[28:31]
	s_waitcnt lgkmcnt(2)
	v_mfma_f32_16x16x32_bf16 v[20:23], v[160:163], v[164:167], v[20:23]
	s_waitcnt lgkmcnt(1)
	v_mfma_f32_16x16x32_bf16 v[12:15], v[160:163], v[176:179], v[12:15]
	s_waitcnt lgkmcnt(0)
	v_mfma_f32_16x16x32_bf16 v[0:3], v[160:163], v[180:183], v[0:3]
	ds_read_b128 v[160:163], v150 offset:1024
	v_mfma_f32_16x16x32_bf16 v[92:95], v[152:155], v[156:159], v[92:95]
	v_mfma_f32_16x16x32_bf16 v[84:87], v[152:155], v[164:167], v[84:87]
	v_mfma_f32_16x16x32_bf16 v[76:79], v[152:155], v[176:179], v[76:79]
	v_mfma_f32_16x16x32_bf16 v[64:67], v[152:155], v[180:183], v[64:67]
	v_add_u32_e32 v151, v149, v112
	ds_read_b128 v[152:155], v151
	v_mfma_f32_16x16x32_bf16 v[80:83], v[168:171], v[164:167], v[80:83]
	v_mfma_f32_16x16x32_bf16 v[16:19], v[172:175], v[164:167], v[16:19]
	ds_read_b128 v[164:167], v150 offset:3072
	v_mfma_f32_16x16x32_bf16 v[88:91], v[168:171], v[156:159], v[88:91]
	v_mfma_f32_16x16x32_bf16 v[24:27], v[172:175], v[156:159], v[24:27]
	v_add_u32_e32 v151, v149, v113
	ds_read_b128 v[156:159], v151
	v_mfma_f32_16x16x32_bf16 v[72:75], v[168:171], v[176:179], v[72:75]
	v_mfma_f32_16x16x32_bf16 v[4:7], v[172:175], v[176:179], v[4:7]
	v_add_u32_e32 v151, v149, v114
	ds_read_b128 v[176:179], v151
	v_mfma_f32_16x16x32_bf16 v[68:71], v[168:171], v[180:183], v[68:71]
	ds_read_b128 v[168:171], v150 offset:5120
	v_mfma_f32_16x16x32_bf16 v[8:11], v[172:175], v[180:183], v[8:11]
	ds_read_b128 v[172:175], v150 offset:7168
	v_add_u32_e32 v151, v149, v115
	ds_read_b128 v[180:183], v151
	s_waitcnt lgkmcnt(6)
	v_mfma_f32_16x16x32_bf16 v[140:143], v[160:163], v[152:155], v[140:143]
	s_waitcnt lgkmcnt(5)
	v_mfma_f32_16x16x32_bf16 v[60:63], v[164:167], v[152:155], v[60:63]
	s_waitcnt lgkmcnt(4)
	v_mfma_f32_16x16x32_bf16 v[132:135], v[160:163], v[156:159], v[132:135]
	v_mfma_f32_16x16x32_bf16 v[52:55], v[164:167], v[156:159], v[52:55]
	s_waitcnt lgkmcnt(3)
	v_mfma_f32_16x16x32_bf16 v[124:127], v[160:163], v[176:179], v[124:127]
	v_mfma_f32_16x16x32_bf16 v[44:47], v[164:167], v[176:179], v[44:47]
	s_waitcnt lgkmcnt(2)
	v_mfma_f32_16x16x32_bf16 v[136:139], v[168:171], v[152:155], v[136:139]
	s_waitcnt lgkmcnt(1)
	v_mfma_f32_16x16x32_bf16 v[56:59], v[172:175], v[152:155], v[56:59]
	v_add_u32_e32 v151, v149, v116
	ds_read_b128 v[152:155], v151
	v_mfma_f32_16x16x32_bf16 v[128:131], v[168:171], v[156:159], v[128:131]
	v_mfma_f32_16x16x32_bf16 v[48:51], v[172:175], v[156:159], v[48:51]
	v_add_u32_e32 v151, v149, v117
	ds_read_b128 v[156:159], v151
	v_mfma_f32_16x16x32_bf16 v[120:123], v[168:171], v[176:179], v[120:123]
	v_mfma_f32_16x16x32_bf16 v[40:43], v[172:175], v[176:179], v[40:43]
	v_add_u32_e32 v151, v149, v118
	ds_read_b128 v[176:179], v151
	s_waitcnt lgkmcnt(3)
	v_mfma_f32_16x16x32_bf16 v[100:103], v[160:163], v[180:183], v[100:103]
	v_mfma_f32_16x16x32_bf16 v[36:39], v[164:167], v[180:183], v[36:39]
	v_mfma_f32_16x16x32_bf16 v[96:99], v[168:171], v[180:183], v[96:99]
	v_mfma_f32_16x16x32_bf16 v[32:35], v[172:175], v[180:183], v[32:35]
	v_add_u32_e32 v151, v149, v119
	ds_read_b128 v[180:183], v151
	s_waitcnt lgkmcnt(3)
	v_mfma_f32_16x16x32_bf16 v[92:95], v[160:163], v[152:155], v[92:95]
	v_mfma_f32_16x16x32_bf16 v[28:31], v[164:167], v[152:155], v[28:31]
	v_mfma_f32_16x16x32_bf16 v[88:91], v[168:171], v[152:155], v[88:91]
	v_mfma_f32_16x16x32_bf16 v[24:27], v[172:175], v[152:155], v[24:27]
	s_waitcnt lgkmcnt(2)
	v_mfma_f32_16x16x32_bf16 v[84:87], v[160:163], v[156:159], v[84:87]
	v_mfma_f32_16x16x32_bf16 v[20:23], v[164:167], v[156:159], v[20:23]
	v_mfma_f32_16x16x32_bf16 v[80:83], v[168:171], v[156:159], v[80:83]
	v_mfma_f32_16x16x32_bf16 v[16:19], v[172:175], v[156:159], v[16:19]
	s_waitcnt vmcnt(0)
	s_add_u32 s2, s2, 0x100
	s_addc_u32 s3, s3, 0
	s_add_i32 s84, s84, 2
	s_cmpk_lg_i32 s2, 0x1000
	s_waitcnt lgkmcnt(0)
	s_barrier
	s_cbranch_scc1 .LBB0_627
	v_mfma_f32_16x16x32_bf16 v[76:79], v[160:163], v[176:179], v[76:79]
	v_mfma_f32_16x16x32_bf16 v[64:67], v[160:163], v[180:183], v[64:67]
	v_mfma_f32_16x16x32_bf16 v[12:15], v[164:167], v[176:179], v[12:15]
	v_mfma_f32_16x16x32_bf16 v[0:3], v[164:167], v[180:183], v[0:3]
	v_mfma_f32_16x16x32_bf16 v[72:75], v[168:171], v[176:179], v[72:75]
	v_mfma_f32_16x16x32_bf16 v[68:71], v[168:171], v[180:183], v[68:71]
	v_mfma_f32_16x16x32_bf16 v[4:7], v[172:175], v[176:179], v[4:7]
	v_mfma_f32_16x16x32_bf16 v[8:11], v[172:175], v[180:183], v[8:11]
	s_nop 15
	s_nop 15
	v_mov_b32_e32 v145, v184
	s_movk_i32 s1, 0x100
	v_and_b32_e32 v167, 15, v145
	v_cmp_gt_u32_e64 s[2:3], s1, v145
	v_cmp_lt_u32_e32 vcc, 13, v167
	s_and_b64 s[4:5], s[2:3], vcc
	s_xor_b64 s[4:5], s[4:5], -1
	v_lshlrev_b32_e32 v149, 6, v167
	s_and_saveexec_b64 s[42:43], s[4:5]
	s_xor_b64 s[4:5], exec, s[42:43]
	v_lshlrev_b32_e32 v149, 6, v167
	s_or_saveexec_b64 s[4:5], s[4:5]
	v_bfe_u32 v152, v145, 4, 2
	v_readlane_b32 s68, v253, 18
	v_readlane_b32 s75, v253, 20
	s_xor_b64 exec, exec, s[4:5]
	s_cbranch_execz .LBB0_632
	v_mov_b32_e32 v104, 0x211c0
	v_lshl_or_b32 v104, v167, 2, v104
	ds_read_b32 v108, v104
	v_and_b32_e32 v104, 0xc0, v145
	v_lshl_add_u32 v104, v104, 2, v149
	v_lshl_or_b32 v109, v152, 4, v104
	v_add_u32_e32 v110, 0x1fc80, v109
	s_waitcnt lgkmcnt(0)
	v_pk_mul_f32 v[104:105], v[64:65], v[108:109] op_sel_hi:[1,0]
	v_pk_mul_f32 v[106:107], v[66:67], v[108:109] op_sel_hi:[1,0]
	v_add_u32_e32 v109, 0x1fd00, v109
	ds_write_b128 v110, v[104:107]
	v_pk_mul_f32 v[104:105], v[0:1], v[108:109] op_sel_hi:[1,0]
	v_pk_mul_f32 v[106:107], v[2:3], v[108:109] op_sel_hi:[1,0]
	ds_write_b128 v109, v[104:107]

.LBB0_696:
	s_ashr_i32 s23, s22, 31
	s_lshl_b64 s[22:23], s[22:23], 20
	s_add_u32 s22, s28, s22
	s_addc_u32 s23, s29, s23
	s_ashr_i32 s25, s24, 31
	s_lshl_b64 s[24:25], s[24:25], 20
	s_add_u32 s24, s6, s24
	s_addc_u32 s25, s7, s25
	s_add_u32 s46, s14, 0x80
	v_and_b32_e32 v8, 48, v7
	v_lshlrev_b32_e32 v9, 6, v7
	v_lshlrev_b32_e32 v7, 2, v7
	s_addc_u32 s47, s15, 0
	v_and_b32_e32 v10, 0x3c0, v9
	v_and_b32_e32 v149, 32, v7
	s_add_u32 s50, s20, 0x80
	v_or_b32_e32 v145, v10, v8
	v_bitop3_b32 v12, v10, v149, v8 bitop3:0x36
	s_waitcnt vmcnt(0)
	s_barrier
	v_lshlrev_b32_e32 v8, 13, v6
	s_addc_u32 s51, s21, 0
	s_add_i32 s27, s1, 0x10000
	v_lshl_add_u64 v[6:7], s[46:47], 0, v[0:1]
	s_mov_b32 s41, m0
	s_mov_b32 m0, s27
	s_nop 0
	global_load_lds_dwordx4 v[6:7], off
	s_mov_b32 m0, s41
	s_add_i32 s26, s1, 0x18000
	v_lshl_add_u64 v[6:7], s[50:51], 0, v[0:1]
	s_mov_b32 s41, m0
	s_mov_b32 m0, s26
	s_nop 0
	global_load_lds_dwordx4 v[6:7], off
	s_mov_b32 m0, s41
	v_lshl_add_u64 v[6:7], s[46:47], 0, v[2:3]
	s_add_i32 s41, s1, 0x12000
	s_mov_b32 s42, m0
	s_mov_b32 m0, s41
	s_nop 0
	global_load_lds_dwordx4 v[6:7], off
	s_mov_b32 m0, s42
	v_lshl_add_u64 v[6:7], s[50:51], 0, v[2:3]
	s_add_i32 s42, s1, 0x1a000
	s_mov_b32 s43, m0
	s_mov_b32 m0, s42
	s_nop 0
	global_load_lds_dwordx4 v[6:7], off
	s_mov_b32 m0, s43
	v_lshl_add_u64 v[6:7], s[46:47], 0, v[4:5]
	s_add_i32 s43, s1, 0x14000
	s_mov_b32 s44, m0
	s_mov_b32 m0, s43
	s_nop 0
	global_load_lds_dwordx4 v[6:7], off
	s_mov_b32 m0, s44
	v_lshl_add_u64 v[6:7], s[50:51], 0, v[4:5]
	s_add_i32 s44, s1, 0x1c000
	s_mov_b32 s45, m0
	s_mov_b32 m0, s44
	s_nop 0
	global_load_lds_dwordx4 v[6:7], off
	s_mov_b32 m0, s45
	v_lshl_add_u64 v[6:7], s[46:47], 0, v[146:147]
	s_add_i32 s45, s1, 0x16000
	s_mov_b32 s46, m0
	s_mov_b32 m0, s45
	s_nop 0
	global_load_lds_dwordx4 v[6:7], off
	s_mov_b32 m0, s46
	v_lshl_add_u64 v[6:7], s[50:51], 0, v[146:147]
	s_add_i32 s46, s1, 0x1e000
	s_mov_b32 s47, m0
	s_mov_b32 m0, s46
	s_nop 0
	global_load_lds_dwordx4 v[6:7], off
	s_mov_b32 m0, s47
	v_and_b32_e32 v182, 0xffffc000, v9
	v_or_b32_e32 v183, 0x800, v182
	v_or_b32_e32 v189, 0x1000, v182
	v_or_b32_e32 v199, 0x1800, v182
	v_or_b32_e32 v200, 0x2000, v182
	v_or_b32_e32 v201, 0x2800, v182
	v_or_b32_e32 v203, 0x3000, v182
	v_or_b32_e32 v206, 0x3800, v182
	s_movk_i32 s47, 0x6000
	v_and_or_b32 v7, v8, s47, v12
	ds_read_b128 v[8:11], v7 offset:32768
	v_or_b32_e32 v6, v12, v182
	ds_read_b128 v[12:15], v7 offset:34816
	ds_read_b128 v[16:19], v7 offset:36864
	ds_read_b128 v[24:27], v7 offset:38912
	ds_read_b128 v[20:23], v6
	ds_read_b128 v[28:31], v6 offset:2048
	ds_read_b128 v[32:35], v6 offset:4096
	ds_read_b128 v[36:39], v6 offset:6144
	s_waitcnt lgkmcnt(3)
	v_mfma_f32_16x16x32_bf16 v[40:43], v[8:11], v[20:23], 0
	v_mfma_f32_16x16x32_bf16 v[44:47], v[12:15], v[20:23], 0
	v_mfma_f32_16x16x32_bf16 v[48:51], v[16:19], v[20:23], 0
	v_mfma_f32_16x16x32_bf16 v[20:23], v[24:27], v[20:23], 0
	ds_read_b128 v[52:55], v6 offset:8192
	s_waitcnt lgkmcnt(3)
	v_mfma_f32_16x16x32_bf16 v[56:59], v[8:11], v[28:31], 0
	v_mfma_f32_16x16x32_bf16 v[60:63], v[12:15], v[28:31], 0
	v_mfma_f32_16x16x32_bf16 v[64:67], v[16:19], v[28:31], 0
	v_mfma_f32_16x16x32_bf16 v[28:31], v[24:27], v[28:31], 0
	ds_read_b128 v[68:71], v6 offset:10240
	s_waitcnt lgkmcnt(3)
	v_mfma_f32_16x16x32_bf16 v[72:75], v[8:11], v[32:35], 0
	v_mfma_f32_16x16x32_bf16 v[76:79], v[12:15], v[32:35], 0
	v_mfma_f32_16x16x32_bf16 v[80:83], v[16:19], v[32:35], 0
	v_mfma_f32_16x16x32_bf16 v[32:35], v[24:27], v[32:35], 0
	ds_read_b128 v[84:87], v6 offset:12288
	s_waitcnt lgkmcnt(3)
	v_mfma_f32_16x16x32_bf16 v[88:91], v[8:11], v[36:39], 0
	v_mfma_f32_16x16x32_bf16 v[92:95], v[12:15], v[36:39], 0
	v_mfma_f32_16x16x32_bf16 v[96:99], v[16:19], v[36:39], 0
	v_mfma_f32_16x16x32_bf16 v[36:39], v[24:27], v[36:39], 0
	ds_read_b128 v[100:103], v6 offset:14336
	s_waitcnt lgkmcnt(3)
	v_mfma_f32_16x16x32_bf16 v[104:107], v[8:11], v[52:55], 0
	v_mfma_f32_16x16x32_bf16 v[108:111], v[12:15], v[52:55], 0
	v_mfma_f32_16x16x32_bf16 v[112:115], v[16:19], v[52:55], 0
	v_mfma_f32_16x16x32_bf16 v[52:55], v[24:27], v[52:55], 0
	s_waitcnt lgkmcnt(2)
	v_mfma_f32_16x16x32_bf16 v[116:119], v[8:11], v[68:71], 0
	v_mfma_f32_16x16x32_bf16 v[120:123], v[12:15], v[68:71], 0
	v_mfma_f32_16x16x32_bf16 v[124:127], v[16:19], v[68:71], 0
	v_mfma_f32_16x16x32_bf16 v[68:71], v[24:27], v[68:71], 0
	s_waitcnt lgkmcnt(1)
	v_mfma_f32_16x16x32_bf16 v[128:131], v[8:11], v[84:87], 0
	v_mfma_f32_16x16x32_bf16 v[132:135], v[12:15], v[84:87], 0
	v_mfma_f32_16x16x32_bf16 v[136:139], v[16:19], v[84:87], 0
	v_mfma_f32_16x16x32_bf16 v[84:87], v[24:27], v[84:87], 0
	s_waitcnt lgkmcnt(0)
	v_mfma_f32_16x16x32_bf16 v[8:11], v[8:11], v[100:103], 0
	v_mfma_f32_16x16x32_bf16 v[12:15], v[12:15], v[100:103], 0
	v_mfma_f32_16x16x32_bf16 v[16:19], v[16:19], v[100:103], 0
	v_mfma_f32_16x16x32_bf16 v[24:27], v[24:27], v[100:103], 0
	ds_read_b128 v[100:103], v7 offset:33792
	ds_read_b128 v[140:143], v7 offset:35840
	ds_read_b128 v[150:153], v7 offset:37888
	ds_read_b128 v[158:161], v7 offset:39936
	ds_read_b128 v[154:157], v6 offset:1024
	ds_read_b128 v[162:165], v6 offset:3072
	ds_read_b128 v[166:169], v6 offset:5120
	ds_read_b128 v[170:173], v6 offset:7168
	s_waitcnt lgkmcnt(3)
	v_mfma_f32_16x16x32_bf16 v[40:43], v[100:103], v[154:157], v[40:43]
	v_mfma_f32_16x16x32_bf16 v[44:47], v[140:143], v[154:157], v[44:47]
	v_mfma_f32_16x16x32_bf16 v[48:51], v[150:153], v[154:157], v[48:51]
	v_mfma_f32_16x16x32_bf16 v[20:23], v[158:161], v[154:157], v[20:23]
	ds_read_b128 v[154:157], v6 offset:9216
	s_waitcnt lgkmcnt(3)
	v_mfma_f32_16x16x32_bf16 v[56:59], v[100:103], v[162:165], v[56:59]
	v_mfma_f32_16x16x32_bf16 v[60:63], v[140:143], v[162:165], v[60:63]
	v_mfma_f32_16x16x32_bf16 v[64:67], v[150:153], v[162:165], v[64:67]
	v_mfma_f32_16x16x32_bf16 v[28:31], v[158:161], v[162:165], v[28:31]
	ds_read_b128 v[162:165], v6 offset:11264
	s_waitcnt lgkmcnt(3)
	v_mfma_f32_16x16x32_bf16 v[72:75], v[100:103], v[166:169], v[72:75]
	v_mfma_f32_16x16x32_bf16 v[76:79], v[140:143], v[166:169], v[76:79]
	v_mfma_f32_16x16x32_bf16 v[80:83], v[150:153], v[166:169], v[80:83]
	v_mfma_f32_16x16x32_bf16 v[32:35], v[158:161], v[166:169], v[32:35]
	ds_read_b128 v[166:169], v6 offset:13312
	s_waitcnt lgkmcnt(3)
	v_mfma_f32_16x16x32_bf16 v[88:91], v[100:103], v[170:173], v[88:91]
	v_mfma_f32_16x16x32_bf16 v[92:95], v[140:143], v[170:173], v[92:95]
	v_mfma_f32_16x16x32_bf16 v[96:99], v[150:153], v[170:173], v[96:99]
	v_mfma_f32_16x16x32_bf16 v[36:39], v[158:161], v[170:173], v[36:39]
	ds_read_b128 v[170:173], v6 offset:15360
	s_waitcnt lgkmcnt(3)
	v_mfma_f32_16x16x32_bf16 v[104:107], v[100:103], v[154:157], v[104:107]
	v_mfma_f32_16x16x32_bf16 v[108:111], v[140:143], v[154:157], v[108:111]
	v_mfma_f32_16x16x32_bf16 v[112:115], v[150:153], v[154:157], v[112:115]
	v_mfma_f32_16x16x32_bf16 v[52:55], v[158:161], v[154:157], v[52:55]
	s_waitcnt lgkmcnt(2)
	v_mfma_f32_16x16x32_bf16 v[116:119], v[100:103], v[162:165], v[116:119]
	v_mfma_f32_16x16x32_bf16 v[120:123], v[140:143], v[162:165], v[120:123]
	v_mfma_f32_16x16x32_bf16 v[124:127], v[150:153], v[162:165], v[124:127]
	v_mfma_f32_16x16x32_bf16 v[68:71], v[158:161], v[162:165], v[68:71]
	s_waitcnt lgkmcnt(1)
	v_mfma_f32_16x16x32_bf16 v[128:131], v[100:103], v[166:169], v[128:131]
	v_mfma_f32_16x16x32_bf16 v[132:135], v[140:143], v[166:169], v[132:135]
	v_mfma_f32_16x16x32_bf16 v[136:139], v[150:153], v[166:169], v[136:139]
	v_mfma_f32_16x16x32_bf16 v[84:87], v[158:161], v[166:169], v[84:87]
	s_waitcnt lgkmcnt(0)
	v_mfma_f32_16x16x32_bf16 v[100:103], v[100:103], v[170:173], v[8:11]
	v_mfma_f32_16x16x32_bf16 v[150:153], v[150:153], v[170:173], v[16:19]
	v_mfma_f32_16x16x32_bf16 v[24:27], v[158:161], v[170:173], v[24:27]
	v_mfma_f32_16x16x32_bf16 v[140:143], v[140:143], v[170:173], v[12:15]
	s_add_u32 s50, s14, 0x100
	s_addc_u32 s51, s15, 0
	s_add_u32 s52, s20, 0x100
	s_waitcnt vmcnt(0)
	s_barrier
	s_addc_u32 s53, s21, 0
	v_lshl_add_u64 v[8:9], s[50:51], 0, v[0:1]
	s_mov_b32 s47, m0
	s_mov_b32 m0, s1
	s_nop 0
	global_load_lds_dwordx4 v[8:9], off
	s_mov_b32 m0, s47
	v_lshl_add_u64 v[8:9], s[52:53], 0, v[0:1]
	s_mov_b32 s47, m0
	s_mov_b32 m0, s34
	s_nop 0
	global_load_lds_dwordx4 v[8:9], off
	s_mov_b32 m0, s47
	v_lshl_add_u64 v[8:9], s[50:51], 0, v[2:3]
	s_mov_b32 s47, m0
	s_mov_b32 m0, s35
	s_nop 0
	global_load_lds_dwordx4 v[8:9], off
	s_mov_b32 m0, s47
	v_lshl_add_u64 v[8:9], s[52:53], 0, v[2:3]
	s_mov_b32 s47, m0
	s_mov_b32 m0, s36
	s_nop 0
	global_load_lds_dwordx4 v[8:9], off
	s_mov_b32 m0, s47
	v_lshl_add_u64 v[8:9], s[50:51], 0, v[4:5]
	s_mov_b32 s47, m0
	s_mov_b32 m0, s37
	s_nop 0
	global_load_lds_dwordx4 v[8:9], off
	s_mov_b32 m0, s47
	v_lshl_add_u64 v[8:9], s[52:53], 0, v[4:5]
	s_mov_b32 s47, m0
	s_mov_b32 m0, s38
	s_nop 0
	global_load_lds_dwordx4 v[8:9], off
	s_mov_b32 m0, s47
	v_lshl_add_u64 v[8:9], s[50:51], 0, v[146:147]
	s_mov_b32 s47, m0
	s_mov_b32 m0, s39
	s_nop 0
	global_load_lds_dwordx4 v[8:9], off
	s_mov_b32 m0, s47
	v_lshl_add_u64 v[8:9], s[52:53], 0, v[146:147]
	s_mov_b32 s47, m0
	s_mov_b32 m0, s40
	s_nop 0
	global_load_lds_dwordx4 v[8:9], off
	s_mov_b32 m0, s47
	v_or_b32_e32 v8, 0x18000, v7
	v_or_b32_e32 v9, 0x18800, v7
	v_or_b32_e32 v11, 0x19000, v7
	v_or_b32_e32 v10, 0x19800, v7
	ds_read_b128 v[154:157], v8
	ds_read_b128 v[158:161], v9
	ds_read_b128 v[162:165], v11
	ds_read_b128 v[166:169], v10
	v_bitop3_b32 v207, v145, s33, v149 bitop3:0xde
	v_add_u32_e32 v12, v207, v182
	ds_read_b128 v[16:19], v12
	v_add_u32_e32 v13, v207, v183
	v_add_u32_e32 v14, v207, v189
	v_add_u32_e32 v15, v207, v199
	ds_read_b128 v[170:173], v13
	ds_read_b128 v[174:177], v14
	ds_read_b128 v[178:181], v15
	s_waitcnt lgkmcnt(3)
	v_mfma_f32_16x16x32_bf16 v[40:43], v[154:157], v[16:19], v[40:43]
	v_mfma_f32_16x16x32_bf16 v[44:47], v[158:161], v[16:19], v[44:47]
	v_mfma_f32_16x16x32_bf16 v[48:51], v[162:165], v[16:19], v[48:51]
	v_mfma_f32_16x16x32_bf16 v[214:217], v[166:169], v[16:19], v[20:23]
	v_add_u32_e32 v16, v207, v200
	v_add_u32_e32 v17, v207, v201
	v_add_u32_e32 v18, v207, v203
	v_add_u32_e32 v19, v207, v206
	ds_read_b128 v[20:23], v16
	s_waitcnt lgkmcnt(3)
	v_mfma_f32_16x16x32_bf16 v[56:59], v[154:157], v[170:173], v[56:59]
	v_mfma_f32_16x16x32_bf16 v[60:63], v[158:161], v[170:173], v[60:63]
	v_mfma_f32_16x16x32_bf16 v[64:67], v[162:165], v[170:173], v[64:67]
	v_mfma_f32_16x16x32_bf16 v[170:173], v[166:169], v[170:173], v[28:31]
	s_nop 2
	ds_read_b128 v[28:31], v17
	s_waitcnt lgkmcnt(3)
	v_mfma_f32_16x16x32_bf16 v[72:75], v[154:157], v[174:177], v[72:75]
	v_mfma_f32_16x16x32_bf16 v[76:79], v[158:161], v[174:177], v[76:79]
	v_mfma_f32_16x16x32_bf16 v[80:83], v[162:165], v[174:177], v[80:83]
	v_mfma_f32_16x16x32_bf16 v[32:35], v[166:169], v[174:177], v[32:35]
	ds_read_b128 v[174:177], v18
	s_waitcnt lgkmcnt(3)
	v_mfma_f32_16x16x32_bf16 v[88:91], v[154:157], v[178:181], v[88:91]
	v_mfma_f32_16x16x32_bf16 v[92:95], v[158:161], v[178:181], v[92:95]
	v_mfma_f32_16x16x32_bf16 v[96:99], v[162:165], v[178:181], v[96:99]
	v_mfma_f32_16x16x32_bf16 v[36:39], v[166:169], v[178:181], v[36:39]
	ds_read_b128 v[178:181], v19
	s_waitcnt lgkmcnt(3)
	v_mfma_f32_16x16x32_bf16 v[104:107], v[154:157], v[20:23], v[104:107]
	v_mfma_f32_16x16x32_bf16 v[108:111], v[158:161], v[20:23], v[108:111]
	v_mfma_f32_16x16x32_bf16 v[112:115], v[162:165], v[20:23], v[112:115]
	v_mfma_f32_16x16x32_bf16 v[52:55], v[166:169], v[20:23], v[52:55]
	s_waitcnt lgkmcnt(2)
	v_mfma_f32_16x16x32_bf16 v[116:119], v[154:157], v[28:31], v[116:119]
	v_mfma_f32_16x16x32_bf16 v[120:123], v[158:161], v[28:31], v[120:123]
	v_mfma_f32_16x16x32_bf16 v[124:127], v[162:165], v[28:31], v[124:127]
	v_mfma_f32_16x16x32_bf16 v[68:71], v[166:169], v[28:31], v[68:71]
	s_waitcnt lgkmcnt(1)
	v_mfma_f32_16x16x32_bf16 v[128:131], v[154:157], v[174:177], v[128:131]
	v_mfma_f32_16x16x32_bf16 v[132:135], v[158:161], v[174:177], v[132:135]
	v_mfma_f32_16x16x32_bf16 v[84:87], v[166:169], v[174:177], v[84:87]
	s_waitcnt lgkmcnt(0)
	v_mfma_f32_16x16x32_bf16 v[100:103], v[154:157], v[178:181], v[100:103]
	v_mfma_f32_16x16x32_bf16 v[150:153], v[162:165], v[178:181], v[150:153]
	v_mfma_f32_16x16x32_bf16 v[154:157], v[166:169], v[178:181], v[24:27]
	v_mfma_f32_16x16x32_bf16 v[136:139], v[162:165], v[174:177], v[136:139]
	v_mfma_f32_16x16x32_bf16 v[140:143], v[158:161], v[178:181], v[140:143]
	v_or_b32_e32 v20, 0x18400, v7
	v_or_b32_e32 v21, 0x18c00, v7
	v_or_b32_e32 v23, 0x19400, v7
	v_or_b32_e32 v22, 0x19c00, v7
	ds_read_b128 v[158:161], v20
	ds_read_b128 v[162:165], v21
	ds_read_b128 v[166:169], v23
	ds_read_b128 v[174:177], v22
	s_mov_b32 s47, 0x10400
	v_bitop3_b32 v145, v145, s47, v149 bitop3:0xde
	v_add_u32_e32 v24, v145, v182
	ds_read_b128 v[28:31], v24
	v_add_u32_e32 v25, v145, v183
	v_add_u32_e32 v26, v145, v189
	v_add_u32_e32 v27, v145, v199
	ds_read_b128 v[178:181], v25
	ds_read_b128 v[218:221], v26
	ds_read_b128 v[222:225], v27
	s_waitcnt lgkmcnt(3)
	v_mfma_f32_16x16x32_bf16 v[40:43], v[158:161], v[28:31], v[40:43]
	v_mfma_f32_16x16x32_bf16 v[44:47], v[162:165], v[28:31], v[44:47]
	v_mfma_f32_16x16x32_bf16 v[48:51], v[166:169], v[28:31], v[48:51]
	v_mfma_f32_16x16x32_bf16 v[214:217], v[174:177], v[28:31], v[214:217]
	v_add_u32_e32 v28, v145, v200
	v_add_u32_e32 v29, v145, v201
	v_add_u32_e32 v30, v145, v203
	v_add_u32_e32 v31, v145, v206
	ds_read_b128 v[226:229], v28
	s_waitcnt lgkmcnt(3)
	v_mfma_f32_16x16x32_bf16 v[56:59], v[158:161], v[178:181], v[56:59]
	v_mfma_f32_16x16x32_bf16 v[60:63], v[162:165], v[178:181], v[60:63]
	v_mfma_f32_16x16x32_bf16 v[64:67], v[166:169], v[178:181], v[64:67]
	v_mfma_f32_16x16x32_bf16 v[170:173], v[174:177], v[178:181], v[170:173]
	ds_read_b128 v[178:181], v29
	s_waitcnt lgkmcnt(3)
	v_mfma_f32_16x16x32_bf16 v[72:75], v[158:161], v[218:221], v[72:75]
	v_mfma_f32_16x16x32_bf16 v[76:79], v[162:165], v[218:221], v[76:79]
	v_mfma_f32_16x16x32_bf16 v[80:83], v[166:169], v[218:221], v[80:83]
	v_mfma_f32_16x16x32_bf16 v[32:35], v[174:177], v[218:221], v[32:35]
	ds_read_b128 v[218:221], v30
	s_waitcnt lgkmcnt(3)
	v_mfma_f32_16x16x32_bf16 v[88:91], v[158:161], v[222:225], v[88:91]
	v_mfma_f32_16x16x32_bf16 v[92:95], v[162:165], v[222:225], v[92:95]
	v_mfma_f32_16x16x32_bf16 v[96:99], v[166:169], v[222:225], v[96:99]
	v_mfma_f32_16x16x32_bf16 v[36:39], v[174:177], v[222:225], v[36:39]
	ds_read_b128 v[222:225], v31
	s_waitcnt lgkmcnt(3)
	v_mfma_f32_16x16x32_bf16 v[104:107], v[158:161], v[226:229], v[104:107]
	v_mfma_f32_16x16x32_bf16 v[108:111], v[162:165], v[226:229], v[108:111]
	v_mfma_f32_16x16x32_bf16 v[112:115], v[166:169], v[226:229], v[112:115]
	v_mfma_f32_16x16x32_bf16 v[52:55], v[174:177], v[226:229], v[52:55]
	s_waitcnt lgkmcnt(2)
	v_mfma_f32_16x16x32_bf16 v[116:119], v[158:161], v[178:181], v[116:119]
	v_mfma_f32_16x16x32_bf16 v[120:123], v[162:165], v[178:181], v[120:123]
	v_mfma_f32_16x16x32_bf16 v[124:127], v[166:169], v[178:181], v[124:127]
	v_mfma_f32_16x16x32_bf16 v[68:71], v[174:177], v[178:181], v[68:71]
	s_waitcnt lgkmcnt(1)
	v_mfma_f32_16x16x32_bf16 v[132:135], v[162:165], v[218:221], v[132:135]
	v_mfma_f32_16x16x32_bf16 v[84:87], v[174:177], v[218:221], v[84:87]
	s_waitcnt lgkmcnt(0)
	v_mfma_f32_16x16x32_bf16 v[100:103], v[158:161], v[222:225], v[100:103]
	v_mfma_f32_16x16x32_bf16 v[150:153], v[166:169], v[222:225], v[150:153]
	v_mfma_f32_16x16x32_bf16 v[154:157], v[174:177], v[222:225], v[154:157]
	v_mfma_f32_16x16x32_bf16 v[128:131], v[158:161], v[218:221], v[128:131]
	v_mfma_f32_16x16x32_bf16 v[136:139], v[166:169], v[218:221], v[136:139]
	v_mfma_f32_16x16x32_bf16 v[140:143], v[162:165], v[222:225], v[140:143]
	s_add_u32 s50, s14, 0x180
	s_addc_u32 s51, s15, 0
	s_add_u32 s52, s20, 0x180
	s_waitcnt vmcnt(0)
	s_barrier
	s_addc_u32 s53, s21, 0
	v_lshl_add_u64 v[158:159], s[50:51], 0, v[0:1]
	s_mov_b32 s47, m0
	s_mov_b32 m0, s27
	s_nop 0
	global_load_lds_dwordx4 v[158:159], off
	s_mov_b32 m0, s47
	v_lshl_add_u64 v[158:159], s[52:53], 0, v[0:1]
	s_mov_b32 s47, m0
	s_mov_b32 m0, s26
	s_nop 0
	global_load_lds_dwordx4 v[158:159], off
	s_mov_b32 m0, s47
	v_lshl_add_u64 v[158:159], s[50:51], 0, v[2:3]
	s_mov_b32 s47, m0
	s_mov_b32 m0, s41
	s_nop 0
	global_load_lds_dwordx4 v[158:159], off
	s_mov_b32 m0, s47
	v_lshl_add_u64 v[158:159], s[52:53], 0, v[2:3]
	s_mov_b32 s47, m0
	s_mov_b32 m0, s42
	s_nop 0
	global_load_lds_dwordx4 v[158:159], off
	s_mov_b32 m0, s47
	v_lshl_add_u64 v[158:159], s[50:51], 0, v[4:5]
	s_mov_b32 s47, m0
	s_mov_b32 m0, s43
	s_nop 0
	global_load_lds_dwordx4 v[158:159], off
	s_mov_b32 m0, s47
	v_lshl_add_u64 v[158:159], s[52:53], 0, v[4:5]
	s_mov_b32 s47, m0
	s_mov_b32 m0, s44
	s_nop 0
	global_load_lds_dwordx4 v[158:159], off
	s_mov_b32 m0, s47
	v_lshl_add_u64 v[158:159], s[50:51], 0, v[146:147]
	s_mov_b32 s47, m0
	s_mov_b32 m0, s45
	s_nop 0
	global_load_lds_dwordx4 v[158:159], off
	s_mov_b32 m0, s47
	v_lshl_add_u64 v[158:159], s[52:53], 0, v[146:147]
	s_mov_b32 s47, m0
	s_mov_b32 m0, s46
	s_nop 0
	global_load_lds_dwordx4 v[158:159], off
	s_mov_b32 m0, s47
	ds_read_b128 v[158:161], v7 offset:32768
	ds_read_b128 v[162:165], v7 offset:34816
	ds_read_b128 v[166:169], v7 offset:36864
	ds_read_b128 v[178:181], v7 offset:38912
	ds_read_b128 v[174:177], v6
	ds_read_b128 v[218:221], v6 offset:2048
	ds_read_b128 v[222:225], v6 offset:4096
	ds_read_b128 v[226:229], v6 offset:6144
	s_waitcnt lgkmcnt(3)
	v_mfma_f32_16x16x32_bf16 v[40:43], v[158:161], v[174:177], v[40:43]
	v_mfma_f32_16x16x32_bf16 v[44:47], v[162:165], v[174:177], v[44:47]
	v_mfma_f32_16x16x32_bf16 v[48:51], v[166:169], v[174:177], v[48:51]
	v_mfma_f32_16x16x32_bf16 v[174:177], v[178:181], v[174:177], v[214:217]
	s_nop 2
	ds_read_b128 v[214:217], v6 offset:8192
	s_waitcnt lgkmcnt(3)
	v_mfma_f32_16x16x32_bf16 v[56:59], v[158:161], v[218:221], v[56:59]
	v_mfma_f32_16x16x32_bf16 v[60:63], v[162:165], v[218:221], v[60:63]
	v_mfma_f32_16x16x32_bf16 v[64:67], v[166:169], v[218:221], v[64:67]
	v_mfma_f32_16x16x32_bf16 v[170:173], v[178:181], v[218:221], v[170:173]
	ds_read_b128 v[218:221], v6 offset:10240
	s_waitcnt lgkmcnt(3)
	v_mfma_f32_16x16x32_bf16 v[72:75], v[158:161], v[222:225], v[72:75]
	v_mfma_f32_16x16x32_bf16 v[76:79], v[162:165], v[222:225], v[76:79]
	v_mfma_f32_16x16x32_bf16 v[80:83], v[166:169], v[222:225], v[80:83]
	v_mfma_f32_16x16x32_bf16 v[32:35], v[178:181], v[222:225], v[32:35]
	ds_read_b128 v[222:225], v6 offset:12288
	s_waitcnt lgkmcnt(3)
	v_mfma_f32_16x16x32_bf16 v[88:91], v[158:161], v[226:229], v[88:91]
	v_mfma_f32_16x16x32_bf16 v[92:95], v[162:165], v[226:229], v[92:95]
	v_mfma_f32_16x16x32_bf16 v[96:99], v[166:169], v[226:229], v[96:99]
	v_mfma_f32_16x16x32_bf16 v[36:39], v[178:181], v[226:229], v[36:39]
	ds_read_b128 v[226:229], v6 offset:14336
	s_waitcnt lgkmcnt(3)
	v_mfma_f32_16x16x32_bf16 v[104:107], v[158:161], v[214:217], v[104:107]
	v_mfma_f32_16x16x32_bf16 v[108:111], v[162:165], v[214:217], v[108:111]
	v_mfma_f32_16x16x32_bf16 v[112:115], v[166:169], v[214:217], v[112:115]
	v_mfma_f32_16x16x32_bf16 v[52:55], v[178:181], v[214:217], v[52:55]
	s_waitcnt lgkmcnt(2)
	v_mfma_f32_16x16x32_bf16 v[116:119], v[158:161], v[218:221], v[116:119]
	v_mfma_f32_16x16x32_bf16 v[120:123], v[162:165], v[218:221], v[120:123]
	v_mfma_f32_16x16x32_bf16 v[124:127], v[166:169], v[218:221], v[124:127]
	v_mfma_f32_16x16x32_bf16 v[68:71], v[178:181], v[218:221], v[68:71]
	s_waitcnt lgkmcnt(1)
	v_mfma_f32_16x16x32_bf16 v[132:135], v[162:165], v[222:225], v[132:135]
	v_mfma_f32_16x16x32_bf16 v[84:87], v[178:181], v[222:225], v[84:87]
	s_waitcnt lgkmcnt(0)
	v_mfma_f32_16x16x32_bf16 v[100:103], v[158:161], v[226:229], v[100:103]
	v_mfma_f32_16x16x32_bf16 v[150:153], v[166:169], v[226:229], v[150:153]
	v_mfma_f32_16x16x32_bf16 v[154:157], v[178:181], v[226:229], v[154:157]
	v_mfma_f32_16x16x32_bf16 v[128:131], v[158:161], v[222:225], v[128:131]
	v_mfma_f32_16x16x32_bf16 v[136:139], v[166:169], v[222:225], v[136:139]
	v_mfma_f32_16x16x32_bf16 v[140:143], v[162:165], v[226:229], v[140:143]
	ds_read_b128 v[158:161], v7 offset:33792
	ds_read_b128 v[162:165], v7 offset:35840
	ds_read_b128 v[166:169], v7 offset:37888
	ds_read_b128 v[214:217], v7 offset:39936
	ds_read_b128 v[178:181], v6 offset:1024
	ds_read_b128 v[218:221], v6 offset:3072
	ds_read_b128 v[222:225], v6 offset:5120
	ds_read_b128 v[226:229], v6 offset:7168
	s_waitcnt lgkmcnt(3)
	v_mfma_f32_16x16x32_bf16 v[40:43], v[158:161], v[178:181], v[40:43]
	v_mfma_f32_16x16x32_bf16 v[44:47], v[162:165], v[178:181], v[44:47]
	v_mfma_f32_16x16x32_bf16 v[48:51], v[166:169], v[178:181], v[48:51]
	v_mfma_f32_16x16x32_bf16 v[174:177], v[214:217], v[178:181], v[174:177]
	ds_read_b128 v[178:181], v6 offset:9216
	s_waitcnt lgkmcnt(3)
	v_mfma_f32_16x16x32_bf16 v[56:59], v[158:161], v[218:221], v[56:59]
	v_mfma_f32_16x16x32_bf16 v[60:63], v[162:165], v[218:221], v[60:63]
	v_mfma_f32_16x16x32_bf16 v[64:67], v[166:169], v[218:221], v[64:67]
	v_mfma_f32_16x16x32_bf16 v[170:173], v[214:217], v[218:221], v[170:173]
	ds_read_b128 v[218:221], v6 offset:11264
	s_waitcnt lgkmcnt(3)
	v_mfma_f32_16x16x32_bf16 v[72:75], v[158:161], v[222:225], v[72:75]
	v_mfma_f32_16x16x32_bf16 v[76:79], v[162:165], v[222:225], v[76:79]
	v_mfma_f32_16x16x32_bf16 v[80:83], v[166:169], v[222:225], v[80:83]
	v_mfma_f32_16x16x32_bf16 v[32:35], v[214:217], v[222:225], v[32:35]
	ds_read_b128 v[222:225], v6 offset:13312
	s_waitcnt lgkmcnt(3)
	v_mfma_f32_16x16x32_bf16 v[88:91], v[158:161], v[226:229], v[88:91]
	v_mfma_f32_16x16x32_bf16 v[92:95], v[162:165], v[226:229], v[92:95]
	v_mfma_f32_16x16x32_bf16 v[96:99], v[166:169], v[226:229], v[96:99]
	v_mfma_f32_16x16x32_bf16 v[36:39], v[214:217], v[226:229], v[36:39]
	ds_read_b128 v[226:229], v6 offset:15360
	s_waitcnt lgkmcnt(3)
	v_mfma_f32_16x16x32_bf16 v[104:107], v[158:161], v[178:181], v[104:107]
	v_mfma_f32_16x16x32_bf16 v[108:111], v[162:165], v[178:181], v[108:111]
	v_mfma_f32_16x16x32_bf16 v[112:115], v[166:169], v[178:181], v[112:115]
	v_mfma_f32_16x16x32_bf16 v[52:55], v[214:217], v[178:181], v[52:55]
	s_waitcnt lgkmcnt(2)
	v_mfma_f32_16x16x32_bf16 v[116:119], v[158:161], v[218:221], v[116:119]
	v_mfma_f32_16x16x32_bf16 v[120:123], v[162:165], v[218:221], v[120:123]
	v_mfma_f32_16x16x32_bf16 v[124:127], v[166:169], v[218:221], v[124:127]
	v_mfma_f32_16x16x32_bf16 v[68:71], v[214:217], v[218:221], v[68:71]
	s_waitcnt lgkmcnt(1)
	v_mfma_f32_16x16x32_bf16 v[132:135], v[162:165], v[222:225], v[132:135]
	v_mfma_f32_16x16x32_bf16 v[84:87], v[214:217], v[222:225], v[84:87]
	s_waitcnt lgkmcnt(0)
	v_mfma_f32_16x16x32_bf16 v[100:103], v[158:161], v[226:229], v[100:103]
	v_mfma_f32_16x16x32_bf16 v[150:153], v[166:169], v[226:229], v[150:153]
	v_mfma_f32_16x16x32_bf16 v[154:157], v[214:217], v[226:229], v[154:157]
	v_mfma_f32_16x16x32_bf16 v[128:131], v[158:161], v[222:225], v[128:131]
	v_mfma_f32_16x16x32_bf16 v[136:139], v[166:169], v[222:225], v[136:139]
	v_mfma_f32_16x16x32_bf16 v[140:143], v[162:165], v[226:229], v[140:143]
	s_add_u32 s50, s14, 0x200
	s_addc_u32 s51, s15, 0
	s_add_u32 s52, s20, 0x200
	s_waitcnt vmcnt(0)
	s_barrier
	s_addc_u32 s53, s21, 0
	s_mov_b32 s47, 0x280
	ds_read_b128 v[158:161], v8
	ds_read_b128 v[162:165], v12
	s_mov_b32 m0, s34
	s_nop 0
	global_load_lds_dwordx4 v0, s[52:53]
	ds_read_b128 v[166:169], v9
	s_mov_b32 m0, s36
	s_nop 0
	global_load_lds_dwordx4 v2, s[52:53]
	ds_read_b128 v[178:181], v13
	ds_read_b128 v[214:217], v11
	s_mov_b32 m0, s38
	s_nop 0
	global_load_lds_dwordx4 v4, s[52:53]
	ds_read_b128 v[218:221], v10
	ds_read_b128 v[222:225], v14
	ds_read_b128 v[226:229], v15
	s_branch .Lmy_rot_r_r2a
.Lmy_rr_r2a:
	ds_read_b128 v[158:161], v8
	ds_read_b128 v[162:165], v12
	s_mov_b32 m0, s34
	v_mfma_f32_16x16x32_bf16 v[128:131], v[166:169], v[222:225], v[128:131]
	global_load_lds_dwordx4 v0, s[52:53]
	v_mfma_f32_16x16x32_bf16 v[100:103], v[166:169], v[226:229], v[100:103]
	ds_read_b128 v[166:169], v9
	v_mfma_f32_16x16x32_bf16 v[132:135], v[178:181], v[222:225], v[132:135]
	s_mov_b32 m0, s36
	v_mfma_f32_16x16x32_bf16 v[140:143], v[178:181], v[226:229], v[140:143]
	global_load_lds_dwordx4 v2, s[52:53]
	ds_read_b128 v[178:181], v13
	v_mfma_f32_16x16x32_bf16 v[136:139], v[214:217], v[222:225], v[136:139]
	v_mfma_f32_16x16x32_bf16 v[150:153], v[214:217], v[226:229], v[150:153]
	ds_read_b128 v[214:217], v11
	s_mov_b32 m0, s38
	v_mfma_f32_16x16x32_bf16 v[84:87], v[218:221], v[222:225], v[84:87]
	global_load_lds_dwordx4 v4, s[52:53]
	v_mfma_f32_16x16x32_bf16 v[154:157], v[218:221], v[226:229], v[154:157]
	ds_read_b128 v[218:221], v10
	ds_read_b128 v[222:225], v14
	ds_read_b128 v[226:229], v15
.Lmy_rot_r_r2a:
	s_waitcnt lgkmcnt(6)
	v_mfma_f32_16x16x32_bf16 v[40:43], v[158:161], v[162:165], v[40:43]
	s_waitcnt lgkmcnt(5)
	s_mov_b32 m0, s40
	v_mfma_f32_16x16x32_bf16 v[44:47], v[166:169], v[162:165], v[44:47]
	global_load_lds_dwordx4 v146, s[52:53]
	s_waitcnt lgkmcnt(4)
	v_mfma_f32_16x16x32_bf16 v[56:59], v[158:161], v[178:181], v[56:59]
	v_mfma_f32_16x16x32_bf16 v[60:63], v[166:169], v[178:181], v[60:63]
	s_waitcnt lgkmcnt(3)
	s_mov_b32 m0, s1
	v_mfma_f32_16x16x32_bf16 v[48:51], v[214:217], v[162:165], v[48:51]
	global_load_lds_dwordx4 v0, s[50:51]
	v_mfma_f32_16x16x32_bf16 v[64:67], v[214:217], v[178:181], v[64:67]
	s_waitcnt lgkmcnt(2)
	v_mfma_f32_16x16x32_bf16 v[174:177], v[218:221], v[162:165], v[174:177]
	ds_read_b128 v[162:165], v16
	s_mov_b32 m0, s35
	v_mfma_f32_16x16x32_bf16 v[170:173], v[218:221], v[178:181], v[170:173]
	global_load_lds_dwordx4 v2, s[50:51]
	ds_read_b128 v[178:181], v17
	s_waitcnt lgkmcnt(3)
	v_mfma_f32_16x16x32_bf16 v[72:75], v[158:161], v[222:225], v[72:75]
	v_mfma_f32_16x16x32_bf16 v[76:79], v[166:169], v[222:225], v[76:79]
	s_mov_b32 m0, s37
	v_mfma_f32_16x16x32_bf16 v[80:83], v[214:217], v[222:225], v[80:83]
	global_load_lds_dwordx4 v4, s[50:51]
	v_mfma_f32_16x16x32_bf16 v[32:35], v[218:221], v[222:225], v[32:35]
	ds_read_b128 v[222:225], v18
	s_waitcnt lgkmcnt(3)
	v_mfma_f32_16x16x32_bf16 v[88:91], v[158:161], v[226:229], v[88:91]
	s_mov_b32 m0, s39
	v_mfma_f32_16x16x32_bf16 v[92:95], v[166:169], v[226:229], v[92:95]
	global_load_lds_dwordx4 v146, s[50:51]
	v_mfma_f32_16x16x32_bf16 v[96:99], v[214:217], v[226:229], v[96:99]
	v_mfma_f32_16x16x32_bf16 v[36:39], v[218:221], v[226:229], v[36:39]
	ds_read_b128 v[226:229], v19
	s_waitcnt lgkmcnt(3)
	v_mfma_f32_16x16x32_bf16 v[108:111], v[166:169], v[162:165], v[108:111]
	s_waitcnt lgkmcnt(2)
	v_mfma_f32_16x16x32_bf16 v[120:123], v[166:169], v[178:181], v[120:123]
	s_waitcnt lgkmcnt(1)
	v_mfma_f32_16x16x32_bf16 v[132:135], v[166:169], v[222:225], v[132:135]
	s_waitcnt lgkmcnt(0)
	v_mfma_f32_16x16x32_bf16 v[140:143], v[166:169], v[226:229], v[140:143]
	ds_read_b128 v[166:169], v20
	v_mfma_f32_16x16x32_bf16 v[104:107], v[158:161], v[162:165], v[104:107]
	v_mfma_f32_16x16x32_bf16 v[116:119], v[158:161], v[178:181], v[116:119]
	v_mfma_f32_16x16x32_bf16 v[128:131], v[158:161], v[222:225], v[128:131]
	v_mfma_f32_16x16x32_bf16 v[100:103], v[158:161], v[226:229], v[100:103]
	ds_read_b128 v[158:161], v24
	v_mfma_f32_16x16x32_bf16 v[124:127], v[214:217], v[178:181], v[124:127]
	v_mfma_f32_16x16x32_bf16 v[68:71], v[218:221], v[178:181], v[68:71]
	ds_read_b128 v[178:181], v21
	v_mfma_f32_16x16x32_bf16 v[112:115], v[214:217], v[162:165], v[112:115]
	v_mfma_f32_16x16x32_bf16 v[52:55], v[218:221], v[162:165], v[52:55]
	ds_read_b128 v[162:165], v25
	v_mfma_f32_16x16x32_bf16 v[136:139], v[214:217], v[222:225], v[136:139]
	v_mfma_f32_16x16x32_bf16 v[84:87], v[218:221], v[222:225], v[84:87]
	ds_read_b128 v[222:225], v26
	v_mfma_f32_16x16x32_bf16 v[150:153], v[214:217], v[226:229], v[150:153]
	ds_read_b128 v[214:217], v23
	v_mfma_f32_16x16x32_bf16 v[154:157], v[218:221], v[226:229], v[154:157]
	ds_read_b128 v[218:221], v22
	ds_read_b128 v[226:229], v27
	s_waitcnt lgkmcnt(6)
	v_mfma_f32_16x16x32_bf16 v[40:43], v[166:169], v[158:161], v[40:43]
	s_waitcnt lgkmcnt(5)
	v_mfma_f32_16x16x32_bf16 v[44:47], v[178:181], v[158:161], v[44:47]
	s_waitcnt lgkmcnt(4)
	v_mfma_f32_16x16x32_bf16 v[56:59], v[166:169], v[162:165], v[56:59]
	v_mfma_f32_16x16x32_bf16 v[60:63], v[178:181], v[162:165], v[60:63]
	s_waitcnt lgkmcnt(3)
	v_mfma_f32_16x16x32_bf16 v[72:75], v[166:169], v[222:225], v[72:75]
	v_mfma_f32_16x16x32_bf16 v[76:79], v[178:181], v[222:225], v[76:79]
	s_waitcnt lgkmcnt(2)
	v_mfma_f32_16x16x32_bf16 v[48:51], v[214:217], v[158:161], v[48:51]
	s_waitcnt lgkmcnt(1)
	v_mfma_f32_16x16x32_bf16 v[174:177], v[218:221], v[158:161], v[174:177]
	ds_read_b128 v[158:161], v28
	v_mfma_f32_16x16x32_bf16 v[64:67], v[214:217], v[162:165], v[64:67]
	v_mfma_f32_16x16x32_bf16 v[170:173], v[218:221], v[162:165], v[170:173]
	ds_read_b128 v[162:165], v29
	v_mfma_f32_16x16x32_bf16 v[80:83], v[214:217], v[222:225], v[80:83]
	v_mfma_f32_16x16x32_bf16 v[32:35], v[218:221], v[222:225], v[32:35]
	ds_read_b128 v[222:225], v30
	s_waitcnt lgkmcnt(3)
	v_mfma_f32_16x16x32_bf16 v[88:91], v[166:169], v[226:229], v[88:91]
	v_mfma_f32_16x16x32_bf16 v[92:95], v[178:181], v[226:229], v[92:95]
	v_mfma_f32_16x16x32_bf16 v[96:99], v[214:217], v[226:229], v[96:99]
	v_mfma_f32_16x16x32_bf16 v[36:39], v[218:221], v[226:229], v[36:39]
	ds_read_b128 v[226:229], v31
	s_waitcnt lgkmcnt(3)
	v_mfma_f32_16x16x32_bf16 v[104:107], v[166:169], v[158:161], v[104:107]
	v_mfma_f32_16x16x32_bf16 v[108:111], v[178:181], v[158:161], v[108:111]
	v_mfma_f32_16x16x32_bf16 v[112:115], v[214:217], v[158:161], v[112:115]
	v_mfma_f32_16x16x32_bf16 v[52:55], v[218:221], v[158:161], v[52:55]
	s_waitcnt lgkmcnt(2)
	v_mfma_f32_16x16x32_bf16 v[116:119], v[166:169], v[162:165], v[116:119]
	v_mfma_f32_16x16x32_bf16 v[120:123], v[178:181], v[162:165], v[120:123]
	v_mfma_f32_16x16x32_bf16 v[124:127], v[214:217], v[162:165], v[124:127]
	v_mfma_f32_16x16x32_bf16 v[68:71], v[218:221], v[162:165], v[68:71]
	s_add_u32 s50, s14, s47
	s_addc_u32 s51, s15, 0
	s_add_u32 s52, s20, s47
	s_addc_u32 s53, s21, 0
	s_add_u32 s47, s47, 0x80
	s_waitcnt vmcnt(0)
	s_waitcnt lgkmcnt(0)
	s_barrier
	ds_read_b128 v[158:161], v7 offset:32768
	ds_read_b128 v[162:165], v6
	s_mov_b32 m0, s26
	v_mfma_f32_16x16x32_bf16 v[128:131], v[166:169], v[222:225], v[128:131]
	global_load_lds_dwordx4 v0, s[52:53]
	v_mfma_f32_16x16x32_bf16 v[100:103], v[166:169], v[226:229], v[100:103]
	ds_read_b128 v[166:169], v7 offset:34816
	v_mfma_f32_16x16x32_bf16 v[132:135], v[178:181], v[222:225], v[132:135]
	s_mov_b32 m0, s42
	v_mfma_f32_16x16x32_bf16 v[140:143], v[178:181], v[226:229], v[140:143]
	global_load_lds_dwordx4 v2, s[52:53]
	ds_read_b128 v[178:181], v6 offset:2048
	v_mfma_f32_16x16x32_bf16 v[136:139], v[214:217], v[222:225], v[136:139]
	v_mfma_f32_16x16x32_bf16 v[150:153], v[214:217], v[226:229], v[150:153]
	ds_read_b128 v[214:217], v7 offset:36864
	s_mov_b32 m0, s44
	v_mfma_f32_16x16x32_bf16 v[84:87], v[218:221], v[222:225], v[84:87]
	global_load_lds_dwordx4 v4, s[52:53]
	v_mfma_f32_16x16x32_bf16 v[154:157], v[218:221], v[226:229], v[154:157]
	ds_read_b128 v[218:221], v7 offset:38912
	ds_read_b128 v[222:225], v6 offset:4096
	ds_read_b128 v[226:229], v6 offset:6144
	s_waitcnt lgkmcnt(6)
	v_mfma_f32_16x16x32_bf16 v[40:43], v[158:161], v[162:165], v[40:43]
	s_waitcnt lgkmcnt(5)
	s_mov_b32 m0, s46
	v_mfma_f32_16x16x32_bf16 v[44:47], v[166:169], v[162:165], v[44:47]
	global_load_lds_dwordx4 v146, s[52:53]
	s_waitcnt lgkmcnt(4)
	v_mfma_f32_16x16x32_bf16 v[56:59], v[158:161], v[178:181], v[56:59]
	v_mfma_f32_16x16x32_bf16 v[60:63], v[166:169], v[178:181], v[60:63]
	s_waitcnt lgkmcnt(3)
	s_mov_b32 m0, s27
	v_mfma_f32_16x16x32_bf16 v[48:51], v[214:217], v[162:165], v[48:51]
	global_load_lds_dwordx4 v0, s[50:51]
	v_mfma_f32_16x16x32_bf16 v[64:67], v[214:217], v[178:181], v[64:67]
	s_waitcnt lgkmcnt(2)
	v_mfma_f32_16x16x32_bf16 v[174:177], v[218:221], v[162:165], v[174:177]
	ds_read_b128 v[162:165], v6 offset:8192
	s_mov_b32 m0, s41
	v_mfma_f32_16x16x32_bf16 v[170:173], v[218:221], v[178:181], v[170:173]
	global_load_lds_dwordx4 v2, s[50:51]
	ds_read_b128 v[178:181], v6 offset:10240
	s_waitcnt lgkmcnt(3)
	v_mfma_f32_16x16x32_bf16 v[72:75], v[158:161], v[222:225], v[72:75]
	v_mfma_f32_16x16x32_bf16 v[76:79], v[166:169], v[222:225], v[76:79]
	s_mov_b32 m0, s43
	v_mfma_f32_16x16x32_bf16 v[80:83], v[214:217], v[222:225], v[80:83]
	global_load_lds_dwordx4 v4, s[50:51]
	v_mfma_f32_16x16x32_bf16 v[32:35], v[218:221], v[222:225], v[32:35]
	ds_read_b128 v[222:225], v6 offset:12288
	s_waitcnt lgkmcnt(3)
	v_mfma_f32_16x16x32_bf16 v[88:91], v[158:161], v[226:229], v[88:91]
	s_mov_b32 m0, s45
	v_mfma_f32_16x16x32_bf16 v[92:95], v[166:169], v[226:229], v[92:95]
	global_load_lds_dwordx4 v146, s[50:51]
	v_mfma_f32_16x16x32_bf16 v[96:99], v[214:217], v[226:229], v[96:99]
	v_mfma_f32_16x16x32_bf16 v[36:39], v[218:221], v[226:229], v[36:39]
	ds_read_b128 v[226:229], v6 offset:14336
	s_waitcnt lgkmcnt(3)
	v_mfma_f32_16x16x32_bf16 v[108:111], v[166:169], v[162:165], v[108:111]
	s_waitcnt lgkmcnt(2)
	v_mfma_f32_16x16x32_bf16 v[120:123], v[166:169], v[178:181], v[120:123]
	s_waitcnt lgkmcnt(1)
	v_mfma_f32_16x16x32_bf16 v[132:135], v[166:169], v[222:225], v[132:135]
	s_waitcnt lgkmcnt(0)
	v_mfma_f32_16x16x32_bf16 v[140:143], v[166:169], v[226:229], v[140:143]
	ds_read_b128 v[166:169], v7 offset:33792
	v_mfma_f32_16x16x32_bf16 v[104:107], v[158:161], v[162:165], v[104:107]
	v_mfma_f32_16x16x32_bf16 v[116:119], v[158:161], v[178:181], v[116:119]
	v_mfma_f32_16x16x32_bf16 v[128:131], v[158:161], v[222:225], v[128:131]
	v_mfma_f32_16x16x32_bf16 v[100:103], v[158:161], v[226:229], v[100:103]
	ds_read_b128 v[158:161], v6 offset:1024
	v_mfma_f32_16x16x32_bf16 v[124:127], v[214:217], v[178:181], v[124:127]
	v_mfma_f32_16x16x32_bf16 v[68:71], v[218:221], v[178:181], v[68:71]
	ds_read_b128 v[178:181], v7 offset:35840
	v_mfma_f32_16x16x32_bf16 v[112:115], v[214:217], v[162:165], v[112:115]
	v_mfma_f32_16x16x32_bf16 v[52:55], v[218:221], v[162:165], v[52:55]
	ds_read_b128 v[162:165], v6 offset:3072
	v_mfma_f32_16x16x32_bf16 v[136:139], v[214:217], v[222:225], v[136:139]
	v_mfma_f32_16x16x32_bf16 v[84:87], v[218:221], v[222:225], v[84:87]
	ds_read_b128 v[222:225], v6 offset:5120
	v_mfma_f32_16x16x32_bf16 v[150:153], v[214:217], v[226:229], v[150:153]
	ds_read_b128 v[214:217], v7 offset:37888
	v_mfma_f32_16x16x32_bf16 v[154:157], v[218:221], v[226:229], v[154:157]
	ds_read_b128 v[218:221], v7 offset:39936
	ds_read_b128 v[226:229], v6 offset:7168
	s_waitcnt lgkmcnt(6)
	v_mfma_f32_16x16x32_bf16 v[40:43], v[166:169], v[158:161], v[40:43]
	s_waitcnt lgkmcnt(5)
	v_mfma_f32_16x16x32_bf16 v[44:47], v[178:181], v[158:161], v[44:47]
	s_waitcnt lgkmcnt(4)
	v_mfma_f32_16x16x32_bf16 v[56:59], v[166:169], v[162:165], v[56:59]
	v_mfma_f32_16x16x32_bf16 v[60:63], v[178:181], v[162:165], v[60:63]
	s_waitcnt lgkmcnt(3)
	v_mfma_f32_16x16x32_bf16 v[72:75], v[166:169], v[222:225], v[72:75]
	v_mfma_f32_16x16x32_bf16 v[76:79], v[178:181], v[222:225], v[76:79]
	s_waitcnt lgkmcnt(2)
	v_mfma_f32_16x16x32_bf16 v[48:51], v[214:217], v[158:161], v[48:51]
	s_waitcnt lgkmcnt(1)
	v_mfma_f32_16x16x32_bf16 v[174:177], v[218:221], v[158:161], v[174:177]
	ds_read_b128 v[158:161], v6 offset:9216
	v_mfma_f32_16x16x32_bf16 v[64:67], v[214:217], v[162:165], v[64:67]
	v_mfma_f32_16x16x32_bf16 v[170:173], v[218:221], v[162:165], v[170:173]
	ds_read_b128 v[162:165], v6 offset:11264
	v_mfma_f32_16x16x32_bf16 v[80:83], v[214:217], v[222:225], v[80:83]
	v_mfma_f32_16x16x32_bf16 v[32:35], v[218:221], v[222:225], v[32:35]
	ds_read_b128 v[222:225], v6 offset:13312
	s_waitcnt lgkmcnt(3)
	v_mfma_f32_16x16x32_bf16 v[88:91], v[166:169], v[226:229], v[88:91]
	v_mfma_f32_16x16x32_bf16 v[92:95], v[178:181], v[226:229], v[92:95]
	v_mfma_f32_16x16x32_bf16 v[96:99], v[214:217], v[226:229], v[96:99]
	v_mfma_f32_16x16x32_bf16 v[36:39], v[218:221], v[226:229], v[36:39]
	ds_read_b128 v[226:229], v6 offset:15360
	s_waitcnt lgkmcnt(3)
	v_mfma_f32_16x16x32_bf16 v[104:107], v[166:169], v[158:161], v[104:107]
	v_mfma_f32_16x16x32_bf16 v[108:111], v[178:181], v[158:161], v[108:111]
	v_mfma_f32_16x16x32_bf16 v[112:115], v[214:217], v[158:161], v[112:115]
	v_mfma_f32_16x16x32_bf16 v[52:55], v[218:221], v[158:161], v[52:55]
	s_waitcnt lgkmcnt(2)
	v_mfma_f32_16x16x32_bf16 v[116:119], v[166:169], v[162:165], v[116:119]
	v_mfma_f32_16x16x32_bf16 v[120:123], v[178:181], v[162:165], v[120:123]
	v_mfma_f32_16x16x32_bf16 v[124:127], v[214:217], v[162:165], v[124:127]
	v_mfma_f32_16x16x32_bf16 v[68:71], v[218:221], v[162:165], v[68:71]
	s_add_u32 s50, s14, s47
	s_addc_u32 s51, s15, 0
	s_add_u32 s52, s20, s47
	s_addc_u32 s53, s21, 0
	s_add_u32 s47, s47, 0x80
	s_cmp_lg_u32 s47, 0xf80
	s_waitcnt vmcnt(0)
	s_waitcnt lgkmcnt(0)
	s_barrier
	s_cbranch_scc1 .Lmy_rr_r2a
	v_mfma_f32_16x16x32_bf16 v[128:131], v[166:169], v[222:225], v[128:131]
	v_mfma_f32_16x16x32_bf16 v[100:103], v[166:169], v[226:229], v[100:103]
	v_mfma_f32_16x16x32_bf16 v[132:135], v[178:181], v[222:225], v[132:135]
	v_mfma_f32_16x16x32_bf16 v[140:143], v[178:181], v[226:229], v[140:143]
	v_mfma_f32_16x16x32_bf16 v[136:139], v[214:217], v[222:225], v[136:139]
	v_mfma_f32_16x16x32_bf16 v[150:153], v[214:217], v[226:229], v[150:153]
	v_mfma_f32_16x16x32_bf16 v[84:87], v[218:221], v[222:225], v[84:87]
	v_mfma_f32_16x16x32_bf16 v[154:157], v[218:221], v[226:229], v[154:157]
	s_nop 15
	s_nop 15
	v_lshl_add_u64 v[158:159], s[50:51], 0, v[0:1]
	s_mov_b32 s47, m0
	s_mov_b32 m0, s1
	s_nop 0
	global_load_lds_dwordx4 v[158:159], off
	s_mov_b32 m0, s47
	v_lshl_add_u64 v[158:159], s[52:53], 0, v[0:1]
	s_mov_b32 s47, m0
	s_mov_b32 m0, s34
	s_nop 0
	global_load_lds_dwordx4 v[158:159], off
	s_mov_b32 m0, s47
	v_lshl_add_u64 v[158:159], s[50:51], 0, v[2:3]
	s_mov_b32 s47, m0
	s_mov_b32 m0, s35
	s_nop 0
	global_load_lds_dwordx4 v[158:159], off
	s_mov_b32 m0, s47
	v_lshl_add_u64 v[158:159], s[52:53], 0, v[2:3]
	s_mov_b32 s47, m0
	s_mov_b32 m0, s36
	s_nop 0
	global_load_lds_dwordx4 v[158:159], off
	s_mov_b32 m0, s47
	v_lshl_add_u64 v[158:159], s[50:51], 0, v[4:5]
	s_mov_b32 s47, m0
	s_mov_b32 m0, s37
	s_nop 0
	global_load_lds_dwordx4 v[158:159], off
	s_mov_b32 m0, s47
	v_lshl_add_u64 v[158:159], s[52:53], 0, v[4:5]
	s_mov_b32 s47, m0
	s_mov_b32 m0, s38
	s_nop 0
	global_load_lds_dwordx4 v[158:159], off
	s_mov_b32 m0, s47
	v_lshl_add_u64 v[158:159], s[50:51], 0, v[146:147]
	s_mov_b32 s47, m0
	s_mov_b32 m0, s39
	s_nop 0
	global_load_lds_dwordx4 v[158:159], off
	s_mov_b32 m0, s47
	v_lshl_add_u64 v[158:159], s[52:53], 0, v[146:147]
	s_mov_b32 s47, m0
	s_mov_b32 m0, s40
	s_nop 0
	global_load_lds_dwordx4 v[158:159], off
	s_mov_b32 m0, s47
	ds_read_b128 v[158:161], v8
	ds_read_b128 v[162:165], v9
	ds_read_b128 v[166:169], v11
	ds_read_b128 v[214:217], v10
	ds_read_b128 v[178:181], v12
	ds_read_b128 v[218:221], v13
	ds_read_b128 v[222:225], v14
	ds_read_b128 v[226:229], v15
	s_waitcnt lgkmcnt(3)
	v_mfma_f32_16x16x32_bf16 v[40:43], v[158:161], v[178:181], v[40:43]
	v_mfma_f32_16x16x32_bf16 v[44:47], v[162:165], v[178:181], v[44:47]
	v_mfma_f32_16x16x32_bf16 v[48:51], v[166:169], v[178:181], v[48:51]
	v_mfma_f32_16x16x32_bf16 v[174:177], v[214:217], v[178:181], v[174:177]
	ds_read_b128 v[178:181], v16
	s_waitcnt lgkmcnt(3)
	v_mfma_f32_16x16x32_bf16 v[56:59], v[158:161], v[218:221], v[56:59]
	v_mfma_f32_16x16x32_bf16 v[60:63], v[162:165], v[218:221], v[60:63]
	v_mfma_f32_16x16x32_bf16 v[64:67], v[166:169], v[218:221], v[64:67]
	v_mfma_f32_16x16x32_bf16 v[170:173], v[214:217], v[218:221], v[170:173]
	ds_read_b128 v[218:221], v17
	s_waitcnt lgkmcnt(3)
	v_mfma_f32_16x16x32_bf16 v[72:75], v[158:161], v[222:225], v[72:75]
	v_mfma_f32_16x16x32_bf16 v[76:79], v[162:165], v[222:225], v[76:79]
	v_mfma_f32_16x16x32_bf16 v[80:83], v[166:169], v[222:225], v[80:83]
	v_mfma_f32_16x16x32_bf16 v[32:35], v[214:217], v[222:225], v[32:35]
	ds_read_b128 v[222:225], v18
	s_waitcnt lgkmcnt(3)
	v_mfma_f32_16x16x32_bf16 v[88:91], v[158:161], v[226:229], v[88:91]
	v_mfma_f32_16x16x32_bf16 v[92:95], v[162:165], v[226:229], v[92:95]
	v_mfma_f32_16x16x32_bf16 v[96:99], v[166:169], v[226:229], v[96:99]
	v_mfma_f32_16x16x32_bf16 v[36:39], v[214:217], v[226:229], v[36:39]
	ds_read_b128 v[226:229], v19
	s_waitcnt lgkmcnt(3)
	v_mfma_f32_16x16x32_bf16 v[104:107], v[158:161], v[178:181], v[104:107]
	v_mfma_f32_16x16x32_bf16 v[108:111], v[162:165], v[178:181], v[108:111]
	v_mfma_f32_16x16x32_bf16 v[112:115], v[166:169], v[178:181], v[112:115]
	v_mfma_f32_16x16x32_bf16 v[52:55], v[214:217], v[178:181], v[52:55]
	s_waitcnt lgkmcnt(2)
	v_mfma_f32_16x16x32_bf16 v[116:119], v[158:161], v[218:221], v[116:119]
	v_mfma_f32_16x16x32_bf16 v[120:123], v[162:165], v[218:221], v[120:123]
	v_mfma_f32_16x16x32_bf16 v[124:127], v[166:169], v[218:221], v[124:127]
	v_mfma_f32_16x16x32_bf16 v[68:71], v[214:217], v[218:221], v[68:71]
	s_waitcnt lgkmcnt(1)
	v_mfma_f32_16x16x32_bf16 v[132:135], v[162:165], v[222:225], v[132:135]
	v_mfma_f32_16x16x32_bf16 v[84:87], v[214:217], v[222:225], v[84:87]
	s_waitcnt lgkmcnt(0)
	v_mfma_f32_16x16x32_bf16 v[100:103], v[158:161], v[226:229], v[100:103]
	v_mfma_f32_16x16x32_bf16 v[150:153], v[166:169], v[226:229], v[150:153]
	v_mfma_f32_16x16x32_bf16 v[154:157], v[214:217], v[226:229], v[154:157]
	v_mfma_f32_16x16x32_bf16 v[128:131], v[158:161], v[222:225], v[128:131]
	v_mfma_f32_16x16x32_bf16 v[136:139], v[166:169], v[222:225], v[136:139]
	v_mfma_f32_16x16x32_bf16 v[140:143], v[162:165], v[226:229], v[140:143]
	ds_read_b128 v[158:161], v20
	ds_read_b128 v[162:165], v21
	ds_read_b128 v[166:169], v23
	ds_read_b128 v[214:217], v22
	ds_read_b128 v[178:181], v24
	ds_read_b128 v[218:221], v25
	ds_read_b128 v[222:225], v26
	ds_read_b128 v[226:229], v27
	s_waitcnt lgkmcnt(3)
	v_mfma_f32_16x16x32_bf16 v[40:43], v[158:161], v[178:181], v[40:43]
	v_mfma_f32_16x16x32_bf16 v[44:47], v[162:165], v[178:181], v[44:47]
	v_mfma_f32_16x16x32_bf16 v[48:51], v[166:169], v[178:181], v[48:51]
	v_mfma_f32_16x16x32_bf16 v[174:177], v[214:217], v[178:181], v[174:177]
	ds_read_b128 v[178:181], v28
	s_waitcnt lgkmcnt(3)
	v_mfma_f32_16x16x32_bf16 v[56:59], v[158:161], v[218:221], v[56:59]
	v_mfma_f32_16x16x32_bf16 v[60:63], v[162:165], v[218:221], v[60:63]
	v_mfma_f32_16x16x32_bf16 v[64:67], v[166:169], v[218:221], v[64:67]
	v_mfma_f32_16x16x32_bf16 v[170:173], v[214:217], v[218:221], v[170:173]
	ds_read_b128 v[218:221], v29
	s_waitcnt lgkmcnt(3)
	v_mfma_f32_16x16x32_bf16 v[72:75], v[158:161], v[222:225], v[72:75]
	v_mfma_f32_16x16x32_bf16 v[76:79], v[162:165], v[222:225], v[76:79]
	v_mfma_f32_16x16x32_bf16 v[80:83], v[166:169], v[222:225], v[80:83]
	v_mfma_f32_16x16x32_bf16 v[32:35], v[214:217], v[222:225], v[32:35]
	ds_read_b128 v[222:225], v30
	s_waitcnt lgkmcnt(3)
	v_mfma_f32_16x16x32_bf16 v[88:91], v[158:161], v[226:229], v[88:91]
	v_mfma_f32_16x16x32_bf16 v[92:95], v[162:165], v[226:229], v[92:95]
	v_mfma_f32_16x16x32_bf16 v[96:99], v[166:169], v[226:229], v[96:99]
	v_mfma_f32_16x16x32_bf16 v[36:39], v[214:217], v[226:229], v[36:39]
	ds_read_b128 v[226:229], v31
	s_waitcnt lgkmcnt(3)
	v_mfma_f32_16x16x32_bf16 v[104:107], v[158:161], v[178:181], v[104:107]
	v_mfma_f32_16x16x32_bf16 v[108:111], v[162:165], v[178:181], v[108:111]
	v_mfma_f32_16x16x32_bf16 v[112:115], v[166:169], v[178:181], v[112:115]
	v_mfma_f32_16x16x32_bf16 v[52:55], v[214:217], v[178:181], v[52:55]
	s_waitcnt lgkmcnt(2)
	v_mfma_f32_16x16x32_bf16 v[116:119], v[158:161], v[218:221], v[116:119]
	v_mfma_f32_16x16x32_bf16 v[120:123], v[162:165], v[218:221], v[120:123]
	v_mfma_f32_16x16x32_bf16 v[124:127], v[166:169], v[218:221], v[124:127]
	v_mfma_f32_16x16x32_bf16 v[68:71], v[214:217], v[218:221], v[68:71]
	s_waitcnt lgkmcnt(1)
	v_mfma_f32_16x16x32_bf16 v[132:135], v[162:165], v[222:225], v[132:135]
	v_mfma_f32_16x16x32_bf16 v[84:87], v[214:217], v[222:225], v[84:87]
	s_waitcnt lgkmcnt(0)
	v_mfma_f32_16x16x32_bf16 v[100:103], v[158:161], v[226:229], v[100:103]
	v_mfma_f32_16x16x32_bf16 v[150:153], v[166:169], v[226:229], v[150:153]
	v_mfma_f32_16x16x32_bf16 v[154:157], v[214:217], v[226:229], v[154:157]
	v_mfma_f32_16x16x32_bf16 v[128:131], v[158:161], v[222:225], v[128:131]
	v_mfma_f32_16x16x32_bf16 v[136:139], v[166:169], v[222:225], v[136:139]
	v_mfma_f32_16x16x32_bf16 v[140:143], v[162:165], v[226:229], v[140:143]
	s_add_u32 s14, s14, 0xf80
	s_addc_u32 s15, s15, 0
	s_add_u32 s20, s20, 0xf80
	s_waitcnt vmcnt(0)
	s_barrier
	s_addc_u32 s21, s21, 0
	v_lshl_add_u64 v[158:159], s[14:15], 0, v[0:1]
	s_mov_b32 s47, m0
	s_mov_b32 m0, s27
	s_nop 0
	global_load_lds_dwordx4 v[158:159], off
	s_mov_b32 m0, s47
	v_lshl_add_u64 v[158:159], s[20:21], 0, v[0:1]
	s_mov_b32 s27, m0
	s_mov_b32 m0, s26
	s_nop 0
	global_load_lds_dwordx4 v[158:159], off
	s_mov_b32 m0, s27
	v_lshl_add_u64 v[158:159], s[14:15], 0, v[2:3]
	s_mov_b32 s26, m0
	s_mov_b32 m0, s41
	s_nop 0
	global_load_lds_dwordx4 v[158:159], off
	s_mov_b32 m0, s26
	v_lshl_add_u64 v[158:159], s[20:21], 0, v[2:3]
	s_mov_b32 s26, m0
	s_mov_b32 m0, s42
	s_nop 0
	global_load_lds_dwordx4 v[158:159], off
	s_mov_b32 m0, s26
	v_lshl_add_u64 v[158:159], s[14:15], 0, v[4:5]
	s_mov_b32 s26, m0
	s_mov_b32 m0, s43
	s_nop 0
	global_load_lds_dwordx4 v[158:159], off
	s_mov_b32 m0, s26
	v_lshl_add_u64 v[158:159], s[20:21], 0, v[4:5]
	s_mov_b32 s26, m0
	s_mov_b32 m0, s44
	s_nop 0
	global_load_lds_dwordx4 v[158:159], off
	s_mov_b32 m0, s26
	v_lshl_add_u64 v[158:159], s[14:15], 0, v[146:147]
	s_mov_b32 s14, m0
	s_mov_b32 m0, s45
	s_nop 0
	global_load_lds_dwordx4 v[158:159], off
	s_mov_b32 m0, s14
	v_lshl_add_u64 v[158:159], s[20:21], 0, v[146:147]
	s_mov_b32 s14, m0
	s_mov_b32 m0, s46
	s_nop 0
	global_load_lds_dwordx4 v[158:159], off
	s_mov_b32 m0, s14
	ds_read_b128 v[158:161], v7 offset:32768
	ds_read_b128 v[162:165], v7 offset:34816
	ds_read_b128 v[166:169], v7 offset:36864
	ds_read_b128 v[214:217], v7 offset:38912
	ds_read_b128 v[178:181], v6
	ds_read_b128 v[218:221], v6 offset:2048
	ds_read_b128 v[222:225], v6 offset:4096
	ds_read_b128 v[226:229], v6 offset:6144
	s_waitcnt lgkmcnt(3)
	v_mfma_f32_16x16x32_bf16 v[40:43], v[158:161], v[178:181], v[40:43]
	v_mfma_f32_16x16x32_bf16 v[44:47], v[162:165], v[178:181], v[44:47]
	v_mfma_f32_16x16x32_bf16 v[48:51], v[166:169], v[178:181], v[48:51]
	v_mfma_f32_16x16x32_bf16 v[174:177], v[214:217], v[178:181], v[174:177]
	ds_read_b128 v[178:181], v6 offset:8192
	s_waitcnt lgkmcnt(3)
	v_mfma_f32_16x16x32_bf16 v[56:59], v[158:161], v[218:221], v[56:59]
	v_mfma_f32_16x16x32_bf16 v[60:63], v[162:165], v[218:221], v[60:63]
	v_mfma_f32_16x16x32_bf16 v[64:67], v[166:169], v[218:221], v[64:67]
	v_mfma_f32_16x16x32_bf16 v[170:173], v[214:217], v[218:221], v[170:173]
	ds_read_b128 v[218:221], v6 offset:10240
	s_waitcnt lgkmcnt(3)
	v_mfma_f32_16x16x32_bf16 v[72:75], v[158:161], v[222:225], v[72:75]
	v_mfma_f32_16x16x32_bf16 v[76:79], v[162:165], v[222:225], v[76:79]
	v_mfma_f32_16x16x32_bf16 v[80:83], v[166:169], v[222:225], v[80:83]
	v_mfma_f32_16x16x32_bf16 v[32:35], v[214:217], v[222:225], v[32:35]
	ds_read_b128 v[222:225], v6 offset:12288
	s_waitcnt lgkmcnt(3)
	v_mfma_f32_16x16x32_bf16 v[88:91], v[158:161], v[226:229], v[88:91]
	v_mfma_f32_16x16x32_bf16 v[92:95], v[162:165], v[226:229], v[92:95]
	v_mfma_f32_16x16x32_bf16 v[96:99], v[166:169], v[226:229], v[96:99]
	v_mfma_f32_16x16x32_bf16 v[36:39], v[214:217], v[226:229], v[36:39]
	ds_read_b128 v[226:229], v6 offset:14336
	s_waitcnt lgkmcnt(3)
	v_mfma_f32_16x16x32_bf16 v[104:107], v[158:161], v[178:181], v[104:107]
	v_mfma_f32_16x16x32_bf16 v[108:111], v[162:165], v[178:181], v[108:111]
	v_mfma_f32_16x16x32_bf16 v[112:115], v[166:169], v[178:181], v[112:115]
	v_mfma_f32_16x16x32_bf16 v[52:55], v[214:217], v[178:181], v[52:55]
	s_waitcnt lgkmcnt(2)
	v_mfma_f32_16x16x32_bf16 v[116:119], v[158:161], v[218:221], v[116:119]
	v_mfma_f32_16x16x32_bf16 v[120:123], v[162:165], v[218:221], v[120:123]
	v_mfma_f32_16x16x32_bf16 v[124:127], v[166:169], v[218:221], v[124:127]
	v_mfma_f32_16x16x32_bf16 v[68:71], v[214:217], v[218:221], v[68:71]
	s_waitcnt lgkmcnt(1)
	v_mfma_f32_16x16x32_bf16 v[132:135], v[162:165], v[222:225], v[132:135]
	v_mfma_f32_16x16x32_bf16 v[84:87], v[214:217], v[222:225], v[84:87]
	s_waitcnt lgkmcnt(0)
	v_mfma_f32_16x16x32_bf16 v[100:103], v[158:161], v[226:229], v[100:103]
	v_mfma_f32_16x16x32_bf16 v[150:153], v[166:169], v[226:229], v[150:153]
	v_mfma_f32_16x16x32_bf16 v[154:157], v[214:217], v[226:229], v[154:157]
	v_mfma_f32_16x16x32_bf16 v[128:131], v[158:161], v[222:225], v[128:131]
	v_mfma_f32_16x16x32_bf16 v[136:139], v[166:169], v[222:225], v[136:139]
	v_mfma_f32_16x16x32_bf16 v[140:143], v[162:165], v[226:229], v[140:143]
	ds_read_b128 v[158:161], v7 offset:33792
	ds_read_b128 v[162:165], v7 offset:35840
	ds_read_b128 v[166:169], v7 offset:37888
	ds_read_b128 v[214:217], v7 offset:39936
	ds_read_b128 v[178:181], v6 offset:1024
	ds_read_b128 v[218:221], v6 offset:3072
	ds_read_b128 v[222:225], v6 offset:5120
	ds_read_b128 v[226:229], v6 offset:7168
	s_waitcnt lgkmcnt(3)
	v_mfma_f32_16x16x32_bf16 v[40:43], v[158:161], v[178:181], v[40:43]
	v_mfma_f32_16x16x32_bf16 v[44:47], v[162:165], v[178:181], v[44:47]
	v_mfma_f32_16x16x32_bf16 v[48:51], v[166:169], v[178:181], v[48:51]
	v_mfma_f32_16x16x32_bf16 v[174:177], v[214:217], v[178:181], v[174:177]
	ds_read_b128 v[178:181], v6 offset:9216
	s_waitcnt lgkmcnt(3)
	v_mfma_f32_16x16x32_bf16 v[56:59], v[158:161], v[218:221], v[56:59]
	v_mfma_f32_16x16x32_bf16 v[60:63], v[162:165], v[218:221], v[60:63]
	v_mfma_f32_16x16x32_bf16 v[64:67], v[166:169], v[218:221], v[64:67]
	v_mfma_f32_16x16x32_bf16 v[170:173], v[214:217], v[218:221], v[170:173]
	ds_read_b128 v[218:221], v6 offset:11264
	s_waitcnt lgkmcnt(3)
	v_mfma_f32_16x16x32_bf16 v[72:75], v[158:161], v[222:225], v[72:75]
	v_mfma_f32_16x16x32_bf16 v[76:79], v[162:165], v[222:225], v[76:79]
	v_mfma_f32_16x16x32_bf16 v[80:83], v[166:169], v[222:225], v[80:83]
	v_mfma_f32_16x16x32_bf16 v[32:35], v[214:217], v[222:225], v[32:35]
	ds_read_b128 v[222:225], v6 offset:13312
	s_waitcnt lgkmcnt(3)
	v_mfma_f32_16x16x32_bf16 v[88:91], v[158:161], v[226:229], v[88:91]
	v_mfma_f32_16x16x32_bf16 v[92:95], v[162:165], v[226:229], v[92:95]
	v_mfma_f32_16x16x32_bf16 v[96:99], v[166:169], v[226:229], v[96:99]
	v_mfma_f32_16x16x32_bf16 v[36:39], v[214:217], v[226:229], v[36:39]
	ds_read_b128 v[226:229], v6 offset:15360
	s_waitcnt lgkmcnt(3)
	v_mfma_f32_16x16x32_bf16 v[104:107], v[158:161], v[178:181], v[104:107]
	v_mfma_f32_16x16x32_bf16 v[108:111], v[162:165], v[178:181], v[108:111]
	v_mfma_f32_16x16x32_bf16 v[112:115], v[166:169], v[178:181], v[112:115]
	v_mfma_f32_16x16x32_bf16 v[52:55], v[214:217], v[178:181], v[52:55]
	s_waitcnt lgkmcnt(2)
	v_mfma_f32_16x16x32_bf16 v[116:119], v[158:161], v[218:221], v[116:119]
	v_mfma_f32_16x16x32_bf16 v[120:123], v[162:165], v[218:221], v[120:123]
	v_mfma_f32_16x16x32_bf16 v[124:127], v[166:169], v[218:221], v[124:127]
	v_mfma_f32_16x16x32_bf16 v[68:71], v[214:217], v[218:221], v[68:71]
	s_waitcnt lgkmcnt(1)
	v_mfma_f32_16x16x32_bf16 v[132:135], v[162:165], v[222:225], v[132:135]
	v_mfma_f32_16x16x32_bf16 v[84:87], v[214:217], v[222:225], v[84:87]
	s_waitcnt lgkmcnt(0)
	v_mfma_f32_16x16x32_bf16 v[100:103], v[158:161], v[226:229], v[100:103]
	v_mfma_f32_16x16x32_bf16 v[150:153], v[166:169], v[226:229], v[150:153]
	v_mfma_f32_16x16x32_bf16 v[154:157], v[214:217], v[226:229], v[154:157]
	v_mfma_f32_16x16x32_bf16 v[128:131], v[158:161], v[222:225], v[128:131]
	v_mfma_f32_16x16x32_bf16 v[136:139], v[166:169], v[222:225], v[136:139]
	v_mfma_f32_16x16x32_bf16 v[140:143], v[162:165], v[226:229], v[140:143]
	s_waitcnt vmcnt(0)
	s_barrier
	v_lshl_add_u64 v[6:7], s[22:23], 0, v[0:1]
	s_mov_b32 s14, m0
	s_mov_b32 m0, s1
	s_nop 0
	global_load_lds_dwordx4 v[6:7], off
	s_mov_b32 m0, s14
	v_lshl_add_u64 v[0:1], s[24:25], 0, v[0:1]
	s_mov_b32 s1, m0
	s_mov_b32 m0, s34
	s_nop 0
	global_load_lds_dwordx4 v[0:1], off
	s_mov_b32 m0, s1
	v_lshl_add_u64 v[0:1], s[22:23], 0, v[2:3]
	s_mov_b32 s1, m0
	s_mov_b32 m0, s35
	s_nop 0
	global_load_lds_dwordx4 v[0:1], off
	s_mov_b32 m0, s1
	v_lshl_add_u64 v[0:1], s[24:25], 0, v[2:3]
	s_mov_b32 s1, m0
	s_mov_b32 m0, s36
	s_nop 0
	global_load_lds_dwordx4 v[0:1], off
	s_mov_b32 m0, s1
	v_lshl_add_u64 v[0:1], s[22:23], 0, v[4:5]
	s_mov_b32 s1, m0
	s_mov_b32 m0, s37
	s_nop 0
	global_load_lds_dwordx4 v[0:1], off
	s_mov_b32 m0, s1
	v_lshl_add_u64 v[0:1], s[24:25], 0, v[4:5]
	s_mov_b32 s1, m0
	s_mov_b32 m0, s38
	s_nop 0
	global_load_lds_dwordx4 v[0:1], off
	s_mov_b32 m0, s1
	v_lshl_add_u64 v[0:1], s[22:23], 0, v[146:147]
	s_mov_b32 s1, m0
	s_mov_b32 m0, s39
	s_nop 0
	global_load_lds_dwordx4 v[0:1], off
	s_mov_b32 m0, s1
	v_lshl_add_u64 v[0:1], s[24:25], 0, v[146:147]
	s_mov_b32 s1, m0
	s_mov_b32 m0, s40
	s_nop 0
	global_load_lds_dwordx4 v[0:1], off
	s_mov_b32 m0, s1
	ds_read_b128 v[0:3], v8
	ds_read_b128 v[4:7], v9
	ds_read_b128 v[158:161], v11
	ds_read_b128 v[8:11], v10
	ds_read_b128 v[162:165], v12
	ds_read_b128 v[166:169], v13
	ds_read_b128 v[178:181], v14
	ds_read_b128 v[12:15], v15
	s_waitcnt lgkmcnt(3)
	v_mfma_f32_16x16x32_bf16 v[40:43], v[0:3], v[162:165], v[40:43]
	v_mfma_f32_16x16x32_bf16 v[44:47], v[4:7], v[162:165], v[44:47]
	v_mfma_f32_16x16x32_bf16 v[48:51], v[158:161], v[162:165], v[48:51]
	v_mfma_f32_16x16x32_bf16 v[162:165], v[8:11], v[162:165], v[174:177]
	s_nop 2
	ds_read_b128 v[174:177], v16
	s_waitcnt lgkmcnt(3)
	v_mfma_f32_16x16x32_bf16 v[56:59], v[0:3], v[166:169], v[56:59]
	v_mfma_f32_16x16x32_bf16 v[60:63], v[4:7], v[166:169], v[60:63]
	v_mfma_f32_16x16x32_bf16 v[64:67], v[158:161], v[166:169], v[64:67]
	v_mfma_f32_16x16x32_bf16 v[166:169], v[8:11], v[166:169], v[170:173]
	s_nop 2
	ds_read_b128 v[170:173], v17
	s_waitcnt lgkmcnt(3)
	v_mfma_f32_16x16x32_bf16 v[72:75], v[0:3], v[178:181], v[72:75]
	v_mfma_f32_16x16x32_bf16 v[76:79], v[4:7], v[178:181], v[76:79]
	v_mfma_f32_16x16x32_bf16 v[80:83], v[158:161], v[178:181], v[80:83]
	v_mfma_f32_16x16x32_bf16 v[32:35], v[8:11], v[178:181], v[32:35]
	ds_read_b128 v[178:181], v18
	s_waitcnt lgkmcnt(3)
	v_mfma_f32_16x16x32_bf16 v[214:217], v[0:3], v[12:15], v[88:91]
	v_mfma_f32_16x16x32_bf16 v[218:221], v[4:7], v[12:15], v[92:95]
	v_mfma_f32_16x16x32_bf16 v[222:225], v[158:161], v[12:15], v[96:99]
	v_mfma_f32_16x16x32_bf16 v[12:15], v[8:11], v[12:15], v[36:39]
	ds_read_b128 v[16:19], v19
	s_waitcnt lgkmcnt(3)
	v_mfma_f32_16x16x32_bf16 v[36:39], v[0:3], v[174:177], v[104:107]
	v_mfma_f32_16x16x32_bf16 v[226:229], v[4:7], v[174:177], v[108:111]
	v_mfma_f32_16x16x32_bf16 v[112:115], v[158:161], v[174:177], v[112:115]
	s_waitcnt lgkmcnt(2)
	v_mfma_f32_16x16x32_bf16 v[116:119], v[0:3], v[170:173], v[116:119]
	v_mfma_f32_16x16x32_bf16 v[120:123], v[4:7], v[170:173], v[120:123]
	v_mfma_f32_16x16x32_bf16 v[124:127], v[158:161], v[170:173], v[124:127]
	s_waitcnt lgkmcnt(1)
	v_mfma_f32_16x16x32_bf16 v[128:131], v[0:3], v[178:181], v[128:131]
	v_mfma_f32_16x16x32_bf16 v[132:135], v[4:7], v[178:181], v[132:135]
	s_waitcnt lgkmcnt(0)
	v_mfma_f32_16x16x32_bf16 v[0:3], v[0:3], v[16:19], v[100:103]
	v_mfma_f32_16x16x32_bf16 v[4:7], v[4:7], v[16:19], v[140:143]
	v_mfma_f32_16x16x32_bf16 v[140:143], v[158:161], v[16:19], v[150:153]
	v_mfma_f32_16x16x32_bf16 v[150:153], v[8:11], v[16:19], v[154:157]
	v_mfma_f32_16x16x32_bf16 v[174:177], v[8:11], v[174:177], v[52:55]
	v_mfma_f32_16x16x32_bf16 v[170:173], v[8:11], v[170:173], v[68:71]
	v_mfma_f32_16x16x32_bf16 v[136:139], v[158:161], v[178:181], v[136:139]
	v_mfma_f32_16x16x32_bf16 v[178:181], v[8:11], v[178:181], v[84:87]
	ds_read_b128 v[8:11], v20
	ds_read_b128 v[154:157], v21
	ds_read_b128 v[158:161], v23
	ds_read_b128 v[230:233], v22
	ds_read_b128 v[16:19], v24
	ds_read_b128 v[20:23], v25
	ds_read_b128 v[52:55], v26
	ds_read_b128 v[24:27], v27
	s_waitcnt lgkmcnt(3)
	v_mfma_f32_16x16x32_bf16 v[234:237], v[8:11], v[16:19], v[40:43]
	v_mfma_f32_16x16x32_bf16 v[238:241], v[154:157], v[16:19], v[44:47]
	v_mfma_f32_16x16x32_bf16 v[242:245], v[158:161], v[16:19], v[48:51]
	v_mfma_f32_16x16x32_bf16 v[162:165], v[230:233], v[16:19], v[162:165]
	ds_read_b128 v[16:19], v28
	s_waitcnt lgkmcnt(3)
	v_mfma_f32_16x16x32_bf16 v[108:111], v[8:11], v[20:23], v[56:59]
	v_mfma_f32_16x16x32_bf16 v[104:107], v[154:157], v[20:23], v[60:63]
	v_mfma_f32_16x16x32_bf16 v[100:103], v[158:161], v[20:23], v[64:67]
	v_mfma_f32_16x16x32_bf16 v[96:99], v[230:233], v[20:23], v[166:169]
	ds_read_b128 v[20:23], v29
	s_waitcnt lgkmcnt(3)
	v_mfma_f32_16x16x32_bf16 v[92:95], v[8:11], v[52:55], v[72:75]
	v_mfma_f32_16x16x32_bf16 v[88:91], v[154:157], v[52:55], v[76:79]
	v_mfma_f32_16x16x32_bf16 v[84:87], v[158:161], v[52:55], v[80:83]
	v_mfma_f32_16x16x32_bf16 v[80:83], v[230:233], v[52:55], v[32:35]
	ds_read_b128 v[166:169], v30
	s_waitcnt lgkmcnt(3)
	v_mfma_f32_16x16x32_bf16 v[76:79], v[8:11], v[24:27], v[214:217]
	v_mfma_f32_16x16x32_bf16 v[72:75], v[154:157], v[24:27], v[218:221]
	v_mfma_f32_16x16x32_bf16 v[68:71], v[158:161], v[24:27], v[222:225]
	v_mfma_f32_16x16x32_bf16 v[64:67], v[230:233], v[24:27], v[12:15]
	ds_read_b128 v[214:217], v31
	s_waitcnt lgkmcnt(3)
	v_mfma_f32_16x16x32_bf16 v[60:63], v[8:11], v[16:19], v[36:39]
	v_mfma_f32_16x16x32_bf16 v[56:59], v[154:157], v[16:19], v[226:229]
	v_mfma_f32_16x16x32_bf16 v[52:55], v[158:161], v[16:19], v[112:115]
	v_mfma_f32_16x16x32_bf16 v[48:51], v[230:233], v[16:19], v[174:177]
	s_waitcnt lgkmcnt(2)
	v_mfma_f32_16x16x32_bf16 v[44:47], v[8:11], v[20:23], v[116:119]
	v_mfma_f32_16x16x32_bf16 v[40:43], v[154:157], v[20:23], v[120:123]
	v_mfma_f32_16x16x32_bf16 v[36:39], v[158:161], v[20:23], v[124:127]
	v_mfma_f32_16x16x32_bf16 v[32:35], v[230:233], v[20:23], v[170:173]
	s_waitcnt lgkmcnt(1)
	v_mfma_f32_16x16x32_bf16 v[28:31], v[8:11], v[166:169], v[128:131]
	v_mfma_f32_16x16x32_bf16 v[24:27], v[154:157], v[166:169], v[132:135]
	v_mfma_f32_16x16x32_bf16 v[20:23], v[158:161], v[166:169], v[136:139]
	v_mfma_f32_16x16x32_bf16 v[16:19], v[230:233], v[166:169], v[178:181]
	s_waitcnt lgkmcnt(0)
	v_mfma_f32_16x16x32_bf16 v[12:15], v[8:11], v[214:217], v[0:3]
	v_mfma_f32_16x16x32_bf16 v[8:11], v[154:157], v[214:217], v[4:7]
	v_mfma_f32_16x16x32_bf16 v[4:7], v[158:161], v[214:217], v[140:143]
	v_mfma_f32_16x16x32_bf16 v[0:3], v[230:233], v[214:217], v[150:153]
	v_mov_b32_e32 v145, v184
	s_waitcnt vmcnt(0)
	s_barrier
	s_lshl_b32 s20, s0, 8
	s_lshl_b32 s14, s12, 8
	v_and_b32_e32 v151, 15, v145
	v_ashrrev_i32_e32 v112, 1, v145
	v_and_b32_e32 v153, 0xffffff80, v112
	v_or_b32_e32 v112, s20, v151
	v_add_u32_e32 v112, v112, v153
	v_ashrrev_i32_e32 v113, 31, v112
	v_lshlrev_b64 v[112:113], 13, v[112:113]
	v_bfe_u32 v150, v145, 6, 2
	v_lshl_add_u64 v[112:113], s[2:3], 0, v[112:113]
	s_ashr_i32 s15, s14, 31
	v_bfe_u32 v152, v145, 4, 2
	v_lshl_add_u64 v[112:113], s[14:15], 2, v[112:113]
	v_lshlrev_b32_e32 v146, 8, v150
	v_lshl_add_u64 v[112:113], v[112:113], 0, v[146:147]
	v_lshlrev_b32_e32 v146, 4, v152
	v_lshl_add_u64 v[154:155], v[112:113], 0, v[146:147]
	global_load_dwordx4 v[120:123], v[154:155], off offset:192
	global_load_dwordx4 v[128:131], v[154:155], off offset:128
	global_load_dwordx4 v[136:139], v[154:155], off offset:64
	global_load_dwordx4 v[140:143], v[154:155], off
	v_add_co_u32_e32 v112, vcc, s66, v154
	v_lshlrev_b32_e32 v158, 2, v152
	s_nop 0
	v_addc_co_u32_e32 v113, vcc, 0, v155, vcc
	global_load_dwordx4 v[132:135], v[112:113], off
	global_load_dwordx4 v[124:127], v[112:113], off offset:64
	global_load_dwordx4 v[116:119], v[112:113], off offset:128
	v_cmp_lt_i32_e32 vcc, v188, v186
	global_load_dwordx4 v[112:115], v[112:113], off offset:192
	v_cmp_eq_u32_e64 s[0:1], 0, v152
	v_cndmask_b32_e32 v146, v185, v188, vcc
	v_cmp_lt_i32_e32 vcc, v187, v186
	v_lshlrev_b32_e32 v149, 2, v146
	v_lshlrev_b32_e32 v157, 6, v150
	v_cndmask_b32_e32 v156, v185, v187, vcc
	v_lshlrev_b32_e32 v146, 2, v156
	v_or_b32_e32 v156, v153, v151
	v_add_u32_e32 v152, s20, v156
	v_ashrrev_i32_e32 v153, 31, v152
	v_lshl_or_b32 v182, v150, 10, v204
	v_or3_b32 v150, v157, s14, v158
	v_lshlrev_b64 v[158:159], 13, v[152:153]
	v_ashrrev_i32_e32 v151, 31, v150
	v_lshlrev_b64 v[160:161], 12, v[152:153]
	v_lshl_add_u64 v[158:159], s[2:3], 0, v[158:159]
	v_lshl_add_u64 v[160:161], s[4:5], 0, v[160:161]
	v_lshl_add_u64 v[166:167], v[150:151], 2, v[158:159]
	v_lshl_add_u64 v[168:169], v[150:151], 1, v[160:161]
	s_waitcnt vmcnt(7)
	v_pk_add_f32 v[158:159], v[162:163], v[120:121]
	s_waitcnt vmcnt(6)
	v_pk_add_f32 v[120:121], v[242:243], v[128:129]
	s_waitcnt vmcnt(5)
	v_pk_add_f32 v[128:129], v[238:239], v[136:137]
	s_waitcnt vmcnt(4)
	v_pk_add_f32 v[136:137], v[234:235], v[140:141]
	v_pk_add_f32 v[160:161], v[164:165], v[122:123]
	v_pk_add_f32 v[122:123], v[244:245], v[130:131]
	v_pk_add_f32 v[130:131], v[240:241], v[138:139]
	v_pk_add_f32 v[138:139], v[236:237], v[142:143]
	v_pk_mul_f32 v[172:173], v[128:129], v[128:129]
	v_pk_mul_f32 v[178:179], v[136:137], v[136:137]
	v_pk_mul_f32 v[162:163], v[120:121], v[120:121]
	v_pk_mul_f32 v[174:175], v[130:131], v[130:131]
	v_cvt_pk_bf16_f32 v176, v136, v137
	v_pk_mul_f32 v[180:181], v[138:139], v[138:139]
	global_store_dwordx4 v[166:167], v[136:139], off
	v_add_f32_e32 v153, v172, v173
	v_add_f32_e32 v157, v178, v179
	v_pk_mul_f32 v[136:137], v[158:159], v[158:159]
	v_pk_mul_f32 v[164:165], v[122:123], v[122:123]
	v_cvt_pk_bf16_f32 v177, v138, v139
	v_pk_mul_f32 v[138:139], v[160:161], v[160:161]
	v_add_f32_e32 v162, v162, v163
	v_add_f32_e32 v136, v136, v137
	v_add_f32_e32 v137, v174, v153
	v_add_f32_e32 v153, v180, v157
	v_add_f32_e32 v157, v164, v162
	v_add_f32_e32 v136, v138, v136
	v_add_f32_e32 v137, v175, v137
	v_add_f32_e32 v138, v181, v153
	v_add_f32_e32 v153, v165, v157
	v_add_f32_e32 v137, v138, v137
	v_add_f32_e32 v137, v137, v153
	v_add_f32_e32 v136, v139, v136
	v_add_f32_e32 v136, v137, v136
	ds_bpermute_b32 v137, v149, v136
	v_cvt_pk_bf16_f32 v170, v128, v129
	v_cvt_pk_bf16_f32 v171, v130, v131
	v_cvt_pk_bf16_f32 v142, v120, v121
	global_store_dwordx2 v[168:169], v[176:177], off
	global_store_dwordx4 v[166:167], v[128:131], off offset:64
	global_store_dwordx2 v[168:169], v[170:171], off offset:32
	global_store_dwordx4 v[166:167], v[120:123], off offset:128
	v_cvt_pk_bf16_f32 v140, v158, v159
	v_cvt_pk_bf16_f32 v141, v160, v161
	s_waitcnt lgkmcnt(0)
	v_add_f32_e32 v120, v136, v137
	ds_bpermute_b32 v121, v146, v120
	v_cvt_pk_bf16_f32 v143, v122, v123
	v_lshl_add_u32 v153, v156, 2, v182
	global_store_dwordx2 v[168:169], v[142:143], off offset:64
	global_store_dwordx4 v[166:167], v[158:161], off offset:192
	global_store_dwordx2 v[168:169], v[140:141], off offset:96
	s_and_saveexec_b64 s[14:15], s[0:1]
	s_cbranch_execz .LBB0_698
	s_waitcnt lgkmcnt(0)
	v_add_f32_e32 v120, v120, v121
	ds_write_b32 v153, v120

.LBB0_757:
	s_ashr_i32 s25, s24, 31
	s_lshl_b64 s[24:25], s[24:25], 20
	s_add_u32 s27, s2, s24
	s_addc_u32 s45, s3, s25
	s_ashr_i32 s47, s46, 1
	s_lshl_b32 s24, s47, 8
	s_ashr_i32 s25, s24, 31
	s_lshl_b64 s[24:25], s[24:25], 1
	s_add_u32 s27, s27, s24
	s_addc_u32 s45, s45, s25
	s_add_i32 s24, s47, s28
	s_ashr_i32 s25, s24, 31
	s_lshl_b64 s[24:25], s[24:25], 18
	s_add_u32 s24, s29, s24
	s_addc_u32 s25, s30, s25
	s_lshl_b32 s46, s46, 17
	v_lshlrev_b32_e32 v3, 6, v1
	s_and_b32 s46, s46, 0x20000
	v_and_b32_e32 v2, 48, v1
	v_and_b32_e32 v4, 0x3c0, v3
	v_lshlrev_b32_e32 v1, 2, v1
	s_add_u32 s46, s24, s46
	v_or_b32_e32 v5, v4, v2
	v_and_b32_e32 v1, 32, v1
	v_lshlrev_b32_e32 v0, 13, v0
	s_mov_b32 s24, 0x18000
	v_and_b32_e32 v143, 0x6000, v0
	v_bitop3_b32 v0, v5, s24, v1 bitop3:0xde
	s_mov_b32 s24, 0x10400
	s_addc_u32 s47, s25, 0
	v_bitop3_b32 v157, v5, s24, v1 bitop3:0xde
	s_add_i32 s24, s31, s63
	s_ashr_i32 s25, s24, 31
	s_lshl_b32 s62, s62, 15
	s_lshl_b64 s[24:25], s[24:25], 18
	s_and_b32 s62, s62, 0x20000
	s_add_i32 s49, s38, 0x10000
	s_add_i32 s50, s38, 0x18000
	s_add_i32 s51, s38, 0x12000
	s_add_i32 s52, s38, 0x1a000
	s_add_i32 s53, s38, 0x14000
	s_add_i32 s54, s38, 0x1c000
	s_add_i32 s55, s38, 0x16000
	s_add_i32 s58, s38, 0x1e000
	s_or_b32 s24, s24, s62
	s_add_u32 s62, s10, s24
	s_addc_u32 s63, s11, s25
	s_add_i32 s24, s64, s65
	s_ashr_i32 s25, s24, 31
	s_lshl_b64 s[24:25], s[24:25], 20
	s_lshl_b64 s[64:65], s[22:23], 1
	s_add_u32 s23, s24, s64
	s_waitcnt vmcnt(0)
	s_addc_u32 s24, s25, s65
	v_and_b32_e32 v145, 0xffffc000, v3
	s_add_u32 s23, s10, s23
	v_mov_b32_e32 v8, 0
	s_mov_b32 s26, 1
	v_bitop3_b32 v142, v4, v1, v2 bitop3:0x36
	v_or_b32_e32 v149, 0x800, v145
	v_or_b32_e32 v150, 0x1000, v145
	v_or_b32_e32 v151, 0x1800, v145
	v_or_b32_e32 v152, 0x2000, v145
	v_or_b32_e32 v153, 0x2800, v145
	v_or_b32_e32 v154, 0x3000, v145
	v_or_b32_e32 v155, 0x3800, v145
	v_bitop3_b32 v156, v5, s33, v1 bitop3:0xde
	s_addc_u32 s64, s11, s24
	s_mov_b64 s[24:25], 0
	v_add_u32_e32 v158, v0, v143
	v_mov_b32_e32 v9, v8
	v_mov_b32_e32 v10, v8
	v_mov_b32_e32 v11, v8
	v_mov_b32_e32 v72, v8
	v_mov_b32_e32 v73, v8
	v_mov_b32_e32 v74, v8
	v_mov_b32_e32 v75, v8
	v_mov_b32_e32 v12, v8
	v_mov_b32_e32 v13, v8
	v_mov_b32_e32 v14, v8
	v_mov_b32_e32 v15, v8
	v_mov_b32_e32 v76, v8
	v_mov_b32_e32 v77, v8
	v_mov_b32_e32 v78, v8
	v_mov_b32_e32 v79, v8
	v_mov_b32_e32 v16, v8
	v_mov_b32_e32 v17, v8
	v_mov_b32_e32 v18, v8
	v_mov_b32_e32 v19, v8
	v_mov_b32_e32 v80, v8
	v_mov_b32_e32 v81, v8
	v_mov_b32_e32 v82, v8
	v_mov_b32_e32 v83, v8
	v_mov_b32_e32 v20, v8
	v_mov_b32_e32 v21, v8
	v_mov_b32_e32 v22, v8
	v_mov_b32_e32 v23, v8
	v_mov_b32_e32 v84, v8
	v_mov_b32_e32 v85, v8
	v_mov_b32_e32 v86, v8
	v_mov_b32_e32 v87, v8
	v_mov_b32_e32 v24, v8
	v_mov_b32_e32 v25, v8
	v_mov_b32_e32 v26, v8
	v_mov_b32_e32 v27, v8
	v_mov_b32_e32 v96, v8
	v_mov_b32_e32 v97, v8
	v_mov_b32_e32 v98, v8
	v_mov_b32_e32 v99, v8
	v_mov_b32_e32 v28, v8
	v_mov_b32_e32 v29, v8
	v_mov_b32_e32 v30, v8
	v_mov_b32_e32 v31, v8
	v_mov_b32_e32 v100, v8
	v_mov_b32_e32 v101, v8
	v_mov_b32_e32 v102, v8
	v_mov_b32_e32 v103, v8
	v_mov_b32_e32 v32, v8
	v_mov_b32_e32 v33, v8
	v_mov_b32_e32 v34, v8
	v_mov_b32_e32 v35, v8
	v_mov_b32_e32 v104, v8
	v_mov_b32_e32 v105, v8
	v_mov_b32_e32 v106, v8
	v_mov_b32_e32 v107, v8
	v_mov_b32_e32 v36, v8
	v_mov_b32_e32 v37, v8
	v_mov_b32_e32 v38, v8
	v_mov_b32_e32 v39, v8
	v_mov_b32_e32 v108, v8
	v_mov_b32_e32 v109, v8
	v_mov_b32_e32 v110, v8
	v_mov_b32_e32 v111, v8
	v_mov_b32_e32 v40, v8
	v_mov_b32_e32 v41, v8
	v_mov_b32_e32 v42, v8
	v_mov_b32_e32 v43, v8
	v_mov_b32_e32 v112, v8
	v_mov_b32_e32 v113, v8
	v_mov_b32_e32 v114, v8
	v_mov_b32_e32 v115, v8
	v_mov_b32_e32 v44, v8
	v_mov_b32_e32 v45, v8
	v_mov_b32_e32 v46, v8
	v_mov_b32_e32 v47, v8
	v_mov_b32_e32 v116, v8
	v_mov_b32_e32 v117, v8
	v_mov_b32_e32 v118, v8
	v_mov_b32_e32 v119, v8
	v_mov_b32_e32 v48, v8
	v_mov_b32_e32 v49, v8
	v_mov_b32_e32 v50, v8
	v_mov_b32_e32 v51, v8
	v_mov_b32_e32 v120, v8
	v_mov_b32_e32 v121, v8
	v_mov_b32_e32 v122, v8
	v_mov_b32_e32 v123, v8
	v_mov_b32_e32 v52, v8
	v_mov_b32_e32 v53, v8
	v_mov_b32_e32 v54, v8
	v_mov_b32_e32 v55, v8
	v_mov_b32_e32 v124, v8
	v_mov_b32_e32 v125, v8
	v_mov_b32_e32 v126, v8
	v_mov_b32_e32 v127, v8
	v_mov_b32_e32 v56, v8
	v_mov_b32_e32 v57, v8
	v_mov_b32_e32 v58, v8
	v_mov_b32_e32 v59, v8
	v_mov_b32_e32 v128, v8
	v_mov_b32_e32 v129, v8
	v_mov_b32_e32 v130, v8
	v_mov_b32_e32 v131, v8
	v_mov_b32_e32 v60, v8
	v_mov_b32_e32 v61, v8
	v_mov_b32_e32 v62, v8
	v_mov_b32_e32 v63, v8
	v_mov_b32_e32 v132, v8
	v_mov_b32_e32 v133, v8
	v_mov_b32_e32 v134, v8
	v_mov_b32_e32 v135, v8
	v_mov_b32_e32 v64, v8
	v_mov_b32_e32 v65, v8
	v_mov_b32_e32 v66, v8
	v_mov_b32_e32 v67, v8
	v_mov_b32_e32 v0, v8
	v_mov_b32_e32 v1, v8
	v_mov_b32_e32 v2, v8
	v_mov_b32_e32 v3, v8
	v_mov_b32_e32 v68, v8
	v_mov_b32_e32 v69, v8
	v_mov_b32_e32 v70, v8
	v_mov_b32_e32 v71, v8
	v_mov_b32_e32 v4, v8
	v_mov_b32_e32 v5, v8
	v_mov_b32_e32 v6, v8
	v_mov_b32_e32 v7, v8
	s_barrier
	s_add_u32 s65, s23, s24
	s_addc_u32 s72, s64, s25
	s_add_u32 s68, s65, 0x21ac0080
	s_addc_u32 s69, s72, 0
	s_add_u32 s73, s62, s24
	s_addc_u32 s74, s63, s25
	s_add_u32 s70, s73, 0x2000080
	s_addc_u32 s71, s74, 0
	v_add_u32_e32 v159, v142, v143
	v_add_u32_e32 v189, v142, v145
	ds_read_b128 v[160:163], v159 offset:32768
	ds_read_b128 v[164:167], v189
	s_mov_b32 m0, s50
	s_nop 0
	global_load_lds_dwordx4 v90, s[70:71]
	ds_read_b128 v[168:171], v159 offset:34816
	s_mov_b32 m0, s52
	s_nop 0
	global_load_lds_dwordx4 v94, s[70:71]
	ds_read_b128 v[172:175], v189 offset:2048
	ds_read_b128 v[176:179], v159 offset:36864
	s_mov_b32 m0, s54
	s_nop 0
	global_load_lds_dwordx4 v138, s[70:71]
	ds_read_b128 v[180:183], v159 offset:38912
	ds_read_b128 v[214:217], v189 offset:4096
	ds_read_b128 v[218:221], v189 offset:6144
	s_branch .Lmy_rot_758
.LBB0_758:
	s_add_u32 s65, s23, s24
	s_addc_u32 s72, s64, s25
	s_add_u32 s68, s65, 0x21ac0080
	s_addc_u32 s69, s72, 0
	s_add_u32 s73, s62, s24
	s_addc_u32 s74, s63, s25
	s_add_u32 s70, s73, 0x2000080
	s_addc_u32 s71, s74, 0
	v_add_u32_e32 v159, v142, v143
	v_add_u32_e32 v189, v142, v145
	ds_read_b128 v[160:163], v159 offset:32768
	ds_read_b128 v[164:167], v189
	s_mov_b32 m0, s50
	v_mfma_f32_16x16x32_bf16 v[76:79], v[168:171], v[214:217], v[76:79]
	global_load_lds_dwordx4 v90, s[70:71]
	v_mfma_f32_16x16x32_bf16 v[64:67], v[168:171], v[218:221], v[64:67]
	ds_read_b128 v[168:171], v159 offset:34816
	v_mfma_f32_16x16x32_bf16 v[12:15], v[172:175], v[214:217], v[12:15]
	s_mov_b32 m0, s52
	v_mfma_f32_16x16x32_bf16 v[0:3], v[172:175], v[218:221], v[0:3]
	global_load_lds_dwordx4 v94, s[70:71]
	ds_read_b128 v[172:175], v189 offset:2048
	v_mfma_f32_16x16x32_bf16 v[72:75], v[176:179], v[214:217], v[72:75]
	v_mfma_f32_16x16x32_bf16 v[68:71], v[176:179], v[218:221], v[68:71]
	ds_read_b128 v[176:179], v159 offset:36864
	s_mov_b32 m0, s54
	v_mfma_f32_16x16x32_bf16 v[8:11], v[180:183], v[214:217], v[8:11]
	global_load_lds_dwordx4 v138, s[70:71]
	v_mfma_f32_16x16x32_bf16 v[4:7], v[180:183], v[218:221], v[4:7]
	ds_read_b128 v[180:183], v159 offset:38912
	ds_read_b128 v[214:217], v189 offset:4096
	ds_read_b128 v[218:221], v189 offset:6144
.Lmy_rot_758:
	s_waitcnt lgkmcnt(6)
	v_mfma_f32_16x16x32_bf16 v[132:135], v[160:163], v[164:167], v[132:135]
	s_waitcnt lgkmcnt(5)
	s_mov_b32 m0, s58
	v_mfma_f32_16x16x32_bf16 v[60:63], v[168:171], v[164:167], v[60:63]
	global_load_lds_dwordx4 v146, s[70:71]
	s_waitcnt lgkmcnt(4)
	v_mfma_f32_16x16x32_bf16 v[124:127], v[160:163], v[172:175], v[124:127]
	v_mfma_f32_16x16x32_bf16 v[52:55], v[168:171], v[172:175], v[52:55]
	s_waitcnt lgkmcnt(3)
	s_mov_b32 m0, s49
	v_mfma_f32_16x16x32_bf16 v[128:131], v[176:179], v[164:167], v[128:131]
	global_load_lds_dwordx4 v88, s[68:69]
	v_mfma_f32_16x16x32_bf16 v[120:123], v[176:179], v[172:175], v[120:123]
	s_waitcnt lgkmcnt(2)
	v_mfma_f32_16x16x32_bf16 v[56:59], v[180:183], v[164:167], v[56:59]
	ds_read_b128 v[164:167], v189 offset:8192
	s_mov_b32 m0, s51
	v_mfma_f32_16x16x32_bf16 v[48:51], v[180:183], v[172:175], v[48:51]
	global_load_lds_dwordx4 v92, s[68:69]
	ds_read_b128 v[172:175], v189 offset:10240
	s_waitcnt lgkmcnt(3)
	v_mfma_f32_16x16x32_bf16 v[116:119], v[160:163], v[214:217], v[116:119]
	v_mfma_f32_16x16x32_bf16 v[44:47], v[168:171], v[214:217], v[44:47]
	s_mov_b32 m0, s53
	v_mfma_f32_16x16x32_bf16 v[112:115], v[176:179], v[214:217], v[112:115]
	global_load_lds_dwordx4 v136, s[68:69]
	v_mfma_f32_16x16x32_bf16 v[40:43], v[180:183], v[214:217], v[40:43]
	ds_read_b128 v[214:217], v189 offset:12288
	s_waitcnt lgkmcnt(3)
	v_mfma_f32_16x16x32_bf16 v[108:111], v[160:163], v[218:221], v[108:111]
	s_mov_b32 m0, s55
	v_mfma_f32_16x16x32_bf16 v[36:39], v[168:171], v[218:221], v[36:39]
	global_load_lds_dwordx4 v140, s[68:69]
	v_mfma_f32_16x16x32_bf16 v[104:107], v[176:179], v[218:221], v[104:107]
	v_mfma_f32_16x16x32_bf16 v[32:35], v[180:183], v[218:221], v[32:35]
	ds_read_b128 v[218:221], v189 offset:14336
	s_waitcnt lgkmcnt(3)
	v_mfma_f32_16x16x32_bf16 v[28:31], v[168:171], v[164:167], v[28:31]
	s_waitcnt lgkmcnt(2)
	v_mfma_f32_16x16x32_bf16 v[20:23], v[168:171], v[172:175], v[20:23]
	s_waitcnt lgkmcnt(1)
	v_mfma_f32_16x16x32_bf16 v[12:15], v[168:171], v[214:217], v[12:15]
	s_waitcnt lgkmcnt(0)
	v_mfma_f32_16x16x32_bf16 v[0:3], v[168:171], v[218:221], v[0:3]
	ds_read_b128 v[168:171], v159 offset:33792
	v_mfma_f32_16x16x32_bf16 v[100:103], v[160:163], v[164:167], v[100:103]
	v_mfma_f32_16x16x32_bf16 v[84:87], v[160:163], v[172:175], v[84:87]
	v_mfma_f32_16x16x32_bf16 v[76:79], v[160:163], v[214:217], v[76:79]
	v_mfma_f32_16x16x32_bf16 v[64:67], v[160:163], v[218:221], v[64:67]
	ds_read_b128 v[160:163], v189 offset:1024
	v_mfma_f32_16x16x32_bf16 v[80:83], v[176:179], v[172:175], v[80:83]
	v_mfma_f32_16x16x32_bf16 v[16:19], v[180:183], v[172:175], v[16:19]
	ds_read_b128 v[172:175], v159 offset:35840
	v_mfma_f32_16x16x32_bf16 v[96:99], v[176:179], v[164:167], v[96:99]
	v_mfma_f32_16x16x32_bf16 v[24:27], v[180:183], v[164:167], v[24:27]
	ds_read_b128 v[164:167], v189 offset:3072
	v_mfma_f32_16x16x32_bf16 v[72:75], v[176:179], v[214:217], v[72:75]
	v_mfma_f32_16x16x32_bf16 v[8:11], v[180:183], v[214:217], v[8:11]
	ds_read_b128 v[214:217], v189 offset:5120
	v_mfma_f32_16x16x32_bf16 v[68:71], v[176:179], v[218:221], v[68:71]
	ds_read_b128 v[176:179], v159 offset:37888
	v_mfma_f32_16x16x32_bf16 v[4:7], v[180:183], v[218:221], v[4:7]
	ds_read_b128 v[180:183], v159 offset:39936
	ds_read_b128 v[218:221], v189 offset:7168
	s_waitcnt lgkmcnt(6)
	v_mfma_f32_16x16x32_bf16 v[132:135], v[168:171], v[160:163], v[132:135]
	s_waitcnt lgkmcnt(5)
	v_mfma_f32_16x16x32_bf16 v[60:63], v[172:175], v[160:163], v[60:63]
	s_waitcnt lgkmcnt(4)
	v_mfma_f32_16x16x32_bf16 v[124:127], v[168:171], v[164:167], v[124:127]
	v_mfma_f32_16x16x32_bf16 v[52:55], v[172:175], v[164:167], v[52:55]
	s_waitcnt lgkmcnt(3)
	v_mfma_f32_16x16x32_bf16 v[116:119], v[168:171], v[214:217], v[116:119]
	v_mfma_f32_16x16x32_bf16 v[44:47], v[172:175], v[214:217], v[44:47]
	s_waitcnt lgkmcnt(2)
	v_mfma_f32_16x16x32_bf16 v[128:131], v[176:179], v[160:163], v[128:131]
	s_waitcnt lgkmcnt(1)
	v_mfma_f32_16x16x32_bf16 v[56:59], v[180:183], v[160:163], v[56:59]
	ds_read_b128 v[160:163], v189 offset:9216
	v_mfma_f32_16x16x32_bf16 v[120:123], v[176:179], v[164:167], v[120:123]
	v_mfma_f32_16x16x32_bf16 v[48:51], v[180:183], v[164:167], v[48:51]
	ds_read_b128 v[164:167], v189 offset:11264
	v_mfma_f32_16x16x32_bf16 v[112:115], v[176:179], v[214:217], v[112:115]
	v_mfma_f32_16x16x32_bf16 v[40:43], v[180:183], v[214:217], v[40:43]
	ds_read_b128 v[214:217], v189 offset:13312
	s_waitcnt lgkmcnt(3)
	v_mfma_f32_16x16x32_bf16 v[108:111], v[168:171], v[218:221], v[108:111]
	v_mfma_f32_16x16x32_bf16 v[36:39], v[172:175], v[218:221], v[36:39]
	v_mfma_f32_16x16x32_bf16 v[104:107], v[176:179], v[218:221], v[104:107]
	v_mfma_f32_16x16x32_bf16 v[32:35], v[180:183], v[218:221], v[32:35]
	ds_read_b128 v[218:221], v189 offset:15360
	s_waitcnt lgkmcnt(3)
	v_mfma_f32_16x16x32_bf16 v[100:103], v[168:171], v[160:163], v[100:103]
	v_mfma_f32_16x16x32_bf16 v[28:31], v[172:175], v[160:163], v[28:31]
	v_mfma_f32_16x16x32_bf16 v[96:99], v[176:179], v[160:163], v[96:99]
	v_mfma_f32_16x16x32_bf16 v[24:27], v[180:183], v[160:163], v[24:27]
	s_waitcnt lgkmcnt(2)
	v_mfma_f32_16x16x32_bf16 v[84:87], v[168:171], v[164:167], v[84:87]
	v_mfma_f32_16x16x32_bf16 v[20:23], v[172:175], v[164:167], v[20:23]
	v_mfma_f32_16x16x32_bf16 v[80:83], v[176:179], v[164:167], v[80:83]
	v_mfma_f32_16x16x32_bf16 v[16:19], v[180:183], v[164:167], v[16:19]
	s_add_u32 s65, s65, 0x21ac0100
	s_addc_u32 s68, s72, 0
	s_add_u32 s70, s73, 0x2000100
	s_addc_u32 s71, s74, 0
	s_cmp_lt_u32 s26, 3
	s_cselect_b32 s69, s68, s45
	s_cselect_b32 s68, s65, s27
	s_waitcnt vmcnt(0)
	s_waitcnt lgkmcnt(0)
	s_barrier
	s_cselect_b32 s71, s71, s47
	s_cselect_b32 s70, s70, s46
	ds_read_b128 v[160:163], v158
	v_add_u32_e32 v159, v156, v145
	ds_read_b128 v[164:167], v159
	s_mov_b32 m0, s1
	v_mfma_f32_16x16x32_bf16 v[76:79], v[168:171], v[214:217], v[76:79]
	global_load_lds_dwordx4 v90, s[70:71]
	v_mfma_f32_16x16x32_bf16 v[64:67], v[168:171], v[218:221], v[64:67]
	ds_read_b128 v[168:171], v158 offset:2048
	v_mfma_f32_16x16x32_bf16 v[12:15], v[172:175], v[214:217], v[12:15]
	s_mov_b32 m0, s40
	v_mfma_f32_16x16x32_bf16 v[0:3], v[172:175], v[218:221], v[0:3]
	global_load_lds_dwordx4 v94, s[70:71]
	v_add_u32_e32 v159, v156, v149
	ds_read_b128 v[172:175], v159
	v_mfma_f32_16x16x32_bf16 v[72:75], v[176:179], v[214:217], v[72:75]
	v_mfma_f32_16x16x32_bf16 v[68:71], v[176:179], v[218:221], v[68:71]
	ds_read_b128 v[176:179], v158 offset:4096
	s_mov_b32 m0, s42
	v_mfma_f32_16x16x32_bf16 v[8:11], v[180:183], v[214:217], v[8:11]
	global_load_lds_dwordx4 v138, s[70:71]
	v_mfma_f32_16x16x32_bf16 v[4:7], v[180:183], v[218:221], v[4:7]
	ds_read_b128 v[180:183], v158 offset:6144
	v_add_u32_e32 v159, v156, v150
	ds_read_b128 v[214:217], v159
	v_add_u32_e32 v159, v156, v151
	ds_read_b128 v[218:221], v159
	s_waitcnt lgkmcnt(6)
	v_mfma_f32_16x16x32_bf16 v[132:135], v[160:163], v[164:167], v[132:135]
	s_waitcnt lgkmcnt(5)
	s_mov_b32 m0, s44
	v_mfma_f32_16x16x32_bf16 v[60:63], v[168:171], v[164:167], v[60:63]
	global_load_lds_dwordx4 v146, s[70:71]
	s_waitcnt lgkmcnt(4)
	v_mfma_f32_16x16x32_bf16 v[124:127], v[160:163], v[172:175], v[124:127]
	v_mfma_f32_16x16x32_bf16 v[52:55], v[168:171], v[172:175], v[52:55]
	s_waitcnt lgkmcnt(3)
	s_mov_b32 m0, s38
	v_mfma_f32_16x16x32_bf16 v[128:131], v[176:179], v[164:167], v[128:131]
	global_load_lds_dwordx4 v88, s[68:69]
	v_mfma_f32_16x16x32_bf16 v[120:123], v[176:179], v[172:175], v[120:123]
	s_waitcnt lgkmcnt(2)
	v_mfma_f32_16x16x32_bf16 v[56:59], v[180:183], v[164:167], v[56:59]
	v_add_u32_e32 v159, v156, v152
	ds_read_b128 v[164:167], v159
	s_mov_b32 m0, s39
	v_mfma_f32_16x16x32_bf16 v[48:51], v[180:183], v[172:175], v[48:51]
	global_load_lds_dwordx4 v92, s[68:69]
	v_add_u32_e32 v159, v156, v153
	ds_read_b128 v[172:175], v159
	s_waitcnt lgkmcnt(3)
	v_mfma_f32_16x16x32_bf16 v[116:119], v[160:163], v[214:217], v[116:119]
	v_mfma_f32_16x16x32_bf16 v[44:47], v[168:171], v[214:217], v[44:47]
	s_mov_b32 m0, s41
	v_mfma_f32_16x16x32_bf16 v[112:115], v[176:179], v[214:217], v[112:115]
	global_load_lds_dwordx4 v136, s[68:69]
	v_mfma_f32_16x16x32_bf16 v[40:43], v[180:183], v[214:217], v[40:43]
	v_add_u32_e32 v159, v156, v154
	ds_read_b128 v[214:217], v159
	s_waitcnt lgkmcnt(3)
	v_mfma_f32_16x16x32_bf16 v[108:111], v[160:163], v[218:221], v[108:111]
	s_mov_b32 m0, s43
	v_mfma_f32_16x16x32_bf16 v[36:39], v[168:171], v[218:221], v[36:39]
	global_load_lds_dwordx4 v140, s[68:69]
	v_mfma_f32_16x16x32_bf16 v[104:107], v[176:179], v[218:221], v[104:107]
	v_mfma_f32_16x16x32_bf16 v[32:35], v[180:183], v[218:221], v[32:35]
	v_add_u32_e32 v159, v156, v155
	ds_read_b128 v[218:221], v159
	s_waitcnt lgkmcnt(3)
	v_mfma_f32_16x16x32_bf16 v[28:31], v[168:171], v[164:167], v[28:31]
	s_waitcnt lgkmcnt(2)
	v_mfma_f32_16x16x32_bf16 v[20:23], v[168:171], v[172:175], v[20:23]
	s_waitcnt lgkmcnt(1)
	v_mfma_f32_16x16x32_bf16 v[12:15], v[168:171], v[214:217], v[12:15]
	s_waitcnt lgkmcnt(0)
	v_mfma_f32_16x16x32_bf16 v[0:3], v[168:171], v[218:221], v[0:3]
	ds_read_b128 v[168:171], v158 offset:1024
	v_mfma_f32_16x16x32_bf16 v[100:103], v[160:163], v[164:167], v[100:103]
	v_mfma_f32_16x16x32_bf16 v[84:87], v[160:163], v[172:175], v[84:87]
	v_mfma_f32_16x16x32_bf16 v[76:79], v[160:163], v[214:217], v[76:79]
	v_mfma_f32_16x16x32_bf16 v[64:67], v[160:163], v[218:221], v[64:67]
	v_add_u32_e32 v159, v157, v145
	ds_read_b128 v[160:163], v159
	v_mfma_f32_16x16x32_bf16 v[80:83], v[176:179], v[172:175], v[80:83]
	v_mfma_f32_16x16x32_bf16 v[16:19], v[180:183], v[172:175], v[16:19]
	ds_read_b128 v[172:175], v158 offset:3072
	v_mfma_f32_16x16x32_bf16 v[96:99], v[176:179], v[164:167], v[96:99]
	v_mfma_f32_16x16x32_bf16 v[24:27], v[180:183], v[164:167], v[24:27]
	v_add_u32_e32 v159, v157, v149
	ds_read_b128 v[164:167], v159
	v_mfma_f32_16x16x32_bf16 v[72:75], v[176:179], v[214:217], v[72:75]
	v_mfma_f32_16x16x32_bf16 v[8:11], v[180:183], v[214:217], v[8:11]
	v_add_u32_e32 v159, v157, v150
	ds_read_b128 v[214:217], v159
	v_mfma_f32_16x16x32_bf16 v[68:71], v[176:179], v[218:221], v[68:71]
	ds_read_b128 v[176:179], v158 offset:5120
	v_mfma_f32_16x16x32_bf16 v[4:7], v[180:183], v[218:221], v[4:7]
	ds_read_b128 v[180:183], v158 offset:7168
	v_add_u32_e32 v159, v157, v151
	ds_read_b128 v[218:221], v159
	s_waitcnt lgkmcnt(6)
	v_mfma_f32_16x16x32_bf16 v[132:135], v[168:171], v[160:163], v[132:135]
	s_waitcnt lgkmcnt(5)
	v_mfma_f32_16x16x32_bf16 v[60:63], v[172:175], v[160:163], v[60:63]
	s_waitcnt lgkmcnt(4)
	v_mfma_f32_16x16x32_bf16 v[124:127], v[168:171], v[164:167], v[124:127]
	v_mfma_f32_16x16x32_bf16 v[52:55], v[172:175], v[164:167], v[52:55]
	s_waitcnt lgkmcnt(3)
	v_mfma_f32_16x16x32_bf16 v[116:119], v[168:171], v[214:217], v[116:119]
	v_mfma_f32_16x16x32_bf16 v[44:47], v[172:175], v[214:217], v[44:47]
	s_waitcnt lgkmcnt(2)
	v_mfma_f32_16x16x32_bf16 v[128:131], v[176:179], v[160:163], v[128:131]
	s_waitcnt lgkmcnt(1)
	v_mfma_f32_16x16x32_bf16 v[56:59], v[180:183], v[160:163], v[56:59]
	v_add_u32_e32 v159, v157, v152
	ds_read_b128 v[160:163], v159
	v_mfma_f32_16x16x32_bf16 v[120:123], v[176:179], v[164:167], v[120:123]
	v_mfma_f32_16x16x32_bf16 v[48:51], v[180:183], v[164:167], v[48:51]
	v_add_u32_e32 v159, v157, v153
	ds_read_b128 v[164:167], v159
	v_mfma_f32_16x16x32_bf16 v[112:115], v[176:179], v[214:217], v[112:115]
	v_mfma_f32_16x16x32_bf16 v[40:43], v[180:183], v[214:217], v[40:43]
	v_add_u32_e32 v159, v157, v154
	ds_read_b128 v[214:217], v159
	s_waitcnt lgkmcnt(3)
	v_mfma_f32_16x16x32_bf16 v[108:111], v[168:171], v[218:221], v[108:111]
	v_mfma_f32_16x16x32_bf16 v[36:39], v[172:175], v[218:221], v[36:39]
	v_mfma_f32_16x16x32_bf16 v[104:107], v[176:179], v[218:221], v[104:107]
	v_mfma_f32_16x16x32_bf16 v[32:35], v[180:183], v[218:221], v[32:35]
	v_add_u32_e32 v159, v157, v155
	ds_read_b128 v[218:221], v159
	s_waitcnt lgkmcnt(3)
	v_mfma_f32_16x16x32_bf16 v[100:103], v[168:171], v[160:163], v[100:103]
	v_mfma_f32_16x16x32_bf16 v[28:31], v[172:175], v[160:163], v[28:31]
	v_mfma_f32_16x16x32_bf16 v[96:99], v[176:179], v[160:163], v[96:99]
	v_mfma_f32_16x16x32_bf16 v[24:27], v[180:183], v[160:163], v[24:27]
	s_waitcnt lgkmcnt(2)
	v_mfma_f32_16x16x32_bf16 v[84:87], v[168:171], v[164:167], v[84:87]
	v_mfma_f32_16x16x32_bf16 v[20:23], v[172:175], v[164:167], v[20:23]
	v_mfma_f32_16x16x32_bf16 v[80:83], v[176:179], v[164:167], v[80:83]
	v_mfma_f32_16x16x32_bf16 v[16:19], v[180:183], v[164:167], v[16:19]
	s_waitcnt vmcnt(0)
	s_add_u32 s24, s24, 0x100
	s_addc_u32 s25, s25, 0
	s_add_i32 s26, s26, 2
	s_cmpk_lg_i32 s24, 0x200
	s_waitcnt lgkmcnt(0)
	s_barrier
	s_cbranch_scc1 .LBB0_758
	v_mfma_f32_16x16x32_bf16 v[76:79], v[168:171], v[214:217], v[76:79]
	v_mfma_f32_16x16x32_bf16 v[64:67], v[168:171], v[218:221], v[64:67]
	v_mfma_f32_16x16x32_bf16 v[12:15], v[172:175], v[214:217], v[12:15]
	v_mfma_f32_16x16x32_bf16 v[0:3], v[172:175], v[218:221], v[0:3]
	v_mfma_f32_16x16x32_bf16 v[72:75], v[176:179], v[214:217], v[72:75]
	v_mfma_f32_16x16x32_bf16 v[68:71], v[176:179], v[218:221], v[68:71]
	v_mfma_f32_16x16x32_bf16 v[8:11], v[180:183], v[214:217], v[8:11]
	v_mfma_f32_16x16x32_bf16 v[4:7], v[180:183], v[218:221], v[4:7]
	s_nop 15
	s_nop 15
	v_mov_b32_e32 v88, v184
	s_lshl_b32 s0, s0, 8
	v_lshrrev_b32_e32 v89, 1, v88
	v_and_b32_e32 v89, 0x60, v89
	v_lshl_or_b32 v89, s37, 7, v89
	v_or_b32_e32 v142, s22, v89
	v_lshrrev_b32_e32 v89, 2, v88
	v_and_b32_e32 v146, 12, v89
	v_ashrrev_i32_e32 v89, 1, v88
	v_and_b32_e32 v89, 0xffffff80, v89
	v_and_or_b32 v88, v88, 15, s0
	v_add_u32_e32 v172, v88, v89
	v_or_b32_e32 v182, v142, v146
	v_ashrrev_i32_e32 v173, 31, v172
	v_ashrrev_i32_e32 v183, 31, v182
	v_lshlrev_b64 v[88:89], 12, v[172:173]
	v_lshlrev_b64 v[92:93], 2, v[182:183]
	v_lshl_add_u64 v[140:141], s[2:3], 0, v[88:89]
	v_lshl_add_u64 v[88:89], s[4:5], 0, v[92:93]
	global_load_dwordx4 v[136:139], v[88:89], off
	s_mov_b32 s24, 0xbfb8aa3b
	s_mov_b32 s25, 0x42ce8ed0
	s_mov_b32 s26, 0xc2b17218
	s_mov_b32 s37, 0x3f2aaaab
	s_mov_b32 s38, 0x3f317218
	v_lshl_add_u64 v[88:89], s[6:7], 0, v[92:93]
	v_lshl_add_u64 v[92:93], s[8:9], 0, v[92:93]
	global_load_dwordx4 v[92:95], v[92:93], off
	s_mov_b32 s27, 0x7f800000
	global_load_dwordx4 v[88:91], v[88:89], off
	s_mov_b32 s39, 0x33800000
	s_mov_b32 s40, 0xbd4ccccd
	s_mov_b32 s44, 0xc1000000
	s_waitcnt vmcnt(2)
	v_mul_f32_e32 v143, 0xbfb8aa3b, v136
	v_fma_f32 v145, v136, s24, -v143
	v_rndne_f32_e32 v149, v143
	v_fmac_f32_e32 v145, 0xb2a5705f, v136
	v_sub_f32_e32 v143, v143, v149
	v_add_f32_e32 v143, v143, v145
	v_exp_f32_e32 v143, v143
	v_cvt_i32_f32_e32 v145, v149
	v_cmp_nlt_f32_e32 vcc, s25, v136
	s_waitcnt vmcnt(1)
	v_add_f32_e32 v128, v128, v92
	v_mul_f32_e32 v128, 0xbfb8aa3b, v128
	v_ldexp_f32 v143, v143, v145
	v_cndmask_b32_e32 v143, 0, v143, vcc
	v_cmp_ngt_f32_e32 vcc, s26, v136
	v_exp_f32_e32 v128, v128
	v_add_f32_e32 v112, v112, v92
	v_cndmask_b32_e32 v143, v209, v143, vcc
	v_add_f32_e32 v136, 1.0, v143
	v_add_f32_e32 v145, -1.0, v136
	v_sub_f32_e32 v149, v145, v136
	v_add_f32_e32 v149, 1.0, v149
	v_sub_f32_e32 v145, v143, v145
	v_add_f32_e32 v145, v145, v149
	v_frexp_mant_f32_e32 v149, v136
	v_cvt_f64_f32_e32 v[150:151], v136
	v_cmp_gt_f32_e32 vcc, s37, v149
	v_frexp_exp_i32_f64_e32 v149, v[150:151]
	v_add_f32_e32 v128, 1.0, v128
	v_subbrev_co_u32_e32 v158, vcc, 0, v149, vcc
	v_sub_u32_e32 v149, 0, v158
	v_ldexp_f32 v136, v136, v149
	v_ldexp_f32 v145, v145, v149
	v_add_f32_e32 v149, -1.0, v136
	v_add_f32_e32 v150, 1.0, v149
	v_sub_f32_e32 v150, v136, v150
	v_add_f32_e32 v150, v145, v150
	v_add_f32_e32 v151, v149, v150
	v_sub_f32_e32 v149, v149, v151
	v_add_f32_e32 v149, v150, v149
	v_add_f32_e32 v150, 1.0, v136
	v_add_f32_e32 v152, -1.0, v150
	v_sub_f32_e32 v136, v136, v152
	v_add_f32_e32 v136, v145, v136
	v_add_f32_e32 v145, v150, v136
	v_rcp_f32_e32 v159, v145
	v_sub_f32_e32 v150, v150, v145
	v_add_f32_e32 v136, v136, v150
	v_cmp_nlt_f32_e32 vcc, s25, v137
	v_mul_f32_e32 v160, v151, v159
	v_mul_f32_e32 v152, v145, v160
	v_fma_f32 v154, v160, v145, -v152
	v_fmac_f32_e32 v154, v160, v136
	v_add_f32_e32 v150, v152, v154
	v_sub_f32_e32 v153, v151, v150
	v_pk_add_f32 v[156:157], v[150:151], v[152:153] neg_lo:[0,1] neg_hi:[0,1]
	v_mov_b32_e32 v155, v150
	v_pk_add_f32 v[150:151], v[156:157], v[154:155] neg_lo:[0,1] neg_hi:[0,1]
	v_mul_f32_e32 v112, 0xbfb8aa3b, v112
	v_add_f32_e32 v149, v149, v151
	v_add_f32_e32 v149, v150, v149
	v_add_f32_e32 v151, v153, v149
	v_mul_f32_e32 v161, v159, v151
	v_mul_f32_e32 v152, v145, v161
	v_fma_f32 v154, v161, v145, -v152
	v_fmac_f32_e32 v154, v161, v136
	v_add_f32_e32 v150, v152, v154
	v_sub_f32_e32 v136, v153, v151
	v_sub_f32_e32 v153, v151, v150
	v_pk_add_f32 v[156:157], v[150:151], v[152:153] neg_lo:[0,1] neg_hi:[0,1]
	v_mov_b32_e32 v155, v150
	v_add_f32_e32 v136, v149, v136
	v_pk_add_f32 v[150:151], v[156:157], v[154:155] neg_lo:[0,1] neg_hi:[0,1]
	v_add_f32_e32 v145, v160, v161
	v_add_f32_e32 v136, v136, v151
	v_add_f32_e32 v136, v150, v136
	v_add_f32_e32 v136, v153, v136
	v_sub_f32_e32 v149, v145, v160
	v_mul_f32_e32 v136, v159, v136
	v_sub_f32_e32 v149, v161, v149
	v_add_f32_e32 v136, v149, v136
	v_add_f32_e32 v151, v145, v136
	v_cvt_f32_i32_e32 v150, v158
	v_mul_f32_e32 v152, v151, v151
	v_fmamk_f32 v149, v152, 0x3e9b6dac, v195
	v_fmaak_f32 v149, v152, v149, 0x3f2aaada
	v_sub_f32_e32 v145, v151, v145
	v_ldexp_f32 v153, v151, 1
	v_mul_f32_e32 v151, v151, v152
	v_pk_mul_f32 v[154:155], v[150:151], v[148:149]
	v_sub_f32_e32 v136, v136, v145
	v_fma_f32 v152, v150, s38, -v154
	v_fmac_f32_e32 v152, 0xb102e308, v150
	v_pk_add_f32 v[156:157], v[154:155], v[152:153]
	v_ldexp_f32 v136, v136, 1
	v_sub_f32_e32 v145, v157, v153
	v_sub_f32_e32 v145, v155, v145
	v_add_f32_e32 v159, v136, v145
	v_mul_f32_e32 v136, 0xbfb8aa3b, v137
	v_fma_f32 v145, v137, s24, -v136
	v_rndne_f32_e32 v149, v136
	v_fmac_f32_e32 v145, 0xb2a5705f, v137
	v_sub_f32_e32 v136, v136, v149
	v_add_f32_e32 v136, v136, v145
	v_exp_f32_e32 v136, v136
	v_cvt_i32_f32_e32 v145, v149
	v_mov_b32_e32 v158, v154
	v_pk_add_f32 v[154:155], v[156:157], v[154:155] neg_lo:[0,1] neg_hi:[0,1]
	v_pk_add_f32 v[160:161], v[156:157], v[158:159]
	v_ldexp_f32 v136, v136, v145
	v_cndmask_b32_e32 v136, 0, v136, vcc
	v_cmp_ngt_f32_e32 vcc, s26, v137
	v_mov_b32_e32 v155, v161
	v_mov_b32_e32 v153, v156
	v_cndmask_b32_e32 v173, v209, v136, vcc
	v_add_f32_e32 v145, 1.0, v173
	v_add_f32_e32 v136, -1.0, v145
	v_sub_f32_e32 v137, v136, v145
	v_add_f32_e32 v137, 1.0, v137
	v_sub_f32_e32 v136, v173, v136
	v_pk_add_f32 v[150:151], v[152:153], v[154:155] neg_lo:[0,1] neg_hi:[0,1]
	v_pk_add_f32 v[152:153], v[152:153], v[154:155]
	v_add_f32_e32 v149, v136, v137
	v_frexp_mant_f32_e32 v136, v145
	v_pk_add_f32 v[154:155], v[152:153], v[156:157] op_sel:[1,0] op_sel_hi:[0,1] neg_lo:[0,1] neg_hi:[0,1]
	v_cmp_gt_f32_e32 vcc, s37, v136
	v_cvt_f64_f32_e32 v[136:137], v145
	v_pk_add_f32 v[162:163], v[160:161], v[154:155] op_sel_hi:[1,0] neg_lo:[0,1] neg_hi:[0,1]
	v_mov_b32_e32 v152, v161
	v_pk_mov_b32 v[154:155], v[156:157], v[154:155] op_sel:[1,0]
	v_frexp_exp_i32_f64_e32 v136, v[136:137]
	v_pk_add_f32 v[154:155], v[152:153], v[154:155] neg_lo:[0,1] neg_hi:[0,1]
	v_subbrev_co_u32_e32 v152, vcc, 0, v136, vcc
	v_sub_u32_e32 v136, 0, v152
	v_ldexp_f32 v145, v145, v136
	v_ldexp_f32 v136, v149, v136
	v_add_f32_e32 v149, -1.0, v145
	v_mov_b32_e32 v158, v159
	v_mov_b32_e32 v159, v156
	v_add_f32_e32 v137, 1.0, v149
	v_pk_add_f32 v[154:155], v[158:159], v[154:155] neg_lo:[0,1] neg_hi:[0,1]
	v_mov_b32_e32 v162, v150
	v_sub_f32_e32 v137, v145, v137
	v_pk_add_f32 v[156:157], v[162:163], v[154:155]
	v_add_f32_e32 v155, v136, v137
	v_add_f32_e32 v137, v149, v155
	v_sub_f32_e32 v149, v149, v137
	v_add_f32_e32 v149, v155, v149
	v_add_f32_e32 v155, 1.0, v145
	v_add_f32_e32 v158, -1.0, v155
	v_sub_f32_e32 v145, v145, v158
	v_add_f32_e32 v136, v136, v145
	v_add_f32_e32 v145, v155, v136
	v_rcp_f32_e32 v164, v145
	v_sub_f32_e32 v155, v155, v145
	v_add_f32_e32 v155, v136, v155
	v_cmp_nlt_f32_e32 vcc, s25, v138
	v_mul_f32_e32 v165, v137, v164
	v_mul_f32_e32 v158, v145, v165
	v_fma_f32 v160, v165, v145, -v158
	v_fmac_f32_e32 v160, v165, v155
	v_add_f32_e32 v136, v158, v160
	v_sub_f32_e32 v159, v137, v136
	v_pk_add_f32 v[162:163], v[136:137], v[158:159] neg_lo:[0,1] neg_hi:[0,1]
	v_mov_b32_e32 v161, v136
	v_pk_add_f32 v[136:137], v[162:163], v[160:161] neg_lo:[0,1] neg_hi:[0,1]
	v_exp_f32_e32 v112, v112
	v_add_f32_e32 v137, v149, v137
	v_add_f32_e32 v136, v136, v137
	v_add_f32_e32 v137, v159, v136
	v_mul_f32_e32 v149, v164, v137
	v_mul_f32_e32 v158, v145, v149
	v_fma_f32 v160, v149, v145, -v158
	v_fmac_f32_e32 v160, v149, v155
	v_sub_f32_e32 v145, v159, v137
	v_add_f32_e32 v145, v136, v145
	v_add_f32_e32 v136, v158, v160
	v_sub_f32_e32 v159, v137, v136
	v_pk_add_f32 v[162:163], v[136:137], v[158:159] neg_lo:[0,1] neg_hi:[0,1]
	v_mov_b32_e32 v161, v136
	v_pk_add_f32 v[136:137], v[162:163], v[160:161] neg_lo:[0,1] neg_hi:[0,1]
	v_add_f32_e32 v72, v72, v92
	v_add_f32_e32 v137, v145, v137
	v_add_f32_e32 v136, v136, v137
	v_add_f32_e32 v137, v165, v149
	v_add_f32_e32 v136, v159, v136
	v_sub_f32_e32 v145, v137, v165
	v_mul_f32_e32 v136, v164, v136
	v_sub_f32_e32 v145, v149, v145
	v_add_f32_e32 v145, v145, v136
	v_add_f32_e32 v155, v137, v145
	v_mul_f32_e32 v158, v155, v155
	v_fmamk_f32 v136, v158, 0x3e9b6dac, v195
	v_fmaak_f32 v149, v158, v136, 0x3f2aaada
	v_cvt_f32_i32_e32 v136, v152
	v_sub_f32_e32 v137, v155, v137
	v_sub_f32_e32 v137, v145, v137
	v_ldexp_f32 v145, v137, 1
	v_mul_f32_e32 v137, v155, v158
	v_pk_mul_f32 v[160:161], v[136:137], v[148:149]
	v_ldexp_f32 v159, v155, 1
	v_fma_f32 v158, v136, s38, -v160
	v_fmac_f32_e32 v158, 0xb102e308, v136
	v_pk_add_f32 v[136:137], v[160:161], v[158:159]
	v_mov_b32_e32 v162, v160
	v_sub_f32_e32 v149, v137, v159
	v_sub_f32_e32 v149, v161, v149
	v_add_f32_e32 v163, v145, v149
	v_pk_add_f32 v[160:161], v[136:137], v[160:161] neg_lo:[0,1] neg_hi:[0,1]
	v_pk_add_f32 v[164:165], v[136:137], v[162:163]
	v_mov_b32_e32 v159, v136
	v_mov_b32_e32 v161, v165
	v_pk_add_f32 v[178:179], v[158:159], v[160:161]
	v_pk_add_f32 v[174:175], v[158:159], v[160:161] neg_lo:[0,1] neg_hi:[0,1]
	v_pk_add_f32 v[158:159], v[178:179], v[136:137] op_sel:[1,0] op_sel_hi:[0,1] neg_lo:[0,1] neg_hi:[0,1]
	v_pk_add_f32 v[160:161], v[164:165], v[158:159] op_sel_hi:[1,0] neg_lo:[0,1] neg_hi:[0,1]
	v_pk_mov_b32 v[158:159], v[136:137], v[158:159] op_sel:[1,0]
	v_mov_b32_e32 v162, v163
	v_mov_b32_e32 v163, v136
	v_mul_f32_e32 v136, 0xbfb8aa3b, v138
	v_fma_f32 v137, v138, s24, -v136
	v_rndne_f32_e32 v145, v136
	v_fmac_f32_e32 v137, 0xb2a5705f, v138
	v_sub_f32_e32 v136, v136, v145
	v_add_f32_e32 v136, v136, v137
	v_exp_f32_e32 v136, v136
	v_cvt_i32_f32_e32 v137, v145
	v_mov_b32_e32 v178, v165
	v_pk_add_f32 v[158:159], v[178:179], v[158:159] neg_lo:[0,1] neg_hi:[0,1]
	v_mov_b32_e32 v160, v174
	v_ldexp_f32 v136, v136, v137
	v_cndmask_b32_e32 v136, 0, v136, vcc
	v_cmp_ngt_f32_e32 vcc, s26, v138
	v_pk_add_f32 v[176:177], v[162:163], v[158:159] neg_lo:[0,1] neg_hi:[0,1]
	v_mul_f32_e32 v72, 0xbfb8aa3b, v72
	v_cndmask_b32_e32 v145, v209, v136, vcc
	v_add_f32_e32 v138, 1.0, v145
	v_add_f32_e32 v136, -1.0, v138
	v_sub_f32_e32 v137, v136, v138
	v_add_f32_e32 v137, 1.0, v137
	v_sub_f32_e32 v136, v145, v136
	v_add_f32_e32 v149, v136, v137
	v_frexp_mant_f32_e32 v136, v138
	v_cmp_gt_f32_e32 vcc, s37, v136
	v_cvt_f64_f32_e32 v[136:137], v138
	v_frexp_exp_i32_f64_e32 v136, v[136:137]
	v_subbrev_co_u32_e32 v152, vcc, 0, v136, vcc
	v_sub_u32_e32 v136, 0, v152
	v_ldexp_f32 v138, v138, v136
	v_ldexp_f32 v136, v149, v136
	v_add_f32_e32 v149, -1.0, v138
	v_add_f32_e32 v137, 1.0, v149
	v_sub_f32_e32 v137, v138, v137
	v_add_f32_e32 v155, v136, v137
	v_add_f32_e32 v137, v149, v155
	v_sub_f32_e32 v149, v149, v137
	v_add_f32_e32 v149, v155, v149
	v_add_f32_e32 v155, 1.0, v138
	v_add_f32_e32 v158, -1.0, v155
	v_sub_f32_e32 v138, v138, v158
	v_add_f32_e32 v136, v136, v138
	v_add_f32_e32 v138, v155, v136
	v_rcp_f32_e32 v164, v138
	v_sub_f32_e32 v155, v155, v138
	v_pk_add_f32 v[180:181], v[160:161], v[176:177]
	v_add_f32_e32 v155, v136, v155
	v_mul_f32_e32 v165, v137, v164
	v_mul_f32_e32 v158, v138, v165
	v_fma_f32 v160, v165, v138, -v158
	v_fmac_f32_e32 v160, v165, v155
	v_add_f32_e32 v136, v158, v160
	v_sub_f32_e32 v159, v137, v136
	v_pk_add_f32 v[162:163], v[136:137], v[158:159] neg_lo:[0,1] neg_hi:[0,1]
	v_mov_b32_e32 v161, v136
	v_pk_add_f32 v[136:137], v[162:163], v[160:161] neg_lo:[0,1] neg_hi:[0,1]
	v_cmp_nlt_f32_e32 vcc, s25, v139
	v_add_f32_e32 v137, v149, v137
	v_add_f32_e32 v136, v136, v137
	v_add_f32_e32 v137, v159, v136
	v_mul_f32_e32 v149, v164, v137
	v_mul_f32_e32 v158, v138, v149
	v_fma_f32 v160, v149, v138, -v158
	v_fmac_f32_e32 v160, v149, v155
	v_sub_f32_e32 v138, v159, v137
	v_add_f32_e32 v138, v136, v138
	v_add_f32_e32 v136, v158, v160
	v_sub_f32_e32 v159, v137, v136
	v_pk_add_f32 v[162:163], v[136:137], v[158:159] neg_lo:[0,1] neg_hi:[0,1]
	v_mov_b32_e32 v161, v136
	v_pk_add_f32 v[136:137], v[162:163], v[160:161] neg_lo:[0,1] neg_hi:[0,1]
	v_exp_f32_e32 v72, v72
	v_add_f32_e32 v137, v138, v137
	v_add_f32_e32 v136, v136, v137
	v_add_f32_e32 v137, v165, v149
	v_add_f32_e32 v136, v159, v136
	v_sub_f32_e32 v138, v137, v165
	v_mul_f32_e32 v136, v164, v136
	v_sub_f32_e32 v138, v149, v138
	v_add_f32_e32 v138, v138, v136
	v_add_f32_e32 v155, v137, v138
	v_mul_f32_e32 v158, v155, v155
	v_fmamk_f32 v136, v158, 0x3e9b6dac, v195
	v_fmaak_f32 v149, v158, v136, 0x3f2aaada
	v_cvt_f32_i32_e32 v136, v152
	v_sub_f32_e32 v137, v155, v137
	v_sub_f32_e32 v137, v138, v137
	v_ldexp_f32 v138, v137, 1
	v_mul_f32_e32 v137, v155, v158
	v_pk_mul_f32 v[158:159], v[136:137], v[148:149]
	v_ldexp_f32 v161, v155, 1
	v_fma_f32 v160, v136, s38, -v158
	v_fmac_f32_e32 v160, 0xb102e308, v136
	v_pk_add_f32 v[136:137], v[158:159], v[160:161]
	v_mov_b32_e32 v162, v158
	v_sub_f32_e32 v149, v137, v161
	v_sub_f32_e32 v149, v159, v149
	v_add_f32_e32 v163, v138, v149
	v_pk_add_f32 v[164:165], v[136:137], v[158:159] neg_lo:[0,1] neg_hi:[0,1]
	v_pk_add_f32 v[166:167], v[136:137], v[162:163]
	v_mov_b32_e32 v161, v136
	v_mov_b32_e32 v165, v167
	v_pk_add_f32 v[158:159], v[160:161], v[164:165] neg_lo:[0,1] neg_hi:[0,1]
	v_pk_add_f32 v[160:161], v[160:161], v[164:165]
	v_mov_b32_e32 v162, v163
	v_pk_add_f32 v[164:165], v[160:161], v[136:137] op_sel:[1,0] op_sel_hi:[0,1] neg_lo:[0,1] neg_hi:[0,1]
	v_pk_add_f32 v[168:169], v[166:167], v[164:165] op_sel_hi:[1,0] neg_lo:[0,1] neg_hi:[0,1]
	v_pk_mov_b32 v[164:165], v[136:137], v[164:165] op_sel:[1,0]
	v_mov_b32_e32 v163, v136
	v_mul_f32_e32 v136, 0xbfb8aa3b, v139
	v_fma_f32 v137, v139, s24, -v136
	v_rndne_f32_e32 v138, v136
	v_fmac_f32_e32 v137, 0xb2a5705f, v139
	v_sub_f32_e32 v136, v136, v138
	v_add_f32_e32 v136, v136, v137
	v_exp_f32_e32 v136, v136
	v_cvt_i32_f32_e32 v137, v138
	v_mov_b32_e32 v160, v167
	v_pk_add_f32 v[164:165], v[160:161], v[164:165] neg_lo:[0,1] neg_hi:[0,1]
	v_mov_b32_e32 v168, v158
	v_ldexp_f32 v136, v136, v137
	v_cndmask_b32_e32 v136, 0, v136, vcc
	v_cmp_ngt_f32_e32 vcc, s26, v139
	v_pk_add_f32 v[162:163], v[162:163], v[164:165] neg_lo:[0,1] neg_hi:[0,1]
	v_add_f32_e32 v112, 1.0, v112
	v_cndmask_b32_e32 v178, v209, v136, vcc
	v_add_f32_e32 v138, 1.0, v178
	v_add_f32_e32 v136, -1.0, v138
	v_sub_f32_e32 v137, v136, v138
	v_add_f32_e32 v137, 1.0, v137
	v_sub_f32_e32 v136, v178, v136
	v_add_f32_e32 v139, v136, v137
	v_frexp_mant_f32_e32 v136, v138
	v_cmp_gt_f32_e32 vcc, s37, v136
	v_cvt_f64_f32_e32 v[136:137], v138
	v_frexp_exp_i32_f64_e32 v136, v[136:137]
	v_subbrev_co_u32_e32 v152, vcc, 0, v136, vcc
	v_sub_u32_e32 v136, 0, v152
	v_ldexp_f32 v138, v138, v136
	v_ldexp_f32 v136, v139, v136
	v_add_f32_e32 v139, -1.0, v138
	v_add_f32_e32 v137, 1.0, v139
	v_sub_f32_e32 v137, v138, v137
	v_add_f32_e32 v149, v136, v137
	v_add_f32_e32 v137, v139, v149
	v_sub_f32_e32 v139, v139, v137
	v_add_f32_e32 v149, v149, v139
	v_add_f32_e32 v139, 1.0, v138
	v_add_f32_e32 v155, -1.0, v139
	v_sub_f32_e32 v138, v138, v155
	v_add_f32_e32 v136, v136, v138
	v_add_f32_e32 v155, v139, v136
	v_pk_add_f32 v[164:165], v[168:169], v[162:163]
	v_rcp_f32_e32 v163, v155
	v_sub_f32_e32 v138, v139, v155
	v_add_f32_e32 v160, v136, v138
	v_rcp_f32_e32 v247, v112
	v_mul_f32_e32 v170, v137, v163
	v_mul_f32_e32 v138, v155, v170
	v_fma_f32 v166, v170, v155, -v138
	v_fmac_f32_e32 v166, v170, v160
	v_add_f32_e32 v136, v138, v166
	v_sub_f32_e32 v139, v137, v136
	v_pk_add_f32 v[168:169], v[136:137], v[138:139] neg_lo:[0,1] neg_hi:[0,1]
	v_mov_b32_e32 v167, v136
	v_pk_add_f32 v[136:137], v[168:169], v[166:167] neg_lo:[0,1] neg_hi:[0,1]
	s_waitcnt vmcnt(0)
	v_add_f32_e32 v112, v117, v89
	v_add_f32_e32 v137, v149, v137
	v_add_f32_e32 v136, v136, v137
	v_add_f32_e32 v137, v139, v136
	v_mul_f32_e32 v149, v163, v137
	v_mul_f32_e32 v138, v155, v149
	v_fma_f32 v166, v149, v155, -v138
	v_fmac_f32_e32 v166, v149, v160
	v_sub_f32_e32 v139, v139, v137
	v_add_f32_e32 v155, v136, v139
	v_add_f32_e32 v136, v138, v166
	v_sub_f32_e32 v139, v137, v136
	v_pk_add_f32 v[168:169], v[136:137], v[138:139] neg_lo:[0,1] neg_hi:[0,1]
	v_mov_b32_e32 v167, v136
	v_pk_add_f32 v[136:137], v[168:169], v[166:167] neg_lo:[0,1] neg_hi:[0,1]
	v_mul_f32_e32 v112, 0xbfb8aa3b, v112
	v_add_f32_e32 v137, v155, v137
	v_add_f32_e32 v136, v136, v137
	v_add_f32_e32 v137, v170, v149
	v_add_f32_e32 v136, v139, v136
	v_sub_f32_e32 v138, v137, v170
	v_mul_f32_e32 v136, v163, v136
	v_sub_f32_e32 v138, v149, v138
	v_add_f32_e32 v138, v138, v136
	v_add_f32_e32 v139, v137, v138
	v_mul_f32_e32 v155, v139, v139
	v_fmamk_f32 v136, v155, 0x3e9b6dac, v195
	v_fmaak_f32 v149, v155, v136, 0x3f2aaada
	v_cvt_f32_i32_e32 v136, v152
	v_sub_f32_e32 v137, v139, v137
	v_sub_f32_e32 v137, v138, v137
	v_ldexp_f32 v152, v137, 1
	v_mul_f32_e32 v137, v139, v155
	v_ldexp_f32 v167, v139, 1
	v_pk_mul_f32 v[138:139], v[136:137], v[148:149]
	v_add_f32_e32 v72, 1.0, v72
	v_fma_f32 v166, v136, s38, -v138
	v_fmac_f32_e32 v166, 0xb102e308, v136
	v_pk_add_f32 v[136:137], v[138:139], v[166:167]
	v_mov_b32_e32 v168, v138
	v_sub_f32_e32 v149, v137, v167
	v_sub_f32_e32 v149, v139, v149
	v_add_f32_e32 v169, v152, v149
	v_pk_add_f32 v[170:171], v[136:137], v[138:139] neg_lo:[0,1] neg_hi:[0,1]
	v_pk_add_f32 v[200:201], v[136:137], v[168:169]
	v_mov_b32_e32 v167, v136
	v_mov_b32_e32 v171, v201
	v_pk_add_f32 v[138:139], v[166:167], v[170:171] neg_lo:[0,1] neg_hi:[0,1]
	v_pk_add_f32 v[170:171], v[166:167], v[170:171]
	v_mov_b32_e32 v168, v169
	v_pk_add_f32 v[166:167], v[170:171], v[136:137] op_sel:[1,0] op_sel_hi:[0,1] neg_lo:[0,1] neg_hi:[0,1]
	v_pk_add_f32 v[206:207], v[200:201], v[166:167] op_sel_hi:[1,0] neg_lo:[0,1] neg_hi:[0,1]
	v_pk_mov_b32 v[166:167], v[136:137], v[166:167] op_sel:[1,0]
	v_mov_b32_e32 v169, v136
	v_lshl_add_u64 v[136:137], v[182:183], 1, v[140:141]
	v_add_co_u32_e32 v200, vcc, s33, v136
	v_mov_b32_e32 v170, v201
	s_nop 0
	v_addc_co_u32_e32 v201, vcc, 0, v137, vcc
	global_load_dwordx2 v[182:183], v[136:137], off
	v_pk_add_f32 v[166:167], v[170:171], v[166:167] neg_lo:[0,1] neg_hi:[0,1]
	global_load_dwordx2 v[200:201], v[200:201], off
	v_pk_add_f32 v[166:167], v[168:169], v[166:167] neg_lo:[0,1] neg_hi:[0,1]
	v_mov_b32_e32 v206, v138
	v_pk_add_f32 v[168:169], v[206:207], v[166:167]
	v_rcp_f32_e32 v167, v128
	v_add_f32_e32 v128, v133, v89
	v_mul_f32_e32 v128, 0xbfb8aa3b, v128
	v_exp_f32_e32 v128, v128
	v_add_f32_e32 v121, v121, v93
	v_exp_f32_e32 v112, v112
	v_rcp_f32_e32 v203, v72
	v_add_f32_e32 v128, 1.0, v128
	v_rcp_f32_e32 v128, v128
	v_add_f32_e32 v72, v77, v89
	v_mul_f32_e32 v121, 0xbfb8aa3b, v121
	v_mul_f32_e32 v72, 0xbfb8aa3b, v72
	v_mul_f32_e32 v241, 0xc1000000, v128
	v_add_f32_e32 v128, v134, v90
	v_exp_f32_e32 v121, v121
	v_exp_f32_e32 v72, v72
	v_mul_f32_e32 v128, 0xbfb8aa3b, v128
	v_exp_f32_e32 v128, v128
	v_add_f32_e32 v120, v120, v92
	v_add_f32_e32 v112, 1.0, v112
	v_add_f32_e32 v96, v96, v92
	v_mul_f32_e32 v120, 0xbfb8aa3b, v120
	v_rcp_f32_e32 v112, v112
	v_mul_f32_e32 v96, 0xbfb8aa3b, v96
	v_exp_f32_e32 v120, v120
	v_add_f32_e32 v121, 1.0, v121
	v_add_f32_e32 v104, v104, v92
	v_exp_f32_e32 v96, v96
	v_add_f32_e32 v73, v73, v93
	v_add_f32_e32 v72, 1.0, v72
	v_rcp_f32_e32 v244, v121
	v_add_f32_e32 v121, v122, v94
	v_mul_f32_e32 v104, 0xbfb8aa3b, v104
	v_rcp_f32_e32 v122, v72
	v_mul_f32_e32 v72, 0xbfb8aa3b, v73
	v_add_f32_e32 v128, 1.0, v128
	v_exp_f32_e32 v104, v104
	v_exp_f32_e32 v72, v72
	v_rcp_f32_e32 v128, v128
	v_mul_f32_e32 v250, 0xc1000000, v112
	v_add_f32_e32 v112, v118, v90
	v_add_f32_e32 v120, 1.0, v120
	v_mul_f32_e32 v112, 0xbfb8aa3b, v112
	v_add_f32_e32 v96, 1.0, v96
	v_add_f32_e32 v129, v129, v93
	v_rcp_f32_e32 v243, v120
	v_add_f32_e32 v120, v125, v89
	v_exp_f32_e32 v112, v112
	v_rcp_f32_e32 v199, v96
	v_add_f32_e32 v96, v101, v89
	v_mul_f32_e32 v129, 0xbfb8aa3b, v129
	v_mul_f32_e32 v120, 0xbfb8aa3b, v120
	v_add_f32_e32 v104, 1.0, v104
	v_mul_f32_e32 v96, 0xbfb8aa3b, v96
	v_add_f32_e32 v72, 1.0, v72
	v_exp_f32_e32 v129, v129
	v_mul_f32_e32 v215, 0xc1000000, v128
	v_add_f32_e32 v128, v135, v91
	v_exp_f32_e32 v120, v120
	v_rcp_f32_e32 v251, v104
	v_add_f32_e32 v104, v109, v89
	v_exp_f32_e32 v96, v96
	v_rcp_f32_e32 v208, v72
	v_add_f32_e32 v72, v78, v90
	v_mul_f32_e32 v128, 0xbfb8aa3b, v128
	v_mul_f32_e32 v104, 0xbfb8aa3b, v104
	v_mul_f32_e32 v72, 0xbfb8aa3b, v72
	v_add_f32_e32 v64, v64, v88
	v_exp_f32_e32 v128, v128
	v_add_f32_e32 v112, 1.0, v112
	v_exp_f32_e32 v104, v104
	v_exp_f32_e32 v72, v72
	v_mul_f32_e32 v64, 0xbfb8aa3b, v64
	v_rcp_f32_e32 v112, v112
	v_exp_f32_e32 v64, v64
	v_add_f32_e32 v129, 1.0, v129
	v_add_f32_e32 v120, 1.0, v120
	v_add_f32_e32 v96, 1.0, v96
	v_rcp_f32_e32 v238, v129
	v_add_f32_e32 v129, v130, v94
	v_rcp_f32_e32 v120, v120
	v_rcp_f32_e32 v96, v96
	v_add_f32_e32 v132, v132, v88
	v_mul_f32_e32 v129, 0xbfb8aa3b, v129
	v_add_f32_e32 v128, 1.0, v128
	v_add_f32_e32 v104, 1.0, v104
	v_add_f32_e32 v73, v74, v94
	v_add_f32_e32 v72, 1.0, v72
	v_mul_f32_e32 v132, 0xbfb8aa3b, v132
	v_exp_f32_e32 v129, v129
	v_rcp_f32_e32 v128, v128
	v_mul_f32_e32 v223, 0xc1000000, v112
	v_add_f32_e32 v112, v119, v91
	v_rcp_f32_e32 v104, v104
	v_add_f32_e32 v98, v98, v94
	v_rcp_f32_e32 v119, v72
	v_mul_f32_e32 v72, 0xbfb8aa3b, v73
	v_add_f32_e32 v68, v68, v92
	v_add_f32_e32 v64, 1.0, v64
	v_exp_f32_e32 v132, v132
	v_mul_f32_e32 v98, 0xbfb8aa3b, v98
	v_exp_f32_e32 v72, v72
	v_rcp_f32_e32 v77, v64
	v_mul_f32_e32 v64, 0xbfb8aa3b, v68
	v_mul_f32_e32 v246, 0xc1000000, v120
	v_add_f32_e32 v120, v126, v90
	v_mul_f32_e32 v101, 0xc1000000, v96
	v_add_f32_e32 v96, v102, v90
	v_exp_f32_e32 v98, v98
	v_exp_f32_e32 v64, v64
	v_mul_f32_e32 v120, 0xbfb8aa3b, v120
	v_mul_f32_e32 v96, 0xbfb8aa3b, v96
	s_waitcnt vmcnt(1)
	v_lshlrev_b32_e32 v163, 16, v182
	v_and_b32_e32 v160, 0xffff0000, v182
	v_add_f32_e32 v129, 1.0, v129
	v_mul_f32_e32 v216, 0xc1000000, v128
	v_ashrrev_i32_e32 v128, 5, v172
	v_lshlrev_b32_e32 v130, 4, v172
	s_waitcnt vmcnt(0)
	v_lshlrev_b32_e32 v182, 16, v201
	v_and_b32_e32 v172, 0xffff0000, v201
	v_exp_f32_e32 v120, v120
	v_mul_f32_e32 v201, 0xc1000000, v104
	v_add_f32_e32 v104, v110, v90
	v_exp_f32_e32 v96, v96
	v_add_f32_e32 v84, v84, v88
	v_add_f32_e32 v132, 1.0, v132
	v_rcp_f32_e32 v214, v129
	v_add_f32_e32 v129, v131, v95
	v_mul_f32_e32 v104, 0xbfb8aa3b, v104
	v_mul_f32_e32 v84, 0xbfb8aa3b, v84
	v_add_f32_e32 v72, 1.0, v72
	v_rcp_f32_e32 v132, v132
	v_mul_f32_e32 v129, 0xbfb8aa3b, v129
	v_exp_f32_e32 v104, v104
	v_add_f32_e32 v98, 1.0, v98
	v_exp_f32_e32 v84, v84
	v_add_f32_e32 v81, v81, v93
	v_rcp_f32_e32 v236, v72
	v_add_f32_e32 v72, v79, v91
	v_add_f32_e32 v64, 1.0, v64
	v_exp_f32_e32 v129, v129
	v_rcp_f32_e32 v230, v98
	v_add_f32_e32 v98, v99, v95
	v_mul_f32_e32 v81, 0xbfb8aa3b, v81
	v_add_f32_e32 v76, v76, v88
	v_mul_f32_e32 v72, 0xbfb8aa3b, v72
	v_rcp_f32_e32 v68, v64
	v_add_f32_e32 v64, v65, v89
	v_add_f32_e32 v120, 1.0, v120
	v_mul_f32_e32 v121, 0xbfb8aa3b, v121
	v_add_f32_e32 v96, 1.0, v96
	v_mul_f32_e32 v98, 0xbfb8aa3b, v98
	v_add_f32_e32 v80, v80, v92
	v_exp_f32_e32 v81, v81
	v_mul_f32_e32 v76, 0xbfb8aa3b, v76
	v_exp_f32_e32 v72, v72
	v_mul_f32_e32 v64, 0xbfb8aa3b, v64
	v_rcp_f32_e32 v120, v120
	v_exp_f32_e32 v121, v121
	v_add_f32_e32 v116, v116, v88
	v_rcp_f32_e32 v96, v96
	v_exp_f32_e32 v98, v98
	v_mul_f32_e32 v80, 0xbfb8aa3b, v80
	v_add_f32_e32 v82, v82, v94
	v_exp_f32_e32 v76, v76
	v_exp_f32_e32 v64, v64
	v_ashrrev_i32_e32 v152, 4, v142
	v_mul_f32_e32 v240, 0xc1000000, v132
	v_and_b32_e32 v132, 0xffffff80, v128
	v_mul_f32_e32 v116, 0xbfb8aa3b, v116
	v_add_f32_e32 v113, v113, v93
	v_add_f32_e32 v104, 1.0, v104
	v_add_f32_e32 v84, 1.0, v84
	v_exp_f32_e32 v80, v80
	v_mul_f32_e32 v82, 0xbfb8aa3b, v82
	v_add_f32_e32 v129, 1.0, v129
	v_add_u32_e32 v128, v132, v152
	v_exp_f32_e32 v116, v116
	v_mul_f32_e32 v113, 0xbfb8aa3b, v113
	v_rcp_f32_e32 v104, v104
	v_rcp_f32_e32 v84, v84
	v_exp_f32_e32 v82, v82
	v_lshlrev_b32_e32 v170, 16, v183
	v_and_b32_e32 v149, 0xffff0000, v183
	v_rcp_f32_e32 v183, v129
	v_ashrrev_i32_e32 v129, 31, v128
	v_and_b32_e32 v133, 0xf8f0, v130
	v_exp_f32_e32 v113, v113
	v_add_f32_e32 v81, 1.0, v81
	v_add_f32_e32 v73, v75, v95
	v_add_f32_e32 v72, 1.0, v72
	v_lshlrev_b64 v[128:129], 16, v[128:129]
	v_add_f32_e32 v121, 1.0, v121
	v_mul_f32_e32 v219, 0xc1000000, v120
	v_add_f32_e32 v120, v127, v91
	v_mul_f32_e32 v231, 0xc1000000, v96
	v_add_f32_e32 v96, v103, v91
	v_add_f32_e32 v98, 1.0, v98
	v_or_b32_e32 v127, 0x400, v133
	v_rcp_f32_e32 v103, v81
	v_add_f32_e32 v81, v86, v90
	v_add_f32_e32 v76, 1.0, v76
	v_rcp_f32_e32 v118, v72
	v_mul_f32_e32 v72, 0xbfb8aa3b, v73
	v_add_f32_e32 v65, v69, v93
	v_add_f32_e32 v64, 1.0, v64
	v_rcp_f32_e32 v218, v121
	v_add_f32_e32 v121, v123, v95
	v_rcp_f32_e32 v229, v98
	v_or3_b32 v98, v128, v127, v146
	v_mov_b32_e32 v99, v129
	v_add_f32_e32 v80, 1.0, v80
	v_mul_f32_e32 v81, 0xbfb8aa3b, v81
	v_rcp_f32_e32 v123, v76
	v_exp_f32_e32 v72, v72
	v_rcp_f32_e32 v76, v64
	v_mul_f32_e32 v64, 0xbfb8aa3b, v65
	v_add_f32_e32 v116, 1.0, v116
	v_mul_f32_e32 v227, 0xc1000000, v104
	v_add_f32_e32 v104, v111, v91
	v_lshl_add_u64 v[110:111], v[98:99], 3, s[14:15]
	v_rcp_f32_e32 v99, v80
	v_mul_f32_e32 v80, 0xc1000000, v84
	v_add_f32_e32 v84, v85, v89
	v_exp_f32_e32 v81, v81
	v_add_f32_e32 v82, 1.0, v82
	v_exp_f32_e32 v64, v64
	v_rcp_f32_e32 v116, v116
	v_add_f32_e32 v113, 1.0, v113
	v_mul_f32_e32 v84, 0xbfb8aa3b, v84
	v_rcp_f32_e32 v234, v82
	v_add_f32_e32 v82, v83, v95
	v_rcp_f32_e32 v248, v113
	v_add_f32_e32 v113, v114, v94
	v_exp_f32_e32 v84, v84
	v_mul_f32_e32 v82, 0xbfb8aa3b, v82
	v_mul_f32_e32 v113, 0xbfb8aa3b, v113
	v_exp_f32_e32 v82, v82
	v_add_f32_e32 v72, 1.0, v72
	v_or_b32_e32 v135, 0x600, v133
	v_exp_f32_e32 v113, v113
	v_add_f32_e32 v81, 1.0, v81
	v_rcp_f32_e32 v79, v72
	v_or3_b32 v72, v128, v135, v146
	v_mov_b32_e32 v73, v129
	v_add_f32_e32 v64, 1.0, v64
	v_mul_f32_e32 v249, 0xc1000000, v116
	v_rcp_f32_e32 v81, v81
	v_lshl_add_u64 v[116:117], v[72:73], 3, s[14:15]
	v_rcp_f32_e32 v189, v64
	v_mov_b32_e32 v64, v180
	v_mov_b32_e32 v65, v156
	v_mov_b32_e32 v72, v181
	v_mov_b32_e32 v73, v157
	v_add_f32_e32 v84, 1.0, v84
	v_pk_add_f32 v[72:73], v[64:65], v[72:73]
	v_mov_b32_e32 v152, v179
	v_rcp_f32_e32 v84, v84
	v_add_f32_e32 v82, 1.0, v82
	v_or_b32_e32 v134, 0x500, v133
	v_pk_add_f32 v[74:75], v[152:153], v[72:73]
	v_mov_b32_e32 v151, v153
	v_mov_b32_e32 v175, v179
	v_add_f32_e32 v113, 1.0, v113
	v_rcp_f32_e32 v233, v82
	v_or3_b32 v82, v128, v134, v146
	v_mov_b32_e32 v83, v129
	v_mov_b32_e32 v157, v75
	v_mov_b32_e32 v181, v74
	v_rcp_f32_e32 v222, v113
	v_add_f32_e32 v113, v115, v95
	v_mul_f32_e32 v235, 0xc1000000, v81
	v_add_f32_e32 v81, v87, v91
	v_lshl_add_u64 v[114:115], v[82:83], 3, s[14:15]
	v_pk_add_f32 v[82:83], v[156:157], v[150:151] neg_lo:[0,1] neg_hi:[0,1]
	v_pk_add_f32 v[86:87], v[180:181], v[174:175] neg_lo:[0,1] neg_hi:[0,1]
	v_add_f32_e32 v124, v124, v88
	v_add_f32_e32 v108, v108, v88
	v_add_f32_e32 v100, v100, v88
	v_mov_b32_e32 v155, v73
	v_mov_b32_e32 v88, v86
	v_mov_b32_e32 v89, v82
	v_mov_b32_e32 v177, v72
	v_mul_f32_e32 v207, 0xc1000000, v84
	v_pk_add_f32 v[84:85], v[154:155], v[82:83] neg_lo:[0,1] neg_hi:[0,1]
	v_pk_add_f32 v[64:65], v[64:65], v[88:89] neg_lo:[0,1] neg_hi:[0,1]
	v_mov_b32_e32 v175, v150
	v_pk_add_f32 v[72:73], v[176:177], v[86:87] neg_lo:[0,1] neg_hi:[0,1]
	v_pk_add_f32 v[64:65], v[174:175], v[64:65] neg_lo:[0,1] neg_hi:[0,1]
	v_mov_b32_e32 v82, v72
	v_mov_b32_e32 v83, v84
	v_pk_add_f32 v[64:65], v[82:83], v[64:65]
	v_mov_b32_e32 v84, v73
	v_pk_add_f32 v[64:65], v[64:65], v[84:85]
	v_cmp_neq_f32_e32 vcc, s27, v173
	v_pk_add_f32 v[64:65], v[74:75], v[64:65]
	v_cmp_lt_f32_e64 s[0:1], |v143|, s39
	v_cndmask_b32_e32 v64, v209, v64, vcc
	v_cmp_neq_f32_e32 vcc, s27, v143
	v_add_f32_e32 v105, v105, v93
	v_mul_f32_e32 v105, 0xbfb8aa3b, v105
	v_cndmask_b32_e32 v65, v209, v65, vcc
	v_cndmask_b32_e64 v65, v65, v143, s[0:1]
	v_mul_f32_e32 v69, v240, v65
	v_mul_f32_e32 v72, 0x3fb8aa3b, v69
	v_exp_f32_e32 v72, v72
	v_add_f32_e32 v69, v69, v69
	v_fmamk_f32 v74, v69, 0x3d2aaaab, v196
	v_fma_f32 v74, v69, v74, 0.5
	v_cmp_lt_f32_e64 vcc, |v173|, s39
	v_fma_f32 v74, v69, v74, 1.0
	v_fma_f32 v73, -v72, v72, 1.0
	v_cndmask_b32_e32 v64, v64, v173, vcc
	v_mul_f32_e64 v74, v74, -v69
	v_cmp_lt_f32_e32 vcc, s40, v69
	v_exp_f32_e32 v105, v105
	v_mul_f32_e32 v124, 0xbfb8aa3b, v124
	v_cndmask_b32_e32 v69, v73, v74, vcc
	v_max_f32_e32 v69, 0, v69
	v_sqrt_f32_e32 v69, v69
	v_add_f32_e32 v105, 1.0, v105
	v_rcp_f32_e32 v252, v105
	v_add_f32_e32 v105, v106, v94
	v_mul_f32_e32 v69, v167, v69
	v_mul_f32_e32 v73, v69, v163
	v_mul_f32_e32 v69, v241, v64
	v_mul_f32_e32 v74, 0x3fb8aa3b, v69
	v_mul_f32_e32 v105, 0xbfb8aa3b, v105
	v_exp_f32_e32 v74, v74
	v_add_f32_e32 v69, v69, v69
	v_exp_f32_e32 v105, v105
	v_fmamk_f32 v78, v69, 0x3d2aaaab, v196
	v_exp_f32_e32 v124, v124
	v_fma_f32 v78, v69, v78, 0.5
	v_mul_f32_e32 v104, 0xbfb8aa3b, v104
	v_fma_f32 v78, v69, v78, 1.0
	v_mul_f32_e32 v108, 0xbfb8aa3b, v108
	v_exp_f32_e32 v104, v104
	v_fma_f32 v75, -v74, v74, 1.0
	v_mul_f32_e64 v78, v78, -v69
	v_cmp_lt_f32_e32 vcc, s40, v69
	v_exp_f32_e32 v108, v108
	v_add_f32_e32 v105, 1.0, v105
	v_cndmask_b32_e32 v69, v75, v78, vcc
	v_add_f32_e32 v124, 1.0, v124
	v_rcp_f32_e32 v226, v105
	v_add_f32_e32 v105, v107, v95
	v_max_f32_e32 v69, 0, v69
	v_rcp_f32_e32 v124, v124
	v_mul_f32_e32 v105, 0xbfb8aa3b, v105
	v_sqrt_f32_e32 v69, v69
	v_add_f32_e32 v104, 1.0, v104
	v_exp_f32_e32 v105, v105
	v_add_f32_e32 v108, 1.0, v108
	v_rcp_f32_e32 v104, v104
	v_rcp_f32_e32 v108, v108
	v_or3_b32 v130, v128, v133, v146
	v_mov_b32_e32 v131, v129
	v_mul_f32_e32 v245, 0xc1000000, v124
	v_mul_f32_e32 v69, v238, v69
	v_lshl_add_u64 v[130:131], v[130:131], 3, s[14:15]
	v_add_f32_e32 v105, 1.0, v105
	v_or_b32_e32 v126, 0x300, v133
	v_mul_f32_e32 v75, v69, v160
	v_mul_f32_e32 v69, v245, v65
	v_rcp_f32_e32 v225, v105
	v_mul_f32_e32 v228, 0xc1000000, v104
	v_or3_b32 v104, v128, v126, v146
	v_mov_b32_e32 v105, v129
	global_store_dwordx4 v[130:131], v[72:75], off
	v_lshlrev_b32_e32 v242, 16, v200
	v_and_b32_e32 v239, 0xffff0000, v200
	v_mul_f32_e32 v72, 0x3fb8aa3b, v69
	v_mul_f32_e32 v200, 0xc1000000, v108
	v_lshl_add_u64 v[108:109], v[104:105], 3, s[14:15]
	v_exp_f32_e32 v104, v72
	v_add_f32_e32 v69, v69, v69
	v_fmamk_f32 v73, v69, 0x3d2aaaab, v196
	v_fma_f32 v73, v69, v73, 0.5
	v_fma_f32 v73, v69, v73, 1.0
	v_fma_f32 v72, -v104, v104, 1.0
	v_mul_f32_e64 v73, v73, -v69
	v_cmp_lt_f32_e32 vcc, s40, v69
	v_mul_f32_e32 v100, 0xbfb8aa3b, v100
	v_exp_f32_e32 v100, v100
	v_cndmask_b32_e32 v69, v72, v73, vcc
	v_max_f32_e32 v69, 0, v69
	v_sqrt_f32_e32 v69, v69
	v_add_f32_e32 v100, 1.0, v100
	v_rcp_f32_e32 v100, v100
	v_mul_f32_e32 v96, 0xbfb8aa3b, v96
	v_mul_f32_e32 v69, v243, v69
	v_mul_f32_e32 v105, v69, v242
	v_mul_f32_e32 v69, v246, v64
	v_mul_f32_e32 v72, 0x3fb8aa3b, v69
	v_exp_f32_e32 v106, v72
	v_add_f32_e32 v69, v69, v69
	v_fmamk_f32 v73, v69, 0x3d2aaaab, v196
	v_fma_f32 v73, v69, v73, 0.5
	v_fma_f32 v73, v69, v73, 1.0
	v_fma_f32 v72, -v106, v106, 1.0
	v_mul_f32_e64 v73, v73, -v69
	v_cmp_lt_f32_e32 vcc, s40, v69
	v_mul_f32_e32 v206, 0xc1000000, v100
	v_exp_f32_e32 v96, v96
	v_cndmask_b32_e32 v69, v72, v73, vcc
	v_max_f32_e32 v69, 0, v69
	v_sqrt_f32_e32 v69, v69
	v_add_f32_e32 v96, 1.0, v96
	v_rcp_f32_e32 v96, v96
	v_add_f32_e32 v97, v97, v93
	v_mul_f32_e32 v69, v244, v69
	v_mul_f32_e32 v107, v69, v239
	v_mul_f32_e32 v69, v249, v65
	v_mul_f32_e32 v72, 0x3fb8aa3b, v69
	v_exp_f32_e32 v100, v72
	v_add_f32_e32 v69, v69, v69
	v_fmamk_f32 v73, v69, 0x3d2aaaab, v196
	v_fma_f32 v73, v69, v73, 0.5
	v_fma_f32 v73, v69, v73, 1.0
	v_fma_f32 v72, -v100, v100, 1.0
	v_mul_f32_e64 v73, v73, -v69
	v_cmp_lt_f32_e32 vcc, s40, v69
	v_mul_f32_e32 v232, 0xc1000000, v96
	v_mul_f32_e32 v81, 0xbfb8aa3b, v81
	v_cndmask_b32_e32 v69, v72, v73, vcc
	v_max_f32_e32 v69, 0, v69
	v_sqrt_f32_e32 v69, v69
	v_exp_f32_e32 v81, v81
	v_mul_f32_e32 v97, 0xbfb8aa3b, v97
	v_exp_f32_e32 v97, v97
	v_mul_f32_e32 v92, v247, v69
	v_mul_f32_e32 v69, v250, v64
	v_mul_f32_e32 v72, 0x3fb8aa3b, v69
	v_exp_f32_e32 v102, v72
	v_add_f32_e32 v69, v69, v69
	v_fmamk_f32 v73, v69, 0x3d2aaaab, v196
	v_fma_f32 v73, v69, v73, 0.5
	v_fma_f32 v73, v69, v73, 1.0
	v_fma_f32 v72, -v102, v102, 1.0
	v_mul_f32_e64 v73, v73, -v69
	v_cmp_lt_f32_e32 vcc, s40, v69
	v_add_f32_e32 v81, 1.0, v81
	v_rcp_f32_e32 v81, v81
	v_cndmask_b32_e32 v69, v72, v73, vcc
	v_max_f32_e32 v69, 0, v69
	v_sqrt_f32_e32 v69, v69
	v_mul_f32_e32 v237, 0xc1000000, v81
	v_add_f32_e32 v97, 1.0, v97
	v_rcp_f32_e32 v97, v97
	v_mul_f32_e32 v93, v248, v69
	v_mul_f32_e32 v69, v200, v65
	v_mul_f32_e32 v72, 0x3fb8aa3b, v69
	v_exp_f32_e32 v96, v72
	v_add_f32_e32 v69, v69, v69
	v_fmamk_f32 v73, v69, 0x3d2aaaab, v196
	v_fma_f32 v73, v69, v73, 0.5
	v_fma_f32 v73, v69, v73, 1.0
	v_fma_f32 v72, -v96, v96, 1.0
	v_mul_f32_e64 v73, v73, -v69
	v_cmp_lt_f32_e32 vcc, s40, v69
	v_pk_mul_f32 v[76:77], v[76:77], s[44:45] op_sel_hi:[1,0]
	v_mov_b32_e32 v160, v171
	v_cndmask_b32_e32 v69, v72, v73, vcc
	v_max_f32_e32 v69, 0, v69
	v_sqrt_f32_e32 v69, v69
	v_mov_b32_e32 v159, v161
	v_mov_b32_e32 v139, v171
	v_mul_f32_e32 v120, 0xbfb8aa3b, v120
	v_mul_f32_e32 v85, v251, v69
	v_mul_f32_e32 v69, v201, v64
	v_mul_f32_e32 v72, 0x3fb8aa3b, v69
	v_exp_f32_e32 v98, v72
	v_add_f32_e32 v69, v69, v69
	v_fmamk_f32 v73, v69, 0x3d2aaaab, v196
	v_fma_f32 v73, v69, v73, 0.5
	v_fma_f32 v73, v69, v73, 1.0
	v_fma_f32 v72, -v98, v98, 1.0
	v_mul_f32_e64 v73, v73, -v69
	v_cmp_lt_f32_e32 vcc, s40, v69
	v_mul_f32_e32 v112, 0xbfb8aa3b, v112
	v_exp_f32_e32 v120, v120
	v_cndmask_b32_e32 v69, v72, v73, vcc
	v_max_f32_e32 v69, 0, v69
	v_sqrt_f32_e32 v69, v69
	v_exp_f32_e32 v112, v112
	v_mul_f32_e32 v121, 0xbfb8aa3b, v121
	v_mul_f32_e32 v113, 0xbfb8aa3b, v113
	v_mul_f32_e32 v89, v252, v69
	v_mul_f32_e32 v69, v206, v65
	v_mul_f32_e32 v72, 0x3fb8aa3b, v69
	v_exp_f32_e32 v84, v72
	v_add_f32_e32 v69, v69, v69
	v_fmamk_f32 v73, v69, 0x3d2aaaab, v196
	v_fma_f32 v73, v69, v73, 0.5
	v_fma_f32 v73, v69, v73, 1.0
	v_fma_f32 v72, -v84, v84, 1.0
	v_mul_f32_e64 v73, v73, -v69
	v_cmp_lt_f32_e32 vcc, s40, v69
	v_add_f32_e32 v120, 1.0, v120
	v_exp_f32_e32 v121, v121
	v_cndmask_b32_e32 v69, v72, v73, vcc
	v_max_f32_e32 v69, 0, v69
	v_sqrt_f32_e32 v69, v69
	v_add_f32_e32 v112, 1.0, v112
	v_exp_f32_e32 v113, v113
	v_rcp_f32_e32 v120, v120
	v_mul_f32_e32 v81, v199, v69
	v_mul_f32_e32 v69, v101, v64
	v_mul_f32_e32 v72, 0x3fb8aa3b, v69
	v_exp_f32_e32 v86, v72
	v_add_f32_e32 v69, v69, v69
	v_fmamk_f32 v73, v69, 0x3d2aaaab, v196
	v_fma_f32 v73, v69, v73, 0.5
	v_fma_f32 v73, v69, v73, 1.0
	v_fma_f32 v72, -v86, v86, 1.0
	v_mul_f32_e64 v73, v73, -v69
	v_cmp_lt_f32_e32 vcc, s40, v69
	v_rcp_f32_e32 v112, v112
	v_add_f32_e32 v121, 1.0, v121
	v_cndmask_b32_e32 v69, v72, v73, vcc
	v_max_f32_e32 v69, 0, v69
	v_sqrt_f32_e32 v69, v69
	v_or_b32_e32 v124, 0x100, v133
	v_add_f32_e32 v113, 1.0, v113
	v_or_b32_e32 v125, 0x200, v133
	v_mul_f32_e32 v87, v97, v69
	v_mul_f32_e32 v69, v80, v65
	v_mul_f32_e32 v72, 0x3fb8aa3b, v69
	v_exp_f32_e32 v80, v72
	v_add_f32_e32 v69, v69, v69
	v_fmamk_f32 v73, v69, 0x3d2aaaab, v196
	v_fma_f32 v73, v69, v73, 0.5
	v_fma_f32 v73, v69, v73, 1.0
	v_fma_f32 v72, -v80, v80, 1.0
	v_mul_f32_e64 v73, v73, -v69
	v_cmp_lt_f32_e32 vcc, s40, v69
	v_rcp_f32_e32 v217, v121
	v_mul_f32_e32 v220, 0xc1000000, v120
	v_cndmask_b32_e32 v69, v72, v73, vcc
	v_max_f32_e32 v69, 0, v69
	v_sqrt_f32_e32 v69, v69
	v_or3_b32 v120, v128, v124, v146
	v_mov_b32_e32 v121, v129
	v_rcp_f32_e32 v221, v113
	v_mul_f32_e32 v75, v99, v69
	v_mul_f32_e32 v69, v207, v64
	v_mul_f32_e32 v72, 0x3fb8aa3b, v69
	v_exp_f32_e32 v82, v72
	v_add_f32_e32 v69, v69, v69
	v_fmamk_f32 v73, v69, 0x3d2aaaab, v196
	v_fma_f32 v73, v69, v73, 0.5
	v_fma_f32 v73, v69, v73, 1.0
	v_fma_f32 v72, -v82, v82, 1.0
	v_mul_f32_e64 v73, v73, -v69
	v_cmp_lt_f32_e32 vcc, s40, v69
	v_mul_f32_e32 v224, 0xc1000000, v112
	v_or3_b32 v112, v128, v125, v146
	v_cndmask_b32_e32 v69, v72, v73, vcc
	v_max_f32_e32 v69, 0, v69
	v_sqrt_f32_e32 v69, v69
	v_pk_mul_f32 v[72:73], v[122:123], s[44:45] op_sel_hi:[1,0]
	v_mov_b32_e32 v113, v129
	v_pk_mul_f32 v[122:123], v[72:73], v[64:65]
	v_mul_f32_e32 v83, v103, v69
	v_mul_f32_e32 v69, 0x3fb8aa3b, v123
	v_exp_f32_e32 v72, v69
	v_pk_add_f32 v[150:151], v[122:123], v[122:123]
	v_pk_mul_f32 v[64:65], v[76:77], v[64:65]
	v_fmamk_f32 v73, v151, 0x3d2aaaab, v196
	v_fma_f32 v73, v151, v73, 0.5
	v_fma_f32 v73, v151, v73, 1.0
	v_fma_f32 v69, -v72, v72, 1.0
	v_mul_f32_e64 v73, v73, -v151
	v_cmp_lt_f32_e64 s[0:1], s40, v151
	v_fmamk_f32 v78, v150, 0x3d2aaaab, v196
	v_fma_f32 v78, v150, v78, 0.5
	v_cndmask_b32_e64 v69, v69, v73, s[0:1]
	v_max_f32_e32 v69, 0, v69
	v_sqrt_f32_e32 v69, v69
	v_fma_f32 v78, v150, v78, 1.0
	v_cmp_lt_f32_e32 vcc, s40, v150
	v_mul_f32_e64 v78, v78, -v150
	v_mul_f32_e32 v73, v203, v69
	v_mul_f32_e32 v69, 0x3fb8aa3b, v122
	v_exp_f32_e32 v74, v69
	v_pk_add_f32 v[122:123], v[64:65], v[64:65]
	v_mul_f32_e32 v64, 0x3fb8aa3b, v64
	v_cmp_lt_f32_e64 s[0:1], s40, v123
	v_fma_f32 v69, -v74, v74, 1.0
	v_cndmask_b32_e32 v69, v69, v78, vcc
	v_max_f32_e32 v69, 0, v69
	v_sqrt_f32_e32 v69, v69
	v_exp_f32_e32 v78, v64
	v_cmp_lt_f32_e32 vcc, s40, v122
	v_lshl_add_u64 v[120:121], v[120:121], 3, s[14:15]
	v_mul_f32_e32 v88, v208, v69
	v_mul_f32_e32 v69, 0x3fb8aa3b, v65
	v_exp_f32_e32 v76, v69
	v_fmamk_f32 v65, v123, 0x3d2aaaab, v196
	v_fma_f32 v65, v123, v65, 0.5
	v_fma_f32 v65, v123, v65, 1.0
	v_fma_f32 v69, -v76, v76, 1.0
	v_mul_f32_e64 v65, v65, -v123
	v_cndmask_b32_e64 v65, v69, v65, s[0:1]
	v_max_f32_e32 v65, 0, v65
	v_sqrt_f32_e32 v65, v65
	v_fma_f32 v64, -v78, v78, 1.0
	v_cmp_lt_f32_e64 s[0:1], |v145|, s39
	v_lshl_add_u64 v[112:113], v[112:113], 3, s[14:15]
	v_mul_f32_e32 v69, v68, v65
	v_fmamk_f32 v65, v122, 0x3d2aaaab, v196
	v_fma_f32 v65, v122, v65, 0.5
	v_fma_f32 v65, v122, v65, 1.0
	v_mul_f32_e64 v65, v65, -v122
	v_cndmask_b32_e32 v64, v64, v65, vcc
	v_max_f32_e32 v64, 0, v64
	v_sqrt_f32_e32 v64, v64
	v_cmp_neq_f32_e32 vcc, s27, v178
	v_mul_f32_e32 v68, v189, v64
	v_add_f32_e32 v64, v66, v90
	v_mul_f32_e32 v64, 0xbfb8aa3b, v64
	v_exp_f32_e32 v64, v64
	v_add_f32_e32 v66, v70, v94
	v_mov_b32_e32 v90, v169
	v_add_f32_e32 v64, 1.0, v64
	v_rcp_f32_e32 v65, v64
	v_mul_f32_e32 v64, 0xbfb8aa3b, v66
	v_add_f32_e32 v66, v71, v95
	v_mul_f32_e32 v66, 0xbfb8aa3b, v66
	v_exp_f32_e32 v64, v64
	v_exp_f32_e32 v66, v66
	v_add_f32_e32 v64, 1.0, v64
	v_add_f32_e32 v66, 1.0, v66
	v_rcp_f32_e32 v70, v64
	v_add_f32_e32 v64, v67, v91
	v_rcp_f32_e32 v71, v66
	v_mov_b32_e32 v66, v168
	v_mov_b32_e32 v67, v164
	v_mov_b32_e32 v91, v165
	v_pk_add_f32 v[90:91], v[66:67], v[90:91]
	v_mul_f32_e32 v64, 0xbfb8aa3b, v64
	v_pk_add_f32 v[94:95], v[160:161], v[90:91]
	v_mov_b32_e32 v163, v91
	v_mov_b32_e32 v165, v95
	v_mov_b32_e32 v169, v94
	v_pk_add_f32 v[122:123], v[164:165], v[158:159] neg_lo:[0,1] neg_hi:[0,1]
	v_pk_add_f32 v[152:153], v[168:169], v[138:139] neg_lo:[0,1] neg_hi:[0,1]
	v_mov_b32_e32 v155, v122
	v_mov_b32_e32 v154, v152
	v_mov_b32_e32 v167, v90
	v_pk_add_f32 v[150:151], v[162:163], v[122:123] neg_lo:[0,1] neg_hi:[0,1]
	v_pk_add_f32 v[66:67], v[66:67], v[154:155] neg_lo:[0,1] neg_hi:[0,1]
	v_mov_b32_e32 v139, v158
	v_pk_add_f32 v[90:91], v[166:167], v[152:153] neg_lo:[0,1] neg_hi:[0,1]
	v_pk_add_f32 v[66:67], v[138:139], v[66:67] neg_lo:[0,1] neg_hi:[0,1]
	v_mov_b32_e32 v122, v90
	v_mov_b32_e32 v123, v150
	v_pk_add_f32 v[66:67], v[122:123], v[66:67]
	v_mov_b32_e32 v150, v91
	v_pk_add_f32 v[66:67], v[66:67], v[150:151]
	v_exp_f32_e32 v64, v64
	v_pk_add_f32 v[66:67], v[94:95], v[66:67]
	v_add_f32_e32 v64, 1.0, v64
	v_cndmask_b32_e32 v66, v209, v66, vcc
	v_cmp_neq_f32_e32 vcc, s27, v145
	v_rcp_f32_e32 v64, v64
	s_nop 0
	v_cndmask_b32_e32 v67, v209, v67, vcc
	v_cndmask_b32_e64 v67, v67, v145, s[0:1]
	v_mul_f32_e32 v77, v215, v67
	v_mul_f32_e32 v90, 0x3fb8aa3b, v77
	v_exp_f32_e32 v150, v90
	v_add_f32_e32 v77, v77, v77
	v_fmamk_f32 v91, v77, 0x3d2aaaab, v196
	v_fma_f32 v91, v77, v91, 0.5
	v_cmp_lt_f32_e64 vcc, |v178|, s39
	v_fma_f32 v91, v77, v91, 1.0
	v_fma_f32 v90, -v150, v150, 1.0
	v_cndmask_b32_e32 v66, v66, v178, vcc
	v_mul_f32_e64 v91, v91, -v77
	v_cmp_lt_f32_e32 vcc, s40, v77
	s_nop 1
	v_cndmask_b32_e32 v77, v90, v91, vcc
	v_max_f32_e32 v77, 0, v77
	v_sqrt_f32_e32 v77, v77
	s_nop 0
	v_mul_f32_e32 v77, v214, v77
	v_mul_f32_e32 v151, v77, v170
	v_mul_f32_e32 v77, v216, v66
	v_mul_f32_e32 v90, 0x3fb8aa3b, v77
	v_exp_f32_e32 v152, v90
	v_add_f32_e32 v77, v77, v77
	v_fmamk_f32 v91, v77, 0x3d2aaaab, v196
	v_fma_f32 v91, v77, v91, 0.5
	v_fma_f32 v91, v77, v91, 1.0
	v_fma_f32 v90, -v152, v152, 1.0
	v_mul_f32_e64 v91, v91, -v77
	v_cmp_lt_f32_e32 vcc, s40, v77
	s_nop 1
	v_cndmask_b32_e32 v77, v90, v91, vcc
	v_max_f32_e32 v77, 0, v77
	v_sqrt_f32_e32 v77, v77
	s_nop 0
	v_mul_f32_e32 v77, v183, v77
	v_mul_f32_e32 v153, v77, v149
	global_store_dwordx4 v[130:131], v[150:153], off offset:16
	v_add_co_u32_e32 v90, vcc, s66, v136
	v_mul_f32_e32 v77, v219, v67
	s_nop 0
	v_addc_co_u32_e32 v91, vcc, 0, v137, vcc
	global_load_dwordx2 v[90:91], v[90:91], off
	v_mul_f32_e32 v94, 0x3fb8aa3b, v77
	v_exp_f32_e32 v150, v94
	v_add_f32_e32 v77, v77, v77
	v_fmamk_f32 v95, v77, 0x3d2aaaab, v196
	v_fma_f32 v95, v77, v95, 0.5
	v_fma_f32 v95, v77, v95, 1.0
	v_fma_f32 v94, -v150, v150, 1.0
	v_mul_f32_e64 v95, v95, -v77
	v_cmp_lt_f32_e32 vcc, s40, v77
	s_nop 1
	v_cndmask_b32_e32 v77, v94, v95, vcc
	v_max_f32_e32 v77, 0, v77
	v_sqrt_f32_e32 v77, v77
	s_nop 0
	v_mul_f32_e32 v77, v218, v77
	v_mul_f32_e32 v151, v77, v182
	v_mul_f32_e32 v77, v220, v66
	v_mul_f32_e32 v94, 0x3fb8aa3b, v77
	v_exp_f32_e32 v152, v94
	v_add_f32_e32 v77, v77, v77
	v_fmamk_f32 v95, v77, 0x3d2aaaab, v196
	v_fma_f32 v95, v77, v95, 0.5
	v_fma_f32 v95, v77, v95, 1.0
	v_fma_f32 v94, -v152, v152, 1.0
	v_mul_f32_e64 v95, v95, -v77
	v_cmp_lt_f32_e32 vcc, s40, v77
	s_nop 1
	v_cndmask_b32_e32 v77, v94, v95, vcc
	v_max_f32_e32 v77, 0, v77
	v_sqrt_f32_e32 v77, v77
	s_nop 0
	v_mul_f32_e32 v77, v217, v77
	v_mul_f32_e32 v153, v77, v172
	global_store_dwordx4 v[120:121], v[104:107], off
	global_store_dwordx4 v[120:121], v[150:153], off offset:16
	v_add_co_u32_e32 v94, vcc, s67, v136
	s_waitcnt vmcnt(2)
	v_lshlrev_b32_e32 v77, 16, v90
	v_addc_co_u32_e32 v95, vcc, 0, v137, vcc
	global_load_dwordx2 v[94:95], v[94:95], off
	v_and_b32_e32 v90, 0xffff0000, v90
	v_mul_f32_e32 v101, v92, v77
	v_mul_f32_e32 v77, v223, v67
	v_mul_f32_e32 v103, v93, v90
	v_mul_f32_e32 v90, 0x3fb8aa3b, v77
	v_exp_f32_e32 v90, v90
	v_add_f32_e32 v77, v77, v77
	v_fmamk_f32 v92, v77, 0x3d2aaaab, v196
	v_fma_f32 v92, v77, v92, 0.5
	v_fma_f32 v92, v77, v92, 1.0
	v_lshlrev_b32_e32 v97, 16, v91
	v_and_b32_e32 v99, 0xffff0000, v91
	v_fma_f32 v91, -v90, v90, 1.0
	v_mul_f32_e64 v92, v92, -v77
	v_cmp_lt_f32_e32 vcc, s40, v77
	s_nop 1
	v_cndmask_b32_e32 v77, v91, v92, vcc
	v_max_f32_e32 v77, 0, v77
	v_sqrt_f32_e32 v77, v77
	s_nop 0
	v_mul_f32_e32 v77, v222, v77
	v_mul_f32_e32 v91, v77, v97
	v_mul_f32_e32 v77, v224, v66
	v_mul_f32_e32 v92, 0x3fb8aa3b, v77
	v_exp_f32_e32 v92, v92
	v_add_f32_e32 v77, v77, v77
	v_fmamk_f32 v97, v77, 0x3d2aaaab, v196
	v_fma_f32 v97, v77, v97, 0.5
	v_fma_f32 v97, v77, v97, 1.0
	v_fma_f32 v93, -v92, v92, 1.0
	v_mul_f32_e64 v97, v97, -v77
	v_cmp_lt_f32_e32 vcc, s40, v77
	s_nop 1
	v_cndmask_b32_e32 v77, v93, v97, vcc
	v_max_f32_e32 v77, 0, v77
	v_sqrt_f32_e32 v77, v77
	s_nop 0
	v_mul_f32_e32 v77, v221, v77
	v_mul_f32_e32 v93, v77, v99
	global_store_dwordx4 v[112:113], v[100:103], off
	global_store_dwordx4 v[112:113], v[90:93], off offset:16
	s_mov_b32 s22, 0x40000
	s_nop 0
	v_add_co_u32_e32 v90, vcc, s22, v136
	s_waitcnt vmcnt(2)
	v_lshlrev_b32_e32 v77, 16, v94
	v_addc_co_u32_e32 v91, vcc, 0, v137, vcc
	global_load_dwordx2 v[100:101], v[90:91], off
	v_mul_f32_e32 v97, v85, v77
	v_mul_f32_e32 v77, v227, v67
	v_and_b32_e32 v90, 0xffff0000, v94
	v_mul_f32_e32 v85, 0x3fb8aa3b, v77
	v_mul_f32_e32 v99, v89, v90
	v_exp_f32_e32 v90, v85
	v_add_f32_e32 v77, v77, v77
	v_fmamk_f32 v89, v77, 0x3d2aaaab, v196
	v_fma_f32 v89, v77, v89, 0.5
	v_fma_f32 v89, v77, v89, 1.0
	v_fma_f32 v85, -v90, v90, 1.0
	v_mul_f32_e64 v89, v89, -v77
	v_cmp_lt_f32_e32 vcc, s40, v77
	v_lshlrev_b32_e32 v91, 16, v95
	v_and_b32_e32 v93, 0xffff0000, v95
	v_cndmask_b32_e32 v77, v85, v89, vcc
	v_max_f32_e32 v77, 0, v77
	v_sqrt_f32_e32 v77, v77
	s_nop 0
	v_mul_f32_e32 v77, v226, v77
	v_mul_f32_e32 v91, v77, v91
	v_mul_f32_e32 v77, v228, v66
	v_mul_f32_e32 v85, 0x3fb8aa3b, v77
	v_exp_f32_e32 v92, v85
	v_add_f32_e32 v77, v77, v77
	v_fmamk_f32 v89, v77, 0x3d2aaaab, v196
	v_fma_f32 v89, v77, v89, 0.5
	v_fma_f32 v89, v77, v89, 1.0
	v_fma_f32 v85, -v92, v92, 1.0
	v_mul_f32_e64 v89, v89, -v77
	v_cmp_lt_f32_e32 vcc, s40, v77
	s_nop 1
	v_cndmask_b32_e32 v77, v85, v89, vcc
	v_max_f32_e32 v77, 0, v77
	v_sqrt_f32_e32 v77, v77
	s_nop 0
	v_mul_f32_e32 v77, v225, v77
	v_mul_f32_e32 v93, v77, v93
	global_store_dwordx4 v[108:109], v[96:99], off
	global_store_dwordx4 v[108:109], v[90:93], off offset:16
	s_mov_b32 s41, 0x50000
	s_nop 0
	v_add_co_u32_e32 v90, vcc, s41, v136
	s_waitcnt vmcnt(2)
	v_lshlrev_b32_e32 v77, 16, v100
	v_addc_co_u32_e32 v91, vcc, 0, v137, vcc
	global_load_dwordx2 v[94:95], v[90:91], off
	v_mul_f32_e32 v85, v81, v77
	v_mul_f32_e32 v77, v231, v67
	v_mul_f32_e32 v81, 0x3fb8aa3b, v77
	v_and_b32_e32 v89, 0xffff0000, v100
	v_exp_f32_e32 v90, v81
	v_add_f32_e32 v77, v77, v77
	v_mul_f32_e32 v87, v87, v89
	v_fmamk_f32 v89, v77, 0x3d2aaaab, v196
	v_fma_f32 v89, v77, v89, 0.5
	v_fma_f32 v89, v77, v89, 1.0
	v_fma_f32 v81, -v90, v90, 1.0
	v_mul_f32_e64 v89, v89, -v77
	v_cmp_lt_f32_e32 vcc, s40, v77
	v_lshlrev_b32_e32 v91, 16, v101
	v_and_b32_e32 v93, 0xffff0000, v101
	v_cndmask_b32_e32 v77, v81, v89, vcc
	v_max_f32_e32 v77, 0, v77
	v_sqrt_f32_e32 v77, v77
	s_nop 0
	v_mul_f32_e32 v77, v230, v77
	v_mul_f32_e32 v91, v77, v91
	v_mul_f32_e32 v77, v232, v66
	v_mul_f32_e32 v81, 0x3fb8aa3b, v77
	v_exp_f32_e32 v92, v81
	v_add_f32_e32 v77, v77, v77
	v_fmamk_f32 v89, v77, 0x3d2aaaab, v196
	v_fma_f32 v89, v77, v89, 0.5
	v_fma_f32 v89, v77, v89, 1.0
	v_fma_f32 v81, -v92, v92, 1.0
	v_mul_f32_e64 v89, v89, -v77
	v_cmp_lt_f32_e32 vcc, s40, v77
	s_nop 1
	v_cndmask_b32_e32 v77, v81, v89, vcc
	v_max_f32_e32 v77, 0, v77
	v_sqrt_f32_e32 v77, v77
	s_nop 0
	v_mul_f32_e32 v77, v229, v77
	v_mul_f32_e32 v93, v77, v93
	global_store_dwordx4 v[110:111], v[84:87], off
	global_store_dwordx4 v[110:111], v[90:93], off offset:16
	s_mov_b32 s23, 0x60000
	v_add_co_u32_e32 v84, vcc, s23, v136
	s_waitcnt vmcnt(2)
	v_lshlrev_b32_e32 v77, 16, v94
	v_addc_co_u32_e32 v85, vcc, 0, v137, vcc
	global_load_dwordx2 v[90:91], v[84:85], off
	v_mul_f32_e32 v81, v75, v77
	v_mul_f32_e32 v75, v235, v67
	v_and_b32_e32 v84, 0xffff0000, v94
	v_mul_f32_e32 v77, 0x3fb8aa3b, v75
	v_mul_f32_e32 v83, v83, v84
	v_exp_f32_e32 v84, v77
	v_add_f32_e32 v75, v75, v75
	v_fmamk_f32 v86, v75, 0x3d2aaaab, v196
	v_fma_f32 v86, v75, v86, 0.5
	v_fma_f32 v86, v75, v86, 1.0
	v_fma_f32 v77, -v84, v84, 1.0
	v_mul_f32_e64 v86, v86, -v75
	v_cmp_lt_f32_e32 vcc, s40, v75
	v_lshlrev_b32_e32 v85, 16, v95
	v_and_b32_e32 v87, 0xffff0000, v95
	v_cndmask_b32_e32 v75, v77, v86, vcc
	v_max_f32_e32 v75, 0, v75
	v_sqrt_f32_e32 v75, v75
	s_nop 0
	v_mul_f32_e32 v75, v234, v75
	v_mul_f32_e32 v85, v75, v85
	v_mul_f32_e32 v75, v237, v66
	v_mul_f32_e32 v77, 0x3fb8aa3b, v75
	v_exp_f32_e32 v86, v77
	v_add_f32_e32 v75, v75, v75
	v_fmamk_f32 v89, v75, 0x3d2aaaab, v196
	v_fma_f32 v89, v75, v89, 0.5
	v_fma_f32 v89, v75, v89, 1.0
	v_fma_f32 v77, -v86, v86, 1.0
	v_mul_f32_e64 v89, v89, -v75
	v_cmp_lt_f32_e32 vcc, s40, v75
	s_nop 1
	v_cndmask_b32_e32 v75, v77, v89, vcc
	v_max_f32_e32 v75, 0, v75
	v_sqrt_f32_e32 v75, v75
	s_nop 0
	v_mul_f32_e32 v75, v233, v75
	v_mul_f32_e32 v87, v75, v87
	global_store_dwordx4 v[114:115], v[80:83], off
	global_store_dwordx4 v[114:115], v[84:87], off offset:16
	s_mov_b32 s42, 0x70000
	v_add_co_u32_e32 v80, vcc, s42, v136
	s_waitcnt vmcnt(2)
	v_lshlrev_b32_e32 v75, 16, v90
	v_addc_co_u32_e32 v81, vcc, 0, v137, vcc
	global_load_dwordx2 v[84:85], v[80:81], off
	v_pk_mul_f32 v[80:81], v[118:119], s[44:45] op_sel_hi:[1,0]
	v_and_b32_e32 v77, 0xffff0000, v90
	v_pk_mul_f32 v[82:83], v[80:81], v[66:67]
	v_mul_f32_e32 v73, v73, v75
	v_mul_f32_e32 v75, v88, v77
	v_mul_f32_e32 v77, 0x3fb8aa3b, v83
	v_exp_f32_e32 v80, v77
	v_pk_add_f32 v[86:87], v[82:83], v[82:83]
	v_lshlrev_b32_e32 v89, 16, v91
	v_fmamk_f32 v81, v87, 0x3d2aaaab, v196
	v_fma_f32 v81, v87, v81, 0.5
	v_fma_f32 v81, v87, v81, 1.0
	v_fma_f32 v77, -v80, v80, 1.0
	v_mul_f32_e64 v81, v81, -v87
	v_cmp_lt_f32_e64 s[0:1], s40, v87
	v_fmamk_f32 v83, v86, 0x3d2aaaab, v196
	v_fma_f32 v83, v86, v83, 0.5
	v_cndmask_b32_e64 v77, v77, v81, s[0:1]
	v_max_f32_e32 v77, 0, v77
	v_sqrt_f32_e32 v77, v77
	v_fma_f32 v83, v86, v83, 1.0
	v_cmp_lt_f32_e32 vcc, s40, v86
	v_mul_f32_e64 v83, v83, -v86
	v_mul_f32_e32 v77, v236, v77
	v_mul_f32_e32 v81, v77, v89
	v_mul_f32_e32 v77, 0x3fb8aa3b, v82
	v_exp_f32_e32 v82, v77
	v_and_b32_e32 v90, 0xffff0000, v91
	v_fma_f32 v77, -v82, v82, 1.0
	v_cndmask_b32_e32 v77, v77, v83, vcc
	v_max_f32_e32 v77, 0, v77
	v_sqrt_f32_e32 v77, v77
	s_nop 0
	v_mul_f32_e32 v77, v79, v77
	v_mul_f32_e32 v83, v77, v90
	global_store_dwordx4 v[116:117], v[72:75], off
	global_store_dwordx4 v[116:117], v[80:83], off offset:16
	v_pk_mul_f32 v[64:65], v[64:65], s[44:45] op_sel_hi:[1,0]
	s_waitcnt vmcnt(2)
	v_lshlrev_b32_e32 v72, 16, v84
	v_pk_mul_f32 v[66:67], v[64:65], v[66:67]
	v_mul_f32_e32 v77, v69, v72
	v_pk_add_f32 v[72:73], v[66:67], v[66:67]
	v_mul_f32_e32 v64, 0x3fb8aa3b, v67
	v_fmamk_f32 v67, v73, 0x3d2aaaab, v196
	v_exp_f32_e32 v64, v64
	v_fma_f32 v67, v73, v67, 0.5
	v_mul_f32_e32 v66, 0x3fb8aa3b, v66
	v_fma_f32 v67, v73, v67, 1.0
	v_exp_f32_e32 v66, v66
	v_mul_f32_e64 v67, v67, -v73
	v_cmp_lt_f32_e32 vcc, s40, v73
	v_fmamk_f32 v73, v72, 0x3d2aaaab, v196
	v_fma_f32 v73, v72, v73, 0.5
	v_fma_f32 v69, -v64, v64, 1.0
	v_fma_f32 v73, v72, v73, 1.0
	v_cndmask_b32_e32 v67, v69, v67, vcc
	v_fma_f32 v69, -v66, v66, 1.0
	v_mul_f32_e64 v73, v73, -v72
	v_cmp_lt_f32_e32 vcc, s40, v72
	v_max_f32_e32 v67, 0, v67
	v_sqrt_f32_e32 v67, v67
	v_cndmask_b32_e32 v69, v69, v73, vcc
	v_max_f32_e32 v69, 0, v69
	v_sqrt_f32_e32 v69, v69
	v_or_b32_e32 v122, 0x700, v133
	v_and_b32_e32 v74, 0xffff0000, v84
	v_lshlrev_b32_e32 v65, 16, v85
	v_mul_f32_e32 v67, v70, v67
	v_or3_b32 v128, v128, v122, v146
	v_and_b32_e32 v75, 0xffff0000, v85
	v_mul_f32_e32 v79, v68, v74
	v_mul_f32_e32 v65, v67, v65
	v_mul_f32_e32 v67, v71, v69
	v_lshl_add_u64 v[68:69], v[128:129], 3, s[14:15]
	v_mul_f32_e32 v67, v67, v75
	global_store_dwordx4 v[68:69], v[76:79], off
	global_store_dwordx4 v[68:69], v[64:67], off offset:16
	v_ashrrev_i32_e32 v143, 31, v142
	v_lshl_add_u64 v[106:107], v[142:143], 0, v[146:147]
	v_lshlrev_b64 v[68:69], 2, v[106:107]
	v_lshl_add_u64 v[64:65], s[4:5], 0, v[68:69]
	global_load_dwordx4 v[72:75], v[64:65], off offset:64
	v_lshl_add_u64 v[64:65], s[6:7], 0, v[68:69]
	v_lshl_add_u64 v[68:69], s[8:9], 0, v[68:69]
	global_load_dwordx4 v[68:71], v[68:69], off offset:64
	v_or_b32_e32 v108, 16, v142
	global_load_dwordx4 v[64:67], v[64:65], off offset:64
	s_waitcnt vmcnt(2)
	v_mul_f32_e32 v76, 0xbfb8aa3b, v72
	v_fma_f32 v77, v72, s24, -v76
	v_rndne_f32_e32 v78, v76
	v_fmac_f32_e32 v77, 0xb2a5705f, v72
	v_sub_f32_e32 v76, v76, v78
	v_add_f32_e32 v76, v76, v77
	v_exp_f32_e32 v76, v76
	v_cvt_i32_f32_e32 v77, v78
	v_cmp_nlt_f32_e32 vcc, s25, v72
	s_waitcnt vmcnt(1)
	v_add_f32_e32 v56, v56, v68
	v_mul_f32_e32 v56, 0xbfb8aa3b, v56
	v_ldexp_f32 v76, v76, v77
	v_cndmask_b32_e32 v76, 0, v76, vcc
	v_cmp_ngt_f32_e32 vcc, s26, v72
	v_exp_f32_e32 v56, v56
	v_add_f32_e32 v57, v57, v69
	v_cndmask_b32_e32 v123, v209, v76, vcc
	v_add_f32_e32 v72, 1.0, v123
	v_add_f32_e32 v76, -1.0, v72
	v_sub_f32_e32 v77, v76, v72
	v_add_f32_e32 v77, 1.0, v77
	v_sub_f32_e32 v76, v123, v76
	v_add_f32_e32 v78, v76, v77
	v_frexp_mant_f32_e32 v76, v72
	v_cmp_gt_f32_e32 vcc, s37, v76
	v_cvt_f64_f32_e32 v[76:77], v72
	v_frexp_exp_i32_f64_e32 v76, v[76:77]
	v_subbrev_co_u32_e32 v84, vcc, 0, v76, vcc
	v_sub_u32_e32 v76, 0, v84
	v_ldexp_f32 v72, v72, v76
	v_ldexp_f32 v76, v78, v76
	v_add_f32_e32 v78, -1.0, v72
	v_add_f32_e32 v77, 1.0, v78
	v_sub_f32_e32 v77, v72, v77
	v_add_f32_e32 v79, v76, v77
	v_add_f32_e32 v77, v78, v79
	v_sub_f32_e32 v78, v78, v77
	v_add_f32_e32 v85, v79, v78
	v_add_f32_e32 v78, 1.0, v72
	v_add_f32_e32 v79, -1.0, v78
	v_sub_f32_e32 v72, v72, v79
	v_add_f32_e32 v72, v76, v72
	v_add_f32_e32 v86, v78, v72
	v_rcp_f32_e32 v87, v86
	v_sub_f32_e32 v76, v78, v86
	v_add_f32_e32 v72, v72, v76
	v_cmp_nlt_f32_e32 vcc, s25, v73
	v_mul_f32_e32 v88, v77, v87
	v_mul_f32_e32 v78, v86, v88
	v_fma_f32 v80, v88, v86, -v78
	v_fmac_f32_e32 v80, v88, v72
	v_add_f32_e32 v76, v78, v80
	v_sub_f32_e32 v79, v77, v76
	v_pk_add_f32 v[82:83], v[76:77], v[78:79] neg_lo:[0,1] neg_hi:[0,1]
	v_mov_b32_e32 v81, v76
	v_pk_add_f32 v[76:77], v[82:83], v[80:81] neg_lo:[0,1] neg_hi:[0,1]
	v_add_f32_e32 v56, 1.0, v56
	v_add_f32_e32 v77, v85, v77
	v_add_f32_e32 v76, v76, v77
	v_add_f32_e32 v77, v79, v76
	v_mul_f32_e32 v85, v87, v77
	v_mul_f32_e32 v78, v86, v85
	v_fma_f32 v80, v85, v86, -v78
	v_fmac_f32_e32 v80, v85, v72
	v_sub_f32_e32 v72, v79, v77
	v_add_f32_e32 v72, v76, v72
	v_add_f32_e32 v76, v78, v80
	v_sub_f32_e32 v79, v77, v76
	v_pk_add_f32 v[82:83], v[76:77], v[78:79] neg_lo:[0,1] neg_hi:[0,1]
	v_mov_b32_e32 v81, v76
	v_pk_add_f32 v[76:77], v[82:83], v[80:81] neg_lo:[0,1] neg_hi:[0,1]
	v_rcp_f32_e32 v145, v56
	v_add_f32_e32 v72, v72, v77
	v_add_f32_e32 v72, v76, v72
	v_add_f32_e32 v77, v88, v85
	v_add_f32_e32 v72, v79, v72
	v_sub_f32_e32 v76, v77, v88
	v_mul_f32_e32 v72, v87, v72
	v_sub_f32_e32 v76, v85, v76
	v_add_f32_e32 v72, v76, v72
	v_add_f32_e32 v78, v77, v72
	v_mul_f32_e32 v80, v78, v78
	v_fmamk_f32 v76, v80, 0x3e9b6dac, v195
	v_fmaak_f32 v149, v80, v76, 0x3f2aaada
	v_cvt_f32_i32_e32 v76, v84
	v_sub_f32_e32 v77, v78, v77
	v_sub_f32_e32 v72, v72, v77
	v_mul_f32_e32 v77, v78, v80
	v_pk_mul_f32 v[80:81], v[76:77], v[148:149]
	v_ldexp_f32 v79, v78, 1
	v_fma_f32 v78, v76, s38, -v80
	v_fmac_f32_e32 v78, 0xb102e308, v76
	v_pk_add_f32 v[82:83], v[80:81], v[78:79]
	v_ldexp_f32 v72, v72, 1
	v_sub_f32_e32 v76, v83, v79
	v_sub_f32_e32 v76, v81, v76
	v_add_f32_e32 v85, v72, v76
	v_mov_b32_e32 v84, v80
	v_pk_add_f32 v[80:81], v[82:83], v[80:81] neg_lo:[0,1] neg_hi:[0,1]
	v_pk_add_f32 v[86:87], v[82:83], v[84:85]
	v_mov_b32_e32 v79, v82
	v_mov_b32_e32 v81, v87
	v_pk_add_f32 v[76:77], v[78:79], v[80:81] neg_lo:[0,1] neg_hi:[0,1]
	v_pk_add_f32 v[78:79], v[78:79], v[80:81]
	v_mov_b32_e32 v84, v85
	v_pk_add_f32 v[80:81], v[78:79], v[82:83] op_sel:[1,0] op_sel_hi:[0,1] neg_lo:[0,1] neg_hi:[0,1]
	v_pk_add_f32 v[88:89], v[86:87], v[80:81] op_sel_hi:[1,0] neg_lo:[0,1] neg_hi:[0,1]
	v_mov_b32_e32 v78, v87
	v_pk_mov_b32 v[80:81], v[82:83], v[80:81] op_sel:[1,0]
	v_mov_b32_e32 v85, v82
	v_pk_add_f32 v[80:81], v[78:79], v[80:81] neg_lo:[0,1] neg_hi:[0,1]
	v_mov_b32_e32 v88, v76
	v_pk_add_f32 v[80:81], v[84:85], v[80:81] neg_lo:[0,1] neg_hi:[0,1]
	v_mul_f32_e32 v72, 0xbfb8aa3b, v73
	v_pk_add_f32 v[82:83], v[88:89], v[80:81]
	v_fma_f32 v78, v73, s24, -v72
	v_rndne_f32_e32 v81, v72
	v_fmac_f32_e32 v78, 0xb2a5705f, v73
	v_sub_f32_e32 v72, v72, v81
	v_add_f32_e32 v72, v72, v78
	v_exp_f32_e32 v72, v72
	v_cvt_i32_f32_e32 v78, v81
	s_waitcnt vmcnt(0)
	v_add_f32_e32 v56, v61, v65
	v_mul_f32_e32 v56, 0xbfb8aa3b, v56
	v_exp_f32_e32 v56, v56
	v_ldexp_f32 v72, v72, v78
	v_cndmask_b32_e32 v72, 0, v72, vcc
	v_cmp_ngt_f32_e32 vcc, s26, v73
	v_add_f32_e32 v56, 1.0, v56
	v_add_f32_e32 v48, v48, v68
	v_cndmask_b32_e32 v129, v209, v72, vcc
	v_add_f32_e32 v78, 1.0, v129
	v_add_f32_e32 v72, -1.0, v78
	v_sub_f32_e32 v73, v72, v78
	v_add_f32_e32 v73, 1.0, v73
	v_sub_f32_e32 v72, v129, v72
	v_add_f32_e32 v81, v72, v73
	v_frexp_mant_f32_e32 v72, v78
	v_cmp_gt_f32_e32 vcc, s37, v72
	v_cvt_f64_f32_e32 v[72:73], v78
	v_frexp_exp_i32_f64_e32 v72, v[72:73]
	v_subbrev_co_u32_e32 v90, vcc, 0, v72, vcc
	v_sub_u32_e32 v72, 0, v90
	v_ldexp_f32 v78, v78, v72
	v_ldexp_f32 v72, v81, v72
	v_add_f32_e32 v81, -1.0, v78
	v_add_f32_e32 v73, 1.0, v81
	v_sub_f32_e32 v73, v78, v73
	v_add_f32_e32 v84, v72, v73
	v_add_f32_e32 v73, v81, v84
	v_sub_f32_e32 v81, v81, v73
	v_add_f32_e32 v81, v84, v81
	v_add_f32_e32 v84, 1.0, v78
	v_add_f32_e32 v85, -1.0, v84
	v_sub_f32_e32 v78, v78, v85
	v_add_f32_e32 v72, v72, v78
	v_add_f32_e32 v78, v84, v72
	v_rcp_f32_e32 v92, v78
	v_sub_f32_e32 v84, v84, v78
	v_add_f32_e32 v91, v72, v84
	v_cmp_nlt_f32_e32 vcc, s25, v74
	v_mul_f32_e32 v93, v73, v92
	v_mul_f32_e32 v84, v78, v93
	v_fma_f32 v86, v93, v78, -v84
	v_fmac_f32_e32 v86, v93, v91
	v_add_f32_e32 v72, v84, v86
	v_sub_f32_e32 v85, v73, v72
	v_pk_add_f32 v[88:89], v[72:73], v[84:85] neg_lo:[0,1] neg_hi:[0,1]
	v_mov_b32_e32 v87, v72
	v_pk_add_f32 v[72:73], v[88:89], v[86:87] neg_lo:[0,1] neg_hi:[0,1]
	v_mul_f32_e32 v48, 0xbfb8aa3b, v48
	v_add_f32_e32 v73, v81, v73
	v_add_f32_e32 v72, v72, v73
	v_add_f32_e32 v73, v85, v72
	v_mul_f32_e32 v81, v92, v73
	v_mul_f32_e32 v84, v78, v81
	v_fma_f32 v86, v81, v78, -v84
	v_fmac_f32_e32 v86, v81, v91
	v_sub_f32_e32 v78, v85, v73
	v_add_f32_e32 v78, v72, v78
	v_add_f32_e32 v72, v84, v86
	v_sub_f32_e32 v85, v73, v72
	v_pk_add_f32 v[88:89], v[72:73], v[84:85] neg_lo:[0,1] neg_hi:[0,1]
	v_mov_b32_e32 v87, v72
	v_pk_add_f32 v[72:73], v[88:89], v[86:87] neg_lo:[0,1] neg_hi:[0,1]
	v_exp_f32_e32 v48, v48
	v_add_f32_e32 v73, v78, v73
	v_add_f32_e32 v72, v72, v73
	v_add_f32_e32 v73, v93, v81
	v_add_f32_e32 v72, v85, v72
	v_sub_f32_e32 v78, v73, v93
	v_mul_f32_e32 v72, v92, v72
	v_sub_f32_e32 v78, v81, v78
	v_add_f32_e32 v78, v78, v72
	v_add_f32_e32 v81, v73, v78
	v_mul_f32_e32 v84, v81, v81
	v_fmamk_f32 v72, v84, 0x3e9b6dac, v195
	v_fmaak_f32 v149, v84, v72, 0x3f2aaada
	v_cvt_f32_i32_e32 v72, v90
	v_sub_f32_e32 v73, v81, v73
	v_sub_f32_e32 v73, v78, v73
	v_ldexp_f32 v78, v73, 1
	v_mul_f32_e32 v73, v81, v84
	v_pk_mul_f32 v[86:87], v[72:73], v[148:149]
	v_ldexp_f32 v85, v81, 1
	v_fma_f32 v84, v72, s38, -v86
	v_fmac_f32_e32 v84, 0xb102e308, v72
	v_pk_add_f32 v[72:73], v[86:87], v[84:85]
	v_mov_b32_e32 v88, v86
	v_sub_f32_e32 v81, v73, v85
	v_sub_f32_e32 v81, v87, v81
	v_add_f32_e32 v89, v78, v81
	v_pk_add_f32 v[86:87], v[72:73], v[86:87] neg_lo:[0,1] neg_hi:[0,1]
	v_pk_add_f32 v[90:91], v[72:73], v[88:89]
	v_mov_b32_e32 v85, v72
	v_mov_b32_e32 v87, v91
	v_pk_add_f32 v[102:103], v[84:85], v[86:87]
	v_pk_add_f32 v[98:99], v[84:85], v[86:87] neg_lo:[0,1] neg_hi:[0,1]
	v_pk_add_f32 v[84:85], v[102:103], v[72:73] op_sel:[1,0] op_sel_hi:[0,1] neg_lo:[0,1] neg_hi:[0,1]
	v_pk_add_f32 v[86:87], v[90:91], v[84:85] op_sel_hi:[1,0] neg_lo:[0,1] neg_hi:[0,1]
	v_pk_mov_b32 v[84:85], v[72:73], v[84:85] op_sel:[1,0]
	v_mov_b32_e32 v88, v89
	v_mov_b32_e32 v89, v72
	v_mul_f32_e32 v72, 0xbfb8aa3b, v74
	v_fma_f32 v73, v74, s24, -v72
	v_rndne_f32_e32 v78, v72
	v_fmac_f32_e32 v73, 0xb2a5705f, v74
	v_sub_f32_e32 v72, v72, v78
	v_add_f32_e32 v72, v72, v73
	v_exp_f32_e32 v72, v72
	v_cvt_i32_f32_e32 v73, v78
	v_mov_b32_e32 v102, v91
	v_pk_add_f32 v[84:85], v[102:103], v[84:85] neg_lo:[0,1] neg_hi:[0,1]
	v_mov_b32_e32 v86, v98
	v_ldexp_f32 v72, v72, v73
	v_cndmask_b32_e32 v72, 0, v72, vcc
	v_cmp_ngt_f32_e32 vcc, s26, v74
	v_pk_add_f32 v[100:101], v[88:89], v[84:85] neg_lo:[0,1] neg_hi:[0,1]
	v_add_f32_e32 v48, 1.0, v48
	v_cndmask_b32_e32 v102, v209, v72, vcc
	v_add_f32_e32 v74, 1.0, v102
	v_add_f32_e32 v72, -1.0, v74
	v_sub_f32_e32 v73, v72, v74
	v_add_f32_e32 v73, 1.0, v73
	v_sub_f32_e32 v72, v102, v72
	v_add_f32_e32 v78, v72, v73
	v_frexp_mant_f32_e32 v72, v74
	v_cmp_gt_f32_e32 vcc, s37, v72
	v_cvt_f64_f32_e32 v[72:73], v74
	v_frexp_exp_i32_f64_e32 v72, v[72:73]
	v_subbrev_co_u32_e32 v81, vcc, 0, v72, vcc
	v_sub_u32_e32 v72, 0, v81
	v_ldexp_f32 v74, v74, v72
	v_ldexp_f32 v72, v78, v72
	v_add_f32_e32 v78, -1.0, v74
	v_add_f32_e32 v73, 1.0, v78
	v_sub_f32_e32 v73, v74, v73
	v_add_f32_e32 v84, v72, v73
	v_add_f32_e32 v73, v78, v84
	v_sub_f32_e32 v78, v78, v73
	v_add_f32_e32 v78, v84, v78
	v_add_f32_e32 v84, 1.0, v74
	v_add_f32_e32 v85, -1.0, v84
	v_sub_f32_e32 v74, v74, v85
	v_add_f32_e32 v72, v72, v74
	v_add_f32_e32 v74, v84, v72
	v_rcp_f32_e32 v91, v74
	v_sub_f32_e32 v84, v84, v74
	v_add_f32_e32 v90, v72, v84
	v_pk_add_f32 v[104:105], v[86:87], v[100:101]
	v_mul_f32_e32 v92, v73, v91
	v_mul_f32_e32 v84, v74, v92
	v_fma_f32 v86, v92, v74, -v84
	v_fmac_f32_e32 v86, v92, v90
	v_add_f32_e32 v72, v84, v86
	v_sub_f32_e32 v85, v73, v72
	v_pk_add_f32 v[88:89], v[72:73], v[84:85] neg_lo:[0,1] neg_hi:[0,1]
	v_mov_b32_e32 v87, v72
	v_pk_add_f32 v[72:73], v[88:89], v[86:87] neg_lo:[0,1] neg_hi:[0,1]
	v_cmp_nlt_f32_e32 vcc, s25, v75
	v_add_f32_e32 v73, v78, v73
	v_add_f32_e32 v72, v72, v73
	v_add_f32_e32 v73, v85, v72
	v_mul_f32_e32 v78, v91, v73
	v_mul_f32_e32 v84, v74, v78
	v_fma_f32 v86, v78, v74, -v84
	v_fmac_f32_e32 v86, v78, v90
	v_sub_f32_e32 v74, v85, v73
	v_add_f32_e32 v74, v72, v74
	v_add_f32_e32 v72, v84, v86
	v_sub_f32_e32 v85, v73, v72
	v_pk_add_f32 v[88:89], v[72:73], v[84:85] neg_lo:[0,1] neg_hi:[0,1]
	v_mov_b32_e32 v87, v72
	v_pk_add_f32 v[72:73], v[88:89], v[86:87] neg_lo:[0,1] neg_hi:[0,1]
	v_add_f32_e32 v24, v24, v68
	v_add_f32_e32 v73, v74, v73
	v_add_f32_e32 v72, v72, v73
	v_add_f32_e32 v73, v92, v78
	v_add_f32_e32 v72, v85, v72
	v_sub_f32_e32 v74, v73, v92
	v_mul_f32_e32 v72, v91, v72
	v_sub_f32_e32 v74, v78, v74
	v_add_f32_e32 v74, v74, v72
	v_add_f32_e32 v78, v73, v74
	v_mul_f32_e32 v84, v78, v78
	v_fmamk_f32 v72, v84, 0x3e9b6dac, v195
	v_fmaak_f32 v149, v84, v72, 0x3f2aaada
	v_cvt_f32_i32_e32 v72, v81
	v_sub_f32_e32 v73, v78, v73
	v_sub_f32_e32 v73, v74, v73
	v_ldexp_f32 v74, v73, 1
	v_mul_f32_e32 v73, v78, v84
	v_pk_mul_f32 v[84:85], v[72:73], v[148:149]
	v_ldexp_f32 v87, v78, 1
	v_fma_f32 v86, v72, s38, -v84
	v_fmac_f32_e32 v86, 0xb102e308, v72
	v_pk_add_f32 v[72:73], v[84:85], v[86:87]
	v_mov_b32_e32 v88, v84
	v_sub_f32_e32 v78, v73, v87
	v_sub_f32_e32 v78, v85, v78
	v_add_f32_e32 v89, v74, v78
	v_pk_add_f32 v[90:91], v[72:73], v[84:85] neg_lo:[0,1] neg_hi:[0,1]
	v_pk_add_f32 v[92:93], v[72:73], v[88:89]
	v_mov_b32_e32 v87, v72
	v_mov_b32_e32 v91, v93
	v_pk_add_f32 v[84:85], v[86:87], v[90:91] neg_lo:[0,1] neg_hi:[0,1]
	v_pk_add_f32 v[86:87], v[86:87], v[90:91]
	v_mov_b32_e32 v88, v89
	v_pk_add_f32 v[90:91], v[86:87], v[72:73] op_sel:[1,0] op_sel_hi:[0,1] neg_lo:[0,1] neg_hi:[0,1]
	v_pk_add_f32 v[94:95], v[92:93], v[90:91] op_sel_hi:[1,0] neg_lo:[0,1] neg_hi:[0,1]
	v_pk_mov_b32 v[90:91], v[72:73], v[90:91] op_sel:[1,0]
	v_mov_b32_e32 v89, v72
	v_mul_f32_e32 v72, 0xbfb8aa3b, v75
	v_fma_f32 v73, v75, s24, -v72
	v_rndne_f32_e32 v74, v72
	v_fmac_f32_e32 v73, 0xb2a5705f, v75
	v_sub_f32_e32 v72, v72, v74
	v_add_f32_e32 v72, v72, v73
	v_exp_f32_e32 v72, v72
	v_cvt_i32_f32_e32 v73, v74
	v_mov_b32_e32 v86, v93
	v_pk_add_f32 v[90:91], v[86:87], v[90:91] neg_lo:[0,1] neg_hi:[0,1]
	v_mov_b32_e32 v94, v84
	v_ldexp_f32 v72, v72, v73
	v_cndmask_b32_e32 v72, 0, v72, vcc
	v_cmp_ngt_f32_e32 vcc, s26, v75
	v_pk_add_f32 v[88:89], v[88:89], v[90:91] neg_lo:[0,1] neg_hi:[0,1]
	v_rcp_f32_e32 v151, v48
	v_cndmask_b32_e32 v128, v209, v72, vcc
	v_add_f32_e32 v74, 1.0, v128
	v_add_f32_e32 v72, -1.0, v74
	v_sub_f32_e32 v73, v72, v74
	v_add_f32_e32 v73, 1.0, v73
	v_sub_f32_e32 v72, v128, v72
	v_add_f32_e32 v75, v72, v73
	v_frexp_mant_f32_e32 v72, v74
	v_cmp_gt_f32_e32 vcc, s37, v72
	v_cvt_f64_f32_e32 v[72:73], v74
	v_frexp_exp_i32_f64_e32 v72, v[72:73]
	v_subbrev_co_u32_e32 v78, vcc, 0, v72, vcc
	v_sub_u32_e32 v72, 0, v78
	v_ldexp_f32 v74, v74, v72
	v_ldexp_f32 v72, v75, v72
	v_add_f32_e32 v75, -1.0, v74
	v_add_f32_e32 v73, 1.0, v75
	v_sub_f32_e32 v73, v74, v73
	v_add_f32_e32 v81, v72, v73
	v_add_f32_e32 v73, v75, v81
	v_sub_f32_e32 v75, v75, v73
	v_add_f32_e32 v81, v81, v75
	v_add_f32_e32 v75, 1.0, v74
	v_add_f32_e32 v86, -1.0, v75
	v_sub_f32_e32 v74, v74, v86
	v_add_f32_e32 v72, v72, v74
	v_add_f32_e32 v86, v75, v72
	v_rcp_f32_e32 v96, v86
	v_sub_f32_e32 v74, v75, v86
	v_pk_add_f32 v[90:91], v[94:95], v[88:89]
	v_add_f32_e32 v89, v72, v74
	v_mul_f32_e32 v97, v73, v96
	v_mul_f32_e32 v74, v86, v97
	v_fma_f32 v92, v97, v86, -v74
	v_fmac_f32_e32 v92, v97, v89
	v_add_f32_e32 v72, v74, v92
	v_sub_f32_e32 v75, v73, v72
	v_pk_add_f32 v[94:95], v[72:73], v[74:75] neg_lo:[0,1] neg_hi:[0,1]
	v_mov_b32_e32 v93, v72
	v_pk_add_f32 v[72:73], v[94:95], v[92:93] neg_lo:[0,1] neg_hi:[0,1]
	v_add_f32_e32 v48, v53, v65
	v_add_f32_e32 v73, v81, v73
	v_add_f32_e32 v72, v72, v73
	v_add_f32_e32 v73, v75, v72
	v_mul_f32_e32 v81, v96, v73
	v_mul_f32_e32 v74, v86, v81
	v_fma_f32 v92, v81, v86, -v74
	v_fmac_f32_e32 v92, v81, v89
	v_sub_f32_e32 v75, v75, v73
	v_add_f32_e32 v86, v72, v75
	v_add_f32_e32 v72, v74, v92
	v_sub_f32_e32 v75, v73, v72
	v_pk_add_f32 v[94:95], v[72:73], v[74:75] neg_lo:[0,1] neg_hi:[0,1]
	v_mov_b32_e32 v93, v72
	v_pk_add_f32 v[72:73], v[94:95], v[92:93] neg_lo:[0,1] neg_hi:[0,1]
	v_mul_f32_e32 v24, 0xbfb8aa3b, v24
	v_add_f32_e32 v73, v86, v73
	v_add_f32_e32 v72, v72, v73
	v_add_f32_e32 v73, v97, v81
	v_add_f32_e32 v72, v75, v72
	v_sub_f32_e32 v74, v73, v97
	v_mul_f32_e32 v72, v96, v72
	v_sub_f32_e32 v74, v81, v74
	v_add_f32_e32 v74, v74, v72
	v_add_f32_e32 v75, v73, v74
	v_mul_f32_e32 v81, v75, v75
	v_fmamk_f32 v72, v81, 0x3e9b6dac, v195
	v_fmaak_f32 v149, v81, v72, 0x3f2aaada
	v_cvt_f32_i32_e32 v72, v78
	v_sub_f32_e32 v73, v75, v73
	v_sub_f32_e32 v73, v74, v73
	v_ldexp_f32 v78, v73, 1
	v_mul_f32_e32 v73, v75, v81
	v_ldexp_f32 v93, v75, 1
	v_pk_mul_f32 v[74:75], v[72:73], v[148:149]
	v_mul_f32_e32 v48, 0xbfb8aa3b, v48
	v_fma_f32 v92, v72, s38, -v74
	v_fmac_f32_e32 v92, 0xb102e308, v72
	v_pk_add_f32 v[72:73], v[74:75], v[92:93]
	v_mov_b32_e32 v94, v74
	v_sub_f32_e32 v81, v73, v93
	v_sub_f32_e32 v81, v75, v81
	v_add_f32_e32 v95, v78, v81
	v_pk_add_f32 v[96:97], v[72:73], v[74:75] neg_lo:[0,1] neg_hi:[0,1]
	v_pk_add_f32 v[110:111], v[72:73], v[94:95]
	v_mov_b32_e32 v93, v72
	v_mov_b32_e32 v97, v111
	v_pk_add_f32 v[74:75], v[92:93], v[96:97] neg_lo:[0,1] neg_hi:[0,1]
	v_pk_add_f32 v[96:97], v[92:93], v[96:97]
	v_mov_b32_e32 v94, v95
	v_pk_add_f32 v[92:93], v[96:97], v[72:73] op_sel:[1,0] op_sel_hi:[0,1] neg_lo:[0,1] neg_hi:[0,1]
	v_pk_add_f32 v[112:113], v[110:111], v[92:93] op_sel_hi:[1,0] neg_lo:[0,1] neg_hi:[0,1]
	v_pk_mov_b32 v[92:93], v[72:73], v[92:93] op_sel:[1,0]
	v_mov_b32_e32 v95, v72
	v_lshl_add_u64 v[72:73], v[106:107], 1, v[140:141]
	v_ashrrev_i32_e32 v78, 4, v108
	v_add_co_u32_e32 v108, vcc, s33, v72
	v_mov_b32_e32 v96, v111
	s_nop 0
	v_addc_co_u32_e32 v109, vcc, 0, v73, vcc
	global_load_dwordx2 v[110:111], v[108:109], off offset:32
	global_load_dwordx2 v[106:107], v[72:73], off offset:32
	v_rcp_f32_e32 v108, v56
	v_mul_f32_e32 v56, 0xbfb8aa3b, v57
	v_exp_f32_e32 v56, v56
	v_exp_f32_e32 v24, v24
	v_exp_f32_e32 v48, v48
	v_add_f32_e32 v57, v58, v70
	v_add_f32_e32 v56, 1.0, v56
	v_rcp_f32_e32 v143, v56
	v_add_f32_e32 v56, v62, v66
	v_mul_f32_e32 v56, 0xbfb8aa3b, v56
	v_exp_f32_e32 v56, v56
	v_pk_add_f32 v[92:93], v[96:97], v[92:93] neg_lo:[0,1] neg_hi:[0,1]
	v_add_f32_e32 v24, 1.0, v24
	v_pk_add_f32 v[92:93], v[94:95], v[92:93] neg_lo:[0,1] neg_hi:[0,1]
	v_add_f32_e32 v56, 1.0, v56
	v_rcp_f32_e32 v61, v56
	v_mul_f32_e32 v56, 0xbfb8aa3b, v57
	v_exp_f32_e32 v56, v56
	v_mov_b32_e32 v112, v74
	v_add_f32_e32 v49, v49, v69
	v_add_f32_e32 v48, 1.0, v48
	v_rcp_f32_e32 v156, v24
	v_add_f32_e32 v24, v29, v65
	v_pk_add_f32 v[94:95], v[112:113], v[92:93]
	v_mul_f32_e32 v24, 0xbfb8aa3b, v24
	v_exp_f32_e32 v24, v24
	v_add_f32_e32 v56, 1.0, v56
	v_add_f32_e32 v60, v60, v64
	v_rcp_f32_e32 v137, v56
	v_add_f32_e32 v56, v63, v67
	v_mul_f32_e32 v60, 0xbfb8aa3b, v60
	v_mul_f32_e32 v56, 0xbfb8aa3b, v56
	v_exp_f32_e32 v60, v60
	v_exp_f32_e32 v56, v56
	v_add_f32_e32 v25, v25, v69
	v_add_f32_e32 v24, 1.0, v24
	v_add_f32_e32 v40, v40, v68
	v_rcp_f32_e32 v116, v24
	v_mul_f32_e32 v24, 0xbfb8aa3b, v25
	v_mul_f32_e32 v40, 0xbfb8aa3b, v40
	v_exp_f32_e32 v24, v24
	v_exp_f32_e32 v40, v40
	v_add_f32_e32 v60, 1.0, v60
	v_add_f32_e32 v57, v59, v71
	v_add_f32_e32 v56, 1.0, v56
	v_rcp_f32_e32 v109, v60
	v_rcp_f32_e32 v60, v56
	v_mul_f32_e32 v56, 0xbfb8aa3b, v57
	v_exp_f32_e32 v56, v56
	v_add_f32_e32 v24, 1.0, v24
	v_add_f32_e32 v50, v50, v70
	v_add_f32_e32 v40, 1.0, v40
	v_rcp_f32_e32 v25, v24
	v_add_f32_e32 v24, v30, v66
	v_rcp_f32_e32 v153, v40
	v_add_f32_e32 v40, v45, v65
	v_mul_f32_e32 v24, 0xbfb8aa3b, v24
	v_add_f32_e32 v16, v16, v68
	v_mul_f32_e32 v40, 0xbfb8aa3b, v40
	v_exp_f32_e32 v24, v24
	v_mul_f32_e32 v16, 0xbfb8aa3b, v16
	v_add_f32_e32 v56, 1.0, v56
	v_exp_f32_e32 v40, v40
	v_exp_f32_e32 v16, v16
	v_rcp_f32_e32 v136, v56
	v_add_u32_e32 v56, v78, v132
	v_ashrrev_i32_e32 v57, 31, v56
	v_lshlrev_b64 v[56:57], 16, v[56:57]
	v_add_f32_e32 v26, v26, v70
	v_add_f32_e32 v24, 1.0, v24
	v_or3_b32 v58, v56, v133, v146
	v_add_f32_e32 v41, v41, v69
	v_add_f32_e32 v40, 1.0, v40
	v_add_f32_e32 v16, 1.0, v16
	v_rcp_f32_e32 v112, v40
	v_mul_f32_e32 v40, 0xbfb8aa3b, v41
	v_rcp_f32_e32 v29, v16
	v_add_f32_e32 v16, v21, v65
	s_waitcnt vmcnt(1)
	v_lshlrev_b32_e32 v149, 16, v110
	v_and_b32_e32 v93, 0xffff0000, v110
	v_rcp_f32_e32 v110, v48
	v_mul_f32_e32 v48, 0xbfb8aa3b, v49
	v_exp_f32_e32 v48, v48
	v_exp_f32_e32 v40, v40
	v_mul_f32_e32 v16, 0xbfb8aa3b, v16
	v_exp_f32_e32 v16, v16
	v_add_f32_e32 v48, 1.0, v48
	v_rcp_f32_e32 v150, v48
	v_add_f32_e32 v48, v54, v66
	v_mul_f32_e32 v48, 0xbfb8aa3b, v48
	v_exp_f32_e32 v48, v48
	v_add_f32_e32 v40, 1.0, v40
	v_rcp_f32_e32 v152, v40
	v_add_f32_e32 v40, v46, v66
	v_add_f32_e32 v48, 1.0, v48
	v_rcp_f32_e32 v49, v48
	v_mul_f32_e32 v48, 0xbfb8aa3b, v50
	v_exp_f32_e32 v48, v48
	v_add_f32_e32 v17, v17, v69
	v_add_f32_e32 v16, 1.0, v16
	v_add_f32_e32 v8, v8, v68
	v_add_f32_e32 v48, 1.0, v48
	v_rcp_f32_e32 v133, v48
	v_add_f32_e32 v48, v55, v67
	v_rcp_f32_e32 v55, v24
	v_mul_f32_e32 v24, 0xbfb8aa3b, v26
	v_exp_f32_e32 v24, v24
	v_mul_f32_e32 v40, 0xbfb8aa3b, v40
	v_rcp_f32_e32 v118, v16
	v_mul_f32_e32 v16, 0xbfb8aa3b, v17
	v_add_f32_e32 v24, 1.0, v24
	v_rcp_f32_e32 v141, v24
	v_add_f32_e32 v24, v31, v67
	v_mul_f32_e32 v24, 0xbfb8aa3b, v24
	v_exp_f32_e32 v24, v24
	v_mul_f32_e32 v8, 0xbfb8aa3b, v8
	v_exp_f32_e32 v40, v40
	v_exp_f32_e32 v16, v16
	v_exp_f32_e32 v8, v8
	v_add_f32_e32 v26, v27, v71
	v_add_f32_e32 v24, 1.0, v24
	v_add_f32_e32 v41, v42, v70
	v_add_f32_e32 v40, 1.0, v40
	v_rcp_f32_e32 v54, v24
	v_mul_f32_e32 v24, 0xbfb8aa3b, v26
	v_or3_b32 v26, v56, v127, v146
	v_mov_b32_e32 v27, v57
	v_add_f32_e32 v16, 1.0, v16
	v_add_f32_e32 v8, 1.0, v8
	s_waitcnt vmcnt(0)
	v_lshlrev_b32_e32 v130, 16, v107
	v_and_b32_e32 v96, 0xffff0000, v107
	v_rcp_f32_e32 v107, v40
	v_mul_f32_e32 v40, 0xbfb8aa3b, v41
	v_add_f32_e32 v41, v43, v71
	v_lshl_add_u64 v[42:43], v[26:27], 3, s[14:15]
	v_rcp_f32_e32 v27, v16
	v_add_f32_e32 v16, v22, v66
	v_rcp_f32_e32 v157, v8
	v_add_f32_e32 v8, v13, v65
	v_mul_f32_e32 v16, 0xbfb8aa3b, v16
	v_mul_f32_e32 v8, 0xbfb8aa3b, v8
	v_exp_f32_e32 v16, v16
	v_exp_f32_e32 v8, v8
	v_add_f32_e32 v17, v18, v70
	v_add_f32_e32 v9, v9, v69
	v_add_f32_e32 v16, 1.0, v16
	v_add_f32_e32 v8, 1.0, v8
	v_rcp_f32_e32 v53, v16
	v_mul_f32_e32 v16, 0xbfb8aa3b, v17
	v_rcp_f32_e32 v120, v8
	v_mul_f32_e32 v8, 0xbfb8aa3b, v9
	v_exp_f32_e32 v16, v16
	v_exp_f32_e32 v8, v8
	v_add_f32_e32 v52, v52, v64
	v_mul_f32_e32 v52, 0xbfb8aa3b, v52
	v_add_f32_e32 v16, 1.0, v16
	v_add_f32_e32 v8, 1.0, v8
	v_rcp_f32_e32 v142, v16
	v_add_f32_e32 v16, v23, v67
	v_rcp_f32_e32 v31, v8
	v_add_f32_e32 v8, v14, v66
	v_mul_f32_e32 v16, 0xbfb8aa3b, v16
	v_mul_f32_e32 v8, 0xbfb8aa3b, v8
	v_add_f32_e32 v0, v0, v64
	v_exp_f32_e32 v52, v52
	v_exp_f32_e32 v40, v40
	v_exp_f32_e32 v16, v16
	v_exp_f32_e32 v8, v8
	v_mul_f32_e32 v0, 0xbfb8aa3b, v0
	v_exp_f32_e32 v0, v0
	v_add_f32_e32 v52, 1.0, v52
	v_add_f32_e32 v40, 1.0, v40
	v_add_f32_e32 v17, v19, v71
	v_add_f32_e32 v16, 1.0, v16
	v_add_f32_e32 v9, v10, v70
	v_add_f32_e32 v8, 1.0, v8
	v_lshlrev_b32_e32 v132, 16, v111
	v_and_b32_e32 v131, 0xffff0000, v111
	v_rcp_f32_e32 v111, v52
	v_rcp_f32_e32 v139, v40
	v_add_f32_e32 v40, v47, v67
	v_rcp_f32_e32 v52, v16
	v_mul_f32_e32 v16, 0xbfb8aa3b, v17
	v_rcp_f32_e32 v47, v8
	v_mul_f32_e32 v8, 0xbfb8aa3b, v9
	v_add_f32_e32 v4, v4, v68
	v_add_f32_e32 v0, 1.0, v0
	v_exp_f32_e32 v16, v16
	v_exp_f32_e32 v8, v8
	v_rcp_f32_e32 v13, v0
	v_mul_f32_e32 v0, 0xbfb8aa3b, v4
	v_exp_f32_e32 v0, v0
	v_add_f32_e32 v16, 1.0, v16
	v_add_f32_e32 v8, 1.0, v8
	v_rcp_f32_e32 v127, v16
	v_or3_b32 v16, v56, v134, v146
	v_rcp_f32_e32 v134, v8
	v_add_f32_e32 v8, v15, v67
	v_add_f32_e32 v0, 1.0, v0
	v_add_f32_e32 v12, v12, v64
	v_mul_f32_e32 v8, 0xbfb8aa3b, v8
	v_rcp_f32_e32 v14, v0
	v_add_f32_e32 v0, v1, v65
	v_mul_f32_e32 v12, 0xbfb8aa3b, v12
	v_exp_f32_e32 v8, v8
	v_mul_f32_e32 v0, 0xbfb8aa3b, v0
	v_exp_f32_e32 v12, v12
	v_exp_f32_e32 v0, v0
	v_add_f32_e32 v9, v11, v71
	v_add_f32_e32 v8, 1.0, v8
	v_add_f32_e32 v36, v36, v64
	v_add_f32_e32 v32, v32, v68
	v_add_f32_e32 v12, 1.0, v12
	v_rcp_f32_e32 v46, v8
	v_mul_f32_e32 v8, 0xbfb8aa3b, v9
	v_add_f32_e32 v1, v5, v69
	v_add_f32_e32 v0, 1.0, v0
	v_mul_f32_e32 v36, 0xbfb8aa3b, v36
	v_mul_f32_e32 v32, 0xbfb8aa3b, v32
	v_rcp_f32_e32 v121, v12
	v_exp_f32_e32 v8, v8
	v_rcp_f32_e32 v12, v0
	v_mul_f32_e32 v0, 0xbfb8aa3b, v1
	v_exp_f32_e32 v36, v36
	v_exp_f32_e32 v32, v32
	v_exp_f32_e32 v0, v0
	v_add_f32_e32 v44, v44, v64
	v_add_f32_e32 v20, v20, v64
	v_mul_f32_e32 v44, 0xbfb8aa3b, v44
	v_mul_f32_e32 v20, 0xbfb8aa3b, v20
	v_add_f32_e32 v8, 1.0, v8
	v_exp_f32_e32 v44, v44
	v_add_f32_e32 v36, 1.0, v36
	v_add_f32_e32 v32, 1.0, v32
	v_exp_f32_e32 v20, v20
	v_rcp_f32_e32 v15, v8
	v_or3_b32 v8, v56, v135, v146
	v_mov_b32_e32 v9, v57
	v_add_f32_e32 v0, 1.0, v0
	v_rcp_f32_e32 v115, v36
	v_rcp_f32_e32 v155, v32
	v_add_f32_e32 v32, v37, v65
	v_lshl_add_u64 v[36:37], v[8:9], 3, s[14:15]
	v_rcp_f32_e32 v4, v0
	v_mov_b32_e32 v0, v104
	v_mov_b32_e32 v1, v82
	v_mov_b32_e32 v8, v105
	v_mov_b32_e32 v9, v83
	v_pk_add_f32 v[8:9], v[0:1], v[8:9]
	v_mov_b32_e32 v78, v103
	v_pk_add_f32 v[10:11], v[78:79], v[8:9]
	v_mov_b32_e32 v77, v79
	v_mov_b32_e32 v99, v103
	v_add_f32_e32 v44, 1.0, v44
	v_add_f32_e32 v20, 1.0, v20
	v_mov_b32_e32 v17, v57
	v_mov_b32_e32 v83, v11
	v_mov_b32_e32 v105, v10
	v_rcp_f32_e32 v113, v44
	v_rcp_f32_e32 v119, v20
	v_lshl_add_u64 v[44:45], v[16:17], 3, s[14:15]
	v_pk_add_f32 v[16:17], v[82:83], v[76:77] neg_lo:[0,1] neg_hi:[0,1]
	v_pk_add_f32 v[20:21], v[104:105], v[98:99] neg_lo:[0,1] neg_hi:[0,1]
	v_mov_b32_e32 v81, v9
	v_mov_b32_e32 v22, v20
	v_mov_b32_e32 v23, v16
	v_mov_b32_e32 v101, v8
	v_mul_f32_e32 v32, 0xbfb8aa3b, v32
	v_pk_add_f32 v[18:19], v[80:81], v[16:17] neg_lo:[0,1] neg_hi:[0,1]
	v_pk_add_f32 v[0:1], v[0:1], v[22:23] neg_lo:[0,1] neg_hi:[0,1]
	v_mov_b32_e32 v99, v76
	v_pk_add_f32 v[8:9], v[100:101], v[20:21] neg_lo:[0,1] neg_hi:[0,1]
	v_exp_f32_e32 v32, v32
	v_pk_add_f32 v[0:1], v[98:99], v[0:1] neg_lo:[0,1] neg_hi:[0,1]
	v_mov_b32_e32 v16, v8
	v_mov_b32_e32 v17, v18
	v_pk_add_f32 v[0:1], v[16:17], v[0:1]
	v_mov_b32_e32 v18, v9
	v_pk_add_f32 v[0:1], v[0:1], v[18:19]
	v_cmp_neq_f32_e32 vcc, s27, v129
	v_pk_add_f32 v[0:1], v[10:11], v[0:1]
	v_add_f32_e32 v33, v33, v69
	v_add_f32_e32 v32, 1.0, v32
	v_cndmask_b32_e32 v0, v209, v0, vcc
	v_cmp_neq_f32_e32 vcc, s27, v123
	v_rcp_f32_e32 v114, v32
	v_mul_f32_e32 v32, 0xbfb8aa3b, v33
	v_cndmask_b32_e32 v1, v209, v1, vcc
	v_cmp_lt_f32_e64 vcc, |v129|, s39
	v_cmp_lt_f32_e64 s[0:1], |v123|, s39
	v_exp_f32_e32 v32, v32
	v_cndmask_b32_e32 v0, v0, v129, vcc
	v_cndmask_b32_e64 v1, v1, v123, s[0:1]
	v_pk_mul_f32 v[8:9], v[108:109], s[44:45] op_sel_hi:[1,0]
	v_add_f32_e32 v32, 1.0, v32
	v_pk_mul_f32 v[10:11], v[8:9], v[0:1]
	v_rcp_f32_e32 v154, v32
	v_mul_f32_e32 v5, 0x3fb8aa3b, v11
	v_exp_f32_e32 v8, v5
	v_pk_add_f32 v[16:17], v[10:11], v[10:11]
	v_add_f32_e32 v32, v38, v66
	v_fmamk_f32 v9, v17, 0x3d2aaaab, v196
	v_fma_f32 v9, v17, v9, 0.5
	v_mul_f32_e32 v32, 0xbfb8aa3b, v32
	v_fma_f32 v9, v17, v9, 1.0
	v_exp_f32_e32 v32, v32
	v_fma_f32 v5, -v8, v8, 1.0
	v_mul_f32_e64 v9, v9, -v17
	v_cmp_lt_f32_e64 s[0:1], s40, v17
	v_add_f32_e32 v33, v34, v70
	v_add_f32_e32 v32, 1.0, v32
	v_cndmask_b32_e64 v5, v5, v9, s[0:1]
	v_max_f32_e32 v5, 0, v5
	v_sqrt_f32_e32 v5, v5
	v_rcp_f32_e32 v63, v32
	v_mul_f32_e32 v32, 0xbfb8aa3b, v33
	v_exp_f32_e32 v32, v32
	v_lshlrev_b32_e32 v89, 16, v106
	v_mul_f32_e32 v5, v145, v5
	v_mul_f32_e32 v9, v5, v89
	v_mul_f32_e32 v5, 0x3fb8aa3b, v10
	v_exp_f32_e32 v10, v5
	v_add_f32_e32 v32, 1.0, v32
	v_fmamk_f32 v11, v16, 0x3d2aaaab, v196
	v_rcp_f32_e32 v140, v32
	v_add_f32_e32 v32, v39, v67
	v_fma_f32 v11, v16, v11, 0.5
	v_mul_f32_e32 v40, 0xbfb8aa3b, v40
	v_mul_f32_e32 v32, 0xbfb8aa3b, v32
	v_fma_f32 v11, v16, v11, 1.0
	v_exp_f32_e32 v40, v40
	v_exp_f32_e32 v32, v32
	v_cmp_lt_f32_e32 vcc, s40, v16
	v_fma_f32 v5, -v10, v10, 1.0
	v_mul_f32_e64 v11, v11, -v16
	v_cndmask_b32_e32 v5, v5, v11, vcc
	v_max_f32_e32 v5, 0, v5
	v_sqrt_f32_e32 v5, v5
	v_add_f32_e32 v50, v51, v71
	v_add_f32_e32 v40, 1.0, v40
	v_add_f32_e32 v33, v35, v71
	v_add_f32_e32 v32, 1.0, v32
	v_and_b32_e32 v86, 0xffff0000, v106
	v_mul_f32_e32 v50, 0xbfb8aa3b, v50
	v_rcp_f32_e32 v106, v40
	v_mul_f32_e32 v40, 0xbfb8aa3b, v41
	v_rcp_f32_e32 v62, v32
	v_mul_f32_e32 v32, 0xbfb8aa3b, v33
	v_exp_f32_e32 v50, v50
	v_exp_f32_e32 v40, v40
	v_exp_f32_e32 v32, v32
	v_mov_b32_e32 v59, v57
	v_mul_f32_e32 v5, v143, v5
	v_lshl_add_u64 v[58:59], v[58:59], 3, s[14:15]
	v_mul_f32_e32 v11, v5, v86
	global_store_dwordx4 v[58:59], v[8:11], off
	v_add_f32_e32 v50, 1.0, v50
	v_add_f32_e32 v40, 1.0, v40
	v_pk_mul_f32 v[8:9], v[110:111], s[44:45] op_sel_hi:[1,0]
	v_add_f32_e32 v32, 1.0, v32
	v_pk_mul_f32 v[8:9], v[8:9], v[0:1]
	v_rcp_f32_e32 v138, v50
	v_or3_b32 v50, v56, v124, v146
	v_rcp_f32_e32 v124, v40
	v_or3_b32 v40, v56, v125, v146
	v_rcp_f32_e32 v125, v32
	v_or3_b32 v32, v56, v126, v146
	v_mov_b32_e32 v33, v57
	v_mul_f32_e32 v5, 0x3fb8aa3b, v9
	v_lshl_add_u64 v[38:39], v[32:33], 3, s[14:15]
	v_exp_f32_e32 v32, v5
	v_pk_add_f32 v[10:11], v[8:9], v[8:9]
	v_add_f32_e32 v28, v28, v64
	v_fmamk_f32 v9, v11, 0x3d2aaaab, v196
	v_fma_f32 v9, v11, v9, 0.5
	v_fma_f32 v9, v11, v9, 1.0
	v_fma_f32 v5, -v32, v32, 1.0
	v_mul_f32_e64 v9, v9, -v11
	v_cmp_lt_f32_e64 s[0:1], s40, v11
	v_cmp_lt_f32_e32 vcc, s40, v10
	v_mul_f32_e32 v28, 0xbfb8aa3b, v28
	v_cndmask_b32_e64 v5, v5, v9, s[0:1]
	v_max_f32_e32 v5, 0, v5
	v_sqrt_f32_e32 v5, v5
	v_exp_f32_e32 v28, v28
	v_exp_f32_e32 v24, v24
	v_pk_mul_f32 v[12:13], v[12:13], s[44:45] op_sel_hi:[1,0]
	v_mul_f32_e32 v5, v151, v5
	v_mul_f32_e32 v33, v5, v149
	v_mul_f32_e32 v5, 0x3fb8aa3b, v8
	v_exp_f32_e32 v34, v5
	v_fmamk_f32 v8, v10, 0x3d2aaaab, v196
	v_fma_f32 v8, v10, v8, 0.5
	v_fma_f32 v8, v10, v8, 1.0
	v_fma_f32 v5, -v34, v34, 1.0
	v_mul_f32_e64 v8, v8, -v10
	v_cndmask_b32_e32 v5, v5, v8, vcc
	v_max_f32_e32 v5, 0, v5
	v_sqrt_f32_e32 v5, v5
	v_pk_mul_f32 v[8:9], v[112:113], s[44:45] op_sel_hi:[1,0]
	v_add_f32_e32 v28, 1.0, v28
	v_pk_mul_f32 v[8:9], v[8:9], v[0:1]
	v_mul_f32_e32 v5, v150, v5
	v_mul_f32_e32 v35, v5, v93
	v_mul_f32_e32 v5, 0x3fb8aa3b, v9
	v_rcp_f32_e32 v117, v28
	v_exp_f32_e32 v28, v5
	v_pk_add_f32 v[10:11], v[8:9], v[8:9]
	v_add_f32_e32 v24, 1.0, v24
	v_fmamk_f32 v9, v11, 0x3d2aaaab, v196
	v_fma_f32 v9, v11, v9, 0.5
	v_fma_f32 v9, v11, v9, 1.0
	v_fma_f32 v5, -v28, v28, 1.0
	v_mul_f32_e64 v9, v9, -v11
	v_cmp_lt_f32_e64 s[0:1], s40, v11
	v_cmp_lt_f32_e32 vcc, s40, v10
	v_rcp_f32_e32 v126, v24
	v_cndmask_b32_e64 v5, v5, v9, s[0:1]
	v_max_f32_e32 v5, 0, v5
	v_sqrt_f32_e32 v5, v5
	v_mov_b32_e32 v86, v97
	v_mov_b32_e32 v85, v87
	v_mov_b32_e32 v75, v97
	v_mul_f32_e32 v68, v153, v5
	v_mul_f32_e32 v5, 0x3fb8aa3b, v8
	v_exp_f32_e32 v30, v5
	v_fmamk_f32 v8, v10, 0x3d2aaaab, v196
	v_fma_f32 v8, v10, v8, 0.5
	v_fma_f32 v8, v10, v8, 1.0
	v_fma_f32 v5, -v30, v30, 1.0
	v_mul_f32_e64 v8, v8, -v10
	v_cndmask_b32_e32 v5, v5, v8, vcc
	v_max_f32_e32 v5, 0, v5
	v_sqrt_f32_e32 v5, v5
	v_pk_mul_f32 v[8:9], v[114:115], s[44:45] op_sel_hi:[1,0]
	v_pk_mul_f32 v[60:61], v[60:61], s[44:45] op_sel_hi:[1,0]
	v_pk_mul_f32 v[8:9], v[8:9], v[0:1]
	v_mul_f32_e32 v69, v152, v5
	v_mul_f32_e32 v5, 0x3fb8aa3b, v9
	v_exp_f32_e32 v24, v5
	v_pk_add_f32 v[10:11], v[8:9], v[8:9]
	v_mul_f32_e32 v48, 0xbfb8aa3b, v48
	v_fmamk_f32 v9, v11, 0x3d2aaaab, v196
	v_fma_f32 v9, v11, v9, 0.5
	v_fma_f32 v9, v11, v9, 1.0
	v_fma_f32 v5, -v24, v24, 1.0
	v_mul_f32_e64 v9, v9, -v11
	v_cmp_lt_f32_e64 s[0:1], s40, v11
	v_cmp_lt_f32_e32 vcc, s40, v10
	v_exp_f32_e32 v48, v48
	v_cndmask_b32_e64 v5, v5, v9, s[0:1]
	v_max_f32_e32 v5, 0, v5
	v_sqrt_f32_e32 v5, v5
	v_add_f32_e32 v48, 1.0, v48
	v_mov_b32_e32 v51, v57
	v_mov_b32_e32 v41, v57
	v_mul_f32_e32 v64, v155, v5
	v_mul_f32_e32 v5, 0x3fb8aa3b, v8
	v_exp_f32_e32 v26, v5
	v_fmamk_f32 v8, v10, 0x3d2aaaab, v196
	v_fma_f32 v8, v10, v8, 0.5
	v_fma_f32 v8, v10, v8, 1.0
	v_fma_f32 v5, -v26, v26, 1.0
	v_mul_f32_e64 v8, v8, -v10
	v_cndmask_b32_e32 v5, v5, v8, vcc
	v_max_f32_e32 v5, 0, v5
	v_sqrt_f32_e32 v5, v5
	v_pk_mul_f32 v[8:9], v[116:117], s[44:45] op_sel_hi:[1,0]
	v_rcp_f32_e32 v48, v48
	v_pk_mul_f32 v[8:9], v[8:9], v[0:1]
	v_mul_f32_e32 v65, v154, v5
	v_mul_f32_e32 v5, 0x3fb8aa3b, v9
	v_exp_f32_e32 v20, v5
	v_pk_add_f32 v[10:11], v[8:9], v[8:9]
	v_lshl_add_u64 v[50:51], v[50:51], 3, s[14:15]
	v_fmamk_f32 v9, v11, 0x3d2aaaab, v196
	v_fma_f32 v9, v11, v9, 0.5
	v_fma_f32 v9, v11, v9, 1.0
	v_fma_f32 v5, -v20, v20, 1.0
	v_mul_f32_e64 v9, v9, -v11
	v_cmp_lt_f32_e64 s[0:1], s40, v11
	v_cmp_lt_f32_e32 vcc, s40, v10
	v_lshl_add_u64 v[40:41], v[40:41], 3, s[14:15]
	v_cndmask_b32_e64 v5, v5, v9, s[0:1]
	v_max_f32_e32 v5, 0, v5
	v_sqrt_f32_e32 v5, v5
	s_nop 0
	v_mul_f32_e32 v21, v156, v5
	v_mul_f32_e32 v5, 0x3fb8aa3b, v8
	v_exp_f32_e32 v22, v5
	v_fmamk_f32 v8, v10, 0x3d2aaaab, v196
	v_fma_f32 v8, v10, v8, 0.5
	v_fma_f32 v8, v10, v8, 1.0
	v_fma_f32 v5, -v22, v22, 1.0
	v_mul_f32_e64 v8, v8, -v10
	v_cndmask_b32_e32 v5, v5, v8, vcc
	v_max_f32_e32 v5, 0, v5
	v_sqrt_f32_e32 v5, v5
	v_pk_mul_f32 v[8:9], v[118:119], s[44:45] op_sel_hi:[1,0]
	v_mul_f32_e32 v23, v25, v5
	v_pk_mul_f32 v[8:9], v[8:9], v[0:1]
	s_nop 0
	v_mul_f32_e32 v5, 0x3fb8aa3b, v9
	v_exp_f32_e32 v16, v5
	v_pk_add_f32 v[10:11], v[8:9], v[8:9]
	v_fma_f32 v5, -v16, v16, 1.0
	v_fmamk_f32 v9, v11, 0x3d2aaaab, v196
	v_fma_f32 v9, v11, v9, 0.5
	v_fma_f32 v9, v11, v9, 1.0
	v_mul_f32_e64 v9, v9, -v11
	v_cmp_lt_f32_e64 s[0:1], s40, v11
	v_cmp_lt_f32_e32 vcc, s40, v10
	s_nop 0
	v_cndmask_b32_e64 v5, v5, v9, s[0:1]
	v_max_f32_e32 v5, 0, v5
	v_sqrt_f32_e32 v5, v5
	s_nop 0
	v_mul_f32_e32 v17, v29, v5
	v_mul_f32_e32 v5, 0x3fb8aa3b, v8
	v_exp_f32_e32 v18, v5
	v_fmamk_f32 v8, v10, 0x3d2aaaab, v196
	v_fma_f32 v8, v10, v8, 0.5
	v_fma_f32 v8, v10, v8, 1.0
	v_fma_f32 v5, -v18, v18, 1.0
	v_mul_f32_e64 v8, v8, -v10
	v_cndmask_b32_e32 v5, v5, v8, vcc
	v_max_f32_e32 v5, 0, v5
	v_sqrt_f32_e32 v5, v5
	v_pk_mul_f32 v[8:9], v[120:121], s[44:45] op_sel_hi:[1,0]
	v_mul_f32_e32 v19, v27, v5
	v_pk_mul_f32 v[10:11], v[8:9], v[0:1]
	v_pk_mul_f32 v[0:1], v[12:13], v[0:1]
	v_mul_f32_e32 v5, 0x3fb8aa3b, v11
	v_exp_f32_e32 v8, v5
	v_pk_add_f32 v[76:77], v[10:11], v[10:11]
	v_fma_f32 v5, -v8, v8, 1.0
	v_fmamk_f32 v9, v77, 0x3d2aaaab, v196
	v_fma_f32 v9, v77, v9, 0.5
	v_fma_f32 v9, v77, v9, 1.0
	v_mul_f32_e64 v9, v9, -v77
	v_cmp_lt_f32_e64 s[0:1], s40, v77
	v_fmamk_f32 v11, v76, 0x3d2aaaab, v196
	v_fma_f32 v11, v76, v11, 0.5
	v_cndmask_b32_e64 v5, v5, v9, s[0:1]
	v_max_f32_e32 v5, 0, v5
	v_sqrt_f32_e32 v5, v5
	v_fma_f32 v11, v76, v11, 1.0
	v_cmp_lt_f32_e32 vcc, s40, v76
	v_mul_f32_e64 v11, v11, -v76
	v_mul_f32_e32 v9, v157, v5
	v_mul_f32_e32 v5, 0x3fb8aa3b, v10
	v_exp_f32_e32 v10, v5
	v_pk_add_f32 v[76:77], v[0:1], v[0:1]
	v_mul_f32_e32 v0, 0x3fb8aa3b, v0
	v_cmp_lt_f32_e64 s[0:1], s40, v77
	v_fma_f32 v5, -v10, v10, 1.0
	v_cndmask_b32_e32 v5, v5, v11, vcc
	v_max_f32_e32 v5, 0, v5
	v_sqrt_f32_e32 v5, v5
	v_cmp_lt_f32_e32 vcc, s40, v76
	v_mul_f32_e32 v11, v31, v5
	v_mul_f32_e32 v5, 0x3fb8aa3b, v1
	v_exp_f32_e32 v12, v5
	v_fmamk_f32 v1, v77, 0x3d2aaaab, v196
	v_fma_f32 v1, v77, v1, 0.5
	v_fma_f32 v1, v77, v1, 1.0
	v_fma_f32 v5, -v12, v12, 1.0
	v_mul_f32_e64 v1, v1, -v77
	v_cndmask_b32_e64 v1, v5, v1, s[0:1]
	v_max_f32_e32 v1, 0, v1
	v_sqrt_f32_e32 v1, v1
	v_cmp_lt_f32_e64 s[0:1], |v102|, s39
	v_mul_f32_e32 v5, v14, v1
	v_exp_f32_e32 v14, v0
	v_fmamk_f32 v1, v76, 0x3d2aaaab, v196
	v_fma_f32 v1, v76, v1, 0.5
	v_fma_f32 v1, v76, v1, 1.0
	v_fma_f32 v0, -v14, v14, 1.0
	v_mul_f32_e64 v1, v1, -v76
	v_cndmask_b32_e32 v0, v0, v1, vcc
	v_max_f32_e32 v0, 0, v0
	v_sqrt_f32_e32 v0, v0
	v_cmp_neq_f32_e32 vcc, s27, v128
	v_mul_f32_e32 v4, v4, v0
	v_add_f32_e32 v0, v2, v66
	v_mul_f32_e32 v0, 0xbfb8aa3b, v0
	v_exp_f32_e32 v0, v0
	v_add_f32_e32 v2, v6, v70
	v_mov_b32_e32 v66, v95
	v_add_f32_e32 v0, 1.0, v0
	v_rcp_f32_e32 v1, v0
	v_mul_f32_e32 v0, 0xbfb8aa3b, v2
	v_add_f32_e32 v2, v7, v71
	v_mul_f32_e32 v2, 0xbfb8aa3b, v2
	v_exp_f32_e32 v0, v0
	v_exp_f32_e32 v2, v2
	v_add_f32_e32 v0, 1.0, v0
	v_add_f32_e32 v2, 1.0, v2
	v_rcp_f32_e32 v6, v0
	v_add_f32_e32 v0, v3, v67
	v_rcp_f32_e32 v7, v2
	v_mov_b32_e32 v2, v94
	v_mov_b32_e32 v3, v90
	v_mov_b32_e32 v67, v91
	v_pk_add_f32 v[66:67], v[2:3], v[66:67]
	v_mul_f32_e32 v0, 0xbfb8aa3b, v0
	v_pk_add_f32 v[70:71], v[86:87], v[66:67]
	v_mov_b32_e32 v89, v67
	v_mov_b32_e32 v91, v71
	v_mov_b32_e32 v95, v70
	v_pk_add_f32 v[76:77], v[90:91], v[84:85] neg_lo:[0,1] neg_hi:[0,1]
	v_pk_add_f32 v[80:81], v[94:95], v[74:75] neg_lo:[0,1] neg_hi:[0,1]
	v_mov_b32_e32 v83, v76
	v_mov_b32_e32 v82, v80
	v_mov_b32_e32 v93, v66
	v_pk_add_f32 v[78:79], v[88:89], v[76:77] neg_lo:[0,1] neg_hi:[0,1]
	v_pk_add_f32 v[2:3], v[2:3], v[82:83] neg_lo:[0,1] neg_hi:[0,1]
	v_mov_b32_e32 v75, v84
	v_pk_add_f32 v[66:67], v[92:93], v[80:81] neg_lo:[0,1] neg_hi:[0,1]
	v_pk_add_f32 v[2:3], v[74:75], v[2:3] neg_lo:[0,1] neg_hi:[0,1]
	v_mov_b32_e32 v74, v66
	v_mov_b32_e32 v75, v78
	v_pk_add_f32 v[2:3], v[74:75], v[2:3]
	v_mov_b32_e32 v78, v67
	v_pk_add_f32 v[2:3], v[2:3], v[78:79]
	v_exp_f32_e32 v0, v0
	v_pk_add_f32 v[2:3], v[70:71], v[2:3]
	v_add_f32_e32 v0, 1.0, v0
	v_cndmask_b32_e32 v2, v209, v2, vcc
	v_cmp_neq_f32_e32 vcc, s27, v102
	v_rcp_f32_e32 v0, v0
	s_nop 0
	v_cndmask_b32_e32 v3, v209, v3, vcc
	v_cmp_lt_f32_e64 vcc, |v128|, s39
	v_cndmask_b32_e64 v3, v3, v102, s[0:1]
	s_nop 0
	v_cndmask_b32_e32 v2, v2, v128, vcc
	v_pk_mul_f32 v[60:61], v[60:61], v[2:3]
	s_nop 0
	v_mul_f32_e32 v13, 0x3fb8aa3b, v61
	v_exp_f32_e32 v74, v13
	v_pk_add_f32 v[66:67], v[60:61], v[60:61]
	v_fma_f32 v13, -v74, v74, 1.0
	v_fmamk_f32 v25, v67, 0x3d2aaaab, v196
	v_fma_f32 v25, v67, v25, 0.5
	v_fma_f32 v25, v67, v25, 1.0
	v_mul_f32_e64 v25, v25, -v67
	v_cmp_lt_f32_e64 s[0:1], s40, v67
	v_cmp_lt_f32_e32 vcc, s40, v66
	s_nop 0
	v_cndmask_b32_e64 v13, v13, v25, s[0:1]
	v_max_f32_e32 v13, 0, v13
	v_sqrt_f32_e32 v13, v13
	v_fmamk_f32 v25, v66, 0x3d2aaaab, v196
	v_fma_f32 v25, v66, v25, 0.5
	v_fma_f32 v25, v66, v25, 1.0
	v_mul_f32_e32 v13, v137, v13
	v_mul_f32_e32 v75, v13, v130
	v_mul_f32_e32 v13, 0x3fb8aa3b, v60
	v_exp_f32_e32 v76, v13
	v_mul_f32_e64 v25, v25, -v66
	v_fma_f32 v13, -v76, v76, 1.0
	v_cndmask_b32_e32 v13, v13, v25, vcc
	v_max_f32_e32 v13, 0, v13
	v_sqrt_f32_e32 v13, v13
	s_nop 0
	v_mul_f32_e32 v13, v136, v13
	v_mul_f32_e32 v77, v13, v96
	global_store_dwordx4 v[58:59], v[74:77], off offset:16
	v_add_co_u32_e32 v58, vcc, s66, v72
	v_pk_mul_f32 v[48:49], v[48:49], s[44:45] op_sel_hi:[1,0]
	s_nop 0
	v_addc_co_u32_e32 v59, vcc, 0, v73, vcc
	global_load_dwordx2 v[66:67], v[58:59], off offset:32
	v_pk_mul_f32 v[48:49], v[48:49], v[2:3]
	s_nop 0
	v_mul_f32_e32 v13, 0x3fb8aa3b, v49
	v_exp_f32_e32 v58, v13
	v_pk_add_f32 v[70:71], v[48:49], v[48:49]
	v_mul_f32_e32 v27, 0x3fb8aa3b, v48
	v_fmamk_f32 v25, v71, 0x3d2aaaab, v196
	v_exp_f32_e32 v60, v27
	v_fma_f32 v25, v71, v25, 0.5
	v_fmamk_f32 v27, v70, 0x3d2aaaab, v196
	v_fma_f32 v25, v71, v25, 1.0
	v_fma_f32 v27, v70, v27, 0.5
	v_fma_f32 v13, -v58, v58, 1.0
	v_mul_f32_e64 v25, v25, -v71
	v_cmp_lt_f32_e32 vcc, s40, v71
	v_fma_f32 v27, v70, v27, 1.0
	v_mul_f32_e64 v27, v27, -v70
	v_cndmask_b32_e32 v13, v13, v25, vcc
	v_fma_f32 v25, -v60, v60, 1.0
	v_cmp_lt_f32_e32 vcc, s40, v70
	v_max_f32_e32 v13, 0, v13
	v_sqrt_f32_e32 v13, v13
	v_cndmask_b32_e32 v25, v25, v27, vcc
	v_max_f32_e32 v25, 0, v25
	v_sqrt_f32_e32 v25, v25
	v_mul_f32_e32 v13, v133, v13
	v_mul_f32_e32 v59, v13, v132
	v_mul_f32_e32 v13, v138, v25
	v_mul_f32_e32 v61, v13, v131
	global_store_dwordx4 v[50:51], v[32:35], off
	global_store_dwordx4 v[50:51], v[58:61], off offset:16
	s_nop 0
	v_add_co_u32_e32 v32, vcc, s67, v72
	s_waitcnt vmcnt(2)
	v_lshlrev_b32_e32 v13, 16, v66
	v_addc_co_u32_e32 v33, vcc, 0, v73, vcc
	global_load_dwordx2 v[48:49], v[32:33], off offset:32
	v_pk_mul_f32 v[32:33], v[106:107], s[44:45] op_sel_hi:[1,0]
	v_mul_f32_e32 v29, v68, v13
	v_pk_mul_f32 v[34:35], v[32:33], v[2:3]
	v_and_b32_e32 v25, 0xffff0000, v66
	v_mul_f32_e32 v13, 0x3fb8aa3b, v35
	v_exp_f32_e32 v32, v13
	v_pk_add_f32 v[50:51], v[34:35], v[34:35]
	v_mul_f32_e32 v31, v69, v25
	v_fmamk_f32 v25, v51, 0x3d2aaaab, v196
	v_fma_f32 v25, v51, v25, 0.5
	v_fma_f32 v25, v51, v25, 1.0
	v_fma_f32 v13, -v32, v32, 1.0
	v_mul_f32_e64 v25, v25, -v51
	v_cmp_lt_f32_e64 s[0:1], s40, v51
	v_lshlrev_b32_e32 v27, 16, v67
	v_cmp_lt_f32_e32 vcc, s40, v50
	v_cndmask_b32_e64 v13, v13, v25, s[0:1]
	v_max_f32_e32 v13, 0, v13
	v_sqrt_f32_e32 v13, v13
	v_fmamk_f32 v25, v50, 0x3d2aaaab, v196
	v_fma_f32 v25, v50, v25, 0.5
	v_fma_f32 v25, v50, v25, 1.0
	v_mul_f32_e32 v13, v139, v13
	v_mul_f32_e32 v33, v13, v27
	v_mul_f32_e32 v13, 0x3fb8aa3b, v34
	v_exp_f32_e32 v34, v13
	v_mul_f32_e64 v25, v25, -v50
	v_and_b32_e32 v58, 0xffff0000, v67
	v_fma_f32 v13, -v34, v34, 1.0
	v_cndmask_b32_e32 v13, v13, v25, vcc
	v_max_f32_e32 v13, 0, v13
	v_sqrt_f32_e32 v13, v13
	s_nop 0
	v_mul_f32_e32 v13, v124, v13
	v_mul_f32_e32 v35, v13, v58
	global_store_dwordx4 v[40:41], v[28:31], off
	global_store_dwordx4 v[40:41], v[32:35], off offset:16
	s_nop 0
	v_add_co_u32_e32 v28, vcc, s22, v72
	s_waitcnt vmcnt(2)
	v_lshlrev_b32_e32 v13, 16, v48
	v_addc_co_u32_e32 v29, vcc, 0, v73, vcc
	global_load_dwordx2 v[32:33], v[28:29], off offset:32
	v_pk_mul_f32 v[28:29], v[62:63], s[44:45] op_sel_hi:[1,0]
	v_mul_f32_e32 v25, v64, v13
	v_pk_mul_f32 v[30:31], v[28:29], v[2:3]
	v_lshlrev_b32_e32 v40, 16, v49
	v_mul_f32_e32 v13, 0x3fb8aa3b, v31
	v_exp_f32_e32 v28, v13
	v_pk_add_f32 v[34:35], v[30:31], v[30:31]
	v_and_b32_e32 v27, 0xffff0000, v48
	v_fmamk_f32 v29, v35, 0x3d2aaaab, v196
	v_fma_f32 v29, v35, v29, 0.5
	v_fma_f32 v29, v35, v29, 1.0
	v_fma_f32 v13, -v28, v28, 1.0
	v_mul_f32_e64 v29, v29, -v35
	v_cmp_lt_f32_e64 s[0:1], s40, v35
	v_fmamk_f32 v31, v34, 0x3d2aaaab, v196
	v_fma_f32 v31, v34, v31, 0.5
	v_cndmask_b32_e64 v13, v13, v29, s[0:1]
	v_max_f32_e32 v13, 0, v13
	v_sqrt_f32_e32 v13, v13
	v_fma_f32 v31, v34, v31, 1.0
	v_cmp_lt_f32_e32 vcc, s40, v34
	v_mul_f32_e64 v31, v31, -v34
	v_mul_f32_e32 v13, v140, v13
	v_mul_f32_e32 v29, v13, v40
	v_mul_f32_e32 v13, 0x3fb8aa3b, v30
	v_exp_f32_e32 v30, v13
	v_and_b32_e32 v41, 0xffff0000, v49
	v_mul_f32_e32 v27, v65, v27
	v_fma_f32 v13, -v30, v30, 1.0
	v_cndmask_b32_e32 v13, v13, v31, vcc
	v_max_f32_e32 v13, 0, v13
	v_sqrt_f32_e32 v13, v13
	s_nop 0
	v_mul_f32_e32 v13, v125, v13
	v_mul_f32_e32 v31, v13, v41
	global_store_dwordx4 v[38:39], v[24:27], off
	global_store_dwordx4 v[38:39], v[28:31], off offset:16
	s_nop 0
	v_add_co_u32_e32 v24, vcc, s41, v72
	s_waitcnt vmcnt(2)
	v_lshlrev_b32_e32 v13, 16, v32
	v_addc_co_u32_e32 v25, vcc, 0, v73, vcc
	global_load_dwordx2 v[28:29], v[24:25], off offset:32
	v_and_b32_e32 v24, 0xffff0000, v32
	v_mul_f32_e32 v23, v23, v24
	v_pk_mul_f32 v[24:25], v[54:55], s[44:45] op_sel_hi:[1,0]
	v_mul_f32_e32 v21, v21, v13
	v_pk_mul_f32 v[26:27], v[24:25], v[2:3]
	v_lshlrev_b32_e32 v32, 16, v33
	v_mul_f32_e32 v13, 0x3fb8aa3b, v27
	v_exp_f32_e32 v24, v13
	v_pk_add_f32 v[30:31], v[26:27], v[26:27]
	v_and_b32_e32 v33, 0xffff0000, v33
	v_fmamk_f32 v25, v31, 0x3d2aaaab, v196
	v_fma_f32 v25, v31, v25, 0.5
	v_fma_f32 v25, v31, v25, 1.0
	v_fma_f32 v13, -v24, v24, 1.0
	v_mul_f32_e64 v25, v25, -v31
	v_cmp_lt_f32_e64 s[0:1], s40, v31
	v_fmamk_f32 v27, v30, 0x3d2aaaab, v196
	v_fma_f32 v27, v30, v27, 0.5
	v_cndmask_b32_e64 v13, v13, v25, s[0:1]
	v_max_f32_e32 v13, 0, v13
	v_sqrt_f32_e32 v13, v13
	v_fma_f32 v27, v30, v27, 1.0
	v_cmp_lt_f32_e32 vcc, s40, v30
	v_mul_f32_e64 v27, v27, -v30
	v_mul_f32_e32 v13, v141, v13
	v_mul_f32_e32 v25, v13, v32
	v_mul_f32_e32 v13, 0x3fb8aa3b, v26
	v_exp_f32_e32 v26, v13
	s_nop 0
	v_fma_f32 v13, -v26, v26, 1.0
	v_cndmask_b32_e32 v13, v13, v27, vcc
	v_max_f32_e32 v13, 0, v13
	v_sqrt_f32_e32 v13, v13
	s_nop 0
	v_mul_f32_e32 v13, v126, v13
	v_mul_f32_e32 v27, v13, v33
	global_store_dwordx4 v[42:43], v[20:23], off
	global_store_dwordx4 v[42:43], v[24:27], off offset:16
	s_nop 0
	v_add_co_u32_e32 v20, vcc, s23, v72
	s_waitcnt vmcnt(2)
	v_lshlrev_b32_e32 v13, 16, v28
	v_addc_co_u32_e32 v21, vcc, 0, v73, vcc
	global_load_dwordx2 v[24:25], v[20:21], off offset:32
	v_and_b32_e32 v20, 0xffff0000, v28
	v_mul_f32_e32 v19, v19, v20
	v_pk_mul_f32 v[20:21], v[52:53], s[44:45] op_sel_hi:[1,0]
	v_mul_f32_e32 v17, v17, v13
	v_pk_mul_f32 v[22:23], v[20:21], v[2:3]
	v_lshlrev_b32_e32 v28, 16, v29
	v_mul_f32_e32 v13, 0x3fb8aa3b, v23
	v_exp_f32_e32 v20, v13
	v_pk_add_f32 v[26:27], v[22:23], v[22:23]
	v_and_b32_e32 v29, 0xffff0000, v29
	v_fmamk_f32 v21, v27, 0x3d2aaaab, v196
	v_fma_f32 v21, v27, v21, 0.5
	v_fma_f32 v21, v27, v21, 1.0
	v_fma_f32 v13, -v20, v20, 1.0
	v_mul_f32_e64 v21, v21, -v27
	v_cmp_lt_f32_e64 s[0:1], s40, v27
	v_fmamk_f32 v23, v26, 0x3d2aaaab, v196
	v_fma_f32 v23, v26, v23, 0.5
	v_cndmask_b32_e64 v13, v13, v21, s[0:1]
	v_max_f32_e32 v13, 0, v13
	v_sqrt_f32_e32 v13, v13
	v_fma_f32 v23, v26, v23, 1.0
	v_cmp_lt_f32_e32 vcc, s40, v26
	v_mul_f32_e64 v23, v23, -v26
	v_mul_f32_e32 v13, v142, v13
	v_mul_f32_e32 v21, v13, v28
	v_mul_f32_e32 v13, 0x3fb8aa3b, v22
	v_exp_f32_e32 v22, v13
	s_nop 0
	v_fma_f32 v13, -v22, v22, 1.0
	v_cndmask_b32_e32 v13, v13, v23, vcc
	v_max_f32_e32 v13, 0, v13
	v_sqrt_f32_e32 v13, v13
	s_nop 0
	v_mul_f32_e32 v13, v127, v13
	v_mul_f32_e32 v23, v13, v29
	global_store_dwordx4 v[44:45], v[16:19], off
	global_store_dwordx4 v[44:45], v[20:23], off offset:16
	s_nop 0
	v_add_co_u32_e32 v16, vcc, s42, v72
	s_waitcnt vmcnt(2)
	v_lshlrev_b32_e32 v13, 16, v24
	v_addc_co_u32_e32 v17, vcc, 0, v73, vcc
	global_load_dwordx2 v[20:21], v[16:17], off offset:32
	v_and_b32_e32 v16, 0xffff0000, v24
	v_mul_f32_e32 v11, v11, v16
	v_pk_mul_f32 v[16:17], v[46:47], s[44:45] op_sel_hi:[1,0]
	v_mul_f32_e32 v9, v9, v13
	v_pk_mul_f32 v[18:19], v[16:17], v[2:3]
	v_lshlrev_b32_e32 v24, 16, v25
	v_mul_f32_e32 v13, 0x3fb8aa3b, v19
	v_exp_f32_e32 v16, v13
	v_pk_add_f32 v[22:23], v[18:19], v[18:19]
	v_and_b32_e32 v25, 0xffff0000, v25
	v_fmamk_f32 v17, v23, 0x3d2aaaab, v196
	v_fma_f32 v17, v23, v17, 0.5
	v_fma_f32 v17, v23, v17, 1.0
	v_fma_f32 v13, -v16, v16, 1.0
	v_mul_f32_e64 v17, v17, -v23
	v_cmp_lt_f32_e64 s[0:1], s40, v23
	v_fmamk_f32 v19, v22, 0x3d2aaaab, v196
	v_fma_f32 v19, v22, v19, 0.5
	v_cndmask_b32_e64 v13, v13, v17, s[0:1]
	v_max_f32_e32 v13, 0, v13
	v_sqrt_f32_e32 v13, v13
	v_fma_f32 v19, v22, v19, 1.0
	v_cmp_lt_f32_e32 vcc, s40, v22
	v_mul_f32_e64 v19, v19, -v22
	v_mul_f32_e32 v13, v134, v13
	v_mul_f32_e32 v17, v13, v24
	v_mul_f32_e32 v13, 0x3fb8aa3b, v18
	v_exp_f32_e32 v18, v13
	s_nop 0
	v_fma_f32 v13, -v18, v18, 1.0
	v_cndmask_b32_e32 v13, v13, v19, vcc
	v_max_f32_e32 v13, 0, v13
	v_sqrt_f32_e32 v13, v13
	s_nop 0
	v_mul_f32_e32 v13, v15, v13
	v_mul_f32_e32 v19, v13, v25
	global_store_dwordx4 v[36:37], v[8:11], off
	global_store_dwordx4 v[36:37], v[16:19], off offset:16
	v_pk_mul_f32 v[0:1], v[0:1], s[44:45] op_sel_hi:[1,0]
	s_waitcnt vmcnt(2)
	v_lshlrev_b32_e32 v8, 16, v20
	v_pk_mul_f32 v[2:3], v[0:1], v[2:3]
	v_mul_f32_e32 v13, v5, v8
	v_pk_add_f32 v[8:9], v[2:3], v[2:3]
	v_mul_f32_e32 v0, 0x3fb8aa3b, v3
	v_fmamk_f32 v3, v9, 0x3d2aaaab, v196
	v_exp_f32_e32 v0, v0
	v_fma_f32 v3, v9, v3, 0.5
	v_mul_f32_e32 v2, 0x3fb8aa3b, v2
	v_fma_f32 v3, v9, v3, 1.0
	v_exp_f32_e32 v2, v2
	v_mul_f32_e64 v3, v3, -v9
	v_cmp_lt_f32_e32 vcc, s40, v9
	v_fmamk_f32 v9, v8, 0x3d2aaaab, v196
	v_fma_f32 v9, v8, v9, 0.5
	v_fma_f32 v5, -v0, v0, 1.0
	v_fma_f32 v9, v8, v9, 1.0
	v_cndmask_b32_e32 v3, v5, v3, vcc
	v_fma_f32 v5, -v2, v2, 1.0
	v_mul_f32_e64 v9, v9, -v8
	v_cmp_lt_f32_e32 vcc, s40, v8
	v_max_f32_e32 v3, 0, v3
	v_sqrt_f32_e32 v3, v3
	v_cndmask_b32_e32 v5, v5, v9, vcc
	v_max_f32_e32 v5, 0, v5
	v_sqrt_f32_e32 v5, v5
	v_and_b32_e32 v10, 0xffff0000, v20
	v_lshlrev_b32_e32 v1, 16, v21
	v_mul_f32_e32 v3, v6, v3
	v_or3_b32 v56, v56, v122, v146
	v_and_b32_e32 v11, 0xffff0000, v21
	v_mul_f32_e32 v15, v4, v10
	v_mul_f32_e32 v1, v3, v1
	v_mul_f32_e32 v3, v7, v5
	v_lshl_add_u64 v[4:5], v[56:57], 3, s[14:15]
	v_mul_f32_e32 v3, v3, v11
	global_store_dwordx4 v[4:5], v[12:15], off
	global_store_dwordx4 v[4:5], v[0:3], off offset:16
	s_mov_b64 s[22:23], s[20:21]
	v_readlane_b32 s68, v253, 18
	v_readlane_b32 s75, v253, 20
	s_barrier
	s_cmpk_gt_i32 s36, 0x1ff
	s_cbranch_scc0 .LBB0_741
	s_branch .LBB0_761

.LBB0_788:
	s_ashr_i32 s29, s28, 31
	s_lshl_b64 s[28:29], s[28:29], 20
	s_add_u32 s28, s35, s28
	s_addc_u32 s29, s36, s29
	s_ashr_i32 s27, s26, 31
	v_lshlrev_b32_e32 v3, 6, v1
	s_lshl_b64 s[26:27], s[26:27], 20
	v_and_b32_e32 v2, 48, v1
	v_and_b32_e32 v4, 0x3c0, v3
	v_lshlrev_b32_e32 v1, 2, v1
	s_add_u32 s30, s10, s26
	v_or_b32_e32 v5, v4, v2
	v_and_b32_e32 v1, 32, v1
	v_lshlrev_b32_e32 v0, 13, v0
	s_mov_b32 s26, 0x18000
	v_and_b32_e32 v135, 0x6000, v0
	v_bitop3_b32 v0, v5, s26, v1 bitop3:0xde
	s_mov_b32 s26, 0x10400
	s_addc_u32 s31, s11, s27
	v_bitop3_b32 v149, v5, s26, v1 bitop3:0xde
	s_add_i32 s26, s55, s58
	s_ashr_i32 s27, s26, 31
	s_waitcnt vmcnt(0)
	s_add_i32 s47, s1, 0x10000
	s_add_i32 s48, s1, 0x18000
	s_add_i32 s49, s1, 0x12000
	s_add_i32 s50, s1, 0x1a000
	s_add_i32 s51, s1, 0x14000
	s_add_i32 s52, s1, 0x1c000
	s_add_i32 s53, s1, 0x16000
	s_add_i32 s54, s1, 0x1e000
	s_lshl_b64 s[26:27], s[26:27], 20
	v_bitop3_b32 v134, v4, v1, v2 bitop3:0x36
	v_and_b32_e32 v136, 0xffffc000, v3
	s_add_u32 s55, s6, s26
	v_mov_b32_e32 v4, 0
	v_or_b32_e32 v137, 0x800, v136
	v_or_b32_e32 v138, 0x1000, v136
	v_or_b32_e32 v139, 0x1800, v136
	v_or_b32_e32 v140, 0x2000, v136
	v_or_b32_e32 v141, 0x2800, v136
	v_or_b32_e32 v142, 0x3000, v136
	v_or_b32_e32 v143, 0x3800, v136
	v_bitop3_b32 v145, v5, s33, v1 bitop3:0xde
	s_addc_u32 s58, s7, s27
	s_mov_b64 s[26:27], 0
	s_mov_b32 s62, 1
	v_add_u32_e32 v150, v0, v135
	v_mov_b32_e32 v5, v4
	v_mov_b32_e32 v6, v4
	v_mov_b32_e32 v7, v4
	v_mov_b32_e32 v12, v4
	v_mov_b32_e32 v13, v4
	v_mov_b32_e32 v14, v4
	v_mov_b32_e32 v15, v4
	v_mov_b32_e32 v16, v4
	v_mov_b32_e32 v17, v4
	v_mov_b32_e32 v18, v4
	v_mov_b32_e32 v19, v4
	v_mov_b32_e32 v20, v4
	v_mov_b32_e32 v21, v4
	v_mov_b32_e32 v22, v4
	v_mov_b32_e32 v23, v4
	v_mov_b32_e32 v24, v4
	v_mov_b32_e32 v25, v4
	v_mov_b32_e32 v26, v4
	v_mov_b32_e32 v27, v4
	v_mov_b32_e32 v28, v4
	v_mov_b32_e32 v29, v4
	v_mov_b32_e32 v30, v4
	v_mov_b32_e32 v31, v4
	v_mov_b32_e32 v32, v4
	v_mov_b32_e32 v33, v4
	v_mov_b32_e32 v34, v4
	v_mov_b32_e32 v35, v4
	v_mov_b32_e32 v36, v4
	v_mov_b32_e32 v37, v4
	v_mov_b32_e32 v38, v4
	v_mov_b32_e32 v39, v4
	v_mov_b32_e32 v40, v4
	v_mov_b32_e32 v41, v4
	v_mov_b32_e32 v42, v4
	v_mov_b32_e32 v43, v4
	v_mov_b32_e32 v44, v4
	v_mov_b32_e32 v45, v4
	v_mov_b32_e32 v46, v4
	v_mov_b32_e32 v47, v4
	v_mov_b32_e32 v48, v4
	v_mov_b32_e32 v49, v4
	v_mov_b32_e32 v50, v4
	v_mov_b32_e32 v51, v4
	v_mov_b32_e32 v52, v4
	v_mov_b32_e32 v53, v4
	v_mov_b32_e32 v54, v4
	v_mov_b32_e32 v55, v4
	v_mov_b32_e32 v56, v4
	v_mov_b32_e32 v57, v4
	v_mov_b32_e32 v58, v4
	v_mov_b32_e32 v59, v4
	v_mov_b32_e32 v60, v4
	v_mov_b32_e32 v61, v4
	v_mov_b32_e32 v62, v4
	v_mov_b32_e32 v63, v4
	v_mov_b32_e32 v64, v4
	v_mov_b32_e32 v65, v4
	v_mov_b32_e32 v66, v4
	v_mov_b32_e32 v67, v4
	v_mov_b32_e32 v68, v4
	v_mov_b32_e32 v69, v4
	v_mov_b32_e32 v70, v4
	v_mov_b32_e32 v71, v4
	v_mov_b32_e32 v72, v4
	v_mov_b32_e32 v73, v4
	v_mov_b32_e32 v74, v4
	v_mov_b32_e32 v75, v4
	v_mov_b32_e32 v76, v4
	v_mov_b32_e32 v77, v4
	v_mov_b32_e32 v78, v4
	v_mov_b32_e32 v79, v4
	v_mov_b32_e32 v80, v4
	v_mov_b32_e32 v81, v4
	v_mov_b32_e32 v82, v4
	v_mov_b32_e32 v83, v4
	v_mov_b32_e32 v84, v4
	v_mov_b32_e32 v85, v4
	v_mov_b32_e32 v86, v4
	v_mov_b32_e32 v87, v4
	v_mov_b32_e32 v88, v4
	v_mov_b32_e32 v89, v4
	v_mov_b32_e32 v90, v4
	v_mov_b32_e32 v91, v4
	v_mov_b32_e32 v92, v4
	v_mov_b32_e32 v93, v4
	v_mov_b32_e32 v94, v4
	v_mov_b32_e32 v95, v4
	v_mov_b32_e32 v96, v4
	v_mov_b32_e32 v97, v4
	v_mov_b32_e32 v98, v4
	v_mov_b32_e32 v99, v4
	v_mov_b32_e32 v100, v4
	v_mov_b32_e32 v101, v4
	v_mov_b32_e32 v102, v4
	v_mov_b32_e32 v103, v4
	v_mov_b32_e32 v104, v4
	v_mov_b32_e32 v105, v4
	v_mov_b32_e32 v106, v4
	v_mov_b32_e32 v107, v4
	v_mov_b32_e32 v108, v4
	v_mov_b32_e32 v109, v4
	v_mov_b32_e32 v110, v4
	v_mov_b32_e32 v111, v4
	v_mov_b32_e32 v112, v4
	v_mov_b32_e32 v113, v4
	v_mov_b32_e32 v114, v4
	v_mov_b32_e32 v115, v4
	v_mov_b32_e32 v116, v4
	v_mov_b32_e32 v117, v4
	v_mov_b32_e32 v118, v4
	v_mov_b32_e32 v119, v4
	v_mov_b32_e32 v120, v4
	v_mov_b32_e32 v121, v4
	v_mov_b32_e32 v122, v4
	v_mov_b32_e32 v123, v4
	v_mov_b32_e32 v124, v4
	v_mov_b32_e32 v125, v4
	v_mov_b32_e32 v126, v4
	v_mov_b32_e32 v127, v4
	v_mov_b32_e32 v8, v4
	v_mov_b32_e32 v9, v4
	v_mov_b32_e32 v10, v4
	v_mov_b32_e32 v11, v4
	v_mov_b32_e32 v0, v4
	v_mov_b32_e32 v1, v4
	v_mov_b32_e32 v2, v4
	v_mov_b32_e32 v3, v4
	s_waitcnt lgkmcnt(0)
	s_barrier
	s_add_u32 s63, s55, s26
	s_addc_u32 s70, s58, s27
	s_add_u32 s64, s63, 0x1b900080
	s_addc_u32 s65, s70, 0
	s_add_u32 s71, s2, s26
	s_addc_u32 s72, s3, s27
	s_add_u32 s68, s71, 0x80
	s_addc_u32 s69, s72, 0
	v_add_u32_e32 v151, v134, v135
	v_add_u32_e32 v189, v134, v136
	ds_read_b128 v[152:155], v151 offset:32768
	ds_read_b128 v[156:159], v189
	s_mov_b32 m0, s48
	s_nop 0
	global_load_lds_dwordx4 v128, s[68:69]
	ds_read_b128 v[160:163], v151 offset:34816
	s_mov_b32 m0, s50
	s_nop 0
	global_load_lds_dwordx4 v130, s[68:69]
	ds_read_b128 v[164:167], v189 offset:2048
	ds_read_b128 v[168:171], v151 offset:36864
	s_mov_b32 m0, s52
	s_nop 0
	global_load_lds_dwordx4 v132, s[68:69]
	ds_read_b128 v[172:175], v151 offset:38912
	ds_read_b128 v[176:179], v189 offset:4096
	ds_read_b128 v[180:183], v189 offset:6144
	s_branch .Lmy_rot_789
.LBB0_789:
	s_add_u32 s63, s55, s26
	s_addc_u32 s70, s58, s27
	s_add_u32 s64, s63, 0x1b900080
	s_addc_u32 s65, s70, 0
	s_add_u32 s71, s2, s26
	s_addc_u32 s72, s3, s27
	s_add_u32 s68, s71, 0x80
	s_addc_u32 s69, s72, 0
	v_add_u32_e32 v151, v134, v135
	v_add_u32_e32 v189, v134, v136
	ds_read_b128 v[152:155], v151 offset:32768
	ds_read_b128 v[156:159], v189
	s_mov_b32 m0, s48
	v_mfma_f32_16x16x32_bf16 v[28:31], v[160:163], v[176:179], v[28:31]
	global_load_lds_dwordx4 v128, s[68:69]
	v_mfma_f32_16x16x32_bf16 v[12:15], v[160:163], v[180:183], v[12:15]
	ds_read_b128 v[160:163], v151 offset:34816
	v_mfma_f32_16x16x32_bf16 v[24:27], v[164:167], v[176:179], v[24:27]
	s_mov_b32 m0, s50
	v_mfma_f32_16x16x32_bf16 v[4:7], v[164:167], v[180:183], v[4:7]
	global_load_lds_dwordx4 v130, s[68:69]
	ds_read_b128 v[164:167], v189 offset:2048
	v_mfma_f32_16x16x32_bf16 v[20:23], v[168:171], v[176:179], v[20:23]
	v_mfma_f32_16x16x32_bf16 v[8:11], v[168:171], v[180:183], v[8:11]
	ds_read_b128 v[168:171], v151 offset:36864
	s_mov_b32 m0, s52
	v_mfma_f32_16x16x32_bf16 v[16:19], v[172:175], v[176:179], v[16:19]
	global_load_lds_dwordx4 v132, s[68:69]
	v_mfma_f32_16x16x32_bf16 v[0:3], v[172:175], v[180:183], v[0:3]
	ds_read_b128 v[172:175], v151 offset:38912
	ds_read_b128 v[176:179], v189 offset:4096
	ds_read_b128 v[180:183], v189 offset:6144
.Lmy_rot_789:
	s_waitcnt lgkmcnt(6)
	v_mfma_f32_16x16x32_bf16 v[124:127], v[152:155], v[156:159], v[124:127]
	s_waitcnt lgkmcnt(5)
	s_mov_b32 m0, s54
	v_mfma_f32_16x16x32_bf16 v[120:123], v[160:163], v[156:159], v[120:123]
	global_load_lds_dwordx4 v146, s[68:69]
	s_waitcnt lgkmcnt(4)
	v_mfma_f32_16x16x32_bf16 v[108:111], v[152:155], v[164:167], v[108:111]
	v_mfma_f32_16x16x32_bf16 v[104:107], v[160:163], v[164:167], v[104:107]
	s_waitcnt lgkmcnt(3)
	s_mov_b32 m0, s47
	v_mfma_f32_16x16x32_bf16 v[116:119], v[168:171], v[156:159], v[116:119]
	global_load_lds_dwordx4 v128, s[64:65]
	v_mfma_f32_16x16x32_bf16 v[100:103], v[168:171], v[164:167], v[100:103]
	s_waitcnt lgkmcnt(2)
	v_mfma_f32_16x16x32_bf16 v[112:115], v[172:175], v[156:159], v[112:115]
	ds_read_b128 v[156:159], v189 offset:8192
	s_mov_b32 m0, s49
	v_mfma_f32_16x16x32_bf16 v[96:99], v[172:175], v[164:167], v[96:99]
	global_load_lds_dwordx4 v130, s[64:65]
	ds_read_b128 v[164:167], v189 offset:10240
	s_waitcnt lgkmcnt(3)
	v_mfma_f32_16x16x32_bf16 v[92:95], v[152:155], v[176:179], v[92:95]
	v_mfma_f32_16x16x32_bf16 v[88:91], v[160:163], v[176:179], v[88:91]
	s_mov_b32 m0, s51
	v_mfma_f32_16x16x32_bf16 v[84:87], v[168:171], v[176:179], v[84:87]
	global_load_lds_dwordx4 v132, s[64:65]
	v_mfma_f32_16x16x32_bf16 v[80:83], v[172:175], v[176:179], v[80:83]
	ds_read_b128 v[176:179], v189 offset:12288
	s_waitcnt lgkmcnt(3)
	v_mfma_f32_16x16x32_bf16 v[76:79], v[152:155], v[180:183], v[76:79]
	s_mov_b32 m0, s53
	v_mfma_f32_16x16x32_bf16 v[72:75], v[160:163], v[180:183], v[72:75]
	global_load_lds_dwordx4 v146, s[64:65]
	v_mfma_f32_16x16x32_bf16 v[68:71], v[168:171], v[180:183], v[68:71]
	v_mfma_f32_16x16x32_bf16 v[64:67], v[172:175], v[180:183], v[64:67]
	ds_read_b128 v[180:183], v189 offset:14336
	s_waitcnt lgkmcnt(3)
	v_mfma_f32_16x16x32_bf16 v[56:59], v[160:163], v[156:159], v[56:59]
	s_waitcnt lgkmcnt(2)
	v_mfma_f32_16x16x32_bf16 v[40:43], v[160:163], v[164:167], v[40:43]
	s_waitcnt lgkmcnt(1)
	v_mfma_f32_16x16x32_bf16 v[24:27], v[160:163], v[176:179], v[24:27]
	s_waitcnt lgkmcnt(0)
	v_mfma_f32_16x16x32_bf16 v[4:7], v[160:163], v[180:183], v[4:7]
	ds_read_b128 v[160:163], v151 offset:33792
	v_mfma_f32_16x16x32_bf16 v[60:63], v[152:155], v[156:159], v[60:63]
	v_mfma_f32_16x16x32_bf16 v[44:47], v[152:155], v[164:167], v[44:47]
	v_mfma_f32_16x16x32_bf16 v[28:31], v[152:155], v[176:179], v[28:31]
	v_mfma_f32_16x16x32_bf16 v[12:15], v[152:155], v[180:183], v[12:15]
	ds_read_b128 v[152:155], v189 offset:1024
	v_mfma_f32_16x16x32_bf16 v[36:39], v[168:171], v[164:167], v[36:39]
	v_mfma_f32_16x16x32_bf16 v[32:35], v[172:175], v[164:167], v[32:35]
	ds_read_b128 v[164:167], v151 offset:35840
	v_mfma_f32_16x16x32_bf16 v[52:55], v[168:171], v[156:159], v[52:55]
	v_mfma_f32_16x16x32_bf16 v[48:51], v[172:175], v[156:159], v[48:51]
	ds_read_b128 v[156:159], v189 offset:3072
	v_mfma_f32_16x16x32_bf16 v[20:23], v[168:171], v[176:179], v[20:23]
	v_mfma_f32_16x16x32_bf16 v[16:19], v[172:175], v[176:179], v[16:19]
	ds_read_b128 v[176:179], v189 offset:5120
	v_mfma_f32_16x16x32_bf16 v[8:11], v[168:171], v[180:183], v[8:11]
	ds_read_b128 v[168:171], v151 offset:37888
	v_mfma_f32_16x16x32_bf16 v[0:3], v[172:175], v[180:183], v[0:3]
	ds_read_b128 v[172:175], v151 offset:39936
	ds_read_b128 v[180:183], v189 offset:7168
	s_waitcnt lgkmcnt(6)
	v_mfma_f32_16x16x32_bf16 v[124:127], v[160:163], v[152:155], v[124:127]
	s_waitcnt lgkmcnt(5)
	v_mfma_f32_16x16x32_bf16 v[120:123], v[164:167], v[152:155], v[120:123]
	s_waitcnt lgkmcnt(4)
	v_mfma_f32_16x16x32_bf16 v[108:111], v[160:163], v[156:159], v[108:111]
	v_mfma_f32_16x16x32_bf16 v[104:107], v[164:167], v[156:159], v[104:107]
	s_waitcnt lgkmcnt(3)
	v_mfma_f32_16x16x32_bf16 v[92:95], v[160:163], v[176:179], v[92:95]
	v_mfma_f32_16x16x32_bf16 v[88:91], v[164:167], v[176:179], v[88:91]
	s_waitcnt lgkmcnt(2)
	v_mfma_f32_16x16x32_bf16 v[116:119], v[168:171], v[152:155], v[116:119]
	s_waitcnt lgkmcnt(1)
	v_mfma_f32_16x16x32_bf16 v[112:115], v[172:175], v[152:155], v[112:115]
	ds_read_b128 v[152:155], v189 offset:9216
	v_mfma_f32_16x16x32_bf16 v[100:103], v[168:171], v[156:159], v[100:103]
	v_mfma_f32_16x16x32_bf16 v[96:99], v[172:175], v[156:159], v[96:99]
	ds_read_b128 v[156:159], v189 offset:11264
	v_mfma_f32_16x16x32_bf16 v[84:87], v[168:171], v[176:179], v[84:87]
	v_mfma_f32_16x16x32_bf16 v[80:83], v[172:175], v[176:179], v[80:83]
	ds_read_b128 v[176:179], v189 offset:13312
	s_waitcnt lgkmcnt(3)
	v_mfma_f32_16x16x32_bf16 v[76:79], v[160:163], v[180:183], v[76:79]
	v_mfma_f32_16x16x32_bf16 v[72:75], v[164:167], v[180:183], v[72:75]
	v_mfma_f32_16x16x32_bf16 v[68:71], v[168:171], v[180:183], v[68:71]
	v_mfma_f32_16x16x32_bf16 v[64:67], v[172:175], v[180:183], v[64:67]
	ds_read_b128 v[180:183], v189 offset:15360
	s_waitcnt lgkmcnt(3)
	v_mfma_f32_16x16x32_bf16 v[60:63], v[160:163], v[152:155], v[60:63]
	v_mfma_f32_16x16x32_bf16 v[56:59], v[164:167], v[152:155], v[56:59]
	v_mfma_f32_16x16x32_bf16 v[52:55], v[168:171], v[152:155], v[52:55]
	v_mfma_f32_16x16x32_bf16 v[48:51], v[172:175], v[152:155], v[48:51]
	s_waitcnt lgkmcnt(2)
	v_mfma_f32_16x16x32_bf16 v[44:47], v[160:163], v[156:159], v[44:47]
	v_mfma_f32_16x16x32_bf16 v[40:43], v[164:167], v[156:159], v[40:43]
	v_mfma_f32_16x16x32_bf16 v[36:39], v[168:171], v[156:159], v[36:39]
	v_mfma_f32_16x16x32_bf16 v[32:35], v[172:175], v[156:159], v[32:35]
	s_add_u32 s63, s63, 0x1b900100
	s_addc_u32 s64, s70, 0
	s_add_u32 s68, s71, 0x100
	s_addc_u32 s69, s72, 0
	s_cmp_lt_u32 s62, 31
	s_cselect_b32 s65, s64, s29
	s_cselect_b32 s64, s63, s28
	s_waitcnt vmcnt(0)
	s_waitcnt lgkmcnt(0)
	s_barrier
	s_cselect_b32 s69, s69, s31
	s_cselect_b32 s68, s68, s30
	ds_read_b128 v[152:155], v150
	v_add_u32_e32 v151, v145, v136
	ds_read_b128 v[156:159], v151
	s_mov_b32 m0, s40
	v_mfma_f32_16x16x32_bf16 v[28:31], v[160:163], v[176:179], v[28:31]
	global_load_lds_dwordx4 v128, s[68:69]
	v_mfma_f32_16x16x32_bf16 v[12:15], v[160:163], v[180:183], v[12:15]
	ds_read_b128 v[160:163], v150 offset:2048
	v_mfma_f32_16x16x32_bf16 v[24:27], v[164:167], v[176:179], v[24:27]
	s_mov_b32 m0, s42
	v_mfma_f32_16x16x32_bf16 v[4:7], v[164:167], v[180:183], v[4:7]
	global_load_lds_dwordx4 v130, s[68:69]
	v_add_u32_e32 v151, v145, v137
	ds_read_b128 v[164:167], v151
	v_mfma_f32_16x16x32_bf16 v[20:23], v[168:171], v[176:179], v[20:23]
	v_mfma_f32_16x16x32_bf16 v[8:11], v[168:171], v[180:183], v[8:11]
	ds_read_b128 v[168:171], v150 offset:4096
	s_mov_b32 m0, s44
	v_mfma_f32_16x16x32_bf16 v[16:19], v[172:175], v[176:179], v[16:19]
	global_load_lds_dwordx4 v132, s[68:69]
	v_mfma_f32_16x16x32_bf16 v[0:3], v[172:175], v[180:183], v[0:3]
	ds_read_b128 v[172:175], v150 offset:6144
	v_add_u32_e32 v151, v145, v138
	ds_read_b128 v[176:179], v151
	v_add_u32_e32 v151, v145, v139
	ds_read_b128 v[180:183], v151
	s_waitcnt lgkmcnt(6)
	v_mfma_f32_16x16x32_bf16 v[124:127], v[152:155], v[156:159], v[124:127]
	s_waitcnt lgkmcnt(5)
	s_mov_b32 m0, s46
	v_mfma_f32_16x16x32_bf16 v[120:123], v[160:163], v[156:159], v[120:123]
	global_load_lds_dwordx4 v146, s[68:69]
	s_waitcnt lgkmcnt(4)
	v_mfma_f32_16x16x32_bf16 v[108:111], v[152:155], v[164:167], v[108:111]
	v_mfma_f32_16x16x32_bf16 v[104:107], v[160:163], v[164:167], v[104:107]
	s_waitcnt lgkmcnt(3)
	s_mov_b32 m0, s1
	v_mfma_f32_16x16x32_bf16 v[116:119], v[168:171], v[156:159], v[116:119]
	global_load_lds_dwordx4 v128, s[64:65]
	v_mfma_f32_16x16x32_bf16 v[100:103], v[168:171], v[164:167], v[100:103]
	s_waitcnt lgkmcnt(2)
	v_mfma_f32_16x16x32_bf16 v[112:115], v[172:175], v[156:159], v[112:115]
	v_add_u32_e32 v151, v145, v140
	ds_read_b128 v[156:159], v151
	s_mov_b32 m0, s41
	v_mfma_f32_16x16x32_bf16 v[96:99], v[172:175], v[164:167], v[96:99]
	global_load_lds_dwordx4 v130, s[64:65]
	v_add_u32_e32 v151, v145, v141
	ds_read_b128 v[164:167], v151
	s_waitcnt lgkmcnt(3)
	v_mfma_f32_16x16x32_bf16 v[92:95], v[152:155], v[176:179], v[92:95]
	v_mfma_f32_16x16x32_bf16 v[88:91], v[160:163], v[176:179], v[88:91]
	s_mov_b32 m0, s43
	v_mfma_f32_16x16x32_bf16 v[84:87], v[168:171], v[176:179], v[84:87]
	global_load_lds_dwordx4 v132, s[64:65]
	v_mfma_f32_16x16x32_bf16 v[80:83], v[172:175], v[176:179], v[80:83]
	v_add_u32_e32 v151, v145, v142
	ds_read_b128 v[176:179], v151
	s_waitcnt lgkmcnt(3)
	v_mfma_f32_16x16x32_bf16 v[76:79], v[152:155], v[180:183], v[76:79]
	s_mov_b32 m0, s45
	v_mfma_f32_16x16x32_bf16 v[72:75], v[160:163], v[180:183], v[72:75]
	global_load_lds_dwordx4 v146, s[64:65]
	v_mfma_f32_16x16x32_bf16 v[68:71], v[168:171], v[180:183], v[68:71]
	v_mfma_f32_16x16x32_bf16 v[64:67], v[172:175], v[180:183], v[64:67]
	v_add_u32_e32 v151, v145, v143
	ds_read_b128 v[180:183], v151
	s_waitcnt lgkmcnt(3)
	v_mfma_f32_16x16x32_bf16 v[56:59], v[160:163], v[156:159], v[56:59]
	s_waitcnt lgkmcnt(2)
	v_mfma_f32_16x16x32_bf16 v[40:43], v[160:163], v[164:167], v[40:43]
	s_waitcnt lgkmcnt(1)
	v_mfma_f32_16x16x32_bf16 v[24:27], v[160:163], v[176:179], v[24:27]
	s_waitcnt lgkmcnt(0)
	v_mfma_f32_16x16x32_bf16 v[4:7], v[160:163], v[180:183], v[4:7]
	ds_read_b128 v[160:163], v150 offset:1024
	v_mfma_f32_16x16x32_bf16 v[60:63], v[152:155], v[156:159], v[60:63]
	v_mfma_f32_16x16x32_bf16 v[44:47], v[152:155], v[164:167], v[44:47]
	v_mfma_f32_16x16x32_bf16 v[28:31], v[152:155], v[176:179], v[28:31]
	v_mfma_f32_16x16x32_bf16 v[12:15], v[152:155], v[180:183], v[12:15]
	v_add_u32_e32 v151, v149, v136
	ds_read_b128 v[152:155], v151
	v_mfma_f32_16x16x32_bf16 v[36:39], v[168:171], v[164:167], v[36:39]
	v_mfma_f32_16x16x32_bf16 v[32:35], v[172:175], v[164:167], v[32:35]
	ds_read_b128 v[164:167], v150 offset:3072
	v_mfma_f32_16x16x32_bf16 v[52:55], v[168:171], v[156:159], v[52:55]
	v_mfma_f32_16x16x32_bf16 v[48:51], v[172:175], v[156:159], v[48:51]
	v_add_u32_e32 v151, v149, v137
	ds_read_b128 v[156:159], v151
	v_mfma_f32_16x16x32_bf16 v[20:23], v[168:171], v[176:179], v[20:23]
	v_mfma_f32_16x16x32_bf16 v[16:19], v[172:175], v[176:179], v[16:19]
	v_add_u32_e32 v151, v149, v138
	ds_read_b128 v[176:179], v151
	v_mfma_f32_16x16x32_bf16 v[8:11], v[168:171], v[180:183], v[8:11]
	ds_read_b128 v[168:171], v150 offset:5120
	v_mfma_f32_16x16x32_bf16 v[0:3], v[172:175], v[180:183], v[0:3]
	ds_read_b128 v[172:175], v150 offset:7168
	v_add_u32_e32 v151, v149, v139
	ds_read_b128 v[180:183], v151
	s_waitcnt lgkmcnt(6)
	v_mfma_f32_16x16x32_bf16 v[124:127], v[160:163], v[152:155], v[124:127]
	s_waitcnt lgkmcnt(5)
	v_mfma_f32_16x16x32_bf16 v[120:123], v[164:167], v[152:155], v[120:123]
	s_waitcnt lgkmcnt(4)
	v_mfma_f32_16x16x32_bf16 v[108:111], v[160:163], v[156:159], v[108:111]
	v_mfma_f32_16x16x32_bf16 v[104:107], v[164:167], v[156:159], v[104:107]
	s_waitcnt lgkmcnt(3)
	v_mfma_f32_16x16x32_bf16 v[92:95], v[160:163], v[176:179], v[92:95]
	v_mfma_f32_16x16x32_bf16 v[88:91], v[164:167], v[176:179], v[88:91]
	s_waitcnt lgkmcnt(2)
	v_mfma_f32_16x16x32_bf16 v[116:119], v[168:171], v[152:155], v[116:119]
	s_waitcnt lgkmcnt(1)
	v_mfma_f32_16x16x32_bf16 v[112:115], v[172:175], v[152:155], v[112:115]
	v_add_u32_e32 v151, v149, v140
	ds_read_b128 v[152:155], v151
	v_mfma_f32_16x16x32_bf16 v[100:103], v[168:171], v[156:159], v[100:103]
	v_mfma_f32_16x16x32_bf16 v[96:99], v[172:175], v[156:159], v[96:99]
	v_add_u32_e32 v151, v149, v141
	ds_read_b128 v[156:159], v151
	v_mfma_f32_16x16x32_bf16 v[84:87], v[168:171], v[176:179], v[84:87]
	v_mfma_f32_16x16x32_bf16 v[80:83], v[172:175], v[176:179], v[80:83]
	v_add_u32_e32 v151, v149, v142
	ds_read_b128 v[176:179], v151
	s_waitcnt lgkmcnt(3)
	v_mfma_f32_16x16x32_bf16 v[76:79], v[160:163], v[180:183], v[76:79]
	v_mfma_f32_16x16x32_bf16 v[72:75], v[164:167], v[180:183], v[72:75]
	v_mfma_f32_16x16x32_bf16 v[68:71], v[168:171], v[180:183], v[68:71]
	v_mfma_f32_16x16x32_bf16 v[64:67], v[172:175], v[180:183], v[64:67]
	v_add_u32_e32 v151, v149, v143
	ds_read_b128 v[180:183], v151
	s_waitcnt lgkmcnt(3)
	v_mfma_f32_16x16x32_bf16 v[60:63], v[160:163], v[152:155], v[60:63]
	v_mfma_f32_16x16x32_bf16 v[56:59], v[164:167], v[152:155], v[56:59]
	v_mfma_f32_16x16x32_bf16 v[52:55], v[168:171], v[152:155], v[52:55]
	v_mfma_f32_16x16x32_bf16 v[48:51], v[172:175], v[152:155], v[48:51]
	s_waitcnt lgkmcnt(2)
	v_mfma_f32_16x16x32_bf16 v[44:47], v[160:163], v[156:159], v[44:47]
	v_mfma_f32_16x16x32_bf16 v[40:43], v[164:167], v[156:159], v[40:43]
	v_mfma_f32_16x16x32_bf16 v[36:39], v[168:171], v[156:159], v[36:39]
	v_mfma_f32_16x16x32_bf16 v[32:35], v[172:175], v[156:159], v[32:35]
	s_waitcnt vmcnt(0)
	s_add_u32 s26, s26, 0x100
	s_addc_u32 s27, s27, 0
	s_add_i32 s62, s62, 2
	s_cmpk_lg_i32 s26, 0x1000
	s_waitcnt lgkmcnt(0)
	s_barrier
	s_cbranch_scc1 .LBB0_789
	v_mfma_f32_16x16x32_bf16 v[28:31], v[160:163], v[176:179], v[28:31]
	v_mfma_f32_16x16x32_bf16 v[12:15], v[160:163], v[180:183], v[12:15]
	v_mfma_f32_16x16x32_bf16 v[24:27], v[164:167], v[176:179], v[24:27]
	v_mfma_f32_16x16x32_bf16 v[4:7], v[164:167], v[180:183], v[4:7]
	v_mfma_f32_16x16x32_bf16 v[20:23], v[168:171], v[176:179], v[20:23]
	v_mfma_f32_16x16x32_bf16 v[8:11], v[168:171], v[180:183], v[8:11]
	v_mfma_f32_16x16x32_bf16 v[16:19], v[172:175], v[176:179], v[16:19]
	v_mfma_f32_16x16x32_bf16 v[0:3], v[172:175], v[180:183], v[0:3]
	s_nop 15
	s_nop 15
	v_mov_b32_e32 v128, v184
	s_movk_i32 s3, 0xff80
	v_and_b32_e32 v130, 15, v128
	v_ashrrev_i32_e32 v131, 1, v128
	v_and_or_b32 v141, v131, s3, v130
	v_lshl_add_u32 v140, v141, 2, v202
	ds_read_b32 v134, v140
	s_lshl_b32 s2, s0, 8
	v_add_u32_e32 v130, s39, v141
	v_and_b32_e32 v129, 0xc0, v128
	s_cmp_gt_i32 s0, 7
	v_lshrrev_b32_e32 v128, 2, v128
	v_ashrrev_i32_e32 v131, 31, v130
	s_cselect_b64 s[0:1], -1, 0
	v_and_b32_e32 v128, 12, v128
	v_lshlrev_b64 v[138:139], 12, v[130:131]
	v_or3_b32 v128, v129, s2, v128
	v_lshl_add_u64 v[132:133], s[20:21], 0, v[138:139]
	s_waitcnt lgkmcnt(0)
	v_pk_mul_f32 v[136:137], v[124:125], v[134:135] op_sel_hi:[1,0]
	v_pk_mul_f32 v[126:127], v[126:127], v[134:135] op_sel_hi:[1,0]
	s_mov_b64 s[2:3], -1
	s_and_b64 vcc, exec, s[0:1]
	s_cbranch_vccz .LBB0_792
	v_mov_b32_e32 v129, v147
	v_cvt_pk_bf16_f32 v124, v136, v137
	v_cvt_pk_bf16_f32 v125, v126, v127
	v_lshl_add_u64 v[142:143], v[128:129], 1, v[132:133]
	global_store_dwordx2 v[142:143], v[124:125], off offset:-4096
	s_mov_b64 s[2:3], 0
